# GEMM K loops: per-cluster s_setprio 1/0 toggling removed; one static priority raise for waves 4-7 (the half that arrives second) during the K loops
# baseline (speedup 1.0000x reference)
.LBB0_189:
	s_cmp_lt_u32 s85, 0x100
	s_cbranch_scc1 .Lprio_189
	s_setprio 1
.Lprio_189:
	s_add_u32 s1, s68, 0xfff80080
	s_addc_u32 s2, s69, -1
	s_add_i32 s3, 0, 0x10000
	v_add_u32_e32 v154, s3, v143
	ds_read_b128 v[138:141], v154
	ds_read_b128 v[146:149], v154 offset:1024
	ds_read_b128 v[150:153], v154 offset:2048
	ds_read_b128 v[154:157], v154 offset:3072
	s_cmp_eq_u32 s87, 28
	s_cselect_b32 s73, s43, s2
	s_cselect_b32 s72, s81, s1
	s_cselect_b32 s71, s41, s86
	s_cselect_b32 s70, s82, s83
	v_lshl_add_u64 v[174:175], s[68:69], 0, v[134:135]
	s_add_i32 m0, s60, 0xc000
	ds_read_b128 v[158:161], v145
	ds_read_b128 v[162:165], v145 offset:1024
	ds_read_b128 v[166:169], v145 offset:2048
	ds_read_b128 v[170:173], v145 offset:3072
	ds_read_b128 v[182:185], v145 offset:4096
	ds_read_b128 v[206:209], v145 offset:5120
	ds_read_b128 v[210:213], v145 offset:6144
	ds_read_b128 v[214:217], v145 offset:7168
	global_load_lds_dwordx4 v[174:175], off
	v_lshl_add_u64 v[174:175], s[68:69], 0, v[136:137]
	s_add_i32 m0, s60, 0xe000
	s_nop 0
	global_load_lds_dwordx4 v[174:175], off
	s_waitcnt lgkmcnt(8)
	s_barrier
	s_waitcnt lgkmcnt(0)
	s_waitcnt lgkmcnt(0)
	v_mfma_f32_16x16x32_bf16 v[124:127], v[138:141], v[158:161], v[124:127]
	v_mfma_f32_16x16x32_bf16 v[120:123], v[150:153], v[158:161], v[120:123]
	v_mfma_f32_16x16x32_bf16 v[116:119], v[138:141], v[166:169], v[116:119]
	v_mfma_f32_16x16x32_bf16 v[108:111], v[150:153], v[166:169], v[108:111]
	v_mfma_f32_16x16x32_bf16 v[100:103], v[138:141], v[182:185], v[100:103]
	v_mfma_f32_16x16x32_bf16 v[92:95], v[150:153], v[182:185], v[92:95]
	v_mfma_f32_16x16x32_bf16 v[84:87], v[138:141], v[210:213], v[84:87]
	v_mfma_f32_16x16x32_bf16 v[76:79], v[150:153], v[210:213], v[76:79]
	v_mfma_f32_16x16x32_bf16 v[124:127], v[146:149], v[162:165], v[124:127]
	v_mfma_f32_16x16x32_bf16 v[120:123], v[154:157], v[162:165], v[120:123]
	v_mfma_f32_16x16x32_bf16 v[116:119], v[146:149], v[170:173], v[116:119]
	v_mfma_f32_16x16x32_bf16 v[108:111], v[154:157], v[170:173], v[108:111]
	v_mfma_f32_16x16x32_bf16 v[100:103], v[146:149], v[206:209], v[100:103]
	v_mfma_f32_16x16x32_bf16 v[92:95], v[154:157], v[206:209], v[92:95]
	v_mfma_f32_16x16x32_bf16 v[84:87], v[146:149], v[214:217], v[84:87]
	v_mfma_f32_16x16x32_bf16 v[76:79], v[154:157], v[214:217], v[76:79]
	s_barrier
	s_add_i32 s1, 0, 0x14000
	v_add_u32_e32 v174, s1, v143
	s_add_i32 s2, s3, s53
	ds_read_b128 v[218:221], v174
	ds_read_b128 v[222:225], v174 offset:1024
	ds_read_b128 v[226:229], v174 offset:2048
	ds_read_b128 v[230:233], v174 offset:3072
	v_lshl_add_u64 v[174:175], s[70:71], 0, v[176:177]
	s_mov_b32 m0, s2
	v_lshl_add_u64 v[186:187], s[70:71], 0, v[128:129]
	global_load_lds_dwordx4 v[174:175], off
	s_add_i32 m0, s2, 0x2000
	s_nop 0
	global_load_lds_dwordx4 v[186:187], off
	s_barrier
	s_waitcnt lgkmcnt(0)
	s_waitcnt lgkmcnt(0)
	v_mfma_f32_16x16x32_bf16 v[112:115], v[218:221], v[158:161], v[112:115]
	v_mfma_f32_16x16x32_bf16 v[104:107], v[226:229], v[158:161], v[104:107]
	v_mfma_f32_16x16x32_bf16 v[96:99], v[218:221], v[166:169], v[96:99]
	v_mfma_f32_16x16x32_bf16 v[88:91], v[226:229], v[166:169], v[88:91]
	v_mfma_f32_16x16x32_bf16 v[80:83], v[218:221], v[182:185], v[80:83]
	v_mfma_f32_16x16x32_bf16 v[72:75], v[226:229], v[182:185], v[72:75]
	v_mfma_f32_16x16x32_bf16 v[68:71], v[218:221], v[210:213], v[68:71]
	v_mfma_f32_16x16x32_bf16 v[64:67], v[226:229], v[210:213], v[64:67]
	v_mfma_f32_16x16x32_bf16 v[112:115], v[222:225], v[162:165], v[112:115]
	v_mfma_f32_16x16x32_bf16 v[104:107], v[230:233], v[162:165], v[104:107]
	v_mfma_f32_16x16x32_bf16 v[96:99], v[222:225], v[170:173], v[96:99]
	v_mfma_f32_16x16x32_bf16 v[88:91], v[230:233], v[170:173], v[88:91]
	v_mfma_f32_16x16x32_bf16 v[80:83], v[222:225], v[206:209], v[80:83]
	v_mfma_f32_16x16x32_bf16 v[72:75], v[230:233], v[206:209], v[72:75]
	v_mfma_f32_16x16x32_bf16 v[68:71], v[222:225], v[214:217], v[68:71]
	v_mfma_f32_16x16x32_bf16 v[64:67], v[230:233], v[214:217], v[64:67]
	s_mov_b32 m0, s60
	v_lshl_add_u64 v[200:201], s[72:73], 0, v[132:133]
	s_barrier
	ds_read_b128 v[158:161], v145 offset:16384
	ds_read_b128 v[162:165], v145 offset:17408
	ds_read_b128 v[166:169], v145 offset:18432
	ds_read_b128 v[170:173], v145 offset:19456
	ds_read_b128 v[182:185], v145 offset:20480
	ds_read_b128 v[206:209], v145 offset:21504
	ds_read_b128 v[210:213], v145 offset:22528
	ds_read_b128 v[214:217], v145 offset:23552
	global_load_lds_dwordx4 v[200:201], off
	v_lshl_add_u64 v[202:203], s[72:73], 0, v[130:131]
	s_mov_b32 m0, s61
	s_nop 0
	global_load_lds_dwordx4 v[202:203], off
	s_barrier
	s_waitcnt lgkmcnt(0)
	s_waitcnt lgkmcnt(0)
	v_mfma_f32_16x16x32_bf16 v[60:63], v[138:141], v[158:161], v[60:63]
	v_mfma_f32_16x16x32_bf16 v[56:59], v[150:153], v[158:161], v[56:59]
	v_mfma_f32_16x16x32_bf16 v[52:55], v[138:141], v[166:169], v[52:55]
	v_mfma_f32_16x16x32_bf16 v[44:47], v[150:153], v[166:169], v[44:47]
	v_mfma_f32_16x16x32_bf16 v[36:39], v[138:141], v[182:185], v[36:39]
	v_mfma_f32_16x16x32_bf16 v[28:31], v[150:153], v[182:185], v[28:31]
	v_mfma_f32_16x16x32_bf16 v[20:23], v[138:141], v[210:213], v[20:23]
	v_mfma_f32_16x16x32_bf16 v[12:15], v[150:153], v[210:213], v[12:15]
	v_mfma_f32_16x16x32_bf16 v[60:63], v[146:149], v[162:165], v[60:63]
	v_mfma_f32_16x16x32_bf16 v[56:59], v[154:157], v[162:165], v[56:59]
	v_mfma_f32_16x16x32_bf16 v[52:55], v[146:149], v[170:173], v[52:55]
	v_mfma_f32_16x16x32_bf16 v[44:47], v[154:157], v[170:173], v[44:47]
	v_mfma_f32_16x16x32_bf16 v[36:39], v[146:149], v[206:209], v[36:39]
	v_mfma_f32_16x16x32_bf16 v[28:31], v[154:157], v[206:209], v[28:31]
	v_mfma_f32_16x16x32_bf16 v[20:23], v[146:149], v[214:217], v[20:23]
	v_mfma_f32_16x16x32_bf16 v[12:15], v[154:157], v[214:217], v[12:15]
	s_barrier
	s_add_u32 s2, s70, 0x80000
	s_addc_u32 s3, s71, 0
	s_add_i32 s1, s1, s53
	v_lshl_add_u64 v[138:139], s[2:3], 0, v[176:177]
	s_mov_b32 m0, s1
	s_nop 0
	global_load_lds_dwordx4 v[138:139], off
	v_lshl_add_u64 v[138:139], s[2:3], 0, v[128:129]
	s_add_i32 m0, s1, 0x2000
	s_nop 0
	global_load_lds_dwordx4 v[138:139], off
	s_waitcnt vmcnt(6)
	s_barrier
	v_mfma_f32_16x16x32_bf16 v[48:51], v[218:221], v[158:161], v[48:51]
	v_mfma_f32_16x16x32_bf16 v[40:43], v[226:229], v[158:161], v[40:43]
	v_mfma_f32_16x16x32_bf16 v[32:35], v[218:221], v[166:169], v[32:35]
	v_mfma_f32_16x16x32_bf16 v[24:27], v[226:229], v[166:169], v[24:27]
	v_mfma_f32_16x16x32_bf16 v[16:19], v[218:221], v[182:185], v[16:19]
	v_mfma_f32_16x16x32_bf16 v[8:11], v[226:229], v[182:185], v[8:11]
	v_mfma_f32_16x16x32_bf16 v[4:7], v[218:221], v[210:213], v[4:7]
	v_mfma_f32_16x16x32_bf16 v[0:3], v[226:229], v[210:213], v[0:3]
	v_mfma_f32_16x16x32_bf16 v[48:51], v[222:225], v[162:165], v[48:51]
	v_mfma_f32_16x16x32_bf16 v[40:43], v[230:233], v[162:165], v[40:43]
	v_mfma_f32_16x16x32_bf16 v[32:35], v[222:225], v[170:173], v[32:35]
	v_mfma_f32_16x16x32_bf16 v[24:27], v[230:233], v[170:173], v[24:27]
	v_mfma_f32_16x16x32_bf16 v[16:19], v[222:225], v[206:209], v[16:19]
	v_mfma_f32_16x16x32_bf16 v[8:11], v[230:233], v[206:209], v[8:11]
	v_mfma_f32_16x16x32_bf16 v[4:7], v[222:225], v[214:217], v[4:7]
	v_mfma_f32_16x16x32_bf16 v[0:3], v[230:233], v[214:217], v[0:3]
	s_add_i32 s1, 0, 0x18000
	v_add_u32_e32 v154, s1, v143
	s_barrier
	ds_read_b128 v[138:141], v154
	ds_read_b128 v[146:149], v154 offset:1024
	ds_read_b128 v[150:153], v154 offset:2048
	ds_read_b128 v[154:157], v154 offset:3072
	s_add_u32 s2, s72, 0x80000
	s_addc_u32 s3, s73, 0
	s_mov_b32 m0, s74
	v_lshl_add_u64 v[204:205], s[2:3], 0, v[132:133]
	ds_read_b128 v[158:161], v145 offset:32768
	ds_read_b128 v[162:165], v145 offset:33792
	ds_read_b128 v[166:169], v145 offset:34816
	ds_read_b128 v[170:173], v145 offset:35840
	ds_read_b128 v[182:185], v145 offset:36864
	ds_read_b128 v[206:209], v145 offset:37888
	ds_read_b128 v[210:213], v145 offset:38912
	ds_read_b128 v[214:217], v145 offset:39936
	global_load_lds_dwordx4 v[204:205], off
	v_lshl_add_u64 v[204:205], s[2:3], 0, v[130:131]
	s_mov_b32 m0, s75
	s_nop 0
	global_load_lds_dwordx4 v[204:205], off
	s_waitcnt lgkmcnt(8)
	s_barrier
	s_waitcnt lgkmcnt(0)
	s_waitcnt lgkmcnt(0)
	v_mfma_f32_16x16x32_bf16 v[124:127], v[138:141], v[158:161], v[124:127]
	v_mfma_f32_16x16x32_bf16 v[120:123], v[150:153], v[158:161], v[120:123]
	v_mfma_f32_16x16x32_bf16 v[116:119], v[138:141], v[166:169], v[116:119]
	v_mfma_f32_16x16x32_bf16 v[108:111], v[150:153], v[166:169], v[108:111]
	v_mfma_f32_16x16x32_bf16 v[100:103], v[138:141], v[182:185], v[100:103]
	v_mfma_f32_16x16x32_bf16 v[92:95], v[150:153], v[182:185], v[92:95]
	v_mfma_f32_16x16x32_bf16 v[84:87], v[138:141], v[210:213], v[84:87]
	v_mfma_f32_16x16x32_bf16 v[76:79], v[150:153], v[210:213], v[76:79]
	v_mfma_f32_16x16x32_bf16 v[124:127], v[146:149], v[162:165], v[124:127]
	v_mfma_f32_16x16x32_bf16 v[120:123], v[154:157], v[162:165], v[120:123]
	v_mfma_f32_16x16x32_bf16 v[116:119], v[146:149], v[170:173], v[116:119]
	v_mfma_f32_16x16x32_bf16 v[108:111], v[154:157], v[170:173], v[108:111]
	v_mfma_f32_16x16x32_bf16 v[100:103], v[146:149], v[206:209], v[100:103]
	v_mfma_f32_16x16x32_bf16 v[92:95], v[154:157], v[206:209], v[92:95]
	v_mfma_f32_16x16x32_bf16 v[84:87], v[146:149], v[214:217], v[84:87]
	v_mfma_f32_16x16x32_bf16 v[76:79], v[154:157], v[214:217], v[76:79]
	s_barrier
	s_add_i32 s12, 0, 0x1c000
	s_add_i32 s1, s1, s53
	v_add_u32_e32 v188, s12, v143
	v_lshl_add_u64 v[174:175], v[174:175], 0, s[20:21]
	s_mov_b32 m0, s1
	ds_read_b128 v[218:221], v188
	ds_read_b128 v[222:225], v188 offset:1024
	ds_read_b128 v[226:229], v188 offset:2048
	ds_read_b128 v[230:233], v188 offset:3072
	global_load_lds_dwordx4 v[174:175], off
	v_lshl_add_u64 v[174:175], v[186:187], 0, s[20:21]
	s_add_i32 m0, s1, 0x2000
	s_nop 0
	global_load_lds_dwordx4 v[174:175], off
	s_barrier
	s_waitcnt lgkmcnt(0)
	s_waitcnt lgkmcnt(0)
	v_mfma_f32_16x16x32_bf16 v[112:115], v[218:221], v[158:161], v[112:115]
	v_mfma_f32_16x16x32_bf16 v[104:107], v[226:229], v[158:161], v[104:107]
	v_mfma_f32_16x16x32_bf16 v[96:99], v[218:221], v[166:169], v[96:99]
	v_mfma_f32_16x16x32_bf16 v[88:91], v[226:229], v[166:169], v[88:91]
	v_mfma_f32_16x16x32_bf16 v[80:83], v[218:221], v[182:185], v[80:83]
	v_mfma_f32_16x16x32_bf16 v[72:75], v[226:229], v[182:185], v[72:75]
	v_mfma_f32_16x16x32_bf16 v[68:71], v[218:221], v[210:213], v[68:71]
	v_mfma_f32_16x16x32_bf16 v[64:67], v[226:229], v[210:213], v[64:67]
	v_mfma_f32_16x16x32_bf16 v[112:115], v[222:225], v[162:165], v[112:115]
	v_mfma_f32_16x16x32_bf16 v[104:107], v[230:233], v[162:165], v[104:107]
	v_mfma_f32_16x16x32_bf16 v[96:99], v[222:225], v[170:173], v[96:99]
	v_mfma_f32_16x16x32_bf16 v[88:91], v[230:233], v[170:173], v[88:91]
	v_mfma_f32_16x16x32_bf16 v[80:83], v[222:225], v[206:209], v[80:83]
	v_mfma_f32_16x16x32_bf16 v[72:75], v[230:233], v[206:209], v[72:75]
	v_mfma_f32_16x16x32_bf16 v[68:71], v[222:225], v[214:217], v[68:71]
	v_mfma_f32_16x16x32_bf16 v[64:67], v[230:233], v[214:217], v[64:67]
	s_mov_b32 m0, s76
	v_lshl_add_u64 v[174:175], v[200:201], 0, s[20:21]
	s_barrier
	ds_read_b128 v[158:161], v145 offset:49152
	ds_read_b128 v[162:165], v145 offset:50176
	ds_read_b128 v[166:169], v145 offset:51200
	ds_read_b128 v[170:173], v145 offset:52224
	ds_read_b128 v[182:185], v145 offset:53248
	ds_read_b128 v[206:209], v145 offset:54272
	ds_read_b128 v[210:213], v145 offset:55296
	ds_read_b128 v[214:217], v145 offset:56320
	global_load_lds_dwordx4 v[174:175], off
	v_lshl_add_u64 v[174:175], v[202:203], 0, s[20:21]
	s_mov_b32 m0, s77
	s_nop 0
	global_load_lds_dwordx4 v[174:175], off
	s_barrier
	s_waitcnt lgkmcnt(0)
	s_waitcnt lgkmcnt(0)
	v_mfma_f32_16x16x32_bf16 v[60:63], v[138:141], v[158:161], v[60:63]
	v_mfma_f32_16x16x32_bf16 v[56:59], v[150:153], v[158:161], v[56:59]
	v_mfma_f32_16x16x32_bf16 v[52:55], v[138:141], v[166:169], v[52:55]
	v_mfma_f32_16x16x32_bf16 v[44:47], v[150:153], v[166:169], v[44:47]
	v_mfma_f32_16x16x32_bf16 v[36:39], v[138:141], v[182:185], v[36:39]
	v_mfma_f32_16x16x32_bf16 v[28:31], v[150:153], v[182:185], v[28:31]
	v_mfma_f32_16x16x32_bf16 v[20:23], v[138:141], v[210:213], v[20:23]
	v_mfma_f32_16x16x32_bf16 v[12:15], v[150:153], v[210:213], v[12:15]
	v_mfma_f32_16x16x32_bf16 v[60:63], v[146:149], v[162:165], v[60:63]
	v_mfma_f32_16x16x32_bf16 v[56:59], v[154:157], v[162:165], v[56:59]
	v_mfma_f32_16x16x32_bf16 v[52:55], v[146:149], v[170:173], v[52:55]
	v_mfma_f32_16x16x32_bf16 v[44:47], v[154:157], v[170:173], v[44:47]
	v_mfma_f32_16x16x32_bf16 v[36:39], v[146:149], v[206:209], v[36:39]
	v_mfma_f32_16x16x32_bf16 v[28:31], v[154:157], v[206:209], v[28:31]
	v_mfma_f32_16x16x32_bf16 v[20:23], v[146:149], v[214:217], v[20:23]
	v_mfma_f32_16x16x32_bf16 v[12:15], v[154:157], v[214:217], v[12:15]
	s_barrier
	s_add_u32 s2, s70, 0x80080
	s_addc_u32 s3, s71, 0
	s_add_i32 s1, s12, s53
	v_lshl_add_u64 v[138:139], s[2:3], 0, v[176:177]
	s_mov_b32 m0, s1
	s_nop 0
	global_load_lds_dwordx4 v[138:139], off
	v_lshl_add_u64 v[138:139], s[2:3], 0, v[128:129]
	s_add_i32 m0, s1, 0x2000
	s_nop 0
	global_load_lds_dwordx4 v[138:139], off
	s_waitcnt vmcnt(6)
	s_barrier
	v_mfma_f32_16x16x32_bf16 v[48:51], v[218:221], v[158:161], v[48:51]
	v_mfma_f32_16x16x32_bf16 v[40:43], v[226:229], v[158:161], v[40:43]
	v_mfma_f32_16x16x32_bf16 v[32:35], v[218:221], v[166:169], v[32:35]
	v_mfma_f32_16x16x32_bf16 v[24:27], v[226:229], v[166:169], v[24:27]
	v_mfma_f32_16x16x32_bf16 v[16:19], v[218:221], v[182:185], v[16:19]
	v_mfma_f32_16x16x32_bf16 v[8:11], v[226:229], v[182:185], v[8:11]
	v_mfma_f32_16x16x32_bf16 v[4:7], v[218:221], v[210:213], v[4:7]
	v_mfma_f32_16x16x32_bf16 v[0:3], v[226:229], v[210:213], v[0:3]
	v_mfma_f32_16x16x32_bf16 v[48:51], v[222:225], v[162:165], v[48:51]
	v_mfma_f32_16x16x32_bf16 v[40:43], v[230:233], v[162:165], v[40:43]
	v_mfma_f32_16x16x32_bf16 v[32:35], v[222:225], v[170:173], v[32:35]
	v_mfma_f32_16x16x32_bf16 v[24:27], v[230:233], v[170:173], v[24:27]
	v_mfma_f32_16x16x32_bf16 v[16:19], v[222:225], v[206:209], v[16:19]
	v_mfma_f32_16x16x32_bf16 v[8:11], v[230:233], v[206:209], v[8:11]
	v_mfma_f32_16x16x32_bf16 v[4:7], v[222:225], v[214:217], v[4:7]
	v_mfma_f32_16x16x32_bf16 v[0:3], v[230:233], v[214:217], v[0:3]
	s_add_i32 s87, s87, 2
	s_add_u32 s68, s68, 0x100
	s_addc_u32 s69, s69, 0
	s_add_u32 s83, s83, 0x100
	s_addc_u32 s86, s86, 0
	s_cmp_gt_u32 s87, 29
	s_barrier
	s_cbranch_scc0 .LBB0_189
	s_setprio 0
	s_cmp_eq_u32 s88, 0
	s_cbranch_scc1 .Lrs_skip
	s_cmp_lg_u32 s89, 0
	s_cbranch_scc1 .Lrs_mul
	v_readlane_b32 s98, v255, 1
	v_readlane_b32 s99, v255, 2
	v_lshl_add_u32 v200, s80, 8, v142
	v_bfe_u32 v201, v144, 3, 2
	v_lshlrev_b32_e32 v201, 5, v201
	v_lshl_add_u32 v200, v200, 7, v201
	v_add_u32_e32 v201, 0x1000, v200
	v_add_u32_e32 v202, 0x4000, v200
	v_add_u32_e32 v203, 0x5000, v200
	v_mbcnt_lo_u32_b32 v204, -1, 0
	v_mbcnt_hi_u32_b32 v204, -1, v204
	v_xor_b32_e32 v205, 16, v204
	v_xor_b32_e32 v204, 32, v204
	v_lshlrev_b32_e32 v205, 2, v205
	v_lshlrev_b32_e32 v204, 2, v204
	global_load_dwordx4 v[208:211], v200, s[98:99]
	global_load_dwordx4 v[212:215], v200, s[98:99] offset:16
	global_load_dwordx4 v[216:219], v200, s[98:99] offset:2048
	global_load_dwordx4 v[220:223], v200, s[98:99] offset:2064
	global_load_dwordx4 v[224:227], v201, s[98:99]
	global_load_dwordx4 v[228:231], v201, s[98:99] offset:16
	global_load_dwordx4 v[232:235], v201, s[98:99] offset:2048
	global_load_dwordx4 v[236:239], v201, s[98:99] offset:2064
	s_waitcnt vmcnt(0)
	v_add_f32_e32 v208, v208, v209
	v_add_f32_e32 v210, v210, v211
	v_add_f32_e32 v212, v212, v213
	v_add_f32_e32 v214, v214, v215
	v_add_f32_e32 v208, v208, v210
	v_add_f32_e32 v212, v212, v214
	v_add_f32_e32 v190, v208, v212
	v_add_f32_e32 v216, v216, v217
	v_add_f32_e32 v218, v218, v219
	v_add_f32_e32 v220, v220, v221
	v_add_f32_e32 v222, v222, v223
	v_add_f32_e32 v216, v216, v218
	v_add_f32_e32 v220, v220, v222
	v_add_f32_e32 v191, v216, v220
	v_add_f32_e32 v224, v224, v225
	v_add_f32_e32 v226, v226, v227
	v_add_f32_e32 v228, v228, v229
	v_add_f32_e32 v230, v230, v231
	v_add_f32_e32 v224, v224, v226
	v_add_f32_e32 v228, v228, v230
	v_add_f32_e32 v192, v224, v228
	v_add_f32_e32 v232, v232, v233
	v_add_f32_e32 v234, v234, v235
	v_add_f32_e32 v236, v236, v237
	v_add_f32_e32 v238, v238, v239
	v_add_f32_e32 v232, v232, v234
	v_add_f32_e32 v236, v236, v238
	v_add_f32_e32 v194, v232, v236
	global_load_dwordx4 v[208:211], v202, s[98:99]
	global_load_dwordx4 v[212:215], v202, s[98:99] offset:16
	global_load_dwordx4 v[216:219], v202, s[98:99] offset:2048
	global_load_dwordx4 v[220:223], v202, s[98:99] offset:2064
	global_load_dwordx4 v[224:227], v203, s[98:99]
	global_load_dwordx4 v[228:231], v203, s[98:99] offset:16
	global_load_dwordx4 v[232:235], v203, s[98:99] offset:2048
	global_load_dwordx4 v[236:239], v203, s[98:99] offset:2064
	s_waitcnt vmcnt(0)
	v_add_f32_e32 v208, v208, v209
	v_add_f32_e32 v210, v210, v211
	v_add_f32_e32 v212, v212, v213
	v_add_f32_e32 v214, v214, v215
	v_add_f32_e32 v208, v208, v210
	v_add_f32_e32 v212, v212, v214
	v_add_f32_e32 v195, v208, v212
	v_add_f32_e32 v216, v216, v217
	v_add_f32_e32 v218, v218, v219
	v_add_f32_e32 v220, v220, v221
	v_add_f32_e32 v222, v222, v223
	v_add_f32_e32 v216, v216, v218
	v_add_f32_e32 v220, v220, v222
	v_add_f32_e32 v196, v216, v220
	v_add_f32_e32 v224, v224, v225
	v_add_f32_e32 v226, v226, v227
	v_add_f32_e32 v228, v228, v229
	v_add_f32_e32 v230, v230, v231
	v_add_f32_e32 v224, v224, v226
	v_add_f32_e32 v228, v228, v230
	v_add_f32_e32 v198, v224, v228
	v_add_f32_e32 v232, v232, v233
	v_add_f32_e32 v234, v234, v235
	v_add_f32_e32 v236, v236, v237
	v_add_f32_e32 v238, v238, v239
	v_add_f32_e32 v232, v232, v234
	v_add_f32_e32 v236, v236, v238
	v_add_f32_e32 v248, v232, v236
	ds_bpermute_b32 v240, v205, v190
	ds_bpermute_b32 v241, v205, v191
	ds_bpermute_b32 v242, v205, v192
	ds_bpermute_b32 v243, v205, v194
	ds_bpermute_b32 v244, v205, v195
	ds_bpermute_b32 v245, v205, v196
	ds_bpermute_b32 v246, v205, v198
	ds_bpermute_b32 v247, v205, v248
	s_waitcnt lgkmcnt(0)
	v_add_f32_e32 v190, v190, v240
	v_add_f32_e32 v191, v191, v241
	v_add_f32_e32 v192, v192, v242
	v_add_f32_e32 v194, v194, v243
	v_add_f32_e32 v195, v195, v244
	v_add_f32_e32 v196, v196, v245
	v_add_f32_e32 v198, v198, v246
	v_add_f32_e32 v248, v248, v247
	ds_bpermute_b32 v240, v204, v190
	ds_bpermute_b32 v241, v204, v191
	ds_bpermute_b32 v242, v204, v192
	ds_bpermute_b32 v243, v204, v194
	ds_bpermute_b32 v244, v204, v195
	ds_bpermute_b32 v245, v204, v196
	ds_bpermute_b32 v246, v204, v198
	ds_bpermute_b32 v247, v204, v248
	s_waitcnt lgkmcnt(0)
	v_add_f32_e32 v190, v190, v240
	v_add_f32_e32 v191, v191, v241
	v_add_f32_e32 v192, v192, v242
	v_add_f32_e32 v194, v194, v243
	v_add_f32_e32 v195, v195, v244
	v_add_f32_e32 v196, v196, v245
	v_add_f32_e32 v198, v198, v246
	v_add_f32_e32 v248, v248, v247
	v_mul_f32_e32 v190, 0x3a000000, v190
	v_add_f32_e32 v190, 0x358637bd, v190
	v_mul_f32_e32 v191, 0x3a000000, v191
	v_add_f32_e32 v191, 0x358637bd, v191
	v_mul_f32_e32 v192, 0x3a000000, v192
	v_add_f32_e32 v192, 0x358637bd, v192
	v_mul_f32_e32 v194, 0x3a000000, v194
	v_add_f32_e32 v194, 0x358637bd, v194
	v_mul_f32_e32 v195, 0x3a000000, v195
	v_add_f32_e32 v195, 0x358637bd, v195
	v_mul_f32_e32 v196, 0x3a000000, v196
	v_add_f32_e32 v196, 0x358637bd, v196
	v_mul_f32_e32 v198, 0x3a000000, v198
	v_add_f32_e32 v198, 0x358637bd, v198
	v_mul_f32_e32 v248, 0x3a000000, v248
	v_add_f32_e32 v248, 0x358637bd, v248
	v_rsq_f32_e32 v190, v190
	v_rsq_f32_e32 v191, v191
	v_rsq_f32_e32 v192, v192
	v_rsq_f32_e32 v194, v194
	v_rsq_f32_e32 v195, v195
	v_rsq_f32_e32 v196, v196
	v_rsq_f32_e32 v198, v198
	v_rsq_f32_e32 v248, v248
	s_mov_b32 s89, 1

.Lprio_326:
	s_add_u32 s1, s70, 0xfffe0080
	s_addc_u32 s2, s71, -1
	s_add_i32 s3, 0, 0x10000
	v_add_u32_e32 v182, s3, v153
	ds_read_b128 v[104:107], v182
	ds_read_b128 v[108:111], v182 offset:1024
	ds_read_b128 v[172:175], v182 offset:2048
	ds_read_b128 v[182:185], v182 offset:3072
	s_cmp_eq_u32 s89, 4
	s_cselect_b32 s75, s45, s2
	s_cselect_b32 s74, s83, s1
	s_cselect_b32 s73, s39, s88
	s_cselect_b32 s72, s86, s87
	v_lshl_add_u64 v[186:187], s[70:71], 0, v[148:149]
	s_add_i32 m0, s61, 0xc000
	ds_read_b128 v[206:209], v164
	ds_read_b128 v[210:213], v164 offset:1024
	ds_read_b128 v[214:217], v164 offset:2048
	ds_read_b128 v[218:221], v164 offset:3072
	ds_read_b128 v[222:225], v164 offset:4096
	ds_read_b128 v[226:229], v164 offset:5120
	ds_read_b128 v[230:233], v164 offset:6144
	ds_read_b128 v[234:237], v164 offset:7168
	global_load_lds_dwordx4 v[186:187], off
	v_lshl_add_u64 v[186:187], s[70:71], 0, v[150:151]
	s_add_i32 m0, s61, 0xe000
	s_nop 0
	global_load_lds_dwordx4 v[186:187], off
	s_waitcnt lgkmcnt(8)
	s_barrier
	s_waitcnt lgkmcnt(0)
	s_waitcnt lgkmcnt(0)
	v_mfma_f32_16x16x32_bf16 v[132:135], v[104:107], v[206:209], v[132:135]
	v_mfma_f32_16x16x32_bf16 v[128:131], v[172:175], v[206:209], v[128:131]
	v_mfma_f32_16x16x32_bf16 v[116:119], v[104:107], v[214:217], v[116:119]
	v_mfma_f32_16x16x32_bf16 v[112:115], v[172:175], v[214:217], v[112:115]
	v_mfma_f32_16x16x32_bf16 v[92:95], v[104:107], v[222:225], v[92:95]
	v_mfma_f32_16x16x32_bf16 v[88:91], v[172:175], v[222:225], v[88:91]
	v_mfma_f32_16x16x32_bf16 v[76:79], v[104:107], v[230:233], v[76:79]
	v_mfma_f32_16x16x32_bf16 v[72:75], v[172:175], v[230:233], v[72:75]
	v_mfma_f32_16x16x32_bf16 v[132:135], v[108:111], v[210:213], v[132:135]
	v_mfma_f32_16x16x32_bf16 v[128:131], v[182:185], v[210:213], v[128:131]
	v_mfma_f32_16x16x32_bf16 v[116:119], v[108:111], v[218:221], v[116:119]
	v_mfma_f32_16x16x32_bf16 v[112:115], v[182:185], v[218:221], v[112:115]
	v_mfma_f32_16x16x32_bf16 v[92:95], v[108:111], v[226:229], v[92:95]
	v_mfma_f32_16x16x32_bf16 v[88:91], v[182:185], v[226:229], v[88:91]
	v_mfma_f32_16x16x32_bf16 v[76:79], v[108:111], v[234:237], v[76:79]
	v_mfma_f32_16x16x32_bf16 v[72:75], v[182:185], v[234:237], v[72:75]
	s_barrier
	s_add_i32 s1, 0, 0x14000
	v_add_u32_e32 v186, s1, v153
	s_add_i32 s2, s3, s60
	ds_read_b128 v[238:241], v186
	ds_read_b128 v[242:245], v186 offset:1024
	ds_read_b128 v[246:249], v186 offset:2048
	ds_read_b128 v[200:203], v186 offset:3072
	v_lshl_add_u64 v[186:187], s[72:73], 0, v[140:141]
	s_mov_b32 m0, s2
	v_lshl_add_u64 v[204:205], s[72:73], 0, v[136:137]
	global_load_lds_dwordx4 v[186:187], off
	s_add_i32 m0, s2, 0x2000
	s_nop 0
	global_load_lds_dwordx4 v[204:205], off
	s_barrier
	s_waitcnt lgkmcnt(0)
	s_waitcnt lgkmcnt(0)
	v_mfma_f32_16x16x32_bf16 v[124:127], v[238:241], v[206:209], v[124:127]
	v_mfma_f32_16x16x32_bf16 v[120:123], v[246:249], v[206:209], v[120:123]
	v_mfma_f32_16x16x32_bf16 v[100:103], v[238:241], v[214:217], v[100:103]
	v_mfma_f32_16x16x32_bf16 v[96:99], v[246:249], v[214:217], v[96:99]
	v_mfma_f32_16x16x32_bf16 v[84:87], v[238:241], v[222:225], v[84:87]
	v_mfma_f32_16x16x32_bf16 v[80:83], v[246:249], v[222:225], v[80:83]
	v_mfma_f32_16x16x32_bf16 v[68:71], v[238:241], v[230:233], v[68:71]
	v_mfma_f32_16x16x32_bf16 v[64:67], v[246:249], v[230:233], v[64:67]
	v_mfma_f32_16x16x32_bf16 v[124:127], v[242:245], v[210:213], v[124:127]
	v_mfma_f32_16x16x32_bf16 v[120:123], v[200:203], v[210:213], v[120:123]
	v_mfma_f32_16x16x32_bf16 v[100:103], v[242:245], v[218:221], v[100:103]
	v_mfma_f32_16x16x32_bf16 v[96:99], v[200:203], v[218:221], v[96:99]
	v_mfma_f32_16x16x32_bf16 v[84:87], v[242:245], v[226:229], v[84:87]
	v_mfma_f32_16x16x32_bf16 v[80:83], v[200:203], v[226:229], v[80:83]
	v_mfma_f32_16x16x32_bf16 v[68:71], v[242:245], v[234:237], v[68:71]
	v_mfma_f32_16x16x32_bf16 v[64:67], v[200:203], v[234:237], v[64:67]
	s_mov_b32 m0, s61
	v_lshl_add_u64 v[190:191], s[74:75], 0, v[142:143]
	s_barrier
	ds_read_b128 v[206:209], v164 offset:16384
	ds_read_b128 v[210:213], v164 offset:17408
	ds_read_b128 v[214:217], v164 offset:18432
	ds_read_b128 v[218:221], v164 offset:19456
	ds_read_b128 v[222:225], v164 offset:20480
	ds_read_b128 v[226:229], v164 offset:21504
	ds_read_b128 v[230:233], v164 offset:22528
	ds_read_b128 v[234:237], v164 offset:23552
	global_load_lds_dwordx4 v[190:191], off
	v_lshl_add_u64 v[194:195], s[74:75], 0, v[138:139]
	s_mov_b32 m0, s76
	s_nop 0
	global_load_lds_dwordx4 v[194:195], off
	s_barrier
	s_waitcnt lgkmcnt(0)
	s_waitcnt lgkmcnt(0)
	v_mfma_f32_16x16x32_bf16 v[60:63], v[104:107], v[206:209], v[60:63]
	v_mfma_f32_16x16x32_bf16 v[56:59], v[172:175], v[206:209], v[56:59]
	v_mfma_f32_16x16x32_bf16 v[44:47], v[104:107], v[214:217], v[44:47]
	v_mfma_f32_16x16x32_bf16 v[40:43], v[172:175], v[214:217], v[40:43]
	v_mfma_f32_16x16x32_bf16 v[28:31], v[104:107], v[222:225], v[28:31]
	v_mfma_f32_16x16x32_bf16 v[24:27], v[172:175], v[222:225], v[24:27]
	v_mfma_f32_16x16x32_bf16 v[12:15], v[104:107], v[230:233], v[12:15]
	v_mfma_f32_16x16x32_bf16 v[8:11], v[172:175], v[230:233], v[8:11]
	v_mfma_f32_16x16x32_bf16 v[60:63], v[108:111], v[210:213], v[60:63]
	v_mfma_f32_16x16x32_bf16 v[56:59], v[182:185], v[210:213], v[56:59]
	v_mfma_f32_16x16x32_bf16 v[44:47], v[108:111], v[218:221], v[44:47]
	v_mfma_f32_16x16x32_bf16 v[40:43], v[182:185], v[218:221], v[40:43]
	v_mfma_f32_16x16x32_bf16 v[28:31], v[108:111], v[226:229], v[28:31]
	v_mfma_f32_16x16x32_bf16 v[24:27], v[182:185], v[226:229], v[24:27]
	v_mfma_f32_16x16x32_bf16 v[12:15], v[108:111], v[234:237], v[12:15]
	v_mfma_f32_16x16x32_bf16 v[8:11], v[182:185], v[234:237], v[8:11]
	s_barrier
	s_add_u32 s2, s72, 0x20000
	s_addc_u32 s3, s73, 0
	s_add_i32 s1, s1, s60
	v_lshl_add_u64 v[104:105], s[2:3], 0, v[140:141]
	s_mov_b32 m0, s1
	s_nop 0
	global_load_lds_dwordx4 v[104:105], off
	v_lshl_add_u64 v[104:105], s[2:3], 0, v[136:137]
	s_add_i32 m0, s1, 0x2000
	s_nop 0
	global_load_lds_dwordx4 v[104:105], off
	s_waitcnt vmcnt(6)
	s_barrier
	v_mfma_f32_16x16x32_bf16 v[52:55], v[238:241], v[206:209], v[52:55]
	v_mfma_f32_16x16x32_bf16 v[48:51], v[246:249], v[206:209], v[48:51]
	v_mfma_f32_16x16x32_bf16 v[36:39], v[238:241], v[214:217], v[36:39]
	v_mfma_f32_16x16x32_bf16 v[32:35], v[246:249], v[214:217], v[32:35]
	v_mfma_f32_16x16x32_bf16 v[20:23], v[238:241], v[222:225], v[20:23]
	v_mfma_f32_16x16x32_bf16 v[16:19], v[246:249], v[222:225], v[16:19]
	v_mfma_f32_16x16x32_bf16 v[4:7], v[238:241], v[230:233], v[4:7]
	v_mfma_f32_16x16x32_bf16 v[0:3], v[246:249], v[230:233], v[0:3]
	v_mfma_f32_16x16x32_bf16 v[52:55], v[242:245], v[210:213], v[52:55]
	v_mfma_f32_16x16x32_bf16 v[48:51], v[200:203], v[210:213], v[48:51]
	v_mfma_f32_16x16x32_bf16 v[36:39], v[242:245], v[218:221], v[36:39]
	v_mfma_f32_16x16x32_bf16 v[32:35], v[200:203], v[218:221], v[32:35]
	v_mfma_f32_16x16x32_bf16 v[20:23], v[242:245], v[226:229], v[20:23]
	v_mfma_f32_16x16x32_bf16 v[16:19], v[200:203], v[226:229], v[16:19]
	v_mfma_f32_16x16x32_bf16 v[4:7], v[242:245], v[234:237], v[4:7]
	v_mfma_f32_16x16x32_bf16 v[0:3], v[200:203], v[234:237], v[0:3]
	s_add_i32 s1, 0, 0x18000
	v_add_u32_e32 v182, s1, v153
	s_barrier
	ds_read_b128 v[104:107], v182
	ds_read_b128 v[108:111], v182 offset:1024
	ds_read_b128 v[172:175], v182 offset:2048
	ds_read_b128 v[182:185], v182 offset:3072
	s_add_u32 s2, s74, 0x20000
	s_addc_u32 s3, s75, 0
	s_mov_b32 m0, s77
	v_lshl_add_u64 v[234:235], s[2:3], 0, v[142:143]
	ds_read_b128 v[200:203], v164 offset:32768
	ds_read_b128 v[206:209], v164 offset:33792
	ds_read_b128 v[210:213], v164 offset:34816
	ds_read_b128 v[214:217], v164 offset:35840
	ds_read_b128 v[218:221], v164 offset:36864
	ds_read_b128 v[222:225], v164 offset:37888
	ds_read_b128 v[226:229], v164 offset:38912
	ds_read_b128 v[230:233], v164 offset:39936
	global_load_lds_dwordx4 v[234:235], off
	v_lshl_add_u64 v[234:235], s[2:3], 0, v[138:139]
	s_mov_b32 m0, s78
	s_nop 0
	global_load_lds_dwordx4 v[234:235], off
	s_waitcnt lgkmcnt(8)
	s_barrier
	s_waitcnt lgkmcnt(0)
	s_waitcnt lgkmcnt(0)
	v_mfma_f32_16x16x32_bf16 v[132:135], v[104:107], v[200:203], v[132:135]
	v_mfma_f32_16x16x32_bf16 v[128:131], v[172:175], v[200:203], v[128:131]
	v_mfma_f32_16x16x32_bf16 v[116:119], v[104:107], v[210:213], v[116:119]
	v_mfma_f32_16x16x32_bf16 v[112:115], v[172:175], v[210:213], v[112:115]
	v_mfma_f32_16x16x32_bf16 v[92:95], v[104:107], v[218:221], v[92:95]
	v_mfma_f32_16x16x32_bf16 v[88:91], v[172:175], v[218:221], v[88:91]
	v_mfma_f32_16x16x32_bf16 v[76:79], v[104:107], v[226:229], v[76:79]
	v_mfma_f32_16x16x32_bf16 v[72:75], v[172:175], v[226:229], v[72:75]
	v_mfma_f32_16x16x32_bf16 v[132:135], v[108:111], v[206:209], v[132:135]
	v_mfma_f32_16x16x32_bf16 v[128:131], v[182:185], v[206:209], v[128:131]
	v_mfma_f32_16x16x32_bf16 v[116:119], v[108:111], v[214:217], v[116:119]
	v_mfma_f32_16x16x32_bf16 v[112:115], v[182:185], v[214:217], v[112:115]
	v_mfma_f32_16x16x32_bf16 v[92:95], v[108:111], v[222:225], v[92:95]
	v_mfma_f32_16x16x32_bf16 v[88:91], v[182:185], v[222:225], v[88:91]
	v_mfma_f32_16x16x32_bf16 v[76:79], v[108:111], v[230:233], v[76:79]
	v_mfma_f32_16x16x32_bf16 v[72:75], v[182:185], v[230:233], v[72:75]
	s_barrier
	s_add_i32 s12, 0, 0x1c000
	s_add_i32 s1, s1, s60
	v_add_u32_e32 v188, s12, v153
	v_lshl_add_u64 v[186:187], v[186:187], 0, s[20:21]
	s_mov_b32 m0, s1
	ds_read_b128 v[234:237], v188
	ds_read_b128 v[238:241], v188 offset:1024
	ds_read_b128 v[242:245], v188 offset:2048
	ds_read_b128 v[246:249], v188 offset:3072
	global_load_lds_dwordx4 v[186:187], off
	v_lshl_add_u64 v[186:187], v[204:205], 0, s[20:21]
	s_add_i32 m0, s1, 0x2000
	s_nop 0
	global_load_lds_dwordx4 v[186:187], off
	s_barrier
	s_waitcnt lgkmcnt(0)
	s_waitcnt lgkmcnt(0)
	v_mfma_f32_16x16x32_bf16 v[124:127], v[234:237], v[200:203], v[124:127]
	v_mfma_f32_16x16x32_bf16 v[120:123], v[242:245], v[200:203], v[120:123]
	v_mfma_f32_16x16x32_bf16 v[100:103], v[234:237], v[210:213], v[100:103]
	v_mfma_f32_16x16x32_bf16 v[96:99], v[242:245], v[210:213], v[96:99]
	v_mfma_f32_16x16x32_bf16 v[84:87], v[234:237], v[218:221], v[84:87]
	v_mfma_f32_16x16x32_bf16 v[80:83], v[242:245], v[218:221], v[80:83]
	v_mfma_f32_16x16x32_bf16 v[68:71], v[234:237], v[226:229], v[68:71]
	v_mfma_f32_16x16x32_bf16 v[64:67], v[242:245], v[226:229], v[64:67]
	v_mfma_f32_16x16x32_bf16 v[124:127], v[238:241], v[206:209], v[124:127]
	v_mfma_f32_16x16x32_bf16 v[120:123], v[246:249], v[206:209], v[120:123]
	v_mfma_f32_16x16x32_bf16 v[100:103], v[238:241], v[214:217], v[100:103]
	v_mfma_f32_16x16x32_bf16 v[96:99], v[246:249], v[214:217], v[96:99]
	v_mfma_f32_16x16x32_bf16 v[84:87], v[238:241], v[222:225], v[84:87]
	v_mfma_f32_16x16x32_bf16 v[80:83], v[246:249], v[222:225], v[80:83]
	v_mfma_f32_16x16x32_bf16 v[68:71], v[238:241], v[230:233], v[68:71]
	v_mfma_f32_16x16x32_bf16 v[64:67], v[246:249], v[230:233], v[64:67]
	s_mov_b32 m0, s34
	v_lshl_add_u64 v[186:187], v[190:191], 0, s[20:21]
	s_barrier
	ds_read_b128 v[200:203], v164 offset:49152
	ds_read_b128 v[206:209], v164 offset:50176
	ds_read_b128 v[210:213], v164 offset:51200
	ds_read_b128 v[214:217], v164 offset:52224
	ds_read_b128 v[218:221], v164 offset:53248
	ds_read_b128 v[222:225], v164 offset:54272
	ds_read_b128 v[226:229], v164 offset:55296
	ds_read_b128 v[230:233], v164 offset:56320
	global_load_lds_dwordx4 v[186:187], off
	v_lshl_add_u64 v[186:187], v[194:195], 0, s[20:21]
	s_mov_b32 m0, s79
	s_nop 0
	global_load_lds_dwordx4 v[186:187], off
	s_barrier
	s_waitcnt lgkmcnt(0)
	s_waitcnt lgkmcnt(0)
	v_mfma_f32_16x16x32_bf16 v[60:63], v[104:107], v[200:203], v[60:63]
	v_mfma_f32_16x16x32_bf16 v[56:59], v[172:175], v[200:203], v[56:59]
	v_mfma_f32_16x16x32_bf16 v[44:47], v[104:107], v[210:213], v[44:47]
	v_mfma_f32_16x16x32_bf16 v[40:43], v[172:175], v[210:213], v[40:43]
	v_mfma_f32_16x16x32_bf16 v[28:31], v[104:107], v[218:221], v[28:31]
	v_mfma_f32_16x16x32_bf16 v[24:27], v[172:175], v[218:221], v[24:27]
	v_mfma_f32_16x16x32_bf16 v[12:15], v[104:107], v[226:229], v[12:15]
	v_mfma_f32_16x16x32_bf16 v[8:11], v[172:175], v[226:229], v[8:11]
	v_mfma_f32_16x16x32_bf16 v[60:63], v[108:111], v[206:209], v[60:63]
	v_mfma_f32_16x16x32_bf16 v[56:59], v[182:185], v[206:209], v[56:59]
	v_mfma_f32_16x16x32_bf16 v[44:47], v[108:111], v[214:217], v[44:47]
	v_mfma_f32_16x16x32_bf16 v[40:43], v[182:185], v[214:217], v[40:43]
	v_mfma_f32_16x16x32_bf16 v[28:31], v[108:111], v[222:225], v[28:31]
	v_mfma_f32_16x16x32_bf16 v[24:27], v[182:185], v[222:225], v[24:27]
	v_mfma_f32_16x16x32_bf16 v[12:15], v[108:111], v[230:233], v[12:15]
	v_mfma_f32_16x16x32_bf16 v[8:11], v[182:185], v[230:233], v[8:11]
	s_barrier
	s_add_u32 s2, s72, 0x20080
	s_addc_u32 s3, s73, 0
	s_add_i32 s1, s12, s60
	v_lshl_add_u64 v[104:105], s[2:3], 0, v[140:141]
	s_mov_b32 m0, s1
	s_nop 0
	global_load_lds_dwordx4 v[104:105], off
	v_lshl_add_u64 v[104:105], s[2:3], 0, v[136:137]
	s_add_i32 m0, s1, 0x2000
	s_nop 0
	global_load_lds_dwordx4 v[104:105], off
	s_waitcnt vmcnt(6)
	s_barrier
	v_mfma_f32_16x16x32_bf16 v[52:55], v[234:237], v[200:203], v[52:55]
	v_mfma_f32_16x16x32_bf16 v[48:51], v[242:245], v[200:203], v[48:51]
	v_mfma_f32_16x16x32_bf16 v[36:39], v[234:237], v[210:213], v[36:39]
	v_mfma_f32_16x16x32_bf16 v[32:35], v[242:245], v[210:213], v[32:35]
	v_mfma_f32_16x16x32_bf16 v[20:23], v[234:237], v[218:221], v[20:23]
	v_mfma_f32_16x16x32_bf16 v[16:19], v[242:245], v[218:221], v[16:19]
	v_mfma_f32_16x16x32_bf16 v[4:7], v[234:237], v[226:229], v[4:7]
	v_mfma_f32_16x16x32_bf16 v[0:3], v[242:245], v[226:229], v[0:3]
	v_mfma_f32_16x16x32_bf16 v[52:55], v[238:241], v[206:209], v[52:55]
	v_mfma_f32_16x16x32_bf16 v[48:51], v[246:249], v[206:209], v[48:51]
	v_mfma_f32_16x16x32_bf16 v[36:39], v[238:241], v[214:217], v[36:39]
	v_mfma_f32_16x16x32_bf16 v[32:35], v[246:249], v[214:217], v[32:35]
	v_mfma_f32_16x16x32_bf16 v[20:23], v[238:241], v[222:225], v[20:23]
	v_mfma_f32_16x16x32_bf16 v[16:19], v[246:249], v[222:225], v[16:19]
	v_mfma_f32_16x16x32_bf16 v[4:7], v[238:241], v[230:233], v[4:7]
	v_mfma_f32_16x16x32_bf16 v[0:3], v[246:249], v[230:233], v[0:3]
	s_add_i32 s89, s89, 2
	s_add_u32 s70, s70, 0x100
	s_addc_u32 s71, s71, 0
	s_add_u32 s87, s87, 0x100
	s_addc_u32 s88, s88, 0
	s_cmp_gt_u32 s89, 5
	s_barrier
	s_cbranch_scc0 .LBB0_326
	s_setprio 0
	v_mul_f32_e32 v105, v133, v133
	v_mul_f32_e32 v106, v135, v135
	v_fmac_f32_e32 v105, v132, v132
	v_fmac_f32_e32 v106, v134, v134
	v_add_f32_e32 v105, v105, v106
	v_mul_f32_e32 v106, v129, v129
	v_fmac_f32_e32 v106, v128, v128
	v_cmp_lt_i32_e32 vcc, v199, v197
	v_add_f32_e32 v105, v105, v106
	v_mul_f32_e32 v106, v131, v131
	v_cndmask_b32_e32 v104, v193, v199, vcc
	v_fmac_f32_e32 v106, v130, v130
	v_lshlrev_b32_e32 v104, 2, v104
	v_add_f32_e32 v106, v106, v105
	ds_bpermute_b32 v107, v104, v106
	v_cmp_lt_i32_e32 vcc, v250, v197
	s_waitcnt lgkmcnt(0)
	v_add_f32_e32 v106, v106, v107
	v_cndmask_b32_e32 v105, v193, v250, vcc
	v_lshlrev_b32_e32 v105, 2, v105
	ds_bpermute_b32 v107, v105, v106
	s_and_saveexec_b64 s[70:71], s[40:41]
	s_cbranch_execz .LBB0_329
	s_waitcnt lgkmcnt(0)
	v_add_f32_e32 v106, v106, v107
	ds_write_b32 v162, v106

.Lprio_357:
	s_add_u32 s1, s70, s30
	s_addc_u32 s12, s71, 0
	s_add_u32 s13, s1, 0x100
	s_addc_u32 s14, s12, 0
	s_and_b64 s[2:3], s[74:75], exec
	s_cselect_b32 s79, s43, s14
	s_cselect_b32 s78, s95, s13
	s_add_u32 s2, s68, s30
	s_addc_u32 s3, s69, 0
	s_add_u32 s13, s2, 0x100
	s_addc_u32 s14, s3, 0
	s_add_i32 s15, 0, 0x10000
	s_and_b64 s[2:3], s[74:75], exec
	s_cselect_b32 s81, s39, s14
	s_cselect_b32 s80, s96, s13
	s_add_u32 s82, s1, 0x10080
	s_addc_u32 s83, s12, 0
	s_add_i32 s12, s15, s61
	s_add_i32 m0, s85, 0xc000
	s_add_i32 s86, s85, 0xe000
	s_add_i32 s13, 0, 0x14000
	s_add_i32 s14, s12, 0x2000
	s_add_u32 s76, s80, 0x10000
	v_add_u32_e32 v134, s15, v137
	s_addc_u32 s77, s81, 0
	s_add_i32 s2, s13, s61
	ds_read_b128 v[140:143], v134
	ds_read_b128 v[144:147], v134 offset:1024
	ds_read_b128 v[148:151], v134 offset:2048
	ds_read_b128 v[152:155], v134 offset:3072
	s_add_i32 s3, s2, 0x2000
	s_add_i32 s97, 0, 0x18000
	s_add_u32 vcc_lo, s78, 0x10000
	s_addc_u32 vcc_hi, s79, 0
	s_add_i32 s30, s97, s61
	s_add_i32 s31, 0, 0x1c000
	s_add_i32 s1, s30, 0x2000
	s_add_u32 s74, s80, 0x10080
	s_addc_u32 s75, s81, 0
	s_add_i32 s34, s31, s61
	s_add_i32 s48, s34, 0x2000
	v_lshl_add_u64 v[134:135], s[82:83], 0, v[132:133]
	ds_read_b128 v[156:159], v139
	ds_read_b128 v[160:163], v139 offset:1024
	ds_read_b128 v[164:167], v139 offset:2048
	ds_read_b128 v[168:171], v139 offset:3072
	ds_read_b128 v[172:175], v139 offset:4096
	ds_read_b128 v[182:185], v139 offset:5120
	ds_read_b128 v[200:203], v139 offset:6144
	ds_read_b128 v[206:209], v139 offset:7168
	global_load_lds_dwordx4 v[134:135], off
	v_lshl_add_u64 v[134:135], s[82:83], 0, v[130:131]
	s_mov_b32 m0, s86
	s_nop 0
	global_load_lds_dwordx4 v[134:135], off
	s_waitcnt lgkmcnt(8)
	s_barrier
	s_waitcnt lgkmcnt(0)
	s_waitcnt lgkmcnt(0)
	v_mfma_f32_16x16x32_bf16 v[124:127], v[140:143], v[156:159], v[124:127]
	v_mfma_f32_16x16x32_bf16 v[120:123], v[148:151], v[156:159], v[120:123]
	v_mfma_f32_16x16x32_bf16 v[116:119], v[140:143], v[164:167], v[116:119]
	v_mfma_f32_16x16x32_bf16 v[108:111], v[148:151], v[164:167], v[108:111]
	v_mfma_f32_16x16x32_bf16 v[100:103], v[140:143], v[172:175], v[100:103]
	v_mfma_f32_16x16x32_bf16 v[92:95], v[148:151], v[172:175], v[92:95]
	v_mfma_f32_16x16x32_bf16 v[84:87], v[140:143], v[200:203], v[84:87]
	v_mfma_f32_16x16x32_bf16 v[76:79], v[148:151], v[200:203], v[76:79]
	v_mfma_f32_16x16x32_bf16 v[124:127], v[144:147], v[160:163], v[124:127]
	v_mfma_f32_16x16x32_bf16 v[120:123], v[152:155], v[160:163], v[120:123]
	v_mfma_f32_16x16x32_bf16 v[116:119], v[144:147], v[168:171], v[116:119]
	v_mfma_f32_16x16x32_bf16 v[108:111], v[152:155], v[168:171], v[108:111]
	v_mfma_f32_16x16x32_bf16 v[100:103], v[144:147], v[182:185], v[100:103]
	v_mfma_f32_16x16x32_bf16 v[92:95], v[152:155], v[182:185], v[92:95]
	v_mfma_f32_16x16x32_bf16 v[84:87], v[144:147], v[206:209], v[84:87]
	v_mfma_f32_16x16x32_bf16 v[76:79], v[152:155], v[206:209], v[76:79]
	s_barrier
	v_add_u32_e32 v134, s13, v137
	s_mov_b32 m0, s12
	ds_read_b128 v[210:213], v134
	ds_read_b128 v[214:217], v134 offset:1024
	ds_read_b128 v[218:221], v134 offset:2048
	ds_read_b128 v[222:225], v134 offset:3072
	v_lshl_add_u64 v[134:135], s[80:81], 0, v[176:177]
	global_load_lds_dwordx4 v[134:135], off
	v_lshl_add_u64 v[186:187], s[80:81], 0, v[128:129]
	s_mov_b32 m0, s14
	s_nop 0
	global_load_lds_dwordx4 v[186:187], off
	s_barrier
	s_waitcnt lgkmcnt(0)
	s_waitcnt lgkmcnt(0)
	v_mfma_f32_16x16x32_bf16 v[112:115], v[210:213], v[156:159], v[112:115]
	v_mfma_f32_16x16x32_bf16 v[104:107], v[218:221], v[156:159], v[104:107]
	v_mfma_f32_16x16x32_bf16 v[96:99], v[210:213], v[164:167], v[96:99]
	v_mfma_f32_16x16x32_bf16 v[88:91], v[218:221], v[164:167], v[88:91]
	v_mfma_f32_16x16x32_bf16 v[80:83], v[210:213], v[172:175], v[80:83]
	v_mfma_f32_16x16x32_bf16 v[72:75], v[218:221], v[172:175], v[72:75]
	v_mfma_f32_16x16x32_bf16 v[68:71], v[210:213], v[200:203], v[68:71]
	v_mfma_f32_16x16x32_bf16 v[64:67], v[218:221], v[200:203], v[64:67]
	v_mfma_f32_16x16x32_bf16 v[112:115], v[214:217], v[160:163], v[112:115]
	v_mfma_f32_16x16x32_bf16 v[104:107], v[222:225], v[160:163], v[104:107]
	v_mfma_f32_16x16x32_bf16 v[96:99], v[214:217], v[168:171], v[96:99]
	v_mfma_f32_16x16x32_bf16 v[88:91], v[222:225], v[168:171], v[88:91]
	v_mfma_f32_16x16x32_bf16 v[80:83], v[214:217], v[182:185], v[80:83]
	v_mfma_f32_16x16x32_bf16 v[72:75], v[222:225], v[182:185], v[72:75]
	v_mfma_f32_16x16x32_bf16 v[68:71], v[214:217], v[206:209], v[68:71]
	v_mfma_f32_16x16x32_bf16 v[64:67], v[222:225], v[206:209], v[64:67]
	s_mov_b32 m0, s85
	v_lshl_add_u64 v[190:191], s[78:79], 0, v[132:133]
	s_barrier
	ds_read_b128 v[156:159], v139 offset:16384
	ds_read_b128 v[160:163], v139 offset:17408
	ds_read_b128 v[164:167], v139 offset:18432
	ds_read_b128 v[168:171], v139 offset:19456
	ds_read_b128 v[172:175], v139 offset:20480
	ds_read_b128 v[182:185], v139 offset:21504
	ds_read_b128 v[200:203], v139 offset:22528
	ds_read_b128 v[206:209], v139 offset:23552
	global_load_lds_dwordx4 v[190:191], off
	v_lshl_add_u64 v[194:195], s[78:79], 0, v[130:131]
	s_mov_b32 m0, s87
	s_nop 0
	global_load_lds_dwordx4 v[194:195], off
	s_barrier
	s_waitcnt lgkmcnt(0)
	s_waitcnt lgkmcnt(0)
	v_mfma_f32_16x16x32_bf16 v[60:63], v[140:143], v[156:159], v[60:63]
	v_mfma_f32_16x16x32_bf16 v[56:59], v[148:151], v[156:159], v[56:59]
	v_mfma_f32_16x16x32_bf16 v[52:55], v[140:143], v[164:167], v[52:55]
	v_mfma_f32_16x16x32_bf16 v[44:47], v[148:151], v[164:167], v[44:47]
	v_mfma_f32_16x16x32_bf16 v[36:39], v[140:143], v[172:175], v[36:39]
	v_mfma_f32_16x16x32_bf16 v[28:31], v[148:151], v[172:175], v[28:31]
	v_mfma_f32_16x16x32_bf16 v[20:23], v[140:143], v[200:203], v[20:23]
	v_mfma_f32_16x16x32_bf16 v[12:15], v[148:151], v[200:203], v[12:15]
	v_mfma_f32_16x16x32_bf16 v[60:63], v[144:147], v[160:163], v[60:63]
	v_mfma_f32_16x16x32_bf16 v[56:59], v[152:155], v[160:163], v[56:59]
	v_mfma_f32_16x16x32_bf16 v[52:55], v[144:147], v[168:171], v[52:55]
	v_mfma_f32_16x16x32_bf16 v[44:47], v[152:155], v[168:171], v[44:47]
	v_mfma_f32_16x16x32_bf16 v[36:39], v[144:147], v[182:185], v[36:39]
	v_mfma_f32_16x16x32_bf16 v[28:31], v[152:155], v[182:185], v[28:31]
	v_mfma_f32_16x16x32_bf16 v[20:23], v[144:147], v[206:209], v[20:23]
	v_mfma_f32_16x16x32_bf16 v[12:15], v[152:155], v[206:209], v[12:15]
	s_barrier
	s_mov_b32 m0, s2
	v_lshl_add_u64 v[140:141], s[76:77], 0, v[176:177]
	global_load_lds_dwordx4 v[140:141], off
	v_lshl_add_u64 v[140:141], s[76:77], 0, v[128:129]
	s_mov_b32 m0, s3
	s_nop 0
	global_load_lds_dwordx4 v[140:141], off
	s_waitcnt vmcnt(6)
	s_barrier
	v_mfma_f32_16x16x32_bf16 v[48:51], v[210:213], v[156:159], v[48:51]
	v_mfma_f32_16x16x32_bf16 v[40:43], v[218:221], v[156:159], v[40:43]
	v_mfma_f32_16x16x32_bf16 v[32:35], v[210:213], v[164:167], v[32:35]
	v_mfma_f32_16x16x32_bf16 v[24:27], v[218:221], v[164:167], v[24:27]
	v_mfma_f32_16x16x32_bf16 v[16:19], v[210:213], v[172:175], v[16:19]
	v_mfma_f32_16x16x32_bf16 v[8:11], v[218:221], v[172:175], v[8:11]
	v_mfma_f32_16x16x32_bf16 v[4:7], v[210:213], v[200:203], v[4:7]
	v_mfma_f32_16x16x32_bf16 v[0:3], v[218:221], v[200:203], v[0:3]
	v_mfma_f32_16x16x32_bf16 v[48:51], v[214:217], v[160:163], v[48:51]
	v_mfma_f32_16x16x32_bf16 v[40:43], v[222:225], v[160:163], v[40:43]
	v_mfma_f32_16x16x32_bf16 v[32:35], v[214:217], v[168:171], v[32:35]
	v_mfma_f32_16x16x32_bf16 v[24:27], v[222:225], v[168:171], v[24:27]
	v_mfma_f32_16x16x32_bf16 v[16:19], v[214:217], v[182:185], v[16:19]
	v_mfma_f32_16x16x32_bf16 v[8:11], v[222:225], v[182:185], v[8:11]
	v_mfma_f32_16x16x32_bf16 v[4:7], v[214:217], v[206:209], v[4:7]
	v_mfma_f32_16x16x32_bf16 v[0:3], v[222:225], v[206:209], v[0:3]
	v_add_u32_e32 v152, s97, v137
	s_barrier
	ds_read_b128 v[140:143], v152
	ds_read_b128 v[144:147], v152 offset:1024
	ds_read_b128 v[148:151], v152 offset:2048
	ds_read_b128 v[152:155], v152 offset:3072
	s_mov_b32 m0, s88
	v_lshl_add_u64 v[204:205], vcc, 0, v[132:133]
	ds_read_b128 v[156:159], v139 offset:32768
	ds_read_b128 v[160:163], v139 offset:33792
	ds_read_b128 v[164:167], v139 offset:34816
	ds_read_b128 v[168:171], v139 offset:35840
	ds_read_b128 v[172:175], v139 offset:36864
	ds_read_b128 v[182:185], v139 offset:37888
	ds_read_b128 v[200:203], v139 offset:38912
	ds_read_b128 v[206:209], v139 offset:39936
	global_load_lds_dwordx4 v[204:205], off
	v_lshl_add_u64 v[204:205], vcc, 0, v[130:131]
	s_mov_b32 m0, s89
	s_nop 0
	global_load_lds_dwordx4 v[204:205], off
	s_waitcnt lgkmcnt(8)
	s_barrier
	s_waitcnt lgkmcnt(0)
	s_waitcnt lgkmcnt(0)
	v_mfma_f32_16x16x32_bf16 v[124:127], v[140:143], v[156:159], v[124:127]
	v_mfma_f32_16x16x32_bf16 v[120:123], v[148:151], v[156:159], v[120:123]
	v_mfma_f32_16x16x32_bf16 v[116:119], v[140:143], v[164:167], v[116:119]
	v_mfma_f32_16x16x32_bf16 v[108:111], v[148:151], v[164:167], v[108:111]
	v_mfma_f32_16x16x32_bf16 v[100:103], v[140:143], v[172:175], v[100:103]
	v_mfma_f32_16x16x32_bf16 v[92:95], v[148:151], v[172:175], v[92:95]
	v_mfma_f32_16x16x32_bf16 v[84:87], v[140:143], v[200:203], v[84:87]
	v_mfma_f32_16x16x32_bf16 v[76:79], v[148:151], v[200:203], v[76:79]
	v_mfma_f32_16x16x32_bf16 v[124:127], v[144:147], v[160:163], v[124:127]
	v_mfma_f32_16x16x32_bf16 v[120:123], v[152:155], v[160:163], v[120:123]
	v_mfma_f32_16x16x32_bf16 v[116:119], v[144:147], v[168:171], v[116:119]
	v_mfma_f32_16x16x32_bf16 v[108:111], v[152:155], v[168:171], v[108:111]
	v_mfma_f32_16x16x32_bf16 v[100:103], v[144:147], v[182:185], v[100:103]
	v_mfma_f32_16x16x32_bf16 v[92:95], v[152:155], v[182:185], v[92:95]
	v_mfma_f32_16x16x32_bf16 v[84:87], v[144:147], v[206:209], v[84:87]
	v_mfma_f32_16x16x32_bf16 v[76:79], v[152:155], v[206:209], v[76:79]
	s_barrier
	s_mov_b32 m0, s30
	v_add_u32_e32 v188, s31, v137
	v_lshl_add_u64 v[134:135], v[134:135], 0, s[20:21]
	ds_read_b128 v[210:213], v188
	ds_read_b128 v[214:217], v188 offset:1024
	ds_read_b128 v[218:221], v188 offset:2048
	ds_read_b128 v[222:225], v188 offset:3072
	global_load_lds_dwordx4 v[134:135], off
	v_lshl_add_u64 v[134:135], v[186:187], 0, s[20:21]
	s_mov_b32 m0, s1
	s_nop 0
	global_load_lds_dwordx4 v[134:135], off
	s_barrier
	s_waitcnt lgkmcnt(0)
	s_waitcnt lgkmcnt(0)
	v_mfma_f32_16x16x32_bf16 v[112:115], v[210:213], v[156:159], v[112:115]
	v_mfma_f32_16x16x32_bf16 v[104:107], v[218:221], v[156:159], v[104:107]
	v_mfma_f32_16x16x32_bf16 v[96:99], v[210:213], v[164:167], v[96:99]
	v_mfma_f32_16x16x32_bf16 v[88:91], v[218:221], v[164:167], v[88:91]
	v_mfma_f32_16x16x32_bf16 v[80:83], v[210:213], v[172:175], v[80:83]
	v_mfma_f32_16x16x32_bf16 v[72:75], v[218:221], v[172:175], v[72:75]
	v_mfma_f32_16x16x32_bf16 v[68:71], v[210:213], v[200:203], v[68:71]
	v_mfma_f32_16x16x32_bf16 v[64:67], v[218:221], v[200:203], v[64:67]
	v_mfma_f32_16x16x32_bf16 v[112:115], v[214:217], v[160:163], v[112:115]
	v_mfma_f32_16x16x32_bf16 v[104:107], v[222:225], v[160:163], v[104:107]
	v_mfma_f32_16x16x32_bf16 v[96:99], v[214:217], v[168:171], v[96:99]
	v_mfma_f32_16x16x32_bf16 v[88:91], v[222:225], v[168:171], v[88:91]
	v_mfma_f32_16x16x32_bf16 v[80:83], v[214:217], v[182:185], v[80:83]
	v_mfma_f32_16x16x32_bf16 v[72:75], v[222:225], v[182:185], v[72:75]
	v_mfma_f32_16x16x32_bf16 v[68:71], v[214:217], v[206:209], v[68:71]
	v_mfma_f32_16x16x32_bf16 v[64:67], v[222:225], v[206:209], v[64:67]
	s_mov_b32 m0, s90
	v_lshl_add_u64 v[134:135], v[190:191], 0, s[20:21]
	s_barrier
	ds_read_b128 v[156:159], v139 offset:49152
	ds_read_b128 v[160:163], v139 offset:50176
	ds_read_b128 v[164:167], v139 offset:51200
	ds_read_b128 v[168:171], v139 offset:52224
	ds_read_b128 v[172:175], v139 offset:53248
	ds_read_b128 v[182:185], v139 offset:54272
	ds_read_b128 v[200:203], v139 offset:55296
	ds_read_b128 v[206:209], v139 offset:56320
	global_load_lds_dwordx4 v[134:135], off
	v_lshl_add_u64 v[134:135], v[194:195], 0, s[20:21]
	s_mov_b32 m0, s91
	s_nop 0
	global_load_lds_dwordx4 v[134:135], off
	s_barrier
	s_waitcnt lgkmcnt(0)
	s_waitcnt lgkmcnt(0)
	v_mfma_f32_16x16x32_bf16 v[60:63], v[140:143], v[156:159], v[60:63]
	v_mfma_f32_16x16x32_bf16 v[56:59], v[148:151], v[156:159], v[56:59]
	v_mfma_f32_16x16x32_bf16 v[52:55], v[140:143], v[164:167], v[52:55]
	v_mfma_f32_16x16x32_bf16 v[44:47], v[148:151], v[164:167], v[44:47]
	v_mfma_f32_16x16x32_bf16 v[36:39], v[140:143], v[172:175], v[36:39]
	v_mfma_f32_16x16x32_bf16 v[28:31], v[148:151], v[172:175], v[28:31]
	v_mfma_f32_16x16x32_bf16 v[20:23], v[140:143], v[200:203], v[20:23]
	v_mfma_f32_16x16x32_bf16 v[12:15], v[148:151], v[200:203], v[12:15]
	v_mfma_f32_16x16x32_bf16 v[60:63], v[144:147], v[160:163], v[60:63]
	v_mfma_f32_16x16x32_bf16 v[56:59], v[152:155], v[160:163], v[56:59]
	v_mfma_f32_16x16x32_bf16 v[52:55], v[144:147], v[168:171], v[52:55]
	v_mfma_f32_16x16x32_bf16 v[44:47], v[152:155], v[168:171], v[44:47]
	v_mfma_f32_16x16x32_bf16 v[36:39], v[144:147], v[182:185], v[36:39]
	v_mfma_f32_16x16x32_bf16 v[28:31], v[152:155], v[182:185], v[28:31]
	v_mfma_f32_16x16x32_bf16 v[20:23], v[144:147], v[206:209], v[20:23]
	v_mfma_f32_16x16x32_bf16 v[12:15], v[152:155], v[206:209], v[12:15]
	s_barrier
	s_mov_b32 m0, s34
	v_lshl_add_u64 v[134:135], s[74:75], 0, v[176:177]
	global_load_lds_dwordx4 v[134:135], off
	v_lshl_add_u64 v[134:135], s[74:75], 0, v[128:129]
	s_mov_b32 m0, s48
	s_nop 0
	global_load_lds_dwordx4 v[134:135], off
	s_waitcnt vmcnt(6)
	s_barrier
	v_mfma_f32_16x16x32_bf16 v[48:51], v[210:213], v[156:159], v[48:51]
	v_mfma_f32_16x16x32_bf16 v[40:43], v[218:221], v[156:159], v[40:43]
	v_mfma_f32_16x16x32_bf16 v[32:35], v[210:213], v[164:167], v[32:35]
	v_mfma_f32_16x16x32_bf16 v[24:27], v[218:221], v[164:167], v[24:27]
	v_mfma_f32_16x16x32_bf16 v[16:19], v[210:213], v[172:175], v[16:19]
	v_mfma_f32_16x16x32_bf16 v[8:11], v[218:221], v[172:175], v[8:11]
	v_mfma_f32_16x16x32_bf16 v[4:7], v[210:213], v[200:203], v[4:7]
	v_mfma_f32_16x16x32_bf16 v[0:3], v[218:221], v[200:203], v[0:3]
	v_mfma_f32_16x16x32_bf16 v[48:51], v[214:217], v[160:163], v[48:51]
	v_mfma_f32_16x16x32_bf16 v[40:43], v[222:225], v[160:163], v[40:43]
	v_mfma_f32_16x16x32_bf16 v[32:35], v[214:217], v[168:171], v[32:35]
	v_mfma_f32_16x16x32_bf16 v[24:27], v[222:225], v[168:171], v[24:27]
	v_mfma_f32_16x16x32_bf16 v[16:19], v[214:217], v[182:185], v[16:19]
	v_mfma_f32_16x16x32_bf16 v[8:11], v[222:225], v[182:185], v[8:11]
	v_mfma_f32_16x16x32_bf16 v[4:7], v[214:217], v[206:209], v[4:7]
	v_mfma_f32_16x16x32_bf16 v[0:3], v[222:225], v[206:209], v[0:3]
	s_movk_i32 s30, 0x100
	s_andn2_b64 vcc, exec, s[72:73]
	s_mov_b64 s[74:75], -1
	s_mov_b64 s[72:73], 0
	s_barrier
	s_cbranch_vccz .LBB0_357
	s_setprio 0
	v_lshl_add_u32 v140, s94, 8, v136
	v_lshl_or_b32 v134, s93, 8, v138
	v_ashrrev_i32_e32 v141, 31, v140
	v_ashrrev_i32_e32 v135, 31, v134
	v_lshlrev_b64 v[142:143], 12, v[140:141]
	v_lshl_add_u64 v[142:143], s[56:57], 0, v[142:143]
	v_lshlrev_b64 v[144:145], 1, v[134:135]
	v_lshl_add_u64 v[134:135], v[142:143], 0, v[144:145]
	v_cvt_pk_bf16_f32 v124, v124, v125
	v_cvt_pk_bf16_f32 v125, v126, v127
	v_cvt_pk_bf16_f32 v126, v120, v121
	v_cvt_pk_bf16_f32 v127, v122, v123
	global_store_dwordx4 v[134:135], v[124:127], off
	v_cvt_pk_bf16_f32 v112, v112, v113
	v_cvt_pk_bf16_f32 v113, v114, v115
	v_cvt_pk_bf16_f32 v114, v104, v105
	v_or_b32_e32 v104, 16, v140
	v_ashrrev_i32_e32 v105, 31, v104
	v_lshlrev_b64 v[104:105], 12, v[104:105]
	v_lshl_add_u64 v[104:105], s[56:57], 0, v[104:105]
	v_cvt_pk_bf16_f32 v115, v106, v107
	global_store_dwordx4 v[134:135], v[112:115], off offset:256
	s_mov_b32 s1, 0x80000
	s_mov_b64 s[2:3], 0x90000
	v_lshl_add_u64 v[112:113], v[104:105], 0, v[144:145]
	v_cvt_pk_bf16_f32 v104, v116, v117
	v_cvt_pk_bf16_f32 v105, v118, v119
	v_cvt_pk_bf16_f32 v106, v108, v109
	v_cvt_pk_bf16_f32 v107, v110, v111
	global_store_dwordx4 v[112:113], v[104:107], off
	v_cvt_pk_bf16_f32 v96, v96, v97
	v_cvt_pk_bf16_f32 v97, v98, v99
	v_cvt_pk_bf16_f32 v98, v88, v89
	v_or_b32_e32 v88, 32, v140
	v_ashrrev_i32_e32 v89, 31, v88
	v_lshlrev_b64 v[88:89], 12, v[88:89]
	v_lshl_add_u64 v[88:89], s[56:57], 0, v[88:89]
	v_cvt_pk_bf16_f32 v99, v90, v91
	global_store_dwordx4 v[112:113], v[96:99], off offset:256
	v_readlane_b32 s30, v255, 27
	s_mov_b32 s93, s38
	v_lshl_add_u64 v[96:97], v[88:89], 0, v[144:145]
	v_cvt_pk_bf16_f32 v88, v100, v101
	v_cvt_pk_bf16_f32 v89, v102, v103
	v_cvt_pk_bf16_f32 v90, v92, v93
	v_cvt_pk_bf16_f32 v91, v94, v95
	global_store_dwordx4 v[96:97], v[88:91], off
	v_cvt_pk_bf16_f32 v80, v80, v81
	v_cvt_pk_bf16_f32 v81, v82, v83
	v_cvt_pk_bf16_f32 v82, v72, v73
	v_or_b32_e32 v72, 48, v140
	v_ashrrev_i32_e32 v73, 31, v72
	v_lshlrev_b64 v[72:73], 12, v[72:73]
	v_lshl_add_u64 v[72:73], s[56:57], 0, v[72:73]
	v_cvt_pk_bf16_f32 v83, v74, v75
	global_store_dwordx4 v[96:97], v[80:83], off offset:256
	s_mov_b32 s94, s42
	s_mov_b64 s[68:69], s[46:47]
	v_lshl_add_u64 v[80:81], v[72:73], 0, v[144:145]
	v_cvt_pk_bf16_f32 v72, v84, v85
	v_cvt_pk_bf16_f32 v73, v86, v87
	v_cvt_pk_bf16_f32 v74, v76, v77
	v_cvt_pk_bf16_f32 v75, v78, v79
	global_store_dwordx4 v[80:81], v[72:75], off
	v_cvt_pk_bf16_f32 v68, v68, v69
	v_cvt_pk_bf16_f32 v69, v70, v71
	v_cvt_pk_bf16_f32 v70, v64, v65
	v_cvt_pk_bf16_f32 v71, v66, v67
	global_store_dwordx4 v[80:81], v[68:71], off offset:256
	v_cvt_pk_bf16_f32 v60, v60, v61
	v_cvt_pk_bf16_f32 v61, v62, v63
	v_cvt_pk_bf16_f32 v62, v56, v57
	v_add_co_u32_e32 v56, vcc, s1, v134
	v_lshl_add_u64 v[64:65], v[134:135], 0, s[36:37]
	s_nop 0
	v_addc_co_u32_e32 v57, vcc, 0, v135, vcc
	s_mov_b32 s1, 0x90000
	v_cvt_pk_bf16_f32 v63, v58, v59
	global_store_dwordx4 v[56:57], v[60:63], off
	v_cvt_pk_bf16_f32 v48, v48, v49
	v_cvt_pk_bf16_f32 v49, v50, v51
	v_cvt_pk_bf16_f32 v50, v40, v41
	v_cvt_pk_bf16_f32 v51, v42, v43
	global_store_dwordx4 v[64:65], v[48:51], off offset:256
	v_cvt_pk_bf16_f32 v40, v52, v53
	v_cvt_pk_bf16_f32 v41, v54, v55
	v_cvt_pk_bf16_f32 v42, v44, v45
	v_add_co_u32_e32 v44, vcc, s1, v134
	s_nop 0
	v_lshl_add_u64 v[48:49], v[134:135], 0, s[2:3]
	v_addc_co_u32_e32 v45, vcc, 0, v135, vcc
	s_mov_b32 s1, 0xa0000
	v_cvt_pk_bf16_f32 v43, v46, v47
	global_store_dwordx4 v[44:45], v[40:43], off
	v_cvt_pk_bf16_f32 v32, v32, v33
	v_cvt_pk_bf16_f32 v33, v34, v35
	v_cvt_pk_bf16_f32 v34, v24, v25
	v_cvt_pk_bf16_f32 v35, v26, v27
	global_store_dwordx4 v[48:49], v[32:35], off offset:256
	s_mov_b64 s[2:3], 0xa0000
	v_cvt_pk_bf16_f32 v24, v36, v37
	v_cvt_pk_bf16_f32 v25, v38, v39
	v_cvt_pk_bf16_f32 v26, v28, v29
	v_add_co_u32_e32 v28, vcc, s1, v134
	v_lshl_add_u64 v[32:33], v[134:135], 0, s[2:3]
	s_nop 0
	v_addc_co_u32_e32 v29, vcc, 0, v135, vcc
	s_mov_b32 s1, 0xb0000
	v_cvt_pk_bf16_f32 v27, v30, v31
	global_store_dwordx4 v[28:29], v[24:27], off
	v_cvt_pk_bf16_f32 v16, v16, v17
	v_cvt_pk_bf16_f32 v17, v18, v19
	v_cvt_pk_bf16_f32 v18, v8, v9
	v_cvt_pk_bf16_f32 v19, v10, v11
	global_store_dwordx4 v[32:33], v[16:19], off offset:256
	v_cvt_pk_bf16_f32 v8, v20, v21
	v_cvt_pk_bf16_f32 v9, v22, v23
	v_cvt_pk_bf16_f32 v10, v12, v13
	v_add_co_u32_e32 v12, vcc, s1, v134
	s_mov_b64 s[2:3], 0xb0000
	s_nop 0
	v_addc_co_u32_e32 v13, vcc, 0, v135, vcc
	v_lshl_add_u64 v[16:17], v[134:135], 0, s[2:3]
	s_and_b64 vcc, exec, s[40:41]
	s_mov_b64 s[70:71], s[44:45]
	v_readlane_b32 s96, v255, 17
	v_readlane_b32 s31, v255, 28
	v_cvt_pk_bf16_f32 v11, v14, v15
	global_store_dwordx4 v[12:13], v[8:11], off
	v_cvt_pk_bf16_f32 v4, v4, v5
	v_cvt_pk_bf16_f32 v5, v6, v7
	v_cvt_pk_bf16_f32 v6, v0, v1
	v_cvt_pk_bf16_f32 v7, v2, v3
	global_store_dwordx4 v[16:17], v[4:7], off offset:256
	v_readlane_b32 s97, v255, 18
	s_cbranch_vccz .LBB0_350
	s_waitcnt vmcnt(0)
	v_readlane_b32 s1, v255, 36
	v_readlane_b32 s90, v255, 23
	s_cmpk_gt_u32 s1, 0xff
	v_readlane_b32 s48, v255, 21
	v_readlane_b32 s91, v255, 24
	v_readlane_b32 s49, v255, 22
	s_cbranch_scc1 .LBB0_361
	s_barrier

.Lprio_521:
	s_add_i32 s92, 0, 0x10000
	v_add_u32_e32 v213, s92, v210
	ds_read_b128 v[128:131], v213
	ds_read_b128 v[140:143], v213 offset:1024
	ds_read_b128 v[144:147], v213 offset:2048
	ds_read_b128 v[148:151], v213 offset:3072
	v_lshl_add_u64 v[190:191], v[132:133], 0, s[44:45]
	s_add_i32 s90, s79, 0xc000
	v_lshl_add_u64 v[194:195], v[190:191], 0, s[18:19]
	s_mov_b32 m0, s90
	ds_read_b128 v[152:155], v211
	ds_read_b128 v[156:159], v211 offset:1024
	ds_read_b128 v[160:163], v211 offset:2048
	ds_read_b128 v[164:167], v211 offset:3072
	ds_read_b128 v[168:171], v211 offset:4096
	ds_read_b128 v[172:175], v211 offset:5120
	ds_read_b128 v[200:203], v211 offset:6144
	ds_read_b128 v[216:219], v211 offset:7168
	global_load_lds_dwordx4 v[194:195], off
	v_lshl_add_u64 v[194:195], v[134:135], 0, s[44:45]
	s_add_i32 s91, s79, 0xe000
	v_lshl_add_u64 v[204:205], v[194:195], 0, s[18:19]
	s_mov_b32 m0, s91
	s_nop 0
	global_load_lds_dwordx4 v[204:205], off
	s_waitcnt lgkmcnt(8)
	s_barrier
	s_waitcnt lgkmcnt(0)
	s_waitcnt lgkmcnt(0)
	v_mfma_f32_16x16x32_bf16 v[60:63], v[128:131], v[152:155], v[60:63]
	v_mfma_f32_16x16x32_bf16 v[56:59], v[144:147], v[152:155], v[56:59]
	v_mfma_f32_16x16x32_bf16 v[92:95], v[128:131], v[160:163], v[92:95]
	v_mfma_f32_16x16x32_bf16 v[88:91], v[144:147], v[160:163], v[88:91]
	v_mfma_f32_16x16x32_bf16 v[124:127], v[128:131], v[168:171], v[124:127]
	v_mfma_f32_16x16x32_bf16 v[120:123], v[144:147], v[168:171], v[120:123]
	v_mfma_f32_16x16x32_bf16 v[108:111], v[128:131], v[200:203], v[108:111]
	v_mfma_f32_16x16x32_bf16 v[104:107], v[144:147], v[200:203], v[104:107]
	v_mfma_f32_16x16x32_bf16 v[60:63], v[140:143], v[156:159], v[60:63]
	v_mfma_f32_16x16x32_bf16 v[56:59], v[148:151], v[156:159], v[56:59]
	v_mfma_f32_16x16x32_bf16 v[92:95], v[140:143], v[164:167], v[92:95]
	v_mfma_f32_16x16x32_bf16 v[88:91], v[148:151], v[164:167], v[88:91]
	v_mfma_f32_16x16x32_bf16 v[124:127], v[140:143], v[172:175], v[124:127]
	v_mfma_f32_16x16x32_bf16 v[120:123], v[148:151], v[172:175], v[120:123]
	v_mfma_f32_16x16x32_bf16 v[108:111], v[140:143], v[216:219], v[108:111]
	v_mfma_f32_16x16x32_bf16 v[104:107], v[148:151], v[216:219], v[104:107]
	s_barrier
	s_add_i32 s94, 0, 0x14000
	v_lshl_add_u64 v[204:205], v[136:137], 0, s[44:45]
	s_add_i32 s92, s92, s77
	v_add_u32_e32 v214, s94, v210
	v_lshl_add_u64 v[236:237], v[204:205], 0, s[24:25]
	s_mov_b32 m0, s92
	v_lshl_add_u64 v[238:239], v[138:139], 0, s[44:45]
	s_add_i32 s93, s92, 0x2000
	ds_read_b128 v[220:223], v214
	ds_read_b128 v[224:227], v214 offset:1024
	ds_read_b128 v[228:231], v214 offset:2048
	ds_read_b128 v[232:235], v214 offset:3072
	global_load_lds_dwordx4 v[236:237], off
	v_lshl_add_u64 v[236:237], v[238:239], 0, s[24:25]
	s_mov_b32 m0, s93
	s_nop 0
	global_load_lds_dwordx4 v[236:237], off
	s_barrier
	s_waitcnt lgkmcnt(0)
	s_waitcnt lgkmcnt(0)
	v_mfma_f32_16x16x32_bf16 v[52:55], v[220:223], v[152:155], v[52:55]
	v_mfma_f32_16x16x32_bf16 v[48:51], v[228:231], v[152:155], v[48:51]
	v_mfma_f32_16x16x32_bf16 v[84:87], v[220:223], v[160:163], v[84:87]
	v_mfma_f32_16x16x32_bf16 v[80:83], v[228:231], v[160:163], v[80:83]
	v_mfma_f32_16x16x32_bf16 v[116:119], v[220:223], v[168:171], v[116:119]
	v_mfma_f32_16x16x32_bf16 v[112:115], v[228:231], v[168:171], v[112:115]
	v_mfma_f32_16x16x32_bf16 v[100:103], v[220:223], v[200:203], v[100:103]
	v_mfma_f32_16x16x32_bf16 v[96:99], v[228:231], v[200:203], v[96:99]
	v_mfma_f32_16x16x32_bf16 v[52:55], v[224:227], v[156:159], v[52:55]
	v_mfma_f32_16x16x32_bf16 v[48:51], v[232:235], v[156:159], v[48:51]
	v_mfma_f32_16x16x32_bf16 v[84:87], v[224:227], v[164:167], v[84:87]
	v_mfma_f32_16x16x32_bf16 v[80:83], v[232:235], v[164:167], v[80:83]
	v_mfma_f32_16x16x32_bf16 v[116:119], v[224:227], v[172:175], v[116:119]
	v_mfma_f32_16x16x32_bf16 v[112:115], v[232:235], v[172:175], v[112:115]
	v_mfma_f32_16x16x32_bf16 v[100:103], v[224:227], v[216:219], v[100:103]
	v_mfma_f32_16x16x32_bf16 v[96:99], v[232:235], v[216:219], v[96:99]
	s_mov_b32 m0, s79
	v_lshl_add_u64 v[236:237], v[190:191], 0, s[24:25]
	s_barrier
	ds_read_b128 v[152:155], v211 offset:16384
	ds_read_b128 v[156:159], v211 offset:17408
	ds_read_b128 v[160:163], v211 offset:18432
	ds_read_b128 v[164:167], v211 offset:19456
	ds_read_b128 v[168:171], v211 offset:20480
	ds_read_b128 v[172:175], v211 offset:21504
	ds_read_b128 v[200:203], v211 offset:22528
	ds_read_b128 v[216:219], v211 offset:23552
	global_load_lds_dwordx4 v[236:237], off
	v_lshl_add_u64 v[236:237], v[194:195], 0, s[24:25]
	s_mov_b32 m0, s80
	s_nop 0
	global_load_lds_dwordx4 v[236:237], off
	s_barrier
	s_waitcnt lgkmcnt(0)
	s_waitcnt lgkmcnt(0)
	v_mfma_f32_16x16x32_bf16 v[76:79], v[128:131], v[152:155], v[76:79]
	v_mfma_f32_16x16x32_bf16 v[72:75], v[144:147], v[152:155], v[72:75]
	v_mfma_f32_16x16x32_bf16 v[44:47], v[128:131], v[160:163], v[44:47]
	v_mfma_f32_16x16x32_bf16 v[40:43], v[144:147], v[160:163], v[40:43]
	v_mfma_f32_16x16x32_bf16 v[28:31], v[128:131], v[168:171], v[28:31]
	v_mfma_f32_16x16x32_bf16 v[24:27], v[144:147], v[168:171], v[24:27]
	v_mfma_f32_16x16x32_bf16 v[12:15], v[128:131], v[200:203], v[12:15]
	v_mfma_f32_16x16x32_bf16 v[8:11], v[144:147], v[200:203], v[8:11]
	v_mfma_f32_16x16x32_bf16 v[76:79], v[140:143], v[156:159], v[76:79]
	v_mfma_f32_16x16x32_bf16 v[72:75], v[148:151], v[156:159], v[72:75]
	v_mfma_f32_16x16x32_bf16 v[44:47], v[140:143], v[164:167], v[44:47]
	v_mfma_f32_16x16x32_bf16 v[40:43], v[148:151], v[164:167], v[40:43]
	v_mfma_f32_16x16x32_bf16 v[28:31], v[140:143], v[172:175], v[28:31]
	v_mfma_f32_16x16x32_bf16 v[24:27], v[148:151], v[172:175], v[24:27]
	v_mfma_f32_16x16x32_bf16 v[12:15], v[140:143], v[216:219], v[12:15]
	v_mfma_f32_16x16x32_bf16 v[8:11], v[148:151], v[216:219], v[8:11]
	s_barrier
	s_add_i32 s94, s94, s77
	v_lshl_add_u64 v[128:129], v[204:205], 0, s[28:29]
	s_mov_b32 m0, s94
	s_add_i32 s95, s94, 0x2000
	global_load_lds_dwordx4 v[128:129], off
	v_lshl_add_u64 v[128:129], v[238:239], 0, s[28:29]
	s_mov_b32 m0, s95
	s_nop 0
	global_load_lds_dwordx4 v[128:129], off
	s_waitcnt vmcnt(6)
	s_barrier
	v_mfma_f32_16x16x32_bf16 v[68:71], v[220:223], v[152:155], v[68:71]
	v_mfma_f32_16x16x32_bf16 v[64:67], v[228:231], v[152:155], v[64:67]
	v_mfma_f32_16x16x32_bf16 v[36:39], v[220:223], v[160:163], v[36:39]
	v_mfma_f32_16x16x32_bf16 v[32:35], v[228:231], v[160:163], v[32:35]
	v_mfma_f32_16x16x32_bf16 v[20:23], v[220:223], v[168:171], v[20:23]
	v_mfma_f32_16x16x32_bf16 v[16:19], v[228:231], v[168:171], v[16:19]
	v_mfma_f32_16x16x32_bf16 v[4:7], v[220:223], v[200:203], v[4:7]
	v_mfma_f32_16x16x32_bf16 v[0:3], v[228:231], v[200:203], v[0:3]
	v_mfma_f32_16x16x32_bf16 v[68:71], v[224:227], v[156:159], v[68:71]
	v_mfma_f32_16x16x32_bf16 v[64:67], v[232:235], v[156:159], v[64:67]
	v_mfma_f32_16x16x32_bf16 v[36:39], v[224:227], v[164:167], v[36:39]
	v_mfma_f32_16x16x32_bf16 v[32:35], v[232:235], v[164:167], v[32:35]
	v_mfma_f32_16x16x32_bf16 v[20:23], v[224:227], v[172:175], v[20:23]
	v_mfma_f32_16x16x32_bf16 v[16:19], v[232:235], v[172:175], v[16:19]
	v_mfma_f32_16x16x32_bf16 v[4:7], v[224:227], v[216:219], v[4:7]
	v_mfma_f32_16x16x32_bf16 v[0:3], v[232:235], v[216:219], v[0:3]
	s_add_i32 s96, 0, 0x18000
	v_add_u32_e32 v215, s96, v210
	s_barrier
	ds_read_b128 v[128:131], v215
	ds_read_b128 v[140:143], v215 offset:1024
	ds_read_b128 v[144:147], v215 offset:2048
	ds_read_b128 v[148:151], v215 offset:3072
	s_mov_b32 m0, s81
	v_lshl_add_u64 v[216:217], v[190:191], 0, s[28:29]
	ds_read_b128 v[152:155], v211 offset:32768
	ds_read_b128 v[156:159], v211 offset:33792
	ds_read_b128 v[160:163], v211 offset:34816
	ds_read_b128 v[164:167], v211 offset:35840
	ds_read_b128 v[168:171], v211 offset:36864
	ds_read_b128 v[172:175], v211 offset:37888
	ds_read_b128 v[200:203], v211 offset:38912
	ds_read_b128 v[218:221], v211 offset:39936
	global_load_lds_dwordx4 v[216:217], off
	v_lshl_add_u64 v[216:217], v[194:195], 0, s[28:29]
	s_mov_b32 m0, s82
	s_nop 0
	global_load_lds_dwordx4 v[216:217], off
	s_waitcnt lgkmcnt(8)
	s_barrier
	s_waitcnt lgkmcnt(0)
	s_waitcnt lgkmcnt(0)
	v_mfma_f32_16x16x32_bf16 v[60:63], v[128:131], v[152:155], v[60:63]
	v_mfma_f32_16x16x32_bf16 v[56:59], v[144:147], v[152:155], v[56:59]
	v_mfma_f32_16x16x32_bf16 v[92:95], v[128:131], v[160:163], v[92:95]
	v_mfma_f32_16x16x32_bf16 v[88:91], v[144:147], v[160:163], v[88:91]
	v_mfma_f32_16x16x32_bf16 v[124:127], v[128:131], v[168:171], v[124:127]
	v_mfma_f32_16x16x32_bf16 v[120:123], v[144:147], v[168:171], v[120:123]
	v_mfma_f32_16x16x32_bf16 v[108:111], v[128:131], v[200:203], v[108:111]
	v_mfma_f32_16x16x32_bf16 v[104:107], v[144:147], v[200:203], v[104:107]
	v_mfma_f32_16x16x32_bf16 v[60:63], v[140:143], v[156:159], v[60:63]
	v_mfma_f32_16x16x32_bf16 v[56:59], v[148:151], v[156:159], v[56:59]
	v_mfma_f32_16x16x32_bf16 v[92:95], v[140:143], v[164:167], v[92:95]
	v_mfma_f32_16x16x32_bf16 v[88:91], v[148:151], v[164:167], v[88:91]
	v_mfma_f32_16x16x32_bf16 v[124:127], v[140:143], v[172:175], v[124:127]
	v_mfma_f32_16x16x32_bf16 v[120:123], v[148:151], v[172:175], v[120:123]
	v_mfma_f32_16x16x32_bf16 v[108:111], v[140:143], v[218:221], v[108:111]
	v_mfma_f32_16x16x32_bf16 v[104:107], v[148:151], v[218:221], v[104:107]
	s_barrier
	s_add_i32 s61, 0, 0x1c000
	s_add_i32 s96, s96, s77
	v_add_u32_e32 v216, s61, v210
	v_lshl_add_u64 v[240:241], v[204:205], 0, s[50:51]
	s_mov_b32 m0, s96
	s_add_i32 s60, s96, 0x2000
	ds_read_b128 v[222:225], v216
	ds_read_b128 v[226:229], v216 offset:1024
	ds_read_b128 v[230:233], v216 offset:2048
	ds_read_b128 v[234:237], v216 offset:3072
	global_load_lds_dwordx4 v[240:241], off
	v_lshl_add_u64 v[240:241], v[238:239], 0, s[50:51]
	s_mov_b32 m0, s60
	s_nop 0
	global_load_lds_dwordx4 v[240:241], off
	s_barrier
	s_waitcnt lgkmcnt(0)
	s_waitcnt lgkmcnt(0)
	v_mfma_f32_16x16x32_bf16 v[52:55], v[222:225], v[152:155], v[52:55]
	v_mfma_f32_16x16x32_bf16 v[48:51], v[230:233], v[152:155], v[48:51]
	v_mfma_f32_16x16x32_bf16 v[84:87], v[222:225], v[160:163], v[84:87]
	v_mfma_f32_16x16x32_bf16 v[80:83], v[230:233], v[160:163], v[80:83]
	v_mfma_f32_16x16x32_bf16 v[116:119], v[222:225], v[168:171], v[116:119]
	v_mfma_f32_16x16x32_bf16 v[112:115], v[230:233], v[168:171], v[112:115]
	v_mfma_f32_16x16x32_bf16 v[100:103], v[222:225], v[200:203], v[100:103]
	v_mfma_f32_16x16x32_bf16 v[96:99], v[230:233], v[200:203], v[96:99]
	v_mfma_f32_16x16x32_bf16 v[52:55], v[226:229], v[156:159], v[52:55]
	v_mfma_f32_16x16x32_bf16 v[48:51], v[234:237], v[156:159], v[48:51]
	v_mfma_f32_16x16x32_bf16 v[84:87], v[226:229], v[164:167], v[84:87]
	v_mfma_f32_16x16x32_bf16 v[80:83], v[234:237], v[164:167], v[80:83]
	v_mfma_f32_16x16x32_bf16 v[116:119], v[226:229], v[172:175], v[116:119]
	v_mfma_f32_16x16x32_bf16 v[112:115], v[234:237], v[172:175], v[112:115]
	v_mfma_f32_16x16x32_bf16 v[100:103], v[226:229], v[218:221], v[100:103]
	v_mfma_f32_16x16x32_bf16 v[96:99], v[234:237], v[218:221], v[96:99]
	s_mov_b32 m0, s87
	v_lshl_add_u64 v[190:191], v[190:191], 0, s[50:51]
	s_barrier
	ds_read_b128 v[152:155], v211 offset:49152
	ds_read_b128 v[156:159], v211 offset:50176
	ds_read_b128 v[160:163], v211 offset:51200
	ds_read_b128 v[164:167], v211 offset:52224
	ds_read_b128 v[168:171], v211 offset:53248
	ds_read_b128 v[172:175], v211 offset:54272
	ds_read_b128 v[200:203], v211 offset:55296
	ds_read_b128 v[218:221], v211 offset:56320
	global_load_lds_dwordx4 v[190:191], off
	v_lshl_add_u64 v[190:191], v[194:195], 0, s[50:51]
	s_mov_b32 m0, s88
	s_nop 0
	global_load_lds_dwordx4 v[190:191], off
	s_barrier
	s_waitcnt lgkmcnt(0)
	s_waitcnt lgkmcnt(0)
	v_mfma_f32_16x16x32_bf16 v[76:79], v[128:131], v[152:155], v[76:79]
	v_mfma_f32_16x16x32_bf16 v[72:75], v[144:147], v[152:155], v[72:75]
	v_mfma_f32_16x16x32_bf16 v[44:47], v[128:131], v[160:163], v[44:47]
	v_mfma_f32_16x16x32_bf16 v[40:43], v[144:147], v[160:163], v[40:43]
	v_mfma_f32_16x16x32_bf16 v[28:31], v[128:131], v[168:171], v[28:31]
	v_mfma_f32_16x16x32_bf16 v[24:27], v[144:147], v[168:171], v[24:27]
	v_mfma_f32_16x16x32_bf16 v[12:15], v[128:131], v[200:203], v[12:15]
	v_mfma_f32_16x16x32_bf16 v[8:11], v[144:147], v[200:203], v[8:11]
	v_mfma_f32_16x16x32_bf16 v[76:79], v[140:143], v[156:159], v[76:79]
	v_mfma_f32_16x16x32_bf16 v[72:75], v[148:151], v[156:159], v[72:75]
	v_mfma_f32_16x16x32_bf16 v[44:47], v[140:143], v[164:167], v[44:47]
	v_mfma_f32_16x16x32_bf16 v[40:43], v[148:151], v[164:167], v[40:43]
	v_mfma_f32_16x16x32_bf16 v[28:31], v[140:143], v[172:175], v[28:31]
	v_mfma_f32_16x16x32_bf16 v[24:27], v[148:151], v[172:175], v[24:27]
	v_mfma_f32_16x16x32_bf16 v[12:15], v[140:143], v[218:221], v[12:15]
	v_mfma_f32_16x16x32_bf16 v[8:11], v[148:151], v[218:221], v[8:11]
	s_barrier
	s_add_i32 s61, s61, s77
	v_lshl_add_u64 v[128:129], v[204:205], 0, s[6:7]
	s_mov_b32 m0, s61
	s_add_i32 s49, s61, 0x2000
	global_load_lds_dwordx4 v[128:129], off
	v_lshl_add_u64 v[128:129], v[238:239], 0, s[6:7]
	s_mov_b32 m0, s49
	s_nop 0
	global_load_lds_dwordx4 v[128:129], off
	s_waitcnt vmcnt(6)
	s_barrier
	v_mfma_f32_16x16x32_bf16 v[68:71], v[222:225], v[152:155], v[68:71]
	v_mfma_f32_16x16x32_bf16 v[64:67], v[230:233], v[152:155], v[64:67]
	v_mfma_f32_16x16x32_bf16 v[36:39], v[222:225], v[160:163], v[36:39]
	v_mfma_f32_16x16x32_bf16 v[32:35], v[230:233], v[160:163], v[32:35]
	v_mfma_f32_16x16x32_bf16 v[20:23], v[222:225], v[168:171], v[20:23]
	v_mfma_f32_16x16x32_bf16 v[16:19], v[230:233], v[168:171], v[16:19]
	v_mfma_f32_16x16x32_bf16 v[4:7], v[222:225], v[200:203], v[4:7]
	v_mfma_f32_16x16x32_bf16 v[0:3], v[230:233], v[200:203], v[0:3]
	v_mfma_f32_16x16x32_bf16 v[68:71], v[226:229], v[156:159], v[68:71]
	v_mfma_f32_16x16x32_bf16 v[64:67], v[234:237], v[156:159], v[64:67]
	v_mfma_f32_16x16x32_bf16 v[36:39], v[226:229], v[164:167], v[36:39]
	v_mfma_f32_16x16x32_bf16 v[32:35], v[234:237], v[164:167], v[32:35]
	v_mfma_f32_16x16x32_bf16 v[20:23], v[226:229], v[172:175], v[20:23]
	v_mfma_f32_16x16x32_bf16 v[16:19], v[234:237], v[172:175], v[16:19]
	v_mfma_f32_16x16x32_bf16 v[4:7], v[226:229], v[218:221], v[4:7]
	v_mfma_f32_16x16x32_bf16 v[0:3], v[234:237], v[218:221], v[0:3]
	s_add_i32 s39, s39, 2
	s_add_u32 s44, s44, 0x100
	s_addc_u32 s45, s45, 0
	s_cmp_gt_u32 s39, 13
	s_barrier
	s_cbranch_scc0 .LBB0_521
	s_setprio 0
	s_lshl_b32 s52, s52, 8
	s_add_i32 s1, s52, s86
	v_mov_b32_e32 v128, v208
	v_readlane_b32 s12, v254, 31
	v_bfe_u32 v154, v128, 4, 2
	v_and_or_b32 v155, v128, 15, s1
	v_lshlrev_b32_e32 v157, 1, v154
	v_lshl_or_b32 v128, v155, 3, v157
	v_ashrrev_i32_e32 v129, 31, v128
	v_readlane_b32 s13, v254, 32
	v_readlane_b32 s2, v254, 29
	v_readlane_b32 s3, v254, 30
	v_lshl_add_u64 v[128:129], v[128:129], 2, s[12:13]
	global_load_dwordx2 v[128:129], v[128:129], off
	v_or_b32_e32 v130, 16, v155
	s_mov_b32 s14, 0x358637bd
	s_waitcnt vmcnt(0)
	v_pk_add_f32 v[158:159], v[128:129], v[128:129] op_sel:[0,1] op_sel_hi:[1,0]
	v_lshl_or_b32 v128, v155, 2, v154
	v_ashrrev_i32_e32 v129, 31, v128
	v_lshl_add_u64 v[128:129], v[128:129], 2, s[2:3]
	global_load_dword v160, v[128:129], off
	v_lshl_or_b32 v128, v130, 3, v157
	v_ashrrev_i32_e32 v129, 31, v128
	v_lshl_add_u64 v[128:129], v[128:129], 2, s[12:13]
	global_load_dwordx2 v[128:129], v[128:129], off
	ds_bpermute_b32 v163, v207, v158
	v_mov_b32_e32 v161, v158
	s_waitcnt vmcnt(0)
	ds_bpermute_b32 v162, v207, v160
	v_pk_add_f32 v[148:149], v[128:129], v[128:129] op_sel:[0,1] op_sel_hi:[1,0]
	v_lshl_or_b32 v128, v130, 2, v154
	v_ashrrev_i32_e32 v129, 31, v128
	v_lshl_add_u64 v[128:129], v[128:129], 2, s[2:3]
	v_or_b32_e32 v130, 32, v155
	global_load_dword v150, v[128:129], off
	v_lshl_or_b32 v128, v130, 3, v157
	v_ashrrev_i32_e32 v129, 31, v128
	v_lshl_add_u64 v[128:129], v[128:129], 2, s[12:13]
	global_load_dwordx2 v[128:129], v[128:129], off
	s_waitcnt lgkmcnt(0)
	v_pk_add_f32 v[158:159], v[160:161], v[162:163]
	ds_bpermute_b32 v161, v206, v159
	ds_bpermute_b32 v160, v206, v158
	ds_bpermute_b32 v153, v207, v148
	v_mov_b32_e32 v151, v148
	s_waitcnt lgkmcnt(1)
	v_pk_add_f32 v[160:161], v[158:159], v[160:161]
	v_mov_b64_e32 v[158:159], s[14:15]
	s_mov_b32 s14, 0x3b000000
	s_mov_b32 s15, 0x3a800000
	v_pk_fma_f32 v[160:161], v[160:161], s[14:15], v[158:159] op_sel_hi:[1,1,0]
	s_waitcnt vmcnt(1)
	ds_bpermute_b32 v152, v207, v150
	v_cmp_gt_f32_e64 s[46:47], s33, v161
	v_cmp_gt_f32_e64 s[44:45], s33, v160
	s_waitcnt vmcnt(0)
	v_pk_add_f32 v[144:145], v[128:129], v[128:129] op_sel:[0,1] op_sel_hi:[1,0]
	v_lshl_or_b32 v128, v130, 2, v154
	v_ashrrev_i32_e32 v129, 31, v128
	v_lshl_add_u64 v[128:129], v[128:129], 2, s[2:3]
	v_or_b32_e32 v130, 48, v155
	global_load_dword v142, v[128:129], off
	v_lshl_or_b32 v128, v130, 3, v157
	v_ashrrev_i32_e32 v129, 31, v128
	v_lshl_add_u64 v[128:129], v[128:129], 2, s[12:13]
	global_load_dwordx2 v[128:129], v[128:129], off
	v_lshl_or_b32 v130, v130, 2, v154
	v_ashrrev_i32_e32 v131, 31, v130
	v_lshl_add_u64 v[130:131], v[130:131], 2, s[2:3]
	global_load_dword v130, v[130:131], off
	s_waitcnt lgkmcnt(0)
	v_pk_add_f32 v[148:149], v[150:151], v[152:153]
	ds_bpermute_b32 v151, v206, v149
	ds_bpermute_b32 v150, v206, v148
	ds_bpermute_b32 v147, v207, v144
	s_waitcnt lgkmcnt(1)
	v_pk_add_f32 v[148:149], v[148:149], v[150:151]
	s_nop 0
	v_pk_fma_f32 v[148:149], v[148:149], s[14:15], v[158:159] op_sel_hi:[1,1,0]
	s_waitcnt vmcnt(2)
	ds_bpermute_b32 v146, v207, v142
	s_waitcnt vmcnt(1)
	v_pk_add_f32 v[128:129], v[128:129], v[128:129] op_sel:[0,1] op_sel_hi:[1,0]
	s_nop 0
	v_mul_f32_e32 v129, 0x4b800000, v161
	v_cndmask_b32_e64 v129, v161, v129, s[46:47]
	v_rsq_f32_e32 v129, v129
	ds_bpermute_b32 v141, v207, v128
	s_waitcnt vmcnt(0)
	ds_bpermute_b32 v140, v207, v130
	v_mul_f32_e32 v131, 0x45800000, v129
	v_cndmask_b32_e64 v129, v129, v131, s[46:47]
	v_mul_f32_e32 v131, 0x4b800000, v160
	v_cndmask_b32_e64 v131, v160, v131, s[44:45]
	v_rsq_f32_e32 v131, v131
	v_mul_f32_e32 v129, v160, v129
	v_cmp_gt_f32_e64 s[46:47], s33, v149
	v_mul_f32_e32 v143, 0x45800000, v131
	v_cndmask_b32_e64 v156, v131, v143, s[44:45]
	v_mul_f32_e32 v160, v129, v156
	v_mul_f32_e32 v129, 0x4b800000, v149
	v_cndmask_b32_e64 v129, v149, v129, s[46:47]
	v_rsq_f32_e32 v129, v129
	v_cmp_gt_f32_e64 s[44:45], s33, v148
	v_pk_mul_f32 v[62:63], v[62:63], v[160:161] op_sel_hi:[1,0]
	v_pk_mul_f32 v[60:61], v[60:61], v[160:161] op_sel_hi:[1,0]
	v_mul_f32_e32 v131, 0x45800000, v129
	v_cndmask_b32_e64 v129, v129, v131, s[46:47]
	v_mul_f32_e32 v131, 0x4b800000, v148
	v_cndmask_b32_e64 v131, v148, v131, s[44:45]
	v_rsq_f32_e32 v131, v131
	v_mul_f32_e32 v129, v148, v129
	v_pk_mul_f32 v[58:59], v[58:59], v[160:161] op_sel_hi:[1,0]
	v_pk_mul_f32 v[56:57], v[56:57], v[160:161] op_sel_hi:[1,0]
	v_mul_f32_e32 v143, 0x45800000, v131
	v_cndmask_b32_e64 v188, v131, v143, s[44:45]
	v_mov_b32_e32 v143, v144
	s_waitcnt lgkmcnt(2)
	v_pk_add_f32 v[142:143], v[142:143], v[146:147]
	ds_bpermute_b32 v145, v206, v143
	ds_bpermute_b32 v144, v206, v142
	v_mul_f32_e32 v148, v129, v188
	v_pk_mul_f32 v[54:55], v[54:55], v[160:161] op_sel_hi:[1,0]
	v_pk_mul_f32 v[52:53], v[52:53], v[160:161] op_sel_hi:[1,0]
	v_pk_mul_f32 v[50:51], v[50:51], v[160:161] op_sel_hi:[1,0]
	s_waitcnt lgkmcnt(0)
	v_pk_add_f32 v[142:143], v[142:143], v[144:145]
	v_pk_mul_f32 v[48:49], v[48:49], v[160:161] op_sel_hi:[1,0]
	v_pk_fma_f32 v[142:143], v[142:143], s[14:15], v[158:159] op_sel_hi:[1,1,0]
	v_pk_mul_f32 v[94:95], v[94:95], v[148:149] op_sel_hi:[1,0]
	v_mul_f32_e32 v129, 0x4b800000, v143
	v_cmp_gt_f32_e64 s[46:47], s33, v143
	v_cmp_gt_f32_e64 s[44:45], s33, v142
	v_pk_mul_f32 v[92:93], v[92:93], v[148:149] op_sel_hi:[1,0]
	v_cndmask_b32_e64 v129, v143, v129, s[46:47]
	v_rsq_f32_e32 v129, v129
	v_pk_mul_f32 v[90:91], v[90:91], v[148:149] op_sel_hi:[1,0]
	v_pk_mul_f32 v[88:89], v[88:89], v[148:149] op_sel_hi:[1,0]
	v_pk_mul_f32 v[86:87], v[86:87], v[148:149] op_sel_hi:[1,0]
	v_mul_f32_e32 v131, 0x45800000, v129
	v_cndmask_b32_e64 v129, v129, v131, s[46:47]
	v_mul_f32_e32 v131, 0x4b800000, v142
	v_cndmask_b32_e64 v131, v142, v131, s[44:45]
	v_rsq_f32_e32 v131, v131
	v_mul_f32_e32 v129, v142, v129
	v_pk_mul_f32 v[84:85], v[84:85], v[148:149] op_sel_hi:[1,0]
	v_pk_mul_f32 v[82:83], v[82:83], v[148:149] op_sel_hi:[1,0]
	v_mul_f32_e32 v143, 0x45800000, v131
	v_cndmask_b32_e64 v190, v131, v143, s[44:45]
	v_mov_b32_e32 v131, v128
	v_mul_f32_e32 v142, v129, v190
	v_pk_add_f32 v[128:129], v[130:131], v[140:141]
	ds_bpermute_b32 v131, v206, v129
	ds_bpermute_b32 v130, v206, v128
	v_pk_mul_f32 v[80:81], v[80:81], v[148:149] op_sel_hi:[1,0]
	v_pk_mul_f32 v[126:127], v[126:127], v[142:143] op_sel_hi:[1,0]
	v_pk_mul_f32 v[124:125], v[124:125], v[142:143] op_sel_hi:[1,0]
	v_pk_mul_f32 v[122:123], v[122:123], v[142:143] op_sel_hi:[1,0]
	s_waitcnt lgkmcnt(0)
	v_pk_add_f32 v[128:129], v[128:129], v[130:131]
	v_pk_mul_f32 v[120:121], v[120:121], v[142:143] op_sel_hi:[1,0]
	v_pk_fma_f32 v[128:129], v[128:129], s[14:15], v[158:159] op_sel_hi:[1,1,0]
	v_pk_mul_f32 v[118:119], v[118:119], v[142:143] op_sel_hi:[1,0]
	v_mul_f32_e32 v130, 0x4b800000, v129
	v_cmp_gt_f32_e64 s[46:47], s33, v129
	v_cmp_gt_f32_e64 s[44:45], s33, v128
	v_pk_mul_f32 v[116:117], v[116:117], v[142:143] op_sel_hi:[1,0]
	v_cndmask_b32_e64 v129, v129, v130, s[46:47]
	v_rsq_f32_e32 v129, v129
	v_pk_mul_f32 v[114:115], v[114:115], v[142:143] op_sel_hi:[1,0]
	v_pk_mul_f32 v[112:113], v[112:113], v[142:143] op_sel_hi:[1,0]
	v_mul_f32_e32 v130, 0x45800000, v129
	v_cndmask_b32_e64 v129, v129, v130, s[46:47]
	v_mul_f32_e32 v130, 0x4b800000, v128
	v_cndmask_b32_e64 v130, v128, v130, s[44:45]
	v_rsq_f32_e32 v130, v130
	v_mul_f32_e32 v128, v128, v129
	v_mul_f32_e32 v131, 0x45800000, v130
	v_cndmask_b32_e64 v192, v130, v131, s[44:45]
	v_mul_f32_e32 v140, v128, v192
	v_pk_mul_f32 v[130:131], v[110:111], v[140:141] op_sel_hi:[1,0]
	v_pk_mul_f32 v[128:129], v[108:109], v[140:141] op_sel_hi:[1,0]
	v_pk_mul_f32 v[110:111], v[106:107], v[140:141] op_sel_hi:[1,0]
	v_pk_mul_f32 v[108:109], v[104:105], v[140:141] op_sel_hi:[1,0]
	v_pk_mul_f32 v[106:107], v[102:103], v[140:141] op_sel_hi:[1,0]
	v_pk_mul_f32 v[104:105], v[100:101], v[140:141] op_sel_hi:[1,0]
	v_pk_mul_f32 v[102:103], v[98:99], v[140:141] op_sel_hi:[1,0]
	v_pk_mul_f32 v[100:101], v[96:97], v[140:141] op_sel_hi:[1,0]
	v_add_u32_e32 v98, 0x80, v155
	v_lshl_or_b32 v96, v98, 3, v157
	v_ashrrev_i32_e32 v97, 31, v96
	v_lshl_add_u64 v[96:97], v[96:97], 2, s[12:13]
	global_load_dwordx2 v[96:97], v[96:97], off
	s_waitcnt vmcnt(0)
	v_pk_add_f32 v[140:141], v[96:97], v[96:97] op_sel:[0,1] op_sel_hi:[1,0]
	v_lshl_or_b32 v96, v98, 2, v154
	v_ashrrev_i32_e32 v97, 31, v96
	v_lshl_add_u64 v[96:97], v[96:97], 2, s[2:3]
	v_add_u32_e32 v98, 0x90, v155
	global_load_dword v142, v[96:97], off
	v_lshl_or_b32 v96, v98, 3, v157
	v_ashrrev_i32_e32 v97, 31, v96
	v_lshl_add_u64 v[96:97], v[96:97], 2, s[12:13]
	global_load_dwordx2 v[96:97], v[96:97], off
	ds_bpermute_b32 v145, v207, v140
	v_mov_b32_e32 v143, v140
	s_waitcnt vmcnt(1)
	ds_bpermute_b32 v144, v207, v142
	s_waitcnt vmcnt(0)
	v_pk_add_f32 v[168:169], v[96:97], v[96:97] op_sel:[0,1] op_sel_hi:[1,0]
	v_lshl_or_b32 v96, v98, 2, v154
	v_ashrrev_i32_e32 v97, 31, v96
	v_lshl_add_u64 v[96:97], v[96:97], 2, s[2:3]
	v_add_u32_e32 v98, 0xa0, v155
	global_load_dword v170, v[96:97], off
	v_lshl_or_b32 v96, v98, 3, v157
	v_ashrrev_i32_e32 v97, 31, v96
	v_lshl_add_u64 v[96:97], v[96:97], 2, s[12:13]
	global_load_dwordx2 v[96:97], v[96:97], off
	s_waitcnt lgkmcnt(0)
	v_pk_add_f32 v[140:141], v[142:143], v[144:145]
	ds_bpermute_b32 v143, v206, v141
	ds_bpermute_b32 v142, v206, v140
	ds_bpermute_b32 v173, v207, v168
	v_mov_b32_e32 v171, v168
	s_waitcnt lgkmcnt(1)
	v_pk_add_f32 v[140:141], v[140:141], v[142:143]
	s_nop 0
	v_pk_fma_f32 v[140:141], v[140:141], s[14:15], v[158:159] op_sel_hi:[1,1,0]
	s_waitcnt vmcnt(1)
	ds_bpermute_b32 v172, v207, v170
	v_cmp_gt_f32_e64 s[46:47], s33, v141
	v_cmp_gt_f32_e64 s[44:45], s33, v140
	s_waitcnt vmcnt(0)
	v_pk_add_f32 v[162:163], v[96:97], v[96:97] op_sel:[0,1] op_sel_hi:[1,0]
	v_lshl_or_b32 v96, v98, 2, v154
	v_ashrrev_i32_e32 v97, 31, v96
	v_lshl_add_u64 v[96:97], v[96:97], 2, s[2:3]
	v_add_u32_e32 v98, 0xb0, v155
	global_load_dword v164, v[96:97], off
	v_lshl_or_b32 v96, v98, 3, v157
	v_ashrrev_i32_e32 v97, 31, v96
	v_lshl_add_u64 v[96:97], v[96:97], 2, s[12:13]
	global_load_dwordx2 v[96:97], v[96:97], off
	v_lshl_or_b32 v98, v98, 2, v154
	v_ashrrev_i32_e32 v99, 31, v98
	v_lshl_add_u64 v[98:99], v[98:99], 2, s[2:3]
	global_load_dword v98, v[98:99], off
	ds_bpermute_b32 v167, v207, v162
	v_mov_b32_e32 v165, v162
	s_waitcnt vmcnt(2)
	ds_bpermute_b32 v166, v207, v164
	s_waitcnt vmcnt(1)
	v_pk_add_f32 v[96:97], v[96:97], v[96:97] op_sel:[0,1] op_sel_hi:[1,0]
	s_nop 0
	v_mul_f32_e32 v97, 0x4b800000, v141
	v_cndmask_b32_e64 v97, v141, v97, s[46:47]
	v_rsq_f32_e32 v97, v97
	ds_bpermute_b32 v161, v207, v96
	s_waitcnt vmcnt(0)
	ds_bpermute_b32 v160, v207, v98
	v_mul_f32_e32 v99, 0x45800000, v97
	v_cndmask_b32_e64 v97, v97, v99, s[46:47]
	v_mul_f32_e32 v99, 0x4b800000, v140
	v_cndmask_b32_e64 v99, v140, v99, s[44:45]
	v_rsq_f32_e32 v99, v99
	v_mul_f32_e32 v97, v140, v97
	v_mul_f32_e32 v141, 0x45800000, v99
	v_cndmask_b32_e64 v194, v99, v141, s[44:45]
	v_mul_f32_e32 v140, v97, v194
	v_pk_mul_f32 v[154:155], v[78:79], v[140:141] op_sel_hi:[1,0]
	v_pk_mul_f32 v[152:153], v[76:77], v[140:141] op_sel_hi:[1,0]
	v_pk_mul_f32 v[150:151], v[74:75], v[140:141] op_sel_hi:[1,0]
	v_pk_mul_f32 v[148:149], v[72:73], v[140:141] op_sel_hi:[1,0]
	v_pk_mul_f32 v[146:147], v[70:71], v[140:141] op_sel_hi:[1,0]
	v_pk_mul_f32 v[144:145], v[68:69], v[140:141] op_sel_hi:[1,0]
	v_pk_mul_f32 v[142:143], v[66:67], v[140:141] op_sel_hi:[1,0]
	v_pk_mul_f32 v[140:141], v[64:65], v[140:141] op_sel_hi:[1,0]
	s_waitcnt lgkmcnt(4)
	v_pk_add_f32 v[64:65], v[170:171], v[172:173]
	ds_bpermute_b32 v67, v206, v65
	ds_bpermute_b32 v66, v206, v64
	v_mov_b32_e32 v99, v96
	s_waitcnt lgkmcnt(0)
	v_pk_add_f32 v[64:65], v[64:65], v[66:67]
	s_nop 0
	v_pk_fma_f32 v[64:65], v[64:65], s[14:15], v[158:159] op_sel_hi:[1,1,0]
	s_nop 0
	v_mul_f32_e32 v66, 0x4b800000, v65
	v_cmp_gt_f32_e64 s[46:47], s33, v65
	v_cmp_gt_f32_e64 s[44:45], s33, v64
	s_nop 0
	v_cndmask_b32_e64 v65, v65, v66, s[46:47]
	v_rsq_f32_e32 v65, v65
	s_nop 0
	v_mul_f32_e32 v66, 0x45800000, v65
	v_cndmask_b32_e64 v65, v65, v66, s[46:47]
	v_mul_f32_e32 v66, 0x4b800000, v64
	v_cndmask_b32_e64 v66, v64, v66, s[44:45]
	v_rsq_f32_e32 v66, v66
	v_mul_f32_e32 v64, v64, v65
	v_mul_f32_e32 v67, 0x45800000, v66
	v_cndmask_b32_e64 v196, v66, v67, s[44:45]
	v_mul_f32_e32 v64, v64, v196
	v_pk_mul_f32 v[46:47], v[46:47], v[64:65] op_sel_hi:[1,0]
	v_pk_mul_f32 v[44:45], v[44:45], v[64:65] op_sel_hi:[1,0]
	v_pk_mul_f32 v[42:43], v[42:43], v[64:65] op_sel_hi:[1,0]
	v_pk_mul_f32 v[40:41], v[40:41], v[64:65] op_sel_hi:[1,0]
	v_pk_mul_f32 v[38:39], v[38:39], v[64:65] op_sel_hi:[1,0]
	v_pk_mul_f32 v[36:37], v[36:37], v[64:65] op_sel_hi:[1,0]
	v_pk_mul_f32 v[34:35], v[34:35], v[64:65] op_sel_hi:[1,0]
	v_pk_mul_f32 v[32:33], v[32:33], v[64:65] op_sel_hi:[1,0]
	v_pk_add_f32 v[64:65], v[164:165], v[166:167]
	ds_bpermute_b32 v67, v206, v65
	ds_bpermute_b32 v66, v206, v64
	s_waitcnt lgkmcnt(0)
	v_pk_add_f32 v[64:65], v[64:65], v[66:67]
	s_nop 0
	v_pk_fma_f32 v[64:65], v[64:65], s[14:15], v[158:159] op_sel_hi:[1,1,0]
	s_nop 0
	v_mul_f32_e32 v66, 0x4b800000, v65
	v_cmp_gt_f32_e64 s[46:47], s33, v65
	v_cmp_gt_f32_e64 s[44:45], s33, v64
	s_nop 0
	v_cndmask_b32_e64 v65, v65, v66, s[46:47]
	v_rsq_f32_e32 v65, v65
	s_nop 0
	v_mul_f32_e32 v66, 0x45800000, v65
	v_cndmask_b32_e64 v65, v65, v66, s[46:47]
	v_mul_f32_e32 v66, 0x4b800000, v64
	v_cndmask_b32_e64 v66, v64, v66, s[44:45]
	v_rsq_f32_e32 v66, v66
	v_mul_f32_e32 v64, v64, v65
	v_mul_f32_e32 v67, 0x45800000, v66
	v_cndmask_b32_e64 v198, v66, v67, s[44:45]
	v_mul_f32_e32 v64, v64, v198
	v_pk_mul_f32 v[30:31], v[30:31], v[64:65] op_sel_hi:[1,0]
	v_pk_mul_f32 v[28:29], v[28:29], v[64:65] op_sel_hi:[1,0]
	v_pk_mul_f32 v[26:27], v[26:27], v[64:65] op_sel_hi:[1,0]
	v_pk_mul_f32 v[24:25], v[24:25], v[64:65] op_sel_hi:[1,0]
	v_pk_mul_f32 v[22:23], v[22:23], v[64:65] op_sel_hi:[1,0]
	v_pk_mul_f32 v[20:21], v[20:21], v[64:65] op_sel_hi:[1,0]
	v_pk_mul_f32 v[18:19], v[18:19], v[64:65] op_sel_hi:[1,0]
	v_pk_mul_f32 v[16:17], v[16:17], v[64:65] op_sel_hi:[1,0]
	v_pk_add_f32 v[64:65], v[98:99], v[160:161]
	ds_bpermute_b32 v67, v206, v65
	ds_bpermute_b32 v66, v206, v64
	s_waitcnt lgkmcnt(0)
	v_pk_add_f32 v[64:65], v[64:65], v[66:67]
	s_nop 0
	v_pk_fma_f32 v[64:65], v[64:65], s[14:15], v[158:159] op_sel_hi:[1,1,0]
	s_nop 0
	v_mul_f32_e32 v66, 0x4b800000, v65
	v_cmp_gt_f32_e64 s[46:47], s33, v65
	v_cmp_gt_f32_e64 s[44:45], s33, v64
	s_nop 0
	v_cndmask_b32_e64 v65, v65, v66, s[46:47]
	v_rsq_f32_e32 v65, v65
	s_nop 0
	v_mul_f32_e32 v66, 0x45800000, v65
	v_cndmask_b32_e64 v65, v65, v66, s[46:47]
	v_mul_f32_e32 v66, 0x4b800000, v64
	v_cndmask_b32_e64 v66, v64, v66, s[44:45]
	v_rsq_f32_e32 v66, v66
	v_mul_f32_e32 v64, v64, v65
	v_mul_f32_e32 v67, 0x45800000, v66
	v_cndmask_b32_e64 v200, v66, v67, s[44:45]
	v_mul_f32_e32 v64, v64, v200
	v_pk_mul_f32 v[14:15], v[14:15], v[64:65] op_sel_hi:[1,0]
	v_pk_mul_f32 v[12:13], v[12:13], v[64:65] op_sel_hi:[1,0]
	v_pk_mul_f32 v[10:11], v[10:11], v[64:65] op_sel_hi:[1,0]
	v_pk_mul_f32 v[8:9], v[8:9], v[64:65] op_sel_hi:[1,0]
	v_pk_mul_f32 v[6:7], v[6:7], v[64:65] op_sel_hi:[1,0]
	v_pk_mul_f32 v[4:5], v[4:5], v[64:65] op_sel_hi:[1,0]
	v_pk_mul_f32 v[2:3], v[2:3], v[64:65] op_sel_hi:[1,0]
	v_pk_mul_f32 v[0:1], v[0:1], v[64:65] op_sel_hi:[1,0]
	s_mov_b32 s30, 14
	s_mov_b64 s[44:45], 0

.Lprio_523:
	ds_read_b128 v[64:67], v213
	ds_read_b128 v[68:71], v213 offset:1024
	ds_read_b128 v[72:75], v213 offset:2048
	ds_read_b128 v[76:79], v213 offset:3072
	v_lshl_add_u64 v[174:175], v[132:133], 0, s[44:45]
	s_mov_b32 m0, s90
	v_lshl_add_u64 v[226:227], v[174:175], 0, s[54:55]
	v_lshl_add_u64 v[242:243], v[134:135], 0, s[44:45]
	ds_read_b128 v[96:99], v211
	ds_read_b128 v[158:161], v211 offset:1024
	ds_read_b128 v[162:165], v211 offset:2048
	ds_read_b128 v[166:169], v211 offset:3072
	ds_read_b128 v[170:173], v211 offset:4096
	ds_read_b128 v[202:205], v211 offset:5120
	ds_read_b128 v[218:221], v211 offset:6144
	ds_read_b128 v[222:225], v211 offset:7168
	global_load_lds_dwordx4 v[226:227], off
	v_lshl_add_u64 v[226:227], v[242:243], 0, s[54:55]
	s_mov_b32 m0, s91
	s_nop 0
	global_load_lds_dwordx4 v[226:227], off
	s_waitcnt lgkmcnt(8)
	s_barrier
	s_waitcnt lgkmcnt(0)
	s_waitcnt lgkmcnt(0)
	v_mfma_f32_16x16x32_bf16 v[60:63], v[64:67], v[96:99], v[60:63]
	v_mfma_f32_16x16x32_bf16 v[56:59], v[72:75], v[96:99], v[56:59]
	v_mfma_f32_16x16x32_bf16 v[92:95], v[64:67], v[162:165], v[92:95]
	v_mfma_f32_16x16x32_bf16 v[88:91], v[72:75], v[162:165], v[88:91]
	v_mfma_f32_16x16x32_bf16 v[124:127], v[64:67], v[170:173], v[124:127]
	v_mfma_f32_16x16x32_bf16 v[120:123], v[72:75], v[170:173], v[120:123]
	v_mfma_f32_16x16x32_bf16 v[128:131], v[64:67], v[218:221], v[128:131]
	v_mfma_f32_16x16x32_bf16 v[108:111], v[72:75], v[218:221], v[108:111]
	v_mfma_f32_16x16x32_bf16 v[60:63], v[68:71], v[158:161], v[60:63]
	v_mfma_f32_16x16x32_bf16 v[56:59], v[76:79], v[158:161], v[56:59]
	v_mfma_f32_16x16x32_bf16 v[92:95], v[68:71], v[166:169], v[92:95]
	v_mfma_f32_16x16x32_bf16 v[88:91], v[76:79], v[166:169], v[88:91]
	v_mfma_f32_16x16x32_bf16 v[124:127], v[68:71], v[202:205], v[124:127]
	v_mfma_f32_16x16x32_bf16 v[120:123], v[76:79], v[202:205], v[120:123]
	v_mfma_f32_16x16x32_bf16 v[128:131], v[68:71], v[222:225], v[128:131]
	v_mfma_f32_16x16x32_bf16 v[108:111], v[76:79], v[222:225], v[108:111]
	s_barrier
	v_lshl_add_u64 v[244:245], v[136:137], 0, s[44:45]
	s_mov_b32 m0, s92
	v_lshl_add_u64 v[246:247], v[244:245], 0, s[4:5]
	ds_read_b128 v[226:229], v214
	ds_read_b128 v[230:233], v214 offset:1024
	ds_read_b128 v[234:237], v214 offset:2048
	ds_read_b128 v[238:241], v214 offset:3072
	global_load_lds_dwordx4 v[246:247], off
	v_lshl_add_u64 v[246:247], v[138:139], 0, s[44:45]
	v_lshl_add_u64 v[248:249], v[246:247], 0, s[4:5]
	s_mov_b32 m0, s93
	s_nop 0
	global_load_lds_dwordx4 v[248:249], off
	s_barrier
	s_waitcnt lgkmcnt(0)
	s_waitcnt lgkmcnt(0)
	v_mfma_f32_16x16x32_bf16 v[52:55], v[226:229], v[96:99], v[52:55]
	v_mfma_f32_16x16x32_bf16 v[48:51], v[234:237], v[96:99], v[48:51]
	v_mfma_f32_16x16x32_bf16 v[84:87], v[226:229], v[162:165], v[84:87]
	v_mfma_f32_16x16x32_bf16 v[80:83], v[234:237], v[162:165], v[80:83]
	v_mfma_f32_16x16x32_bf16 v[112:115], v[234:237], v[170:173], v[112:115]
	v_mfma_f32_16x16x32_bf16 v[104:107], v[226:229], v[218:221], v[104:107]
	v_mfma_f32_16x16x32_bf16 v[100:103], v[234:237], v[218:221], v[100:103]
	v_mfma_f32_16x16x32_bf16 v[52:55], v[230:233], v[158:161], v[52:55]
	v_mfma_f32_16x16x32_bf16 v[48:51], v[238:241], v[158:161], v[48:51]
	v_mfma_f32_16x16x32_bf16 v[84:87], v[230:233], v[166:169], v[84:87]
	v_mfma_f32_16x16x32_bf16 v[80:83], v[238:241], v[166:169], v[80:83]
	v_mfma_f32_16x16x32_bf16 v[96:99], v[226:229], v[170:173], v[116:119]
	v_mfma_f32_16x16x32_bf16 v[112:115], v[238:241], v[202:205], v[112:115]
	v_mfma_f32_16x16x32_bf16 v[104:107], v[230:233], v[222:225], v[104:107]
	v_mfma_f32_16x16x32_bf16 v[100:103], v[238:241], v[222:225], v[100:103]
	v_mfma_f32_16x16x32_bf16 v[96:99], v[230:233], v[202:205], v[96:99]
	s_mov_b32 m0, s79
	v_lshl_add_u64 v[248:249], v[174:175], 0, s[4:5]
	s_barrier
	ds_read_b128 v[116:119], v211 offset:16384
	ds_read_b128 v[158:161], v211 offset:17408
	ds_read_b128 v[162:165], v211 offset:18432
	ds_read_b128 v[166:169], v211 offset:19456
	ds_read_b128 v[170:173], v211 offset:20480
	ds_read_b128 v[202:205], v211 offset:21504
	ds_read_b128 v[218:221], v211 offset:22528
	ds_read_b128 v[222:225], v211 offset:23552
	global_load_lds_dwordx4 v[248:249], off
	v_lshl_add_u64 v[248:249], v[242:243], 0, s[4:5]
	s_mov_b32 m0, s80
	s_nop 0
	global_load_lds_dwordx4 v[248:249], off
	s_barrier
	s_waitcnt lgkmcnt(0)
	s_waitcnt lgkmcnt(0)
	v_mfma_f32_16x16x32_bf16 v[152:155], v[64:67], v[116:119], v[152:155]
	v_mfma_f32_16x16x32_bf16 v[148:151], v[72:75], v[116:119], v[148:151]
	v_mfma_f32_16x16x32_bf16 v[44:47], v[64:67], v[162:165], v[44:47]
	v_mfma_f32_16x16x32_bf16 v[40:43], v[72:75], v[162:165], v[40:43]
	v_mfma_f32_16x16x32_bf16 v[28:31], v[64:67], v[170:173], v[28:31]
	v_mfma_f32_16x16x32_bf16 v[24:27], v[72:75], v[170:173], v[24:27]
	v_mfma_f32_16x16x32_bf16 v[12:15], v[64:67], v[218:221], v[12:15]
	v_mfma_f32_16x16x32_bf16 v[8:11], v[72:75], v[218:221], v[8:11]
	v_mfma_f32_16x16x32_bf16 v[152:155], v[68:71], v[158:161], v[152:155]
	v_mfma_f32_16x16x32_bf16 v[148:151], v[76:79], v[158:161], v[148:151]
	v_mfma_f32_16x16x32_bf16 v[44:47], v[68:71], v[166:169], v[44:47]
	v_mfma_f32_16x16x32_bf16 v[40:43], v[76:79], v[166:169], v[40:43]
	v_mfma_f32_16x16x32_bf16 v[28:31], v[68:71], v[202:205], v[28:31]
	v_mfma_f32_16x16x32_bf16 v[24:27], v[76:79], v[202:205], v[24:27]
	v_mfma_f32_16x16x32_bf16 v[12:15], v[68:71], v[222:225], v[12:15]
	v_mfma_f32_16x16x32_bf16 v[8:11], v[76:79], v[222:225], v[8:11]
	s_barrier
	s_mov_b32 m0, s94
	v_lshl_add_u64 v[64:65], v[244:245], 0, s[66:67]
	global_load_lds_dwordx4 v[64:65], off
	v_lshl_add_u64 v[64:65], v[246:247], 0, s[66:67]
	s_mov_b32 m0, s95
	s_nop 0
	global_load_lds_dwordx4 v[64:65], off
	s_waitcnt vmcnt(6)
	s_barrier
	v_mfma_f32_16x16x32_bf16 v[36:39], v[226:229], v[162:165], v[36:39]
	v_mfma_f32_16x16x32_bf16 v[32:35], v[234:237], v[162:165], v[32:35]
	v_mfma_f32_16x16x32_bf16 v[20:23], v[226:229], v[170:173], v[20:23]
	v_mfma_f32_16x16x32_bf16 v[16:19], v[234:237], v[170:173], v[16:19]
	v_mfma_f32_16x16x32_bf16 v[4:7], v[226:229], v[218:221], v[4:7]
	v_mfma_f32_16x16x32_bf16 v[0:3], v[234:237], v[218:221], v[0:3]
	v_mfma_f32_16x16x32_bf16 v[64:67], v[226:229], v[116:119], v[144:147]
	v_mfma_f32_16x16x32_bf16 v[68:71], v[234:237], v[116:119], v[140:143]
	v_mfma_f32_16x16x32_bf16 v[36:39], v[230:233], v[166:169], v[36:39]
	v_mfma_f32_16x16x32_bf16 v[32:35], v[238:241], v[166:169], v[32:35]
	v_mfma_f32_16x16x32_bf16 v[20:23], v[230:233], v[202:205], v[20:23]
	v_mfma_f32_16x16x32_bf16 v[16:19], v[238:241], v[202:205], v[16:19]
	v_mfma_f32_16x16x32_bf16 v[4:7], v[230:233], v[222:225], v[4:7]
	v_mfma_f32_16x16x32_bf16 v[0:3], v[238:241], v[222:225], v[0:3]
	v_mfma_f32_16x16x32_bf16 v[64:67], v[230:233], v[158:161], v[64:67]
	v_mfma_f32_16x16x32_bf16 v[68:71], v[238:241], v[158:161], v[68:71]
	s_barrier
	ds_read_b128 v[72:75], v215
	ds_read_b128 v[76:79], v215 offset:1024
	ds_read_b128 v[140:143], v215 offset:2048
	ds_read_b128 v[144:147], v215 offset:3072
	s_mov_b32 m0, s81
	v_lshl_add_u64 v[226:227], v[174:175], 0, s[66:67]
	ds_read_b128 v[116:119], v211 offset:32768
	ds_read_b128 v[158:161], v211 offset:33792
	ds_read_b128 v[162:165], v211 offset:34816
	ds_read_b128 v[166:169], v211 offset:35840
	ds_read_b128 v[170:173], v211 offset:36864
	ds_read_b128 v[202:205], v211 offset:37888
	ds_read_b128 v[218:221], v211 offset:38912
	ds_read_b128 v[222:225], v211 offset:39936
	global_load_lds_dwordx4 v[226:227], off
	v_lshl_add_u64 v[226:227], v[242:243], 0, s[66:67]
	s_mov_b32 m0, s82
	s_nop 0
	global_load_lds_dwordx4 v[226:227], off
	s_waitcnt lgkmcnt(8)
	s_barrier
	s_waitcnt lgkmcnt(0)
	s_waitcnt lgkmcnt(0)
	v_mfma_f32_16x16x32_bf16 v[60:63], v[72:75], v[116:119], v[60:63]
	v_mfma_f32_16x16x32_bf16 v[56:59], v[140:143], v[116:119], v[56:59]
	v_mfma_f32_16x16x32_bf16 v[92:95], v[72:75], v[162:165], v[92:95]
	v_mfma_f32_16x16x32_bf16 v[88:91], v[140:143], v[162:165], v[88:91]
	v_mfma_f32_16x16x32_bf16 v[124:127], v[72:75], v[170:173], v[124:127]
	v_mfma_f32_16x16x32_bf16 v[120:123], v[140:143], v[170:173], v[120:123]
	v_mfma_f32_16x16x32_bf16 v[128:131], v[72:75], v[218:221], v[128:131]
	v_mfma_f32_16x16x32_bf16 v[108:111], v[140:143], v[218:221], v[108:111]
	v_mfma_f32_16x16x32_bf16 v[60:63], v[76:79], v[158:161], v[60:63]
	v_mfma_f32_16x16x32_bf16 v[56:59], v[144:147], v[158:161], v[56:59]
	v_mfma_f32_16x16x32_bf16 v[92:95], v[76:79], v[166:169], v[92:95]
	v_mfma_f32_16x16x32_bf16 v[88:91], v[144:147], v[166:169], v[88:91]
	v_mfma_f32_16x16x32_bf16 v[124:127], v[76:79], v[202:205], v[124:127]
	v_mfma_f32_16x16x32_bf16 v[120:123], v[144:147], v[202:205], v[120:123]
	v_mfma_f32_16x16x32_bf16 v[128:131], v[76:79], v[222:225], v[128:131]
	v_mfma_f32_16x16x32_bf16 v[108:111], v[144:147], v[222:225], v[108:111]
	s_barrier
	s_mov_b32 m0, s96
	v_lshl_add_u64 v[248:249], v[244:245], 0, s[22:23]
	ds_read_b128 v[226:229], v216
	ds_read_b128 v[230:233], v216 offset:1024
	ds_read_b128 v[234:237], v216 offset:2048
	ds_read_b128 v[238:241], v216 offset:3072
	global_load_lds_dwordx4 v[248:249], off
	v_lshl_add_u64 v[248:249], v[246:247], 0, s[22:23]
	s_mov_b32 m0, s60
	s_nop 0
	global_load_lds_dwordx4 v[248:249], off
	s_barrier
	s_waitcnt lgkmcnt(0)
	s_waitcnt lgkmcnt(0)
	v_mfma_f32_16x16x32_bf16 v[96:99], v[226:229], v[170:173], v[96:99]
	v_mfma_f32_16x16x32_bf16 v[52:55], v[226:229], v[116:119], v[52:55]
	v_mfma_f32_16x16x32_bf16 v[48:51], v[234:237], v[116:119], v[48:51]
	v_mfma_f32_16x16x32_bf16 v[116:119], v[230:233], v[202:205], v[96:99]
	v_mfma_f32_16x16x32_bf16 v[96:99], v[234:237], v[170:173], v[112:115]
	v_mfma_f32_16x16x32_bf16 v[112:115], v[238:241], v[202:205], v[96:99]
	v_mfma_f32_16x16x32_bf16 v[96:99], v[226:229], v[218:221], v[104:107]
	v_mfma_f32_16x16x32_bf16 v[84:87], v[226:229], v[162:165], v[84:87]
	v_mfma_f32_16x16x32_bf16 v[80:83], v[234:237], v[162:165], v[80:83]
	v_mfma_f32_16x16x32_bf16 v[104:107], v[230:233], v[222:225], v[96:99]
	v_mfma_f32_16x16x32_bf16 v[96:99], v[234:237], v[218:221], v[100:103]
	v_mfma_f32_16x16x32_bf16 v[52:55], v[230:233], v[158:161], v[52:55]
	v_mfma_f32_16x16x32_bf16 v[48:51], v[238:241], v[158:161], v[48:51]
	v_mfma_f32_16x16x32_bf16 v[84:87], v[230:233], v[166:169], v[84:87]
	v_mfma_f32_16x16x32_bf16 v[80:83], v[238:241], v[166:169], v[80:83]
	v_mfma_f32_16x16x32_bf16 v[100:103], v[238:241], v[222:225], v[96:99]
	s_mov_b32 m0, s87
	v_lshl_add_u64 v[174:175], v[174:175], 0, s[22:23]
	s_barrier
	ds_read_b128 v[96:99], v211 offset:49152
	ds_read_b128 v[158:161], v211 offset:50176
	ds_read_b128 v[162:165], v211 offset:51200
	ds_read_b128 v[166:169], v211 offset:52224
	ds_read_b128 v[170:173], v211 offset:53248
	ds_read_b128 v[202:205], v211 offset:54272
	ds_read_b128 v[218:221], v211 offset:55296
	ds_read_b128 v[222:225], v211 offset:56320
	global_load_lds_dwordx4 v[174:175], off
	v_lshl_add_u64 v[174:175], v[242:243], 0, s[22:23]
	s_mov_b32 m0, s88
	s_nop 0
	global_load_lds_dwordx4 v[174:175], off
	s_barrier
	s_waitcnt lgkmcnt(0)
	s_waitcnt lgkmcnt(0)
	v_mfma_f32_16x16x32_bf16 v[152:155], v[72:75], v[96:99], v[152:155]
	v_mfma_f32_16x16x32_bf16 v[148:151], v[140:143], v[96:99], v[148:151]
	v_mfma_f32_16x16x32_bf16 v[44:47], v[72:75], v[162:165], v[44:47]
	v_mfma_f32_16x16x32_bf16 v[40:43], v[140:143], v[162:165], v[40:43]
	v_mfma_f32_16x16x32_bf16 v[28:31], v[72:75], v[170:173], v[28:31]
	v_mfma_f32_16x16x32_bf16 v[24:27], v[140:143], v[170:173], v[24:27]
	v_mfma_f32_16x16x32_bf16 v[12:15], v[72:75], v[218:221], v[12:15]
	v_mfma_f32_16x16x32_bf16 v[8:11], v[140:143], v[218:221], v[8:11]
	v_mfma_f32_16x16x32_bf16 v[152:155], v[76:79], v[158:161], v[152:155]
	v_mfma_f32_16x16x32_bf16 v[148:151], v[144:147], v[158:161], v[148:151]
	v_mfma_f32_16x16x32_bf16 v[44:47], v[76:79], v[166:169], v[44:47]
	v_mfma_f32_16x16x32_bf16 v[40:43], v[144:147], v[166:169], v[40:43]
	v_mfma_f32_16x16x32_bf16 v[28:31], v[76:79], v[202:205], v[28:31]
	v_mfma_f32_16x16x32_bf16 v[24:27], v[144:147], v[202:205], v[24:27]
	v_mfma_f32_16x16x32_bf16 v[12:15], v[76:79], v[222:225], v[12:15]
	v_mfma_f32_16x16x32_bf16 v[8:11], v[144:147], v[222:225], v[8:11]
	s_barrier
	s_mov_b32 m0, s61
	v_lshl_add_u64 v[72:73], v[244:245], 0, s[64:65]
	global_load_lds_dwordx4 v[72:73], off
	v_lshl_add_u64 v[72:73], v[246:247], 0, s[64:65]
	s_mov_b32 m0, s49
	s_nop 0
	global_load_lds_dwordx4 v[72:73], off
	s_waitcnt vmcnt(6)
	s_barrier
	v_mfma_f32_16x16x32_bf16 v[64:67], v[226:229], v[96:99], v[64:67]
	v_mfma_f32_16x16x32_bf16 v[144:147], v[230:233], v[158:161], v[64:67]
	v_mfma_f32_16x16x32_bf16 v[64:67], v[234:237], v[96:99], v[68:71]
	v_mfma_f32_16x16x32_bf16 v[36:39], v[226:229], v[162:165], v[36:39]
	v_mfma_f32_16x16x32_bf16 v[32:35], v[234:237], v[162:165], v[32:35]
	v_mfma_f32_16x16x32_bf16 v[20:23], v[226:229], v[170:173], v[20:23]
	v_mfma_f32_16x16x32_bf16 v[16:19], v[234:237], v[170:173], v[16:19]
	v_mfma_f32_16x16x32_bf16 v[4:7], v[226:229], v[218:221], v[4:7]
	v_mfma_f32_16x16x32_bf16 v[0:3], v[234:237], v[218:221], v[0:3]
	v_mfma_f32_16x16x32_bf16 v[140:143], v[238:241], v[158:161], v[64:67]
	v_mfma_f32_16x16x32_bf16 v[36:39], v[230:233], v[166:169], v[36:39]
	v_mfma_f32_16x16x32_bf16 v[32:35], v[238:241], v[166:169], v[32:35]
	v_mfma_f32_16x16x32_bf16 v[20:23], v[230:233], v[202:205], v[20:23]
	v_mfma_f32_16x16x32_bf16 v[16:19], v[238:241], v[202:205], v[16:19]
	v_mfma_f32_16x16x32_bf16 v[4:7], v[230:233], v[222:225], v[4:7]
	v_mfma_f32_16x16x32_bf16 v[0:3], v[238:241], v[222:225], v[0:3]
	s_add_i32 s30, s30, 2
	s_add_u32 s44, s44, 0x100
	s_addc_u32 s45, s45, 0
	s_cmp_lt_u32 s30, 22
	s_barrier
	s_cbranch_scc1 .LBB0_523
	s_setprio 0
	s_ashr_i32 s69, s68, 31
	s_lshl_b64 s[2:3], s[68:69], 20
	v_readlane_b32 s12, v255, 1
	v_readlane_b32 s13, v255, 2
	s_add_u32 s44, s12, s2
	s_addc_u32 s45, s13, s3
	s_and_b64 s[2:3], vcc, exec
	s_cselect_b32 s53, s45, s73
	s_cselect_b32 s69, s44, s72
	s_ashr_i32 s39, s38, 31
	s_lshl_b64 s[2:3], s[38:39], 20
	s_add_u32 s46, s34, s2
	s_addc_u32 s47, s78, s3
	s_and_b64 s[2:3], vcc, exec
	s_cselect_b32 s30, s47, s71
	s_cselect_b32 s31, s46, s70
	v_pk_mul_f32 v[174:175], v[156:157], v[62:63] op_sel_hi:[0,1]
	v_pk_mul_f32 v[172:173], v[156:157], v[60:61] op_sel_hi:[0,1]
	v_pk_mul_f32 v[170:171], v[156:157], v[58:59] op_sel_hi:[0,1]
	v_pk_mul_f32 v[168:169], v[156:157], v[56:57] op_sel_hi:[0,1]
	v_pk_mul_f32 v[166:167], v[156:157], v[54:55] op_sel_hi:[0,1]
	v_pk_mul_f32 v[164:165], v[156:157], v[52:53] op_sel_hi:[0,1]
	v_pk_mul_f32 v[162:163], v[156:157], v[50:51] op_sel_hi:[0,1]
	v_pk_mul_f32 v[160:161], v[156:157], v[48:49] op_sel_hi:[0,1]
	v_pk_mul_f32 v[158:159], v[188:189], v[94:95] op_sel_hi:[0,1]
	v_pk_mul_f32 v[156:157], v[188:189], v[92:93] op_sel_hi:[0,1]
	v_pk_mul_f32 v[138:139], v[188:189], v[90:91] op_sel_hi:[0,1]
	v_pk_mul_f32 v[136:137], v[188:189], v[88:89] op_sel_hi:[0,1]
	v_pk_mul_f32 v[134:135], v[188:189], v[86:87] op_sel_hi:[0,1]
	v_pk_mul_f32 v[132:133], v[188:189], v[84:85] op_sel_hi:[0,1]
	v_pk_mul_f32 v[98:99], v[188:189], v[82:83] op_sel_hi:[0,1]
	v_pk_mul_f32 v[96:97], v[188:189], v[80:81] op_sel_hi:[0,1]
	v_pk_mul_f32 v[94:95], v[190:191], v[126:127] op_sel_hi:[0,1]
	v_pk_mul_f32 v[92:93], v[190:191], v[124:125] op_sel_hi:[0,1]
	v_pk_mul_f32 v[90:91], v[190:191], v[122:123] op_sel_hi:[0,1]
	v_pk_mul_f32 v[88:89], v[190:191], v[120:121] op_sel_hi:[0,1]
	v_pk_mul_f32 v[86:87], v[190:191], v[118:119] op_sel_hi:[0,1]
	v_pk_mul_f32 v[84:85], v[190:191], v[116:117] op_sel_hi:[0,1]
	v_pk_mul_f32 v[82:83], v[190:191], v[114:115] op_sel_hi:[0,1]
	v_pk_mul_f32 v[80:81], v[190:191], v[112:113] op_sel_hi:[0,1]
	v_pk_mul_f32 v[78:79], v[192:193], v[130:131] op_sel_hi:[0,1]
	v_pk_mul_f32 v[76:77], v[192:193], v[128:129] op_sel_hi:[0,1]
	v_pk_mul_f32 v[74:75], v[192:193], v[110:111] op_sel_hi:[0,1]
	v_pk_mul_f32 v[72:73], v[192:193], v[108:109] op_sel_hi:[0,1]
	v_pk_mul_f32 v[70:71], v[192:193], v[106:107] op_sel_hi:[0,1]
	v_pk_mul_f32 v[68:69], v[192:193], v[104:105] op_sel_hi:[0,1]
	v_pk_mul_f32 v[66:67], v[192:193], v[102:103] op_sel_hi:[0,1]
	v_pk_mul_f32 v[64:65], v[192:193], v[100:101] op_sel_hi:[0,1]
	v_pk_mul_f32 v[62:63], v[194:195], v[154:155] op_sel_hi:[0,1]
	v_pk_mul_f32 v[60:61], v[194:195], v[152:153] op_sel_hi:[0,1]
	v_pk_mul_f32 v[58:59], v[194:195], v[150:151] op_sel_hi:[0,1]
	v_pk_mul_f32 v[56:57], v[194:195], v[148:149] op_sel_hi:[0,1]
	v_pk_mul_f32 v[54:55], v[194:195], v[146:147] op_sel_hi:[0,1]
	v_pk_mul_f32 v[52:53], v[194:195], v[144:145] op_sel_hi:[0,1]
	v_pk_mul_f32 v[50:51], v[194:195], v[142:143] op_sel_hi:[0,1]
	v_pk_mul_f32 v[48:49], v[194:195], v[140:141] op_sel_hi:[0,1]
	v_pk_mul_f32 v[46:47], v[196:197], v[46:47] op_sel_hi:[0,1]
	v_pk_mul_f32 v[44:45], v[196:197], v[44:45] op_sel_hi:[0,1]
	v_pk_mul_f32 v[42:43], v[196:197], v[42:43] op_sel_hi:[0,1]
	v_pk_mul_f32 v[40:41], v[196:197], v[40:41] op_sel_hi:[0,1]
	v_pk_mul_f32 v[38:39], v[196:197], v[38:39] op_sel_hi:[0,1]
	v_pk_mul_f32 v[36:37], v[196:197], v[36:37] op_sel_hi:[0,1]
	v_pk_mul_f32 v[34:35], v[196:197], v[34:35] op_sel_hi:[0,1]
	v_pk_mul_f32 v[32:33], v[196:197], v[32:33] op_sel_hi:[0,1]
	v_pk_mul_f32 v[30:31], v[198:199], v[30:31] op_sel_hi:[0,1]
	v_pk_mul_f32 v[28:29], v[198:199], v[28:29] op_sel_hi:[0,1]
	v_pk_mul_f32 v[26:27], v[198:199], v[26:27] op_sel_hi:[0,1]
	v_pk_mul_f32 v[24:25], v[198:199], v[24:25] op_sel_hi:[0,1]
	v_pk_mul_f32 v[22:23], v[198:199], v[22:23] op_sel_hi:[0,1]
	v_pk_mul_f32 v[20:21], v[198:199], v[20:21] op_sel_hi:[0,1]
	v_pk_mul_f32 v[18:19], v[198:199], v[18:19] op_sel_hi:[0,1]
	v_pk_mul_f32 v[16:17], v[198:199], v[16:17] op_sel_hi:[0,1]
	v_pk_mul_f32 v[14:15], v[200:201], v[14:15] op_sel_hi:[0,1]
	v_pk_mul_f32 v[12:13], v[200:201], v[12:13] op_sel_hi:[0,1]
	v_pk_mul_f32 v[10:11], v[200:201], v[10:11] op_sel_hi:[0,1]
	v_pk_mul_f32 v[8:9], v[200:201], v[8:9] op_sel_hi:[0,1]
	v_pk_mul_f32 v[6:7], v[200:201], v[6:7] op_sel_hi:[0,1]
	v_pk_mul_f32 v[4:5], v[200:201], v[4:5] op_sel_hi:[0,1]
	v_pk_mul_f32 v[2:3], v[200:201], v[2:3] op_sel_hi:[0,1]
	v_pk_mul_f32 v[0:1], v[200:201], v[0:1] op_sel_hi:[0,1]
	s_add_u32 s72, s72, 0x80c80
	s_addc_u32 s73, s73, 0
	s_add_u32 s39, s70, 0xd00
	s_addc_u32 s97, s71, 0
	s_mov_b32 vcc_lo, 22

.Lprio_525:
	ds_read_b128 v[100:103], v213
	ds_read_b128 v[104:107], v213 offset:1024
	ds_read_b128 v[108:111], v213 offset:2048
	ds_read_b128 v[112:115], v213 offset:3072
	s_add_u32 s1, s72, 0xfff80080
	s_addc_u32 s2, s73, -1
	s_cmp_eq_u32 vcc_lo, 28
	s_cselect_b32 s75, s53, s2
	s_cselect_b32 s74, s69, s1
	s_cselect_b32 s71, s30, s97
	s_cselect_b32 s70, s31, s39
	s_mov_b32 m0, s90
	v_lshl_add_u64 v[190:191], s[72:73], 0, v[184:185]
	ds_read_b128 v[116:119], v211
	ds_read_b128 v[120:123], v211 offset:1024
	ds_read_b128 v[124:127], v211 offset:2048
	ds_read_b128 v[128:131], v211 offset:3072
	ds_read_b128 v[140:143], v211 offset:4096
	ds_read_b128 v[144:147], v211 offset:5120
	ds_read_b128 v[148:151], v211 offset:6144
	ds_read_b128 v[152:155], v211 offset:7168
	global_load_lds_dwordx4 v[190:191], off
	v_lshl_add_u64 v[190:191], s[72:73], 0, v[186:187]
	s_mov_b32 m0, s91
	s_nop 0
	global_load_lds_dwordx4 v[190:191], off
	s_waitcnt lgkmcnt(8)
	s_barrier
	s_waitcnt lgkmcnt(0)
	s_waitcnt lgkmcnt(0)
	v_mfma_f32_16x16x32_bf16 v[172:175], v[100:103], v[116:119], v[172:175]
	v_mfma_f32_16x16x32_bf16 v[168:171], v[108:111], v[116:119], v[168:171]
	v_mfma_f32_16x16x32_bf16 v[156:159], v[100:103], v[124:127], v[156:159]
	v_mfma_f32_16x16x32_bf16 v[136:139], v[108:111], v[124:127], v[136:139]
	v_mfma_f32_16x16x32_bf16 v[92:95], v[100:103], v[140:143], v[92:95]
	v_mfma_f32_16x16x32_bf16 v[88:91], v[108:111], v[140:143], v[88:91]
	v_mfma_f32_16x16x32_bf16 v[76:79], v[100:103], v[148:151], v[76:79]
	v_mfma_f32_16x16x32_bf16 v[72:75], v[108:111], v[148:151], v[72:75]
	v_mfma_f32_16x16x32_bf16 v[172:175], v[104:107], v[120:123], v[172:175]
	v_mfma_f32_16x16x32_bf16 v[168:171], v[112:115], v[120:123], v[168:171]
	v_mfma_f32_16x16x32_bf16 v[156:159], v[104:107], v[128:131], v[156:159]
	v_mfma_f32_16x16x32_bf16 v[136:139], v[112:115], v[128:131], v[136:139]
	v_mfma_f32_16x16x32_bf16 v[92:95], v[104:107], v[144:147], v[92:95]
	v_mfma_f32_16x16x32_bf16 v[88:91], v[112:115], v[144:147], v[88:91]
	v_mfma_f32_16x16x32_bf16 v[76:79], v[104:107], v[152:155], v[76:79]
	v_mfma_f32_16x16x32_bf16 v[72:75], v[112:115], v[152:155], v[72:75]
	s_barrier
	s_mov_b32 m0, s92
	v_lshl_add_u64 v[190:191], s[70:71], 0, v[176:177]
	ds_read_b128 v[200:203], v214
	ds_read_b128 v[218:221], v214 offset:1024
	ds_read_b128 v[222:225], v214 offset:2048
	ds_read_b128 v[226:229], v214 offset:3072
	global_load_lds_dwordx4 v[190:191], off
	v_lshl_add_u64 v[194:195], s[70:71], 0, v[182:183]
	s_mov_b32 m0, s93
	s_nop 0
	global_load_lds_dwordx4 v[194:195], off
	s_barrier
	s_waitcnt lgkmcnt(0)
	s_waitcnt lgkmcnt(0)
	v_mfma_f32_16x16x32_bf16 v[164:167], v[200:203], v[116:119], v[164:167]
	v_mfma_f32_16x16x32_bf16 v[116:119], v[222:225], v[116:119], v[160:163]
	v_mfma_f32_16x16x32_bf16 v[96:99], v[222:225], v[124:127], v[96:99]
	v_mfma_f32_16x16x32_bf16 v[84:87], v[200:203], v[140:143], v[84:87]
	v_mfma_f32_16x16x32_bf16 v[80:83], v[222:225], v[140:143], v[80:83]
	v_mfma_f32_16x16x32_bf16 v[68:71], v[200:203], v[148:151], v[68:71]
	v_mfma_f32_16x16x32_bf16 v[64:67], v[222:225], v[148:151], v[64:67]
	v_mfma_f32_16x16x32_bf16 v[164:167], v[218:221], v[120:123], v[164:167]
	v_mfma_f32_16x16x32_bf16 v[116:119], v[226:229], v[120:123], v[116:119]
	v_mfma_f32_16x16x32_bf16 v[120:123], v[200:203], v[124:127], v[132:135]
	v_mfma_f32_16x16x32_bf16 v[96:99], v[226:229], v[128:131], v[96:99]
	v_mfma_f32_16x16x32_bf16 v[84:87], v[218:221], v[144:147], v[84:87]
	v_mfma_f32_16x16x32_bf16 v[80:83], v[226:229], v[144:147], v[80:83]
	v_mfma_f32_16x16x32_bf16 v[68:71], v[218:221], v[152:155], v[68:71]
	v_mfma_f32_16x16x32_bf16 v[64:67], v[226:229], v[152:155], v[64:67]
	v_mfma_f32_16x16x32_bf16 v[120:123], v[218:221], v[128:131], v[120:123]
	s_mov_b32 m0, s79
	v_lshl_add_u64 v[204:205], s[74:75], 0, v[176:177]
	s_barrier
	ds_read_b128 v[124:127], v211 offset:16384
	ds_read_b128 v[128:131], v211 offset:17408
	ds_read_b128 v[132:135], v211 offset:18432
	ds_read_b128 v[140:143], v211 offset:19456
	ds_read_b128 v[144:147], v211 offset:20480
	ds_read_b128 v[148:151], v211 offset:21504
	ds_read_b128 v[152:155], v211 offset:22528
	ds_read_b128 v[160:163], v211 offset:23552
	global_load_lds_dwordx4 v[204:205], off
	v_lshl_add_u64 v[238:239], s[74:75], 0, v[182:183]
	s_mov_b32 m0, s80
	s_nop 0
	global_load_lds_dwordx4 v[238:239], off
	s_barrier
	s_waitcnt lgkmcnt(0)
	s_waitcnt lgkmcnt(0)
	v_mfma_f32_16x16x32_bf16 v[60:63], v[100:103], v[124:127], v[60:63]
	v_mfma_f32_16x16x32_bf16 v[56:59], v[108:111], v[124:127], v[56:59]
	v_mfma_f32_16x16x32_bf16 v[44:47], v[100:103], v[132:135], v[44:47]
	v_mfma_f32_16x16x32_bf16 v[40:43], v[108:111], v[132:135], v[40:43]
	v_mfma_f32_16x16x32_bf16 v[28:31], v[100:103], v[144:147], v[28:31]
	v_mfma_f32_16x16x32_bf16 v[24:27], v[108:111], v[144:147], v[24:27]
	v_mfma_f32_16x16x32_bf16 v[12:15], v[100:103], v[152:155], v[12:15]
	v_mfma_f32_16x16x32_bf16 v[8:11], v[108:111], v[152:155], v[8:11]
	v_mfma_f32_16x16x32_bf16 v[60:63], v[104:107], v[128:131], v[60:63]
	v_mfma_f32_16x16x32_bf16 v[56:59], v[112:115], v[128:131], v[56:59]
	v_mfma_f32_16x16x32_bf16 v[44:47], v[104:107], v[140:143], v[44:47]
	v_mfma_f32_16x16x32_bf16 v[40:43], v[112:115], v[140:143], v[40:43]
	v_mfma_f32_16x16x32_bf16 v[28:31], v[104:107], v[148:151], v[28:31]
	v_mfma_f32_16x16x32_bf16 v[24:27], v[112:115], v[148:151], v[24:27]
	v_mfma_f32_16x16x32_bf16 v[12:15], v[104:107], v[160:163], v[12:15]
	v_mfma_f32_16x16x32_bf16 v[8:11], v[112:115], v[160:163], v[8:11]
	s_barrier
	s_add_u32 s2, s70, 0x80000
	s_addc_u32 s3, s71, 0
	s_mov_b32 m0, s94
	v_lshl_add_u64 v[100:101], s[2:3], 0, v[176:177]
	global_load_lds_dwordx4 v[100:101], off
	v_lshl_add_u64 v[100:101], s[2:3], 0, v[182:183]
	s_mov_b32 m0, s95
	s_nop 0
	global_load_lds_dwordx4 v[100:101], off
	s_waitcnt vmcnt(6)
	s_barrier
	v_mfma_f32_16x16x32_bf16 v[52:55], v[200:203], v[124:127], v[52:55]
	v_mfma_f32_16x16x32_bf16 v[48:51], v[222:225], v[124:127], v[48:51]
	v_mfma_f32_16x16x32_bf16 v[36:39], v[200:203], v[132:135], v[36:39]
	v_mfma_f32_16x16x32_bf16 v[32:35], v[222:225], v[132:135], v[32:35]
	v_mfma_f32_16x16x32_bf16 v[20:23], v[200:203], v[144:147], v[20:23]
	v_mfma_f32_16x16x32_bf16 v[16:19], v[222:225], v[144:147], v[16:19]
	v_mfma_f32_16x16x32_bf16 v[4:7], v[200:203], v[152:155], v[4:7]
	v_mfma_f32_16x16x32_bf16 v[0:3], v[222:225], v[152:155], v[0:3]
	v_mfma_f32_16x16x32_bf16 v[52:55], v[218:221], v[128:131], v[52:55]
	v_mfma_f32_16x16x32_bf16 v[48:51], v[226:229], v[128:131], v[48:51]
	v_mfma_f32_16x16x32_bf16 v[36:39], v[218:221], v[140:143], v[36:39]
	v_mfma_f32_16x16x32_bf16 v[32:35], v[226:229], v[140:143], v[32:35]
	v_mfma_f32_16x16x32_bf16 v[20:23], v[218:221], v[148:151], v[20:23]
	v_mfma_f32_16x16x32_bf16 v[16:19], v[226:229], v[148:151], v[16:19]
	v_mfma_f32_16x16x32_bf16 v[4:7], v[218:221], v[160:163], v[4:7]
	v_mfma_f32_16x16x32_bf16 v[0:3], v[226:229], v[160:163], v[0:3]
	s_barrier
	ds_read_b128 v[100:103], v215
	ds_read_b128 v[104:107], v215 offset:1024
	ds_read_b128 v[108:111], v215 offset:2048
	ds_read_b128 v[112:115], v215 offset:3072
	s_add_u32 s2, s74, 0x80000
	s_addc_u32 s3, s75, 0
	s_mov_b32 m0, s81
	v_lshl_add_u64 v[132:133], s[2:3], 0, v[176:177]
	ds_read_b128 v[124:127], v211 offset:32768
	ds_read_b128 v[128:131], v211 offset:33792
	ds_read_b128 v[140:143], v211 offset:34816
	ds_read_b128 v[144:147], v211 offset:35840
	ds_read_b128 v[148:151], v211 offset:36864
	ds_read_b128 v[152:155], v211 offset:37888
	ds_read_b128 v[200:203], v211 offset:38912
	ds_read_b128 v[218:221], v211 offset:39936
	global_load_lds_dwordx4 v[132:133], off
	v_lshl_add_u64 v[132:133], s[2:3], 0, v[182:183]
	s_mov_b32 m0, s82
	s_nop 0
	global_load_lds_dwordx4 v[132:133], off
	s_waitcnt lgkmcnt(8)
	s_barrier
	s_waitcnt lgkmcnt(0)
	s_waitcnt lgkmcnt(0)
	v_mfma_f32_16x16x32_bf16 v[132:135], v[100:103], v[124:127], v[172:175]
	v_mfma_f32_16x16x32_bf16 v[172:175], v[104:107], v[128:131], v[132:135]
	v_mfma_f32_16x16x32_bf16 v[132:135], v[108:111], v[124:127], v[168:171]
	v_mfma_f32_16x16x32_bf16 v[168:171], v[112:115], v[128:131], v[132:135]
	v_mfma_f32_16x16x32_bf16 v[132:135], v[100:103], v[140:143], v[156:159]
	v_mfma_f32_16x16x32_bf16 v[156:159], v[104:107], v[144:147], v[132:135]
	v_mfma_f32_16x16x32_bf16 v[132:135], v[108:111], v[140:143], v[136:139]
	v_mfma_f32_16x16x32_bf16 v[92:95], v[100:103], v[148:151], v[92:95]
	v_mfma_f32_16x16x32_bf16 v[88:91], v[108:111], v[148:151], v[88:91]
	v_mfma_f32_16x16x32_bf16 v[76:79], v[100:103], v[200:203], v[76:79]
	v_mfma_f32_16x16x32_bf16 v[72:75], v[108:111], v[200:203], v[72:75]
	v_mfma_f32_16x16x32_bf16 v[136:139], v[112:115], v[144:147], v[132:135]
	v_mfma_f32_16x16x32_bf16 v[92:95], v[104:107], v[152:155], v[92:95]
	v_mfma_f32_16x16x32_bf16 v[88:91], v[112:115], v[152:155], v[88:91]
	v_mfma_f32_16x16x32_bf16 v[76:79], v[104:107], v[218:221], v[76:79]
	v_mfma_f32_16x16x32_bf16 v[72:75], v[112:115], v[218:221], v[72:75]
	s_barrier
	s_mov_b32 m0, s96
	v_lshl_add_u64 v[132:133], v[190:191], 0, s[20:21]
	ds_read_b128 v[222:225], v216
	ds_read_b128 v[226:229], v216 offset:1024
	ds_read_b128 v[230:233], v216 offset:2048
	ds_read_b128 v[234:237], v216 offset:3072
	global_load_lds_dwordx4 v[132:133], off
	v_lshl_add_u64 v[132:133], v[194:195], 0, s[20:21]
	s_mov_b32 m0, s60
	s_nop 0
	global_load_lds_dwordx4 v[132:133], off
	s_barrier
	s_waitcnt lgkmcnt(0)
	s_waitcnt lgkmcnt(0)
	v_mfma_f32_16x16x32_bf16 v[116:119], v[230:233], v[124:127], v[116:119]
	v_mfma_f32_16x16x32_bf16 v[132:135], v[222:225], v[124:127], v[164:167]
	v_mfma_f32_16x16x32_bf16 v[160:163], v[234:237], v[128:131], v[116:119]
	v_mfma_f32_16x16x32_bf16 v[116:119], v[222:225], v[140:143], v[120:123]
	v_mfma_f32_16x16x32_bf16 v[96:99], v[230:233], v[140:143], v[96:99]
	v_mfma_f32_16x16x32_bf16 v[84:87], v[222:225], v[148:151], v[84:87]
	v_mfma_f32_16x16x32_bf16 v[80:83], v[230:233], v[148:151], v[80:83]
	v_mfma_f32_16x16x32_bf16 v[68:71], v[222:225], v[200:203], v[68:71]
	v_mfma_f32_16x16x32_bf16 v[64:67], v[230:233], v[200:203], v[64:67]
	v_mfma_f32_16x16x32_bf16 v[164:167], v[226:229], v[128:131], v[132:135]
	v_mfma_f32_16x16x32_bf16 v[132:135], v[226:229], v[144:147], v[116:119]
	v_mfma_f32_16x16x32_bf16 v[96:99], v[234:237], v[144:147], v[96:99]
	v_mfma_f32_16x16x32_bf16 v[84:87], v[226:229], v[152:155], v[84:87]
	v_mfma_f32_16x16x32_bf16 v[80:83], v[234:237], v[152:155], v[80:83]
	v_mfma_f32_16x16x32_bf16 v[68:71], v[226:229], v[218:221], v[68:71]
	v_mfma_f32_16x16x32_bf16 v[64:67], v[234:237], v[218:221], v[64:67]
	s_mov_b32 m0, s87
	v_lshl_add_u64 v[190:191], v[204:205], 0, s[20:21]
	s_barrier
	ds_read_b128 v[116:119], v211 offset:49152
	ds_read_b128 v[120:123], v211 offset:50176
	ds_read_b128 v[124:127], v211 offset:51200
	ds_read_b128 v[128:131], v211 offset:52224
	ds_read_b128 v[140:143], v211 offset:53248
	ds_read_b128 v[144:147], v211 offset:54272
	ds_read_b128 v[148:151], v211 offset:55296
	ds_read_b128 v[152:155], v211 offset:56320
	global_load_lds_dwordx4 v[190:191], off
	v_lshl_add_u64 v[190:191], v[238:239], 0, s[20:21]
	s_mov_b32 m0, s88
	s_nop 0
	global_load_lds_dwordx4 v[190:191], off
	s_barrier
	s_waitcnt lgkmcnt(0)
	s_waitcnt lgkmcnt(0)
	v_mfma_f32_16x16x32_bf16 v[60:63], v[100:103], v[116:119], v[60:63]
	v_mfma_f32_16x16x32_bf16 v[56:59], v[108:111], v[116:119], v[56:59]
	v_mfma_f32_16x16x32_bf16 v[44:47], v[100:103], v[124:127], v[44:47]
	v_mfma_f32_16x16x32_bf16 v[40:43], v[108:111], v[124:127], v[40:43]
	v_mfma_f32_16x16x32_bf16 v[28:31], v[100:103], v[140:143], v[28:31]
	v_mfma_f32_16x16x32_bf16 v[24:27], v[108:111], v[140:143], v[24:27]
	v_mfma_f32_16x16x32_bf16 v[12:15], v[100:103], v[148:151], v[12:15]
	v_mfma_f32_16x16x32_bf16 v[8:11], v[108:111], v[148:151], v[8:11]
	v_mfma_f32_16x16x32_bf16 v[60:63], v[104:107], v[120:123], v[60:63]
	v_mfma_f32_16x16x32_bf16 v[56:59], v[112:115], v[120:123], v[56:59]
	v_mfma_f32_16x16x32_bf16 v[44:47], v[104:107], v[128:131], v[44:47]
	v_mfma_f32_16x16x32_bf16 v[40:43], v[112:115], v[128:131], v[40:43]
	v_mfma_f32_16x16x32_bf16 v[28:31], v[104:107], v[144:147], v[28:31]
	v_mfma_f32_16x16x32_bf16 v[24:27], v[112:115], v[144:147], v[24:27]
	v_mfma_f32_16x16x32_bf16 v[12:15], v[104:107], v[152:155], v[12:15]
	v_mfma_f32_16x16x32_bf16 v[8:11], v[112:115], v[152:155], v[8:11]
	s_barrier
	s_add_u32 s2, s70, 0x80080
	s_addc_u32 s3, s71, 0
	s_mov_b32 m0, s61
	v_lshl_add_u64 v[100:101], s[2:3], 0, v[176:177]
	global_load_lds_dwordx4 v[100:101], off
	v_lshl_add_u64 v[100:101], s[2:3], 0, v[182:183]
	s_mov_b32 m0, s49
	s_nop 0
	global_load_lds_dwordx4 v[100:101], off
	s_waitcnt vmcnt(6)
	s_barrier
	v_mfma_f32_16x16x32_bf16 v[52:55], v[222:225], v[116:119], v[52:55]
	v_mfma_f32_16x16x32_bf16 v[48:51], v[230:233], v[116:119], v[48:51]
	v_mfma_f32_16x16x32_bf16 v[36:39], v[222:225], v[124:127], v[36:39]
	v_mfma_f32_16x16x32_bf16 v[32:35], v[230:233], v[124:127], v[32:35]
	v_mfma_f32_16x16x32_bf16 v[20:23], v[222:225], v[140:143], v[20:23]
	v_mfma_f32_16x16x32_bf16 v[16:19], v[230:233], v[140:143], v[16:19]
	v_mfma_f32_16x16x32_bf16 v[4:7], v[222:225], v[148:151], v[4:7]
	v_mfma_f32_16x16x32_bf16 v[0:3], v[230:233], v[148:151], v[0:3]
	v_mfma_f32_16x16x32_bf16 v[52:55], v[226:229], v[120:123], v[52:55]
	v_mfma_f32_16x16x32_bf16 v[48:51], v[234:237], v[120:123], v[48:51]
	v_mfma_f32_16x16x32_bf16 v[36:39], v[226:229], v[128:131], v[36:39]
	v_mfma_f32_16x16x32_bf16 v[32:35], v[234:237], v[128:131], v[32:35]
	v_mfma_f32_16x16x32_bf16 v[20:23], v[226:229], v[144:147], v[20:23]
	v_mfma_f32_16x16x32_bf16 v[16:19], v[234:237], v[144:147], v[16:19]
	v_mfma_f32_16x16x32_bf16 v[4:7], v[226:229], v[152:155], v[4:7]
	v_mfma_f32_16x16x32_bf16 v[0:3], v[234:237], v[152:155], v[0:3]
	s_add_i32 vcc_lo, vcc_lo, 2
	s_add_u32 s72, s72, 0x100
	s_addc_u32 s73, s73, 0
	s_add_u32 s39, s39, 0x100
	s_addc_u32 s97, s97, 0
	s_cmp_lt_u32 vcc_lo, 30
	s_barrier
	s_cbranch_scc1 .LBB0_525
	s_setprio 0
	v_readlane_b32 s90, v255, 23
	v_readlane_b32 s96, v255, 17
	v_readlane_b32 s94, v255, 19
	v_readlane_b32 s48, v255, 21
	v_readlane_b32 s91, v255, 24
	v_readlane_b32 s93, v255, 25
	v_readlane_b32 s92, v255, 26
	v_readlane_b32 s97, v255, 18
	v_readlane_b32 s95, v255, 20
	v_readlane_b32 s49, v255, 22
	v_readlane_b32 s30, v255, 27
	v_readlane_b32 s31, v255, 28
	s_movk_i32 s14, 0x3fff
	v_add_u32_e32 v213, s52, v209
	v_lshl_or_b32 v252, s76, 8, v212
	v_lshlrev_b32_e32 v196, 12, v213
	v_lshl_add_u32 v196, v252, 1, v196
	v_mov_b32_e32 v192, v196
	global_load_dwordx2 v[100:101], v192, s[62:63] offset:0
	global_load_dwordx2 v[102:103], v192, s[62:63] offset:32
	global_load_dwordx2 v[104:105], v192, s[62:63] offset:256
	global_load_dwordx2 v[106:107], v192, s[62:63] offset:288
	v_add_u32_e32 v124, 0x10000, v196
	global_load_dwordx2 v[108:109], v124, s[62:63] offset:0
	global_load_dwordx2 v[110:111], v124, s[62:63] offset:32
	global_load_dwordx2 v[112:113], v124, s[62:63] offset:256
	global_load_dwordx2 v[114:115], v124, s[62:63] offset:288
	v_add_u32_e32 v192, 0x20000, v196
	global_load_dwordx2 v[200:201], v192, s[62:63] offset:0
	global_load_dwordx2 v[202:203], v192, s[62:63] offset:32
	global_load_dwordx2 v[204:205], v192, s[62:63] offset:256
	global_load_dwordx2 v[214:215], v192, s[62:63] offset:288
	v_add_u32_e32 v124, 0x30000, v196
	global_load_dwordx2 v[216:217], v124, s[62:63] offset:0
	global_load_dwordx2 v[218:219], v124, s[62:63] offset:32
	global_load_dwordx2 v[220:221], v124, s[62:63] offset:256
	global_load_dwordx2 v[222:223], v124, s[62:63] offset:288
	v_add_u32_e32 v192, 0x80000, v196
	global_load_dwordx2 v[224:225], v192, s[62:63] offset:0
	global_load_dwordx2 v[226:227], v192, s[62:63] offset:32
	global_load_dwordx2 v[228:229], v192, s[62:63] offset:256
	global_load_dwordx2 v[230:231], v192, s[62:63] offset:288
	v_add_u32_e32 v124, 0x90000, v196
	global_load_dwordx2 v[232:233], v124, s[62:63] offset:0
	global_load_dwordx2 v[234:235], v124, s[62:63] offset:32
	global_load_dwordx2 v[236:237], v124, s[62:63] offset:256
	global_load_dwordx2 v[238:239], v124, s[62:63] offset:288
	v_add_u32_e32 v192, 0xa0000, v196
	global_load_dwordx2 v[240:241], v192, s[62:63] offset:0
	global_load_dwordx2 v[242:243], v192, s[62:63] offset:32
	global_load_dwordx2 v[244:245], v192, s[62:63] offset:256
	global_load_dwordx2 v[246:247], v192, s[62:63] offset:288
	v_add_u32_e32 v124, 0xb0000, v196
	global_load_dwordx2 v[248:249], v124, s[62:63] offset:0
	global_load_dwordx2 v[190:191], v124, s[62:63] offset:32
	global_load_dwordx2 v[194:195], v124, s[62:63] offset:256
	global_load_dwordx2 v[146:147], v124, s[62:63] offset:288
	s_lshl_b32 s1, s76, 2
	s_or_b32 s1, s1, s83
	s_lshl_b32 s1, s1, 2
	v_lshl_add_u32 v188, v213, 7, s1
	s_waitcnt vmcnt(28)
	v_mov_b32_e32 v192, v196
	v_lshlrev_b32_e32 v198, 16, v100
	v_and_b32_e32 v100, 0xffff0000, v100
	v_lshlrev_b32_e32 v155, 16, v101
	v_and_b32_e32 v101, 0xffff0000, v101
	v_add_f32_e32 v172, v172, v198
	v_add_f32_e32 v173, v173, v100
	v_add_f32_e32 v174, v174, v155
	v_add_f32_e32 v175, v175, v101
	v_cvt_pk_bf16_f32 v100, v172, v173
	v_cvt_pk_bf16_f32 v101, v174, v175
	global_store_dwordx2 v192, v[100:101], s[58:59] offset:0
	v_mul_f32_e32 v198, v173, v173
	v_fmac_f32_e32 v198, v172, v172
	v_fmac_f32_e32 v198, v174, v174
	v_fmac_f32_e32 v198, v175, v175
	v_mov_b32_e32 v172, v198
	v_lshlrev_b32_e32 v198, 16, v102
	v_and_b32_e32 v102, 0xffff0000, v102
	v_lshlrev_b32_e32 v155, 16, v103
	v_and_b32_e32 v103, 0xffff0000, v103
	v_add_f32_e32 v168, v168, v198
	v_add_f32_e32 v169, v169, v102
	v_add_f32_e32 v170, v170, v155
	v_add_f32_e32 v171, v171, v103
	v_cvt_pk_bf16_f32 v102, v168, v169
	v_cvt_pk_bf16_f32 v103, v170, v171
	global_store_dwordx2 v192, v[102:103], s[58:59] offset:32
	v_fmac_f32_e32 v172, v168, v168
	v_fmac_f32_e32 v172, v169, v169
	v_fmac_f32_e32 v172, v170, v170
	v_fmac_f32_e32 v172, v171, v171
	v_lshlrev_b32_e32 v198, 16, v104
	v_and_b32_e32 v104, 0xffff0000, v104
	v_lshlrev_b32_e32 v155, 16, v105
	v_and_b32_e32 v105, 0xffff0000, v105
	v_add_f32_e32 v164, v164, v198
	v_add_f32_e32 v165, v165, v104
	v_add_f32_e32 v166, v166, v155
	v_add_f32_e32 v167, v167, v105
	v_cvt_pk_bf16_f32 v104, v164, v165
	v_cvt_pk_bf16_f32 v105, v166, v167
	global_store_dwordx2 v192, v[104:105], s[58:59] offset:256
	v_fmac_f32_e32 v172, v164, v164
	v_fmac_f32_e32 v172, v165, v165
	v_fmac_f32_e32 v172, v166, v166
	v_fmac_f32_e32 v172, v167, v167
	v_lshlrev_b32_e32 v198, 16, v106
	v_and_b32_e32 v106, 0xffff0000, v106
	v_lshlrev_b32_e32 v155, 16, v107
	v_and_b32_e32 v107, 0xffff0000, v107
	v_add_f32_e32 v160, v160, v198
	v_add_f32_e32 v161, v161, v106
	v_add_f32_e32 v162, v162, v155
	v_add_f32_e32 v163, v163, v107
	v_cvt_pk_bf16_f32 v106, v160, v161
	v_cvt_pk_bf16_f32 v107, v162, v163
	global_store_dwordx2 v192, v[106:107], s[58:59] offset:288
	v_fmac_f32_e32 v172, v160, v160
	v_fmac_f32_e32 v172, v161, v161
	v_fmac_f32_e32 v172, v162, v162
	v_fmac_f32_e32 v172, v163, v163
	s_waitcnt vmcnt(28)
	v_add_u32_e32 v124, 0x10000, v196
	v_lshlrev_b32_e32 v198, 16, v108
	v_and_b32_e32 v108, 0xffff0000, v108
	v_lshlrev_b32_e32 v155, 16, v109
	v_and_b32_e32 v109, 0xffff0000, v109
	v_add_f32_e32 v156, v156, v198
	v_add_f32_e32 v157, v157, v108
	v_add_f32_e32 v158, v158, v155
	v_add_f32_e32 v159, v159, v109
	v_cvt_pk_bf16_f32 v108, v156, v157
	v_cvt_pk_bf16_f32 v109, v158, v159
	global_store_dwordx2 v124, v[108:109], s[58:59] offset:0
	v_mul_f32_e32 v198, v157, v157
	v_fmac_f32_e32 v198, v156, v156
	v_fmac_f32_e32 v198, v158, v158
	v_fmac_f32_e32 v198, v159, v159
	v_mov_b32_e32 v156, v198
	v_lshlrev_b32_e32 v198, 16, v110
	v_and_b32_e32 v110, 0xffff0000, v110
	v_lshlrev_b32_e32 v155, 16, v111
	v_and_b32_e32 v111, 0xffff0000, v111
	v_add_f32_e32 v136, v136, v198
	v_add_f32_e32 v137, v137, v110
	v_add_f32_e32 v138, v138, v155
	v_add_f32_e32 v139, v139, v111
	v_cvt_pk_bf16_f32 v110, v136, v137
	v_cvt_pk_bf16_f32 v111, v138, v139
	global_store_dwordx2 v124, v[110:111], s[58:59] offset:32
	v_fmac_f32_e32 v156, v136, v136
	v_fmac_f32_e32 v156, v137, v137
	v_fmac_f32_e32 v156, v138, v138
	v_fmac_f32_e32 v156, v139, v139
	v_lshlrev_b32_e32 v198, 16, v112
	v_and_b32_e32 v112, 0xffff0000, v112
	v_lshlrev_b32_e32 v155, 16, v113
	v_and_b32_e32 v113, 0xffff0000, v113
	v_add_f32_e32 v132, v132, v198
	v_add_f32_e32 v133, v133, v112
	v_add_f32_e32 v134, v134, v155
	v_add_f32_e32 v135, v135, v113
	v_cvt_pk_bf16_f32 v112, v132, v133
	v_cvt_pk_bf16_f32 v113, v134, v135
	global_store_dwordx2 v124, v[112:113], s[58:59] offset:256
	v_fmac_f32_e32 v156, v132, v132
	v_fmac_f32_e32 v156, v133, v133
	v_fmac_f32_e32 v156, v134, v134
	v_fmac_f32_e32 v156, v135, v135
	v_lshlrev_b32_e32 v198, 16, v114
	v_and_b32_e32 v114, 0xffff0000, v114
	v_lshlrev_b32_e32 v155, 16, v115
	v_and_b32_e32 v115, 0xffff0000, v115
	v_add_f32_e32 v96, v96, v198
	v_add_f32_e32 v97, v97, v114
	v_add_f32_e32 v98, v98, v155
	v_add_f32_e32 v99, v99, v115
	v_cvt_pk_bf16_f32 v114, v96, v97
	v_cvt_pk_bf16_f32 v115, v98, v99
	global_store_dwordx2 v124, v[114:115], s[58:59] offset:288
	v_fmac_f32_e32 v156, v96, v96
	v_fmac_f32_e32 v156, v97, v97
	v_fmac_f32_e32 v156, v98, v98
	v_fmac_f32_e32 v156, v99, v99
	s_waitcnt vmcnt(28)
	v_add_u32_e32 v192, 0x20000, v196
	v_lshlrev_b32_e32 v198, 16, v200
	v_and_b32_e32 v200, 0xffff0000, v200
	v_lshlrev_b32_e32 v155, 16, v201
	v_and_b32_e32 v201, 0xffff0000, v201
	v_add_f32_e32 v92, v92, v198
	v_add_f32_e32 v93, v93, v200
	v_add_f32_e32 v94, v94, v155
	v_add_f32_e32 v95, v95, v201
	v_cvt_pk_bf16_f32 v200, v92, v93
	v_cvt_pk_bf16_f32 v201, v94, v95
	global_store_dwordx2 v192, v[200:201], s[58:59] offset:0
	v_mul_f32_e32 v198, v93, v93
	v_fmac_f32_e32 v198, v92, v92
	v_fmac_f32_e32 v198, v94, v94
	v_fmac_f32_e32 v198, v95, v95
	v_mov_b32_e32 v92, v198
	v_lshlrev_b32_e32 v198, 16, v202
	v_and_b32_e32 v202, 0xffff0000, v202
	v_lshlrev_b32_e32 v155, 16, v203
	v_and_b32_e32 v203, 0xffff0000, v203
	v_add_f32_e32 v88, v88, v198
	v_add_f32_e32 v89, v89, v202
	v_add_f32_e32 v90, v90, v155
	v_add_f32_e32 v91, v91, v203
	v_cvt_pk_bf16_f32 v202, v88, v89
	v_cvt_pk_bf16_f32 v203, v90, v91
	global_store_dwordx2 v192, v[202:203], s[58:59] offset:32
	v_fmac_f32_e32 v92, v88, v88
	v_fmac_f32_e32 v92, v89, v89
	v_fmac_f32_e32 v92, v90, v90
	v_fmac_f32_e32 v92, v91, v91
	v_lshlrev_b32_e32 v198, 16, v204
	v_and_b32_e32 v204, 0xffff0000, v204
	v_lshlrev_b32_e32 v155, 16, v205
	v_and_b32_e32 v205, 0xffff0000, v205
	v_add_f32_e32 v84, v84, v198
	v_add_f32_e32 v85, v85, v204
	v_add_f32_e32 v86, v86, v155
	v_add_f32_e32 v87, v87, v205
	v_cvt_pk_bf16_f32 v204, v84, v85
	v_cvt_pk_bf16_f32 v205, v86, v87
	global_store_dwordx2 v192, v[204:205], s[58:59] offset:256
	v_fmac_f32_e32 v92, v84, v84
	v_fmac_f32_e32 v92, v85, v85
	v_fmac_f32_e32 v92, v86, v86
	v_fmac_f32_e32 v92, v87, v87
	v_lshlrev_b32_e32 v198, 16, v214
	v_and_b32_e32 v214, 0xffff0000, v214
	v_lshlrev_b32_e32 v155, 16, v215
	v_and_b32_e32 v215, 0xffff0000, v215
	v_add_f32_e32 v80, v80, v198
	v_add_f32_e32 v81, v81, v214
	v_add_f32_e32 v82, v82, v155
	v_add_f32_e32 v83, v83, v215
	v_cvt_pk_bf16_f32 v214, v80, v81
	v_cvt_pk_bf16_f32 v215, v82, v83
	global_store_dwordx2 v192, v[214:215], s[58:59] offset:288
	v_fmac_f32_e32 v92, v80, v80
	v_fmac_f32_e32 v92, v81, v81
	v_fmac_f32_e32 v92, v82, v82
	v_fmac_f32_e32 v92, v83, v83
	s_waitcnt vmcnt(28)
	v_add_u32_e32 v124, 0x30000, v196
	v_lshlrev_b32_e32 v198, 16, v216
	v_and_b32_e32 v216, 0xffff0000, v216
	v_lshlrev_b32_e32 v155, 16, v217
	v_and_b32_e32 v217, 0xffff0000, v217
	v_add_f32_e32 v76, v76, v198
	v_add_f32_e32 v77, v77, v216
	v_add_f32_e32 v78, v78, v155
	v_add_f32_e32 v79, v79, v217
	v_cvt_pk_bf16_f32 v216, v76, v77
	v_cvt_pk_bf16_f32 v217, v78, v79
	global_store_dwordx2 v124, v[216:217], s[58:59] offset:0
	v_mul_f32_e32 v198, v77, v77
	v_fmac_f32_e32 v198, v76, v76
	v_fmac_f32_e32 v198, v78, v78
	v_fmac_f32_e32 v198, v79, v79
	v_mov_b32_e32 v76, v198
	v_lshlrev_b32_e32 v198, 16, v218
	v_and_b32_e32 v218, 0xffff0000, v218
	v_lshlrev_b32_e32 v155, 16, v219
	v_and_b32_e32 v219, 0xffff0000, v219
	v_add_f32_e32 v72, v72, v198
	v_add_f32_e32 v73, v73, v218
	v_add_f32_e32 v74, v74, v155
	v_add_f32_e32 v75, v75, v219
	v_cvt_pk_bf16_f32 v218, v72, v73
	v_cvt_pk_bf16_f32 v219, v74, v75
	global_store_dwordx2 v124, v[218:219], s[58:59] offset:32
	v_fmac_f32_e32 v76, v72, v72
	v_fmac_f32_e32 v76, v73, v73
	v_fmac_f32_e32 v76, v74, v74
	v_fmac_f32_e32 v76, v75, v75
	v_lshlrev_b32_e32 v198, 16, v220
	v_and_b32_e32 v220, 0xffff0000, v220
	v_lshlrev_b32_e32 v155, 16, v221
	v_and_b32_e32 v221, 0xffff0000, v221
	v_add_f32_e32 v68, v68, v198
	v_add_f32_e32 v69, v69, v220
	v_add_f32_e32 v70, v70, v155
	v_add_f32_e32 v71, v71, v221
	v_cvt_pk_bf16_f32 v220, v68, v69
	v_cvt_pk_bf16_f32 v221, v70, v71
	global_store_dwordx2 v124, v[220:221], s[58:59] offset:256
	v_fmac_f32_e32 v76, v68, v68
	v_fmac_f32_e32 v76, v69, v69
	v_fmac_f32_e32 v76, v70, v70
	v_fmac_f32_e32 v76, v71, v71
	v_lshlrev_b32_e32 v198, 16, v222
	v_and_b32_e32 v222, 0xffff0000, v222
	v_lshlrev_b32_e32 v155, 16, v223
	v_and_b32_e32 v223, 0xffff0000, v223
	v_add_f32_e32 v64, v64, v198
	v_add_f32_e32 v65, v65, v222
	v_add_f32_e32 v66, v66, v155
	v_add_f32_e32 v67, v67, v223
	v_cvt_pk_bf16_f32 v222, v64, v65
	v_cvt_pk_bf16_f32 v223, v66, v67
	global_store_dwordx2 v124, v[222:223], s[58:59] offset:288
	v_fmac_f32_e32 v76, v64, v64
	v_fmac_f32_e32 v76, v65, v65
	v_fmac_f32_e32 v76, v66, v66
	v_fmac_f32_e32 v76, v67, v67
	s_waitcnt vmcnt(28)
	v_add_u32_e32 v192, 0x80000, v196
	v_lshlrev_b32_e32 v198, 16, v224
	v_and_b32_e32 v224, 0xffff0000, v224
	v_lshlrev_b32_e32 v155, 16, v225
	v_and_b32_e32 v225, 0xffff0000, v225
	v_add_f32_e32 v60, v60, v198
	v_add_f32_e32 v61, v61, v224
	v_add_f32_e32 v62, v62, v155
	v_add_f32_e32 v63, v63, v225
	v_cvt_pk_bf16_f32 v224, v60, v61
	v_cvt_pk_bf16_f32 v225, v62, v63
	global_store_dwordx2 v192, v[224:225], s[58:59] offset:0
	v_mul_f32_e32 v198, v61, v61
	v_fmac_f32_e32 v198, v60, v60
	v_fmac_f32_e32 v198, v62, v62
	v_fmac_f32_e32 v198, v63, v63
	v_mov_b32_e32 v60, v198
	v_lshlrev_b32_e32 v198, 16, v226
	v_and_b32_e32 v226, 0xffff0000, v226
	v_lshlrev_b32_e32 v155, 16, v227
	v_and_b32_e32 v227, 0xffff0000, v227
	v_add_f32_e32 v56, v56, v198
	v_add_f32_e32 v57, v57, v226
	v_add_f32_e32 v58, v58, v155
	v_add_f32_e32 v59, v59, v227
	v_cvt_pk_bf16_f32 v226, v56, v57
	v_cvt_pk_bf16_f32 v227, v58, v59
	global_store_dwordx2 v192, v[226:227], s[58:59] offset:32
	v_fmac_f32_e32 v60, v56, v56
	v_fmac_f32_e32 v60, v57, v57
	v_fmac_f32_e32 v60, v58, v58
	v_fmac_f32_e32 v60, v59, v59
	v_lshlrev_b32_e32 v198, 16, v228
	v_and_b32_e32 v228, 0xffff0000, v228
	v_lshlrev_b32_e32 v155, 16, v229
	v_and_b32_e32 v229, 0xffff0000, v229
	v_add_f32_e32 v52, v52, v198
	v_add_f32_e32 v53, v53, v228
	v_add_f32_e32 v54, v54, v155
	v_add_f32_e32 v55, v55, v229
	v_cvt_pk_bf16_f32 v228, v52, v53
	v_cvt_pk_bf16_f32 v229, v54, v55
	global_store_dwordx2 v192, v[228:229], s[58:59] offset:256
	v_fmac_f32_e32 v60, v52, v52
	v_fmac_f32_e32 v60, v53, v53
	v_fmac_f32_e32 v60, v54, v54
	v_fmac_f32_e32 v60, v55, v55
	v_lshlrev_b32_e32 v198, 16, v230
	v_and_b32_e32 v230, 0xffff0000, v230
	v_lshlrev_b32_e32 v155, 16, v231
	v_and_b32_e32 v231, 0xffff0000, v231
	v_add_f32_e32 v48, v48, v198
	v_add_f32_e32 v49, v49, v230
	v_add_f32_e32 v50, v50, v155
	v_add_f32_e32 v51, v51, v231
	v_cvt_pk_bf16_f32 v230, v48, v49
	v_cvt_pk_bf16_f32 v231, v50, v51
	global_store_dwordx2 v192, v[230:231], s[58:59] offset:288
	v_fmac_f32_e32 v60, v48, v48
	v_fmac_f32_e32 v60, v49, v49
	v_fmac_f32_e32 v60, v50, v50
	v_fmac_f32_e32 v60, v51, v51
	s_waitcnt vmcnt(28)
	v_add_u32_e32 v124, 0x90000, v196
	v_lshlrev_b32_e32 v198, 16, v232
	v_and_b32_e32 v232, 0xffff0000, v232
	v_lshlrev_b32_e32 v155, 16, v233
	v_and_b32_e32 v233, 0xffff0000, v233
	v_add_f32_e32 v44, v44, v198
	v_add_f32_e32 v45, v45, v232
	v_add_f32_e32 v46, v46, v155
	v_add_f32_e32 v47, v47, v233
	v_cvt_pk_bf16_f32 v232, v44, v45
	v_cvt_pk_bf16_f32 v233, v46, v47
	global_store_dwordx2 v124, v[232:233], s[58:59] offset:0
	v_mul_f32_e32 v198, v45, v45
	v_fmac_f32_e32 v198, v44, v44
	v_fmac_f32_e32 v198, v46, v46
	v_fmac_f32_e32 v198, v47, v47
	v_mov_b32_e32 v44, v198
	v_lshlrev_b32_e32 v198, 16, v234
	v_and_b32_e32 v234, 0xffff0000, v234
	v_lshlrev_b32_e32 v155, 16, v235
	v_and_b32_e32 v235, 0xffff0000, v235
	v_add_f32_e32 v40, v40, v198
	v_add_f32_e32 v41, v41, v234
	v_add_f32_e32 v42, v42, v155
	v_add_f32_e32 v43, v43, v235
	v_cvt_pk_bf16_f32 v234, v40, v41
	v_cvt_pk_bf16_f32 v235, v42, v43
	global_store_dwordx2 v124, v[234:235], s[58:59] offset:32
	v_fmac_f32_e32 v44, v40, v40
	v_fmac_f32_e32 v44, v41, v41
	v_fmac_f32_e32 v44, v42, v42
	v_fmac_f32_e32 v44, v43, v43
	v_lshlrev_b32_e32 v198, 16, v236
	v_and_b32_e32 v236, 0xffff0000, v236
	v_lshlrev_b32_e32 v155, 16, v237
	v_and_b32_e32 v237, 0xffff0000, v237
	v_add_f32_e32 v36, v36, v198
	v_add_f32_e32 v37, v37, v236
	v_add_f32_e32 v38, v38, v155
	v_add_f32_e32 v39, v39, v237
	v_cvt_pk_bf16_f32 v236, v36, v37
	v_cvt_pk_bf16_f32 v237, v38, v39
	global_store_dwordx2 v124, v[236:237], s[58:59] offset:256
	v_fmac_f32_e32 v44, v36, v36
	v_fmac_f32_e32 v44, v37, v37
	v_fmac_f32_e32 v44, v38, v38
	v_fmac_f32_e32 v44, v39, v39
	v_lshlrev_b32_e32 v198, 16, v238
	v_and_b32_e32 v238, 0xffff0000, v238
	v_lshlrev_b32_e32 v155, 16, v239
	v_and_b32_e32 v239, 0xffff0000, v239
	v_add_f32_e32 v32, v32, v198
	v_add_f32_e32 v33, v33, v238
	v_add_f32_e32 v34, v34, v155
	v_add_f32_e32 v35, v35, v239
	v_cvt_pk_bf16_f32 v238, v32, v33
	v_cvt_pk_bf16_f32 v239, v34, v35
	global_store_dwordx2 v124, v[238:239], s[58:59] offset:288
	v_fmac_f32_e32 v44, v32, v32
	v_fmac_f32_e32 v44, v33, v33
	v_fmac_f32_e32 v44, v34, v34
	v_fmac_f32_e32 v44, v35, v35
	s_waitcnt vmcnt(28)
	v_add_u32_e32 v192, 0xa0000, v196
	v_lshlrev_b32_e32 v198, 16, v240
	v_and_b32_e32 v240, 0xffff0000, v240
	v_lshlrev_b32_e32 v155, 16, v241
	v_and_b32_e32 v241, 0xffff0000, v241
	v_add_f32_e32 v28, v28, v198
	v_add_f32_e32 v29, v29, v240
	v_add_f32_e32 v30, v30, v155
	v_add_f32_e32 v31, v31, v241
	v_cvt_pk_bf16_f32 v240, v28, v29
	v_cvt_pk_bf16_f32 v241, v30, v31
	global_store_dwordx2 v192, v[240:241], s[58:59] offset:0
	v_mul_f32_e32 v198, v29, v29
	v_fmac_f32_e32 v198, v28, v28
	v_fmac_f32_e32 v198, v30, v30
	v_fmac_f32_e32 v198, v31, v31
	v_mov_b32_e32 v28, v198
	v_lshlrev_b32_e32 v198, 16, v242
	v_and_b32_e32 v242, 0xffff0000, v242
	v_lshlrev_b32_e32 v155, 16, v243
	v_and_b32_e32 v243, 0xffff0000, v243
	v_add_f32_e32 v24, v24, v198
	v_add_f32_e32 v25, v25, v242
	v_add_f32_e32 v26, v26, v155
	v_add_f32_e32 v27, v27, v243
	v_cvt_pk_bf16_f32 v242, v24, v25
	v_cvt_pk_bf16_f32 v243, v26, v27
	global_store_dwordx2 v192, v[242:243], s[58:59] offset:32
	v_fmac_f32_e32 v28, v24, v24
	v_fmac_f32_e32 v28, v25, v25
	v_fmac_f32_e32 v28, v26, v26
	v_fmac_f32_e32 v28, v27, v27
	v_lshlrev_b32_e32 v198, 16, v244
	v_and_b32_e32 v244, 0xffff0000, v244
	v_lshlrev_b32_e32 v155, 16, v245
	v_and_b32_e32 v245, 0xffff0000, v245
	v_add_f32_e32 v20, v20, v198
	v_add_f32_e32 v21, v21, v244
	v_add_f32_e32 v22, v22, v155
	v_add_f32_e32 v23, v23, v245
	v_cvt_pk_bf16_f32 v244, v20, v21
	v_cvt_pk_bf16_f32 v245, v22, v23
	global_store_dwordx2 v192, v[244:245], s[58:59] offset:256
	v_fmac_f32_e32 v28, v20, v20
	v_fmac_f32_e32 v28, v21, v21
	v_fmac_f32_e32 v28, v22, v22
	v_fmac_f32_e32 v28, v23, v23
	v_lshlrev_b32_e32 v198, 16, v246
	v_and_b32_e32 v246, 0xffff0000, v246
	v_lshlrev_b32_e32 v155, 16, v247
	v_and_b32_e32 v247, 0xffff0000, v247
	v_add_f32_e32 v16, v16, v198
	v_add_f32_e32 v17, v17, v246
	v_add_f32_e32 v18, v18, v155
	v_add_f32_e32 v19, v19, v247
	v_cvt_pk_bf16_f32 v246, v16, v17
	v_cvt_pk_bf16_f32 v247, v18, v19
	global_store_dwordx2 v192, v[246:247], s[58:59] offset:288
	v_fmac_f32_e32 v28, v16, v16
	v_fmac_f32_e32 v28, v17, v17
	v_fmac_f32_e32 v28, v18, v18
	v_fmac_f32_e32 v28, v19, v19
	s_waitcnt vmcnt(28)
	v_add_u32_e32 v124, 0xb0000, v196
	v_lshlrev_b32_e32 v198, 16, v248
	v_and_b32_e32 v248, 0xffff0000, v248
	v_lshlrev_b32_e32 v155, 16, v249
	v_and_b32_e32 v249, 0xffff0000, v249
	v_add_f32_e32 v12, v12, v198
	v_add_f32_e32 v13, v13, v248
	v_add_f32_e32 v14, v14, v155
	v_add_f32_e32 v15, v15, v249
	v_cvt_pk_bf16_f32 v248, v12, v13
	v_cvt_pk_bf16_f32 v249, v14, v15
	global_store_dwordx2 v124, v[248:249], s[58:59] offset:0
	v_mul_f32_e32 v198, v13, v13
	v_fmac_f32_e32 v198, v12, v12
	v_fmac_f32_e32 v198, v14, v14
	v_fmac_f32_e32 v198, v15, v15
	v_mov_b32_e32 v12, v198
	v_lshlrev_b32_e32 v198, 16, v190
	v_and_b32_e32 v190, 0xffff0000, v190
	v_lshlrev_b32_e32 v155, 16, v191
	v_and_b32_e32 v191, 0xffff0000, v191
	v_add_f32_e32 v8, v8, v198
	v_add_f32_e32 v9, v9, v190
	v_add_f32_e32 v10, v10, v155
	v_add_f32_e32 v11, v11, v191
	v_cvt_pk_bf16_f32 v190, v8, v9
	v_cvt_pk_bf16_f32 v191, v10, v11
	global_store_dwordx2 v124, v[190:191], s[58:59] offset:32
	v_fmac_f32_e32 v12, v8, v8
	v_fmac_f32_e32 v12, v9, v9
	v_fmac_f32_e32 v12, v10, v10
	v_fmac_f32_e32 v12, v11, v11
	v_lshlrev_b32_e32 v198, 16, v194
	v_and_b32_e32 v194, 0xffff0000, v194
	v_lshlrev_b32_e32 v155, 16, v195
	v_and_b32_e32 v195, 0xffff0000, v195
	v_add_f32_e32 v4, v4, v198
	v_add_f32_e32 v5, v5, v194
	v_add_f32_e32 v6, v6, v155
	v_add_f32_e32 v7, v7, v195
	v_cvt_pk_bf16_f32 v194, v4, v5
	v_cvt_pk_bf16_f32 v195, v6, v7
	global_store_dwordx2 v124, v[194:195], s[58:59] offset:256
	v_fmac_f32_e32 v12, v4, v4
	v_fmac_f32_e32 v12, v5, v5
	v_fmac_f32_e32 v12, v6, v6
	v_fmac_f32_e32 v12, v7, v7
	v_lshlrev_b32_e32 v198, 16, v146
	v_and_b32_e32 v146, 0xffff0000, v146
	v_lshlrev_b32_e32 v155, 16, v147
	v_and_b32_e32 v147, 0xffff0000, v147
	v_add_f32_e32 v0, v0, v198
	v_add_f32_e32 v1, v1, v146
	v_add_f32_e32 v2, v2, v155
	v_add_f32_e32 v3, v3, v147
	v_cvt_pk_bf16_f32 v146, v0, v1
	v_cvt_pk_bf16_f32 v147, v2, v3
	global_store_dwordx2 v124, v[146:147], s[58:59] offset:288
	v_fmac_f32_e32 v12, v0, v0
	v_fmac_f32_e32 v12, v1, v1
	v_fmac_f32_e32 v12, v2, v2
	v_fmac_f32_e32 v12, v3, v3
	ds_bpermute_b32 v100, v207, v172
	ds_bpermute_b32 v101, v207, v156
	ds_bpermute_b32 v102, v207, v92
	ds_bpermute_b32 v103, v207, v76
	ds_bpermute_b32 v104, v207, v60
	ds_bpermute_b32 v105, v207, v44
	ds_bpermute_b32 v106, v207, v28
	ds_bpermute_b32 v107, v207, v12
	s_waitcnt lgkmcnt(0)
	v_add_f32_e32 v172, v172, v100
	v_add_f32_e32 v156, v156, v101
	v_add_f32_e32 v92, v92, v102
	v_add_f32_e32 v76, v76, v103
	v_add_f32_e32 v60, v60, v104
	v_add_f32_e32 v44, v44, v105
	v_add_f32_e32 v28, v28, v106
	v_add_f32_e32 v12, v12, v107
	ds_bpermute_b32 v100, v206, v172
	ds_bpermute_b32 v101, v206, v156
	ds_bpermute_b32 v102, v206, v92
	ds_bpermute_b32 v103, v206, v76
	ds_bpermute_b32 v104, v206, v60
	ds_bpermute_b32 v105, v206, v44
	ds_bpermute_b32 v106, v206, v28
	ds_bpermute_b32 v107, v206, v12
	s_waitcnt lgkmcnt(0)
	v_add_f32_e32 v172, v172, v100
	v_add_f32_e32 v156, v156, v101
	v_add_f32_e32 v92, v92, v102
	v_add_f32_e32 v76, v76, v103
	v_add_f32_e32 v60, v60, v104
	v_add_f32_e32 v44, v44, v105
	v_add_f32_e32 v28, v28, v106
	v_add_f32_e32 v12, v12, v107
	s_and_saveexec_b64 s[2:3], s[40:41]
	v_mov_b32_e32 v192, v188
	global_store_dword v192, v172, s[16:17]
	v_add_u32_e32 v124, 0x800, v188
	global_store_dword v124, v156, s[16:17]
	v_add_u32_e32 v192, 0x1000, v188
	global_store_dword v192, v92, s[16:17]
	v_add_u32_e32 v124, 0x1800, v188
	global_store_dword v124, v76, s[16:17]
	v_add_u32_e32 v192, 0x4000, v188
	global_store_dword v192, v60, s[16:17]
	v_add_u32_e32 v124, 0x4800, v188
	global_store_dword v124, v44, s[16:17]
	v_add_u32_e32 v192, 0x5000, v188
	global_store_dword v192, v28, s[16:17]
	v_add_u32_e32 v124, 0x5800, v188
	global_store_dword v124, v12, s[16:17]
	s_or_b64 exec, exec, s[2:3]
	s_branch .LBB0_513

.Lprio_559:
	s_add_i32 s94, 0, 0x10000
	v_add_u32_e32 v213, s94, v210
	ds_read_b128 v[132:135], v213
	ds_read_b128 v[136:139], v213 offset:1024
	ds_read_b128 v[140:143], v213 offset:2048
	ds_read_b128 v[144:147], v213 offset:3072
	v_lshl_add_u64 v[190:191], v[128:129], 0, s[44:45]
	s_add_i32 s81, s92, 0xc000
	v_lshl_add_u64 v[194:195], v[190:191], 0, s[18:19]
	s_mov_b32 m0, s81
	ds_read_b128 v[152:155], v211
	ds_read_b128 v[156:159], v211 offset:1024
	ds_read_b128 v[160:163], v211 offset:2048
	ds_read_b128 v[164:167], v211 offset:3072
	ds_read_b128 v[168:171], v211 offset:4096
	ds_read_b128 v[172:175], v211 offset:5120
	ds_read_b128 v[200:203], v211 offset:6144
	ds_read_b128 v[216:219], v211 offset:7168
	global_load_lds_dwordx4 v[194:195], off
	v_lshl_add_u64 v[194:195], v[130:131], 0, s[44:45]
	s_add_i32 s93, s92, 0xe000
	v_lshl_add_u64 v[204:205], v[194:195], 0, s[18:19]
	s_mov_b32 m0, s93
	s_nop 0
	global_load_lds_dwordx4 v[204:205], off
	s_waitcnt lgkmcnt(8)
	s_barrier
	s_waitcnt lgkmcnt(0)
	s_waitcnt lgkmcnt(0)
	v_mfma_f32_16x16x32_bf16 v[60:63], v[132:135], v[152:155], v[60:63]
	v_mfma_f32_16x16x32_bf16 v[56:59], v[140:143], v[152:155], v[56:59]
	v_mfma_f32_16x16x32_bf16 v[92:95], v[132:135], v[160:163], v[92:95]
	v_mfma_f32_16x16x32_bf16 v[88:91], v[140:143], v[160:163], v[88:91]
	v_mfma_f32_16x16x32_bf16 v[124:127], v[132:135], v[168:171], v[124:127]
	v_mfma_f32_16x16x32_bf16 v[120:123], v[140:143], v[168:171], v[120:123]
	v_mfma_f32_16x16x32_bf16 v[108:111], v[132:135], v[200:203], v[108:111]
	v_mfma_f32_16x16x32_bf16 v[104:107], v[140:143], v[200:203], v[104:107]
	v_mfma_f32_16x16x32_bf16 v[60:63], v[136:139], v[156:159], v[60:63]
	v_mfma_f32_16x16x32_bf16 v[56:59], v[144:147], v[156:159], v[56:59]
	v_mfma_f32_16x16x32_bf16 v[92:95], v[136:139], v[164:167], v[92:95]
	v_mfma_f32_16x16x32_bf16 v[88:91], v[144:147], v[164:167], v[88:91]
	v_mfma_f32_16x16x32_bf16 v[124:127], v[136:139], v[172:175], v[124:127]
	v_mfma_f32_16x16x32_bf16 v[120:123], v[144:147], v[172:175], v[120:123]
	v_mfma_f32_16x16x32_bf16 v[108:111], v[136:139], v[216:219], v[108:111]
	v_mfma_f32_16x16x32_bf16 v[104:107], v[144:147], v[216:219], v[104:107]
	s_barrier
	s_add_i32 s96, 0, 0x14000
	v_lshl_add_u64 v[204:205], v[148:149], 0, s[44:45]
	s_add_i32 s94, s94, s80
	v_add_u32_e32 v214, s96, v210
	v_lshl_add_u64 v[236:237], v[204:205], 0, s[24:25]
	s_mov_b32 m0, s94
	v_lshl_add_u64 v[238:239], v[150:151], 0, s[44:45]
	s_add_i32 s95, s94, 0x2000
	ds_read_b128 v[220:223], v214
	ds_read_b128 v[224:227], v214 offset:1024
	ds_read_b128 v[228:231], v214 offset:2048
	ds_read_b128 v[232:235], v214 offset:3072
	global_load_lds_dwordx4 v[236:237], off
	v_lshl_add_u64 v[236:237], v[238:239], 0, s[24:25]
	s_mov_b32 m0, s95
	s_nop 0
	global_load_lds_dwordx4 v[236:237], off
	s_barrier
	s_waitcnt lgkmcnt(0)
	s_waitcnt lgkmcnt(0)
	v_mfma_f32_16x16x32_bf16 v[52:55], v[220:223], v[152:155], v[52:55]
	v_mfma_f32_16x16x32_bf16 v[48:51], v[228:231], v[152:155], v[48:51]
	v_mfma_f32_16x16x32_bf16 v[84:87], v[220:223], v[160:163], v[84:87]
	v_mfma_f32_16x16x32_bf16 v[80:83], v[228:231], v[160:163], v[80:83]
	v_mfma_f32_16x16x32_bf16 v[116:119], v[220:223], v[168:171], v[116:119]
	v_mfma_f32_16x16x32_bf16 v[112:115], v[228:231], v[168:171], v[112:115]
	v_mfma_f32_16x16x32_bf16 v[100:103], v[220:223], v[200:203], v[100:103]
	v_mfma_f32_16x16x32_bf16 v[96:99], v[228:231], v[200:203], v[96:99]
	v_mfma_f32_16x16x32_bf16 v[52:55], v[224:227], v[156:159], v[52:55]
	v_mfma_f32_16x16x32_bf16 v[48:51], v[232:235], v[156:159], v[48:51]
	v_mfma_f32_16x16x32_bf16 v[84:87], v[224:227], v[164:167], v[84:87]
	v_mfma_f32_16x16x32_bf16 v[80:83], v[232:235], v[164:167], v[80:83]
	v_mfma_f32_16x16x32_bf16 v[116:119], v[224:227], v[172:175], v[116:119]
	v_mfma_f32_16x16x32_bf16 v[112:115], v[232:235], v[172:175], v[112:115]
	v_mfma_f32_16x16x32_bf16 v[100:103], v[224:227], v[216:219], v[100:103]
	v_mfma_f32_16x16x32_bf16 v[96:99], v[232:235], v[216:219], v[96:99]
	s_mov_b32 m0, s92
	v_lshl_add_u64 v[236:237], v[190:191], 0, s[24:25]
	s_barrier
	ds_read_b128 v[152:155], v211 offset:16384
	ds_read_b128 v[156:159], v211 offset:17408
	ds_read_b128 v[160:163], v211 offset:18432
	ds_read_b128 v[164:167], v211 offset:19456
	ds_read_b128 v[168:171], v211 offset:20480
	ds_read_b128 v[172:175], v211 offset:21504
	ds_read_b128 v[200:203], v211 offset:22528
	ds_read_b128 v[216:219], v211 offset:23552
	global_load_lds_dwordx4 v[236:237], off
	v_lshl_add_u64 v[236:237], v[194:195], 0, s[24:25]
	s_mov_b32 m0, s82
	s_nop 0
	global_load_lds_dwordx4 v[236:237], off
	s_barrier
	s_waitcnt lgkmcnt(0)
	s_waitcnt lgkmcnt(0)
	v_mfma_f32_16x16x32_bf16 v[76:79], v[132:135], v[152:155], v[76:79]
	v_mfma_f32_16x16x32_bf16 v[72:75], v[140:143], v[152:155], v[72:75]
	v_mfma_f32_16x16x32_bf16 v[44:47], v[132:135], v[160:163], v[44:47]
	v_mfma_f32_16x16x32_bf16 v[40:43], v[140:143], v[160:163], v[40:43]
	v_mfma_f32_16x16x32_bf16 v[28:31], v[132:135], v[168:171], v[28:31]
	v_mfma_f32_16x16x32_bf16 v[24:27], v[140:143], v[168:171], v[24:27]
	v_mfma_f32_16x16x32_bf16 v[12:15], v[132:135], v[200:203], v[12:15]
	v_mfma_f32_16x16x32_bf16 v[8:11], v[140:143], v[200:203], v[8:11]
	v_mfma_f32_16x16x32_bf16 v[76:79], v[136:139], v[156:159], v[76:79]
	v_mfma_f32_16x16x32_bf16 v[72:75], v[144:147], v[156:159], v[72:75]
	v_mfma_f32_16x16x32_bf16 v[44:47], v[136:139], v[164:167], v[44:47]
	v_mfma_f32_16x16x32_bf16 v[40:43], v[144:147], v[164:167], v[40:43]
	v_mfma_f32_16x16x32_bf16 v[28:31], v[136:139], v[172:175], v[28:31]
	v_mfma_f32_16x16x32_bf16 v[24:27], v[144:147], v[172:175], v[24:27]
	v_mfma_f32_16x16x32_bf16 v[12:15], v[136:139], v[216:219], v[12:15]
	v_mfma_f32_16x16x32_bf16 v[8:11], v[144:147], v[216:219], v[8:11]
	s_barrier
	s_add_i32 s96, s96, s80
	v_lshl_add_u64 v[132:133], v[204:205], 0, s[28:29]
	s_mov_b32 m0, s96
	s_add_i32 s97, s96, 0x2000
	global_load_lds_dwordx4 v[132:133], off
	v_lshl_add_u64 v[132:133], v[238:239], 0, s[28:29]
	s_mov_b32 m0, s97
	s_nop 0
	global_load_lds_dwordx4 v[132:133], off
	s_waitcnt vmcnt(6)
	s_barrier
	v_mfma_f32_16x16x32_bf16 v[68:71], v[220:223], v[152:155], v[68:71]
	v_mfma_f32_16x16x32_bf16 v[64:67], v[228:231], v[152:155], v[64:67]
	v_mfma_f32_16x16x32_bf16 v[36:39], v[220:223], v[160:163], v[36:39]
	v_mfma_f32_16x16x32_bf16 v[32:35], v[228:231], v[160:163], v[32:35]
	v_mfma_f32_16x16x32_bf16 v[20:23], v[220:223], v[168:171], v[20:23]
	v_mfma_f32_16x16x32_bf16 v[16:19], v[228:231], v[168:171], v[16:19]
	v_mfma_f32_16x16x32_bf16 v[4:7], v[220:223], v[200:203], v[4:7]
	v_mfma_f32_16x16x32_bf16 v[0:3], v[228:231], v[200:203], v[0:3]
	v_mfma_f32_16x16x32_bf16 v[68:71], v[224:227], v[156:159], v[68:71]
	v_mfma_f32_16x16x32_bf16 v[64:67], v[232:235], v[156:159], v[64:67]
	v_mfma_f32_16x16x32_bf16 v[36:39], v[224:227], v[164:167], v[36:39]
	v_mfma_f32_16x16x32_bf16 v[32:35], v[232:235], v[164:167], v[32:35]
	v_mfma_f32_16x16x32_bf16 v[20:23], v[224:227], v[172:175], v[20:23]
	v_mfma_f32_16x16x32_bf16 v[16:19], v[232:235], v[172:175], v[16:19]
	v_mfma_f32_16x16x32_bf16 v[4:7], v[224:227], v[216:219], v[4:7]
	v_mfma_f32_16x16x32_bf16 v[0:3], v[232:235], v[216:219], v[0:3]
	s_add_i32 s60, 0, 0x18000
	v_add_u32_e32 v215, s60, v210
	s_barrier
	ds_read_b128 v[132:135], v215
	ds_read_b128 v[136:139], v215 offset:1024
	ds_read_b128 v[140:143], v215 offset:2048
	ds_read_b128 v[144:147], v215 offset:3072
	s_mov_b32 m0, s83
	v_lshl_add_u64 v[216:217], v[190:191], 0, s[28:29]
	ds_read_b128 v[152:155], v211 offset:32768
	ds_read_b128 v[156:159], v211 offset:33792
	ds_read_b128 v[160:163], v211 offset:34816
	ds_read_b128 v[164:167], v211 offset:35840
	ds_read_b128 v[168:171], v211 offset:36864
	ds_read_b128 v[172:175], v211 offset:37888
	ds_read_b128 v[200:203], v211 offset:38912
	ds_read_b128 v[218:221], v211 offset:39936
	global_load_lds_dwordx4 v[216:217], off
	v_lshl_add_u64 v[216:217], v[194:195], 0, s[28:29]
	s_mov_b32 m0, s86
	s_nop 0
	global_load_lds_dwordx4 v[216:217], off
	s_waitcnt lgkmcnt(8)
	s_barrier
	s_waitcnt lgkmcnt(0)
	s_waitcnt lgkmcnt(0)
	v_mfma_f32_16x16x32_bf16 v[60:63], v[132:135], v[152:155], v[60:63]
	v_mfma_f32_16x16x32_bf16 v[56:59], v[140:143], v[152:155], v[56:59]
	v_mfma_f32_16x16x32_bf16 v[92:95], v[132:135], v[160:163], v[92:95]
	v_mfma_f32_16x16x32_bf16 v[88:91], v[140:143], v[160:163], v[88:91]
	v_mfma_f32_16x16x32_bf16 v[124:127], v[132:135], v[168:171], v[124:127]
	v_mfma_f32_16x16x32_bf16 v[120:123], v[140:143], v[168:171], v[120:123]
	v_mfma_f32_16x16x32_bf16 v[108:111], v[132:135], v[200:203], v[108:111]
	v_mfma_f32_16x16x32_bf16 v[104:107], v[140:143], v[200:203], v[104:107]
	v_mfma_f32_16x16x32_bf16 v[60:63], v[136:139], v[156:159], v[60:63]
	v_mfma_f32_16x16x32_bf16 v[56:59], v[144:147], v[156:159], v[56:59]
	v_mfma_f32_16x16x32_bf16 v[92:95], v[136:139], v[164:167], v[92:95]
	v_mfma_f32_16x16x32_bf16 v[88:91], v[144:147], v[164:167], v[88:91]
	v_mfma_f32_16x16x32_bf16 v[124:127], v[136:139], v[172:175], v[124:127]
	v_mfma_f32_16x16x32_bf16 v[120:123], v[144:147], v[172:175], v[120:123]
	v_mfma_f32_16x16x32_bf16 v[108:111], v[136:139], v[218:221], v[108:111]
	v_mfma_f32_16x16x32_bf16 v[104:107], v[144:147], v[218:221], v[104:107]
	s_barrier
	s_add_i32 s49, 0, 0x1c000
	s_add_i32 s60, s60, s80
	v_add_u32_e32 v216, s49, v210
	v_lshl_add_u64 v[240:241], v[204:205], 0, s[50:51]
	s_mov_b32 m0, s60
	s_add_i32 s61, s60, 0x2000
	ds_read_b128 v[222:225], v216
	ds_read_b128 v[226:229], v216 offset:1024
	ds_read_b128 v[230:233], v216 offset:2048
	ds_read_b128 v[234:237], v216 offset:3072
	global_load_lds_dwordx4 v[240:241], off
	v_lshl_add_u64 v[240:241], v[238:239], 0, s[50:51]
	s_mov_b32 m0, s61
	s_nop 0
	global_load_lds_dwordx4 v[240:241], off
	s_barrier
	s_waitcnt lgkmcnt(0)
	s_waitcnt lgkmcnt(0)
	v_mfma_f32_16x16x32_bf16 v[52:55], v[222:225], v[152:155], v[52:55]
	v_mfma_f32_16x16x32_bf16 v[48:51], v[230:233], v[152:155], v[48:51]
	v_mfma_f32_16x16x32_bf16 v[84:87], v[222:225], v[160:163], v[84:87]
	v_mfma_f32_16x16x32_bf16 v[80:83], v[230:233], v[160:163], v[80:83]
	v_mfma_f32_16x16x32_bf16 v[116:119], v[222:225], v[168:171], v[116:119]
	v_mfma_f32_16x16x32_bf16 v[112:115], v[230:233], v[168:171], v[112:115]
	v_mfma_f32_16x16x32_bf16 v[100:103], v[222:225], v[200:203], v[100:103]
	v_mfma_f32_16x16x32_bf16 v[96:99], v[230:233], v[200:203], v[96:99]
	v_mfma_f32_16x16x32_bf16 v[52:55], v[226:229], v[156:159], v[52:55]
	v_mfma_f32_16x16x32_bf16 v[48:51], v[234:237], v[156:159], v[48:51]
	v_mfma_f32_16x16x32_bf16 v[84:87], v[226:229], v[164:167], v[84:87]
	v_mfma_f32_16x16x32_bf16 v[80:83], v[234:237], v[164:167], v[80:83]
	v_mfma_f32_16x16x32_bf16 v[116:119], v[226:229], v[172:175], v[116:119]
	v_mfma_f32_16x16x32_bf16 v[112:115], v[234:237], v[172:175], v[112:115]
	v_mfma_f32_16x16x32_bf16 v[100:103], v[226:229], v[218:221], v[100:103]
	v_mfma_f32_16x16x32_bf16 v[96:99], v[234:237], v[218:221], v[96:99]
	s_mov_b32 m0, s89
	v_lshl_add_u64 v[190:191], v[190:191], 0, s[50:51]
	s_barrier
	ds_read_b128 v[152:155], v211 offset:49152
	ds_read_b128 v[156:159], v211 offset:50176
	ds_read_b128 v[160:163], v211 offset:51200
	ds_read_b128 v[164:167], v211 offset:52224
	ds_read_b128 v[168:171], v211 offset:53248
	ds_read_b128 v[172:175], v211 offset:54272
	ds_read_b128 v[200:203], v211 offset:55296
	ds_read_b128 v[218:221], v211 offset:56320
	global_load_lds_dwordx4 v[190:191], off
	v_lshl_add_u64 v[190:191], v[194:195], 0, s[50:51]
	s_mov_b32 m0, s79
	s_nop 0
	global_load_lds_dwordx4 v[190:191], off
	s_barrier
	s_waitcnt lgkmcnt(0)
	s_waitcnt lgkmcnt(0)
	v_mfma_f32_16x16x32_bf16 v[76:79], v[132:135], v[152:155], v[76:79]
	v_mfma_f32_16x16x32_bf16 v[72:75], v[140:143], v[152:155], v[72:75]
	v_mfma_f32_16x16x32_bf16 v[44:47], v[132:135], v[160:163], v[44:47]
	v_mfma_f32_16x16x32_bf16 v[40:43], v[140:143], v[160:163], v[40:43]
	v_mfma_f32_16x16x32_bf16 v[28:31], v[132:135], v[168:171], v[28:31]
	v_mfma_f32_16x16x32_bf16 v[24:27], v[140:143], v[168:171], v[24:27]
	v_mfma_f32_16x16x32_bf16 v[12:15], v[132:135], v[200:203], v[12:15]
	v_mfma_f32_16x16x32_bf16 v[8:11], v[140:143], v[200:203], v[8:11]
	v_mfma_f32_16x16x32_bf16 v[76:79], v[136:139], v[156:159], v[76:79]
	v_mfma_f32_16x16x32_bf16 v[72:75], v[144:147], v[156:159], v[72:75]
	v_mfma_f32_16x16x32_bf16 v[44:47], v[136:139], v[164:167], v[44:47]
	v_mfma_f32_16x16x32_bf16 v[40:43], v[144:147], v[164:167], v[40:43]
	v_mfma_f32_16x16x32_bf16 v[28:31], v[136:139], v[172:175], v[28:31]
	v_mfma_f32_16x16x32_bf16 v[24:27], v[144:147], v[172:175], v[24:27]
	v_mfma_f32_16x16x32_bf16 v[12:15], v[136:139], v[218:221], v[12:15]
	v_mfma_f32_16x16x32_bf16 v[8:11], v[144:147], v[218:221], v[8:11]
	s_barrier
	s_add_i32 s49, s49, s80
	v_lshl_add_u64 v[132:133], v[204:205], 0, s[6:7]
	s_mov_b32 m0, s49
	s_add_i32 s52, s49, 0x2000
	global_load_lds_dwordx4 v[132:133], off
	v_lshl_add_u64 v[132:133], v[238:239], 0, s[6:7]
	s_mov_b32 m0, s52
	s_nop 0
	global_load_lds_dwordx4 v[132:133], off
	s_waitcnt vmcnt(6)
	s_barrier
	v_mfma_f32_16x16x32_bf16 v[68:71], v[222:225], v[152:155], v[68:71]
	v_mfma_f32_16x16x32_bf16 v[64:67], v[230:233], v[152:155], v[64:67]
	v_mfma_f32_16x16x32_bf16 v[36:39], v[222:225], v[160:163], v[36:39]
	v_mfma_f32_16x16x32_bf16 v[32:35], v[230:233], v[160:163], v[32:35]
	v_mfma_f32_16x16x32_bf16 v[20:23], v[222:225], v[168:171], v[20:23]
	v_mfma_f32_16x16x32_bf16 v[16:19], v[230:233], v[168:171], v[16:19]
	v_mfma_f32_16x16x32_bf16 v[4:7], v[222:225], v[200:203], v[4:7]
	v_mfma_f32_16x16x32_bf16 v[0:3], v[230:233], v[200:203], v[0:3]
	v_mfma_f32_16x16x32_bf16 v[68:71], v[226:229], v[156:159], v[68:71]
	v_mfma_f32_16x16x32_bf16 v[64:67], v[234:237], v[156:159], v[64:67]
	v_mfma_f32_16x16x32_bf16 v[36:39], v[226:229], v[164:167], v[36:39]
	v_mfma_f32_16x16x32_bf16 v[32:35], v[234:237], v[164:167], v[32:35]
	v_mfma_f32_16x16x32_bf16 v[20:23], v[226:229], v[172:175], v[20:23]
	v_mfma_f32_16x16x32_bf16 v[16:19], v[234:237], v[172:175], v[16:19]
	v_mfma_f32_16x16x32_bf16 v[4:7], v[226:229], v[218:221], v[4:7]
	v_mfma_f32_16x16x32_bf16 v[0:3], v[234:237], v[218:221], v[0:3]
	s_add_i32 s46, s46, 2
	s_add_u32 s44, s44, 0x100
	s_addc_u32 s45, s45, 0
	s_cmp_gt_u32 s46, 13
	s_barrier
	s_cbranch_scc0 .LBB0_559
	s_setprio 0
	s_lshl_b32 s53, s53, 8
	s_add_i32 s1, s53, s48
	v_mov_b32_e32 v132, v208
	v_readlane_b32 s12, v254, 31
	v_bfe_u32 v153, v132, 4, 2
	v_and_or_b32 v158, v132, 15, s1
	v_lshlrev_b32_e32 v159, 1, v153
	v_lshl_or_b32 v132, v158, 3, v159
	v_ashrrev_i32_e32 v133, 31, v132
	v_readlane_b32 s13, v254, 32
	v_readlane_b32 s2, v254, 29
	v_readlane_b32 s3, v254, 30
	v_lshl_add_u64 v[132:133], v[132:133], 2, s[12:13]
	global_load_dwordx2 v[132:133], v[132:133], off
	v_or_b32_e32 v134, 16, v158
	s_mov_b32 s14, 0x358637bd
	s_waitcnt vmcnt(0)
	v_pk_add_f32 v[154:155], v[132:133], v[132:133] op_sel:[0,1] op_sel_hi:[1,0]
	v_lshl_or_b32 v132, v158, 2, v153
	v_ashrrev_i32_e32 v133, 31, v132
	v_lshl_add_u64 v[132:133], v[132:133], 2, s[2:3]
	global_load_dword v160, v[132:133], off
	v_lshl_or_b32 v132, v134, 3, v159
	v_ashrrev_i32_e32 v133, 31, v132
	v_lshl_add_u64 v[132:133], v[132:133], 2, s[12:13]
	global_load_dwordx2 v[132:133], v[132:133], off
	ds_bpermute_b32 v163, v207, v154
	v_mov_b32_e32 v161, v154
	s_waitcnt vmcnt(0)
	ds_bpermute_b32 v162, v207, v160
	v_pk_add_f32 v[144:145], v[132:133], v[132:133] op_sel:[0,1] op_sel_hi:[1,0]
	v_lshl_or_b32 v132, v134, 2, v153
	v_ashrrev_i32_e32 v133, 31, v132
	v_lshl_add_u64 v[132:133], v[132:133], 2, s[2:3]
	v_or_b32_e32 v134, 32, v158
	global_load_dword v146, v[132:133], off
	v_lshl_or_b32 v132, v134, 3, v159
	v_ashrrev_i32_e32 v133, 31, v132
	v_lshl_add_u64 v[132:133], v[132:133], 2, s[12:13]
	global_load_dwordx2 v[132:133], v[132:133], off
	s_waitcnt lgkmcnt(0)
	v_pk_add_f32 v[154:155], v[160:161], v[162:163]
	ds_bpermute_b32 v161, v206, v155
	ds_bpermute_b32 v160, v206, v154
	ds_bpermute_b32 v157, v207, v144
	v_mov_b32_e32 v147, v144
	s_waitcnt lgkmcnt(1)
	v_pk_add_f32 v[160:161], v[154:155], v[160:161]
	v_mov_b64_e32 v[154:155], s[14:15]
	s_mov_b32 s14, 0x3b000000
	s_mov_b32 s15, 0x3a800000
	v_pk_fma_f32 v[160:161], v[160:161], s[14:15], v[154:155] op_sel_hi:[1,1,0]
	s_waitcnt vmcnt(1)
	ds_bpermute_b32 v156, v207, v146
	v_cmp_gt_f32_e64 s[46:47], s33, v161
	v_cmp_gt_f32_e64 s[44:45], s33, v160
	s_waitcnt vmcnt(0)
	v_pk_add_f32 v[140:141], v[132:133], v[132:133] op_sel:[0,1] op_sel_hi:[1,0]
	v_lshl_or_b32 v132, v134, 2, v153
	v_ashrrev_i32_e32 v133, 31, v132
	v_lshl_add_u64 v[132:133], v[132:133], 2, s[2:3]
	v_or_b32_e32 v134, 48, v158
	global_load_dword v138, v[132:133], off
	v_lshl_or_b32 v132, v134, 3, v159
	v_ashrrev_i32_e32 v133, 31, v132
	v_lshl_add_u64 v[132:133], v[132:133], 2, s[12:13]
	global_load_dwordx2 v[132:133], v[132:133], off
	v_lshl_or_b32 v134, v134, 2, v153
	v_ashrrev_i32_e32 v135, 31, v134
	v_lshl_add_u64 v[134:135], v[134:135], 2, s[2:3]
	global_load_dword v134, v[134:135], off
	s_waitcnt lgkmcnt(0)
	v_pk_add_f32 v[144:145], v[146:147], v[156:157]
	ds_bpermute_b32 v147, v206, v145
	ds_bpermute_b32 v146, v206, v144
	ds_bpermute_b32 v143, v207, v140
	s_waitcnt lgkmcnt(1)
	v_pk_add_f32 v[144:145], v[144:145], v[146:147]
	s_nop 0
	v_pk_fma_f32 v[144:145], v[144:145], s[14:15], v[154:155] op_sel_hi:[1,1,0]
	s_waitcnt vmcnt(2)
	ds_bpermute_b32 v142, v207, v138
	s_waitcnt vmcnt(1)
	v_pk_add_f32 v[132:133], v[132:133], v[132:133] op_sel:[0,1] op_sel_hi:[1,0]
	s_nop 0
	v_mul_f32_e32 v133, 0x4b800000, v161
	v_cndmask_b32_e64 v133, v161, v133, s[46:47]
	v_rsq_f32_e32 v133, v133
	ds_bpermute_b32 v137, v207, v132
	s_waitcnt vmcnt(0)
	ds_bpermute_b32 v136, v207, v134
	v_mul_f32_e32 v135, 0x45800000, v133
	v_cndmask_b32_e64 v133, v133, v135, s[46:47]
	v_mul_f32_e32 v135, 0x4b800000, v160
	v_cndmask_b32_e64 v135, v160, v135, s[44:45]
	v_rsq_f32_e32 v135, v135
	v_mul_f32_e32 v133, v160, v133
	v_cmp_gt_f32_e64 s[46:47], s33, v145
	v_mul_f32_e32 v139, 0x45800000, v135
	v_cndmask_b32_e64 v152, v135, v139, s[44:45]
	v_mul_f32_e32 v160, v133, v152
	v_mul_f32_e32 v133, 0x4b800000, v145
	v_cndmask_b32_e64 v133, v145, v133, s[46:47]
	v_rsq_f32_e32 v133, v133
	v_cmp_gt_f32_e64 s[44:45], s33, v144
	v_pk_mul_f32 v[62:63], v[62:63], v[160:161] op_sel_hi:[1,0]
	v_pk_mul_f32 v[60:61], v[60:61], v[160:161] op_sel_hi:[1,0]
	v_mul_f32_e32 v135, 0x45800000, v133
	v_cndmask_b32_e64 v133, v133, v135, s[46:47]
	v_mul_f32_e32 v135, 0x4b800000, v144
	v_cndmask_b32_e64 v135, v144, v135, s[44:45]
	v_rsq_f32_e32 v135, v135
	v_mul_f32_e32 v133, v144, v133
	v_pk_mul_f32 v[58:59], v[58:59], v[160:161] op_sel_hi:[1,0]
	v_pk_mul_f32 v[56:57], v[56:57], v[160:161] op_sel_hi:[1,0]
	v_mul_f32_e32 v139, 0x45800000, v135
	v_cndmask_b32_e64 v188, v135, v139, s[44:45]
	v_mov_b32_e32 v139, v140
	s_waitcnt lgkmcnt(2)
	v_pk_add_f32 v[138:139], v[138:139], v[142:143]
	ds_bpermute_b32 v141, v206, v139
	ds_bpermute_b32 v140, v206, v138
	v_mul_f32_e32 v144, v133, v188
	v_pk_mul_f32 v[54:55], v[54:55], v[160:161] op_sel_hi:[1,0]
	v_pk_mul_f32 v[52:53], v[52:53], v[160:161] op_sel_hi:[1,0]
	v_pk_mul_f32 v[50:51], v[50:51], v[160:161] op_sel_hi:[1,0]
	s_waitcnt lgkmcnt(0)
	v_pk_add_f32 v[138:139], v[138:139], v[140:141]
	v_pk_mul_f32 v[48:49], v[48:49], v[160:161] op_sel_hi:[1,0]
	v_pk_fma_f32 v[138:139], v[138:139], s[14:15], v[154:155] op_sel_hi:[1,1,0]
	v_pk_mul_f32 v[94:95], v[94:95], v[144:145] op_sel_hi:[1,0]
	v_mul_f32_e32 v133, 0x4b800000, v139
	v_cmp_gt_f32_e64 s[46:47], s33, v139
	v_cmp_gt_f32_e64 s[44:45], s33, v138
	v_pk_mul_f32 v[92:93], v[92:93], v[144:145] op_sel_hi:[1,0]
	v_cndmask_b32_e64 v133, v139, v133, s[46:47]
	v_rsq_f32_e32 v133, v133
	v_pk_mul_f32 v[90:91], v[90:91], v[144:145] op_sel_hi:[1,0]
	v_pk_mul_f32 v[88:89], v[88:89], v[144:145] op_sel_hi:[1,0]
	v_pk_mul_f32 v[86:87], v[86:87], v[144:145] op_sel_hi:[1,0]
	v_mul_f32_e32 v135, 0x45800000, v133
	v_cndmask_b32_e64 v133, v133, v135, s[46:47]
	v_mul_f32_e32 v135, 0x4b800000, v138
	v_cndmask_b32_e64 v135, v138, v135, s[44:45]
	v_rsq_f32_e32 v135, v135
	v_mul_f32_e32 v133, v138, v133
	v_pk_mul_f32 v[84:85], v[84:85], v[144:145] op_sel_hi:[1,0]
	v_pk_mul_f32 v[82:83], v[82:83], v[144:145] op_sel_hi:[1,0]
	v_mul_f32_e32 v139, 0x45800000, v135
	v_cndmask_b32_e64 v190, v135, v139, s[44:45]
	v_mov_b32_e32 v135, v132
	v_mul_f32_e32 v138, v133, v190
	v_pk_add_f32 v[132:133], v[134:135], v[136:137]
	ds_bpermute_b32 v135, v206, v133
	ds_bpermute_b32 v134, v206, v132
	v_pk_mul_f32 v[80:81], v[80:81], v[144:145] op_sel_hi:[1,0]
	v_pk_mul_f32 v[126:127], v[126:127], v[138:139] op_sel_hi:[1,0]
	v_pk_mul_f32 v[124:125], v[124:125], v[138:139] op_sel_hi:[1,0]
	v_pk_mul_f32 v[122:123], v[122:123], v[138:139] op_sel_hi:[1,0]
	s_waitcnt lgkmcnt(0)
	v_pk_add_f32 v[132:133], v[132:133], v[134:135]
	v_pk_mul_f32 v[120:121], v[120:121], v[138:139] op_sel_hi:[1,0]
	v_pk_fma_f32 v[132:133], v[132:133], s[14:15], v[154:155] op_sel_hi:[1,1,0]
	v_pk_mul_f32 v[118:119], v[118:119], v[138:139] op_sel_hi:[1,0]
	v_mul_f32_e32 v134, 0x4b800000, v133
	v_cmp_gt_f32_e64 s[46:47], s33, v133
	v_cmp_gt_f32_e64 s[44:45], s33, v132
	v_pk_mul_f32 v[116:117], v[116:117], v[138:139] op_sel_hi:[1,0]
	v_cndmask_b32_e64 v133, v133, v134, s[46:47]
	v_rsq_f32_e32 v133, v133
	v_pk_mul_f32 v[114:115], v[114:115], v[138:139] op_sel_hi:[1,0]
	v_pk_mul_f32 v[112:113], v[112:113], v[138:139] op_sel_hi:[1,0]
	v_mul_f32_e32 v134, 0x45800000, v133
	v_cndmask_b32_e64 v133, v133, v134, s[46:47]
	v_mul_f32_e32 v134, 0x4b800000, v132
	v_cndmask_b32_e64 v134, v132, v134, s[44:45]
	v_rsq_f32_e32 v134, v134
	v_mul_f32_e32 v132, v132, v133
	v_mul_f32_e32 v135, 0x45800000, v134
	v_cndmask_b32_e64 v192, v134, v135, s[44:45]
	v_mul_f32_e32 v132, v132, v192
	v_pk_mul_f32 v[110:111], v[110:111], v[132:133] op_sel_hi:[1,0]
	v_pk_mul_f32 v[108:109], v[108:109], v[132:133] op_sel_hi:[1,0]
	v_pk_mul_f32 v[106:107], v[106:107], v[132:133] op_sel_hi:[1,0]
	v_pk_mul_f32 v[104:105], v[104:105], v[132:133] op_sel_hi:[1,0]
	v_pk_mul_f32 v[102:103], v[102:103], v[132:133] op_sel_hi:[1,0]
	v_pk_mul_f32 v[100:101], v[100:101], v[132:133] op_sel_hi:[1,0]
	v_pk_mul_f32 v[98:99], v[98:99], v[132:133] op_sel_hi:[1,0]
	v_pk_mul_f32 v[96:97], v[96:97], v[132:133] op_sel_hi:[1,0]
	v_add_u32_e32 v134, 0x80, v158
	v_lshl_or_b32 v132, v134, 3, v159
	v_ashrrev_i32_e32 v133, 31, v132
	v_lshl_add_u64 v[132:133], v[132:133], 2, s[12:13]
	global_load_dwordx2 v[132:133], v[132:133], off
	v_lshl_or_b32 v134, v134, 2, v153
	v_ashrrev_i32_e32 v135, 31, v134
	v_lshl_add_u64 v[134:135], v[134:135], 2, s[2:3]
	global_load_dword v134, v[134:135], off
	s_waitcnt vmcnt(1)
	v_pk_add_f32 v[132:133], v[132:133], v[132:133] op_sel:[0,1] op_sel_hi:[1,0]
	s_nop 0
	v_add_u32_e32 v133, 0x90, v158
	v_lshl_or_b32 v136, v133, 3, v159
	v_ashrrev_i32_e32 v137, 31, v136
	v_lshl_add_u64 v[136:137], v[136:137], 2, s[12:13]
	global_load_dwordx2 v[136:137], v[136:137], off
	v_mov_b32_e32 v135, v132
	s_waitcnt vmcnt(0)
	v_pk_add_f32 v[168:169], v[136:137], v[136:137] op_sel:[0,1] op_sel_hi:[1,0]
	v_lshl_or_b32 v136, v133, 2, v153
	v_ashrrev_i32_e32 v137, 31, v136
	v_lshl_add_u64 v[136:137], v[136:137], 2, s[2:3]
	v_add_u32_e32 v133, 0xa0, v158
	global_load_dword v170, v[136:137], off
	v_lshl_or_b32 v136, v133, 3, v159
	v_ashrrev_i32_e32 v137, 31, v136
	v_lshl_add_u64 v[136:137], v[136:137], 2, s[12:13]
	global_load_dwordx2 v[136:137], v[136:137], off
	ds_bpermute_b32 v173, v207, v168
	v_mov_b32_e32 v171, v168
	s_waitcnt vmcnt(1)
	ds_bpermute_b32 v172, v207, v170
	s_waitcnt vmcnt(0)
	v_pk_add_f32 v[162:163], v[136:137], v[136:137] op_sel:[0,1] op_sel_hi:[1,0]
	v_lshl_or_b32 v136, v133, 2, v153
	v_ashrrev_i32_e32 v137, 31, v136
	v_lshl_add_u64 v[136:137], v[136:137], 2, s[2:3]
	v_add_u32_e32 v133, 0xb0, v158
	global_load_dword v164, v[136:137], off
	v_lshl_or_b32 v136, v133, 3, v159
	v_ashrrev_i32_e32 v137, 31, v136
	v_lshl_add_u64 v[136:137], v[136:137], 2, s[12:13]
	global_load_dwordx2 v[136:137], v[136:137], off
	ds_bpermute_b32 v167, v207, v162
	v_mov_b32_e32 v165, v162
	s_waitcnt vmcnt(1)
	ds_bpermute_b32 v166, v207, v164
	s_waitcnt vmcnt(0)
	v_pk_add_f32 v[156:157], v[136:137], v[136:137] op_sel:[0,1] op_sel_hi:[1,0]
	v_lshl_or_b32 v136, v133, 2, v153
	v_ashrrev_i32_e32 v137, 31, v136
	v_lshl_add_u64 v[136:137], v[136:137], 2, s[2:3]
	global_load_dword v158, v[136:137], off
	ds_bpermute_b32 v137, v207, v132
	ds_bpermute_b32 v136, v207, v134
	ds_bpermute_b32 v161, v207, v156
	v_mov_b32_e32 v159, v156
	s_waitcnt lgkmcnt(1)
	v_pk_add_f32 v[132:133], v[134:135], v[136:137]
	ds_bpermute_b32 v135, v206, v133
	ds_bpermute_b32 v134, v206, v132
	s_waitcnt lgkmcnt(0)
	v_pk_add_f32 v[132:133], v[132:133], v[134:135]
	s_nop 0
	v_pk_fma_f32 v[132:133], v[132:133], s[14:15], v[154:155] op_sel_hi:[1,1,0]
	s_waitcnt vmcnt(0)
	ds_bpermute_b32 v160, v207, v158
	v_mul_f32_e32 v134, 0x4b800000, v133
	v_cmp_gt_f32_e64 s[46:47], s33, v133
	v_cmp_gt_f32_e64 s[44:45], s33, v132
	s_nop 0
	v_cndmask_b32_e64 v133, v133, v134, s[46:47]
	v_rsq_f32_e32 v133, v133
	s_nop 0
	v_mul_f32_e32 v134, 0x45800000, v133
	v_cndmask_b32_e64 v133, v133, v134, s[46:47]
	v_mul_f32_e32 v134, 0x4b800000, v132
	v_cndmask_b32_e64 v134, v132, v134, s[44:45]
	v_rsq_f32_e32 v134, v134
	v_mul_f32_e32 v132, v132, v133
	v_mul_f32_e32 v135, 0x45800000, v134
	v_cndmask_b32_e64 v194, v134, v135, s[44:45]
	v_mul_f32_e32 v132, v132, v194
	v_pk_mul_f32 v[146:147], v[78:79], v[132:133] op_sel_hi:[1,0]
	v_pk_mul_f32 v[144:145], v[76:77], v[132:133] op_sel_hi:[1,0]
	v_pk_mul_f32 v[142:143], v[74:75], v[132:133] op_sel_hi:[1,0]
	v_pk_mul_f32 v[140:141], v[72:73], v[132:133] op_sel_hi:[1,0]
	v_pk_mul_f32 v[138:139], v[70:71], v[132:133] op_sel_hi:[1,0]
	v_pk_mul_f32 v[136:137], v[68:69], v[132:133] op_sel_hi:[1,0]
	v_pk_mul_f32 v[134:135], v[66:67], v[132:133] op_sel_hi:[1,0]
	v_pk_mul_f32 v[132:133], v[64:65], v[132:133] op_sel_hi:[1,0]
	v_pk_add_f32 v[64:65], v[170:171], v[172:173]
	ds_bpermute_b32 v67, v206, v65
	ds_bpermute_b32 v66, v206, v64
	s_waitcnt lgkmcnt(0)
	v_pk_add_f32 v[64:65], v[64:65], v[66:67]
	s_nop 0
	v_pk_fma_f32 v[64:65], v[64:65], s[14:15], v[154:155] op_sel_hi:[1,1,0]
	s_nop 0
	v_mul_f32_e32 v66, 0x4b800000, v65
	v_cmp_gt_f32_e64 s[46:47], s33, v65
	v_cmp_gt_f32_e64 s[44:45], s33, v64
	s_nop 0
	v_cndmask_b32_e64 v65, v65, v66, s[46:47]
	v_rsq_f32_e32 v65, v65
	s_nop 0
	v_mul_f32_e32 v66, 0x45800000, v65
	v_cndmask_b32_e64 v65, v65, v66, s[46:47]
	v_mul_f32_e32 v66, 0x4b800000, v64
	v_cndmask_b32_e64 v66, v64, v66, s[44:45]
	v_rsq_f32_e32 v66, v66
	v_mul_f32_e32 v64, v64, v65
	v_mul_f32_e32 v67, 0x45800000, v66
	v_cndmask_b32_e64 v196, v66, v67, s[44:45]
	v_mul_f32_e32 v64, v64, v196
	v_pk_mul_f32 v[46:47], v[46:47], v[64:65] op_sel_hi:[1,0]
	v_pk_mul_f32 v[44:45], v[44:45], v[64:65] op_sel_hi:[1,0]
	v_pk_mul_f32 v[42:43], v[42:43], v[64:65] op_sel_hi:[1,0]
	v_pk_mul_f32 v[40:41], v[40:41], v[64:65] op_sel_hi:[1,0]
	v_pk_mul_f32 v[38:39], v[38:39], v[64:65] op_sel_hi:[1,0]
	v_pk_mul_f32 v[36:37], v[36:37], v[64:65] op_sel_hi:[1,0]
	v_pk_mul_f32 v[34:35], v[34:35], v[64:65] op_sel_hi:[1,0]
	v_pk_mul_f32 v[32:33], v[32:33], v[64:65] op_sel_hi:[1,0]
	v_pk_add_f32 v[64:65], v[164:165], v[166:167]
	ds_bpermute_b32 v67, v206, v65
	ds_bpermute_b32 v66, v206, v64
	s_waitcnt lgkmcnt(0)
	v_pk_add_f32 v[64:65], v[64:65], v[66:67]
	s_nop 0
	v_pk_fma_f32 v[64:65], v[64:65], s[14:15], v[154:155] op_sel_hi:[1,1,0]
	s_nop 0
	v_mul_f32_e32 v66, 0x4b800000, v65
	v_cmp_gt_f32_e64 s[46:47], s33, v65
	v_cmp_gt_f32_e64 s[44:45], s33, v64
	s_nop 0
	v_cndmask_b32_e64 v65, v65, v66, s[46:47]
	v_rsq_f32_e32 v65, v65
	s_nop 0
	v_mul_f32_e32 v66, 0x45800000, v65
	v_cndmask_b32_e64 v65, v65, v66, s[46:47]
	v_mul_f32_e32 v66, 0x4b800000, v64
	v_cndmask_b32_e64 v66, v64, v66, s[44:45]
	v_rsq_f32_e32 v66, v66
	v_mul_f32_e32 v64, v64, v65
	v_mul_f32_e32 v67, 0x45800000, v66
	v_cndmask_b32_e64 v198, v66, v67, s[44:45]
	v_mul_f32_e32 v64, v64, v198
	v_pk_mul_f32 v[30:31], v[30:31], v[64:65] op_sel_hi:[1,0]
	v_pk_mul_f32 v[28:29], v[28:29], v[64:65] op_sel_hi:[1,0]
	v_pk_mul_f32 v[26:27], v[26:27], v[64:65] op_sel_hi:[1,0]
	v_pk_mul_f32 v[24:25], v[24:25], v[64:65] op_sel_hi:[1,0]
	v_pk_mul_f32 v[22:23], v[22:23], v[64:65] op_sel_hi:[1,0]
	v_pk_mul_f32 v[20:21], v[20:21], v[64:65] op_sel_hi:[1,0]
	v_pk_mul_f32 v[18:19], v[18:19], v[64:65] op_sel_hi:[1,0]
	v_pk_mul_f32 v[16:17], v[16:17], v[64:65] op_sel_hi:[1,0]
	v_pk_add_f32 v[64:65], v[158:159], v[160:161]
	ds_bpermute_b32 v67, v206, v65
	ds_bpermute_b32 v66, v206, v64
	s_waitcnt lgkmcnt(0)
	v_pk_add_f32 v[64:65], v[64:65], v[66:67]
	s_nop 0
	v_pk_fma_f32 v[64:65], v[64:65], s[14:15], v[154:155] op_sel_hi:[1,1,0]
	s_nop 0
	v_mul_f32_e32 v66, 0x4b800000, v65
	v_cmp_gt_f32_e64 s[46:47], s33, v65
	v_cmp_gt_f32_e64 s[44:45], s33, v64
	s_nop 0
	v_cndmask_b32_e64 v65, v65, v66, s[46:47]
	v_rsq_f32_e32 v65, v65
	s_nop 0
	v_mul_f32_e32 v66, 0x45800000, v65
	v_cndmask_b32_e64 v65, v65, v66, s[46:47]
	v_mul_f32_e32 v66, 0x4b800000, v64
	v_cndmask_b32_e64 v66, v64, v66, s[44:45]
	v_rsq_f32_e32 v66, v66
	v_mul_f32_e32 v64, v64, v65
	v_mul_f32_e32 v67, 0x45800000, v66
	v_cndmask_b32_e64 v200, v66, v67, s[44:45]
	v_mul_f32_e32 v64, v64, v200
	v_pk_mul_f32 v[14:15], v[14:15], v[64:65] op_sel_hi:[1,0]
	v_pk_mul_f32 v[12:13], v[12:13], v[64:65] op_sel_hi:[1,0]
	v_pk_mul_f32 v[10:11], v[10:11], v[64:65] op_sel_hi:[1,0]
	v_pk_mul_f32 v[8:9], v[8:9], v[64:65] op_sel_hi:[1,0]
	v_pk_mul_f32 v[6:7], v[6:7], v[64:65] op_sel_hi:[1,0]
	v_pk_mul_f32 v[4:5], v[4:5], v[64:65] op_sel_hi:[1,0]
	v_pk_mul_f32 v[2:3], v[2:3], v[64:65] op_sel_hi:[1,0]
	v_pk_mul_f32 v[0:1], v[0:1], v[64:65] op_sel_hi:[1,0]
	s_mov_b32 s30, 14
	s_mov_b64 s[44:45], 0

.Lprio_561:
	ds_read_b128 v[64:67], v213
	ds_read_b128 v[68:71], v213 offset:1024
	ds_read_b128 v[72:75], v213 offset:2048
	ds_read_b128 v[76:79], v213 offset:3072
	v_lshl_add_u64 v[174:175], v[128:129], 0, s[44:45]
	s_mov_b32 m0, s81
	v_lshl_add_u64 v[226:227], v[174:175], 0, s[54:55]
	v_lshl_add_u64 v[242:243], v[130:131], 0, s[44:45]
	ds_read_b128 v[154:157], v211
	ds_read_b128 v[158:161], v211 offset:1024
	ds_read_b128 v[162:165], v211 offset:2048
	ds_read_b128 v[166:169], v211 offset:3072
	ds_read_b128 v[170:173], v211 offset:4096
	ds_read_b128 v[202:205], v211 offset:5120
	ds_read_b128 v[218:221], v211 offset:6144
	ds_read_b128 v[222:225], v211 offset:7168
	global_load_lds_dwordx4 v[226:227], off
	v_lshl_add_u64 v[226:227], v[242:243], 0, s[54:55]
	s_mov_b32 m0, s93
	s_nop 0
	global_load_lds_dwordx4 v[226:227], off
	s_waitcnt lgkmcnt(8)
	s_barrier
	s_waitcnt lgkmcnt(0)
	s_waitcnt lgkmcnt(0)
	v_mfma_f32_16x16x32_bf16 v[60:63], v[64:67], v[154:157], v[60:63]
	v_mfma_f32_16x16x32_bf16 v[56:59], v[72:75], v[154:157], v[56:59]
	v_mfma_f32_16x16x32_bf16 v[92:95], v[64:67], v[162:165], v[92:95]
	v_mfma_f32_16x16x32_bf16 v[88:91], v[72:75], v[162:165], v[88:91]
	v_mfma_f32_16x16x32_bf16 v[124:127], v[64:67], v[170:173], v[124:127]
	v_mfma_f32_16x16x32_bf16 v[120:123], v[72:75], v[170:173], v[120:123]
	v_mfma_f32_16x16x32_bf16 v[108:111], v[64:67], v[218:221], v[108:111]
	v_mfma_f32_16x16x32_bf16 v[104:107], v[72:75], v[218:221], v[104:107]
	v_mfma_f32_16x16x32_bf16 v[60:63], v[68:71], v[158:161], v[60:63]
	v_mfma_f32_16x16x32_bf16 v[56:59], v[76:79], v[158:161], v[56:59]
	v_mfma_f32_16x16x32_bf16 v[92:95], v[68:71], v[166:169], v[92:95]
	v_mfma_f32_16x16x32_bf16 v[88:91], v[76:79], v[166:169], v[88:91]
	v_mfma_f32_16x16x32_bf16 v[124:127], v[68:71], v[202:205], v[124:127]
	v_mfma_f32_16x16x32_bf16 v[120:123], v[76:79], v[202:205], v[120:123]
	v_mfma_f32_16x16x32_bf16 v[108:111], v[68:71], v[222:225], v[108:111]
	v_mfma_f32_16x16x32_bf16 v[104:107], v[76:79], v[222:225], v[104:107]
	s_barrier
	v_lshl_add_u64 v[244:245], v[148:149], 0, s[44:45]
	s_mov_b32 m0, s94
	v_lshl_add_u64 v[246:247], v[244:245], 0, s[4:5]
	ds_read_b128 v[226:229], v214
	ds_read_b128 v[230:233], v214 offset:1024
	ds_read_b128 v[234:237], v214 offset:2048
	ds_read_b128 v[238:241], v214 offset:3072
	global_load_lds_dwordx4 v[246:247], off
	v_lshl_add_u64 v[246:247], v[150:151], 0, s[44:45]
	v_lshl_add_u64 v[248:249], v[246:247], 0, s[4:5]
	s_mov_b32 m0, s95
	s_nop 0
	global_load_lds_dwordx4 v[248:249], off
	s_barrier
	s_waitcnt lgkmcnt(0)
	s_waitcnt lgkmcnt(0)
	v_mfma_f32_16x16x32_bf16 v[52:55], v[226:229], v[154:157], v[52:55]
	v_mfma_f32_16x16x32_bf16 v[48:51], v[234:237], v[154:157], v[48:51]
	v_mfma_f32_16x16x32_bf16 v[84:87], v[226:229], v[162:165], v[84:87]
	v_mfma_f32_16x16x32_bf16 v[80:83], v[234:237], v[162:165], v[80:83]
	v_mfma_f32_16x16x32_bf16 v[116:119], v[226:229], v[170:173], v[116:119]
	v_mfma_f32_16x16x32_bf16 v[112:115], v[234:237], v[170:173], v[112:115]
	v_mfma_f32_16x16x32_bf16 v[100:103], v[226:229], v[218:221], v[100:103]
	v_mfma_f32_16x16x32_bf16 v[96:99], v[234:237], v[218:221], v[96:99]
	v_mfma_f32_16x16x32_bf16 v[52:55], v[230:233], v[158:161], v[52:55]
	v_mfma_f32_16x16x32_bf16 v[48:51], v[238:241], v[158:161], v[48:51]
	v_mfma_f32_16x16x32_bf16 v[84:87], v[230:233], v[166:169], v[84:87]
	v_mfma_f32_16x16x32_bf16 v[80:83], v[238:241], v[166:169], v[80:83]
	v_mfma_f32_16x16x32_bf16 v[116:119], v[230:233], v[202:205], v[116:119]
	v_mfma_f32_16x16x32_bf16 v[112:115], v[238:241], v[202:205], v[112:115]
	v_mfma_f32_16x16x32_bf16 v[100:103], v[230:233], v[222:225], v[100:103]
	v_mfma_f32_16x16x32_bf16 v[96:99], v[238:241], v[222:225], v[96:99]
	s_mov_b32 m0, s92
	v_lshl_add_u64 v[248:249], v[174:175], 0, s[4:5]
	s_barrier
	ds_read_b128 v[154:157], v211 offset:16384
	ds_read_b128 v[158:161], v211 offset:17408
	ds_read_b128 v[162:165], v211 offset:18432
	ds_read_b128 v[166:169], v211 offset:19456
	ds_read_b128 v[170:173], v211 offset:20480
	ds_read_b128 v[202:205], v211 offset:21504
	ds_read_b128 v[218:221], v211 offset:22528
	ds_read_b128 v[222:225], v211 offset:23552
	global_load_lds_dwordx4 v[248:249], off
	v_lshl_add_u64 v[248:249], v[242:243], 0, s[4:5]
	s_mov_b32 m0, s82
	s_nop 0
	global_load_lds_dwordx4 v[248:249], off
	s_barrier
	s_waitcnt lgkmcnt(0)
	s_waitcnt lgkmcnt(0)
	v_mfma_f32_16x16x32_bf16 v[144:147], v[64:67], v[154:157], v[144:147]
	v_mfma_f32_16x16x32_bf16 v[140:143], v[72:75], v[154:157], v[140:143]
	v_mfma_f32_16x16x32_bf16 v[44:47], v[64:67], v[162:165], v[44:47]
	v_mfma_f32_16x16x32_bf16 v[40:43], v[72:75], v[162:165], v[40:43]
	v_mfma_f32_16x16x32_bf16 v[28:31], v[64:67], v[170:173], v[28:31]
	v_mfma_f32_16x16x32_bf16 v[24:27], v[72:75], v[170:173], v[24:27]
	v_mfma_f32_16x16x32_bf16 v[12:15], v[64:67], v[218:221], v[12:15]
	v_mfma_f32_16x16x32_bf16 v[8:11], v[72:75], v[218:221], v[8:11]
	v_mfma_f32_16x16x32_bf16 v[144:147], v[68:71], v[158:161], v[144:147]
	v_mfma_f32_16x16x32_bf16 v[140:143], v[76:79], v[158:161], v[140:143]
	v_mfma_f32_16x16x32_bf16 v[44:47], v[68:71], v[166:169], v[44:47]
	v_mfma_f32_16x16x32_bf16 v[40:43], v[76:79], v[166:169], v[40:43]
	v_mfma_f32_16x16x32_bf16 v[28:31], v[68:71], v[202:205], v[28:31]
	v_mfma_f32_16x16x32_bf16 v[24:27], v[76:79], v[202:205], v[24:27]
	v_mfma_f32_16x16x32_bf16 v[12:15], v[68:71], v[222:225], v[12:15]
	v_mfma_f32_16x16x32_bf16 v[8:11], v[76:79], v[222:225], v[8:11]
	s_barrier
	s_mov_b32 m0, s96
	v_lshl_add_u64 v[64:65], v[244:245], 0, s[66:67]
	global_load_lds_dwordx4 v[64:65], off
	v_lshl_add_u64 v[64:65], v[246:247], 0, s[66:67]
	s_mov_b32 m0, s97
	s_nop 0
	global_load_lds_dwordx4 v[64:65], off
	s_waitcnt vmcnt(6)
	s_barrier
	v_mfma_f32_16x16x32_bf16 v[36:39], v[226:229], v[162:165], v[36:39]
	v_mfma_f32_16x16x32_bf16 v[32:35], v[234:237], v[162:165], v[32:35]
	v_mfma_f32_16x16x32_bf16 v[20:23], v[226:229], v[170:173], v[20:23]
	v_mfma_f32_16x16x32_bf16 v[16:19], v[234:237], v[170:173], v[16:19]
	v_mfma_f32_16x16x32_bf16 v[4:7], v[226:229], v[218:221], v[4:7]
	v_mfma_f32_16x16x32_bf16 v[0:3], v[234:237], v[218:221], v[0:3]
	v_mfma_f32_16x16x32_bf16 v[64:67], v[226:229], v[154:157], v[136:139]
	v_mfma_f32_16x16x32_bf16 v[68:71], v[234:237], v[154:157], v[132:135]
	v_mfma_f32_16x16x32_bf16 v[36:39], v[230:233], v[166:169], v[36:39]
	v_mfma_f32_16x16x32_bf16 v[32:35], v[238:241], v[166:169], v[32:35]
	v_mfma_f32_16x16x32_bf16 v[20:23], v[230:233], v[202:205], v[20:23]
	v_mfma_f32_16x16x32_bf16 v[16:19], v[238:241], v[202:205], v[16:19]
	v_mfma_f32_16x16x32_bf16 v[4:7], v[230:233], v[222:225], v[4:7]
	v_mfma_f32_16x16x32_bf16 v[0:3], v[238:241], v[222:225], v[0:3]
	v_mfma_f32_16x16x32_bf16 v[64:67], v[230:233], v[158:161], v[64:67]
	v_mfma_f32_16x16x32_bf16 v[68:71], v[238:241], v[158:161], v[68:71]
	s_barrier
	ds_read_b128 v[72:75], v215
	ds_read_b128 v[76:79], v215 offset:1024
	ds_read_b128 v[132:135], v215 offset:2048
	ds_read_b128 v[136:139], v215 offset:3072
	s_mov_b32 m0, s83
	v_lshl_add_u64 v[226:227], v[174:175], 0, s[66:67]
	ds_read_b128 v[154:157], v211 offset:32768
	ds_read_b128 v[158:161], v211 offset:33792
	ds_read_b128 v[162:165], v211 offset:34816
	ds_read_b128 v[166:169], v211 offset:35840
	ds_read_b128 v[170:173], v211 offset:36864
	ds_read_b128 v[202:205], v211 offset:37888
	ds_read_b128 v[218:221], v211 offset:38912
	ds_read_b128 v[222:225], v211 offset:39936
	global_load_lds_dwordx4 v[226:227], off
	v_lshl_add_u64 v[226:227], v[242:243], 0, s[66:67]
	s_mov_b32 m0, s86
	s_nop 0
	global_load_lds_dwordx4 v[226:227], off
	s_waitcnt lgkmcnt(8)
	s_barrier
	s_waitcnt lgkmcnt(0)
	s_waitcnt lgkmcnt(0)
	v_mfma_f32_16x16x32_bf16 v[60:63], v[72:75], v[154:157], v[60:63]
	v_mfma_f32_16x16x32_bf16 v[56:59], v[132:135], v[154:157], v[56:59]
	v_mfma_f32_16x16x32_bf16 v[92:95], v[72:75], v[162:165], v[92:95]
	v_mfma_f32_16x16x32_bf16 v[88:91], v[132:135], v[162:165], v[88:91]
	v_mfma_f32_16x16x32_bf16 v[124:127], v[72:75], v[170:173], v[124:127]
	v_mfma_f32_16x16x32_bf16 v[120:123], v[132:135], v[170:173], v[120:123]
	v_mfma_f32_16x16x32_bf16 v[108:111], v[72:75], v[218:221], v[108:111]
	v_mfma_f32_16x16x32_bf16 v[104:107], v[132:135], v[218:221], v[104:107]
	v_mfma_f32_16x16x32_bf16 v[60:63], v[76:79], v[158:161], v[60:63]
	v_mfma_f32_16x16x32_bf16 v[56:59], v[136:139], v[158:161], v[56:59]
	v_mfma_f32_16x16x32_bf16 v[92:95], v[76:79], v[166:169], v[92:95]
	v_mfma_f32_16x16x32_bf16 v[88:91], v[136:139], v[166:169], v[88:91]
	v_mfma_f32_16x16x32_bf16 v[124:127], v[76:79], v[202:205], v[124:127]
	v_mfma_f32_16x16x32_bf16 v[120:123], v[136:139], v[202:205], v[120:123]
	v_mfma_f32_16x16x32_bf16 v[108:111], v[76:79], v[222:225], v[108:111]
	v_mfma_f32_16x16x32_bf16 v[104:107], v[136:139], v[222:225], v[104:107]
	s_barrier
	s_mov_b32 m0, s60
	v_lshl_add_u64 v[248:249], v[244:245], 0, s[22:23]
	ds_read_b128 v[226:229], v216
	ds_read_b128 v[230:233], v216 offset:1024
	ds_read_b128 v[234:237], v216 offset:2048
	ds_read_b128 v[238:241], v216 offset:3072
	global_load_lds_dwordx4 v[248:249], off
	v_lshl_add_u64 v[248:249], v[246:247], 0, s[22:23]
	s_mov_b32 m0, s61
	s_nop 0
	global_load_lds_dwordx4 v[248:249], off
	s_barrier
	s_waitcnt lgkmcnt(0)
	s_waitcnt lgkmcnt(0)
	v_mfma_f32_16x16x32_bf16 v[52:55], v[226:229], v[154:157], v[52:55]
	v_mfma_f32_16x16x32_bf16 v[48:51], v[234:237], v[154:157], v[48:51]
	v_mfma_f32_16x16x32_bf16 v[84:87], v[226:229], v[162:165], v[84:87]
	v_mfma_f32_16x16x32_bf16 v[80:83], v[234:237], v[162:165], v[80:83]
	v_mfma_f32_16x16x32_bf16 v[116:119], v[226:229], v[170:173], v[116:119]
	v_mfma_f32_16x16x32_bf16 v[112:115], v[234:237], v[170:173], v[112:115]
	v_mfma_f32_16x16x32_bf16 v[100:103], v[226:229], v[218:221], v[100:103]
	v_mfma_f32_16x16x32_bf16 v[96:99], v[234:237], v[218:221], v[96:99]
	v_mfma_f32_16x16x32_bf16 v[52:55], v[230:233], v[158:161], v[52:55]
	v_mfma_f32_16x16x32_bf16 v[48:51], v[238:241], v[158:161], v[48:51]
	v_mfma_f32_16x16x32_bf16 v[84:87], v[230:233], v[166:169], v[84:87]
	v_mfma_f32_16x16x32_bf16 v[80:83], v[238:241], v[166:169], v[80:83]
	v_mfma_f32_16x16x32_bf16 v[116:119], v[230:233], v[202:205], v[116:119]
	v_mfma_f32_16x16x32_bf16 v[112:115], v[238:241], v[202:205], v[112:115]
	v_mfma_f32_16x16x32_bf16 v[100:103], v[230:233], v[222:225], v[100:103]
	v_mfma_f32_16x16x32_bf16 v[96:99], v[238:241], v[222:225], v[96:99]
	s_mov_b32 m0, s89
	v_lshl_add_u64 v[174:175], v[174:175], 0, s[22:23]
	s_barrier
	ds_read_b128 v[154:157], v211 offset:49152
	ds_read_b128 v[158:161], v211 offset:50176
	ds_read_b128 v[162:165], v211 offset:51200
	ds_read_b128 v[166:169], v211 offset:52224
	ds_read_b128 v[170:173], v211 offset:53248
	ds_read_b128 v[202:205], v211 offset:54272
	ds_read_b128 v[218:221], v211 offset:55296
	ds_read_b128 v[222:225], v211 offset:56320
	global_load_lds_dwordx4 v[174:175], off
	v_lshl_add_u64 v[174:175], v[242:243], 0, s[22:23]
	s_mov_b32 m0, s79
	s_nop 0
	global_load_lds_dwordx4 v[174:175], off
	s_barrier
	s_waitcnt lgkmcnt(0)
	s_waitcnt lgkmcnt(0)
	v_mfma_f32_16x16x32_bf16 v[144:147], v[72:75], v[154:157], v[144:147]
	v_mfma_f32_16x16x32_bf16 v[140:143], v[132:135], v[154:157], v[140:143]
	v_mfma_f32_16x16x32_bf16 v[44:47], v[72:75], v[162:165], v[44:47]
	v_mfma_f32_16x16x32_bf16 v[40:43], v[132:135], v[162:165], v[40:43]
	v_mfma_f32_16x16x32_bf16 v[28:31], v[72:75], v[170:173], v[28:31]
	v_mfma_f32_16x16x32_bf16 v[24:27], v[132:135], v[170:173], v[24:27]
	v_mfma_f32_16x16x32_bf16 v[12:15], v[72:75], v[218:221], v[12:15]
	v_mfma_f32_16x16x32_bf16 v[8:11], v[132:135], v[218:221], v[8:11]
	v_mfma_f32_16x16x32_bf16 v[144:147], v[76:79], v[158:161], v[144:147]
	v_mfma_f32_16x16x32_bf16 v[140:143], v[136:139], v[158:161], v[140:143]
	v_mfma_f32_16x16x32_bf16 v[44:47], v[76:79], v[166:169], v[44:47]
	v_mfma_f32_16x16x32_bf16 v[40:43], v[136:139], v[166:169], v[40:43]
	v_mfma_f32_16x16x32_bf16 v[28:31], v[76:79], v[202:205], v[28:31]
	v_mfma_f32_16x16x32_bf16 v[24:27], v[136:139], v[202:205], v[24:27]
	v_mfma_f32_16x16x32_bf16 v[12:15], v[76:79], v[222:225], v[12:15]
	v_mfma_f32_16x16x32_bf16 v[8:11], v[136:139], v[222:225], v[8:11]
	s_barrier
	s_mov_b32 m0, s49
	v_lshl_add_u64 v[72:73], v[244:245], 0, s[64:65]
	global_load_lds_dwordx4 v[72:73], off
	v_lshl_add_u64 v[72:73], v[246:247], 0, s[64:65]
	s_mov_b32 m0, s52
	s_nop 0
	global_load_lds_dwordx4 v[72:73], off
	s_waitcnt vmcnt(6)
	s_barrier
	v_mfma_f32_16x16x32_bf16 v[64:67], v[226:229], v[154:157], v[64:67]
	v_mfma_f32_16x16x32_bf16 v[136:139], v[230:233], v[158:161], v[64:67]
	v_mfma_f32_16x16x32_bf16 v[64:67], v[234:237], v[154:157], v[68:71]
	v_mfma_f32_16x16x32_bf16 v[36:39], v[226:229], v[162:165], v[36:39]
	v_mfma_f32_16x16x32_bf16 v[32:35], v[234:237], v[162:165], v[32:35]
	v_mfma_f32_16x16x32_bf16 v[20:23], v[226:229], v[170:173], v[20:23]
	v_mfma_f32_16x16x32_bf16 v[16:19], v[234:237], v[170:173], v[16:19]
	v_mfma_f32_16x16x32_bf16 v[4:7], v[226:229], v[218:221], v[4:7]
	v_mfma_f32_16x16x32_bf16 v[0:3], v[234:237], v[218:221], v[0:3]
	v_mfma_f32_16x16x32_bf16 v[132:135], v[238:241], v[158:161], v[64:67]
	v_mfma_f32_16x16x32_bf16 v[36:39], v[230:233], v[166:169], v[36:39]
	v_mfma_f32_16x16x32_bf16 v[32:35], v[238:241], v[166:169], v[32:35]
	v_mfma_f32_16x16x32_bf16 v[20:23], v[230:233], v[202:205], v[20:23]
	v_mfma_f32_16x16x32_bf16 v[16:19], v[238:241], v[202:205], v[16:19]
	v_mfma_f32_16x16x32_bf16 v[4:7], v[230:233], v[222:225], v[4:7]
	v_mfma_f32_16x16x32_bf16 v[0:3], v[238:241], v[222:225], v[0:3]
	s_add_i32 s30, s30, 2
	s_add_u32 s44, s44, 0x100
	s_addc_u32 s45, s45, 0
	s_cmp_lt_u32 s30, 22
	s_barrier
	s_cbranch_scc1 .LBB0_561
	s_setprio 0
	s_ashr_i32 s71, s70, 31
	s_lshl_b64 s[2:3], s[70:71], 20
	v_readlane_b32 s12, v255, 1
	v_readlane_b32 s13, v255, 2
	s_add_u32 s44, s12, s2
	s_addc_u32 s45, s13, s3
	s_and_b64 s[2:3], vcc, exec
	s_cselect_b32 s71, s45, s75
	s_cselect_b32 s30, s44, s74
	s_ashr_i32 s69, s68, 31
	s_lshl_b64 s[2:3], s[68:69], 20
	s_add_u32 s46, s34, s2
	s_addc_u32 s47, s78, s3
	s_and_b64 s[2:3], vcc, exec
	s_cselect_b32 s31, s47, s73
	s_cselect_b32 s69, s46, s72
	v_pk_mul_f32 v[174:175], v[152:153], v[62:63] op_sel_hi:[0,1]
	v_pk_mul_f32 v[172:173], v[152:153], v[60:61] op_sel_hi:[0,1]
	v_pk_mul_f32 v[170:171], v[152:153], v[58:59] op_sel_hi:[0,1]
	v_pk_mul_f32 v[168:169], v[152:153], v[56:57] op_sel_hi:[0,1]
	v_pk_mul_f32 v[166:167], v[152:153], v[54:55] op_sel_hi:[0,1]
	v_pk_mul_f32 v[164:165], v[152:153], v[52:53] op_sel_hi:[0,1]
	v_pk_mul_f32 v[162:163], v[152:153], v[50:51] op_sel_hi:[0,1]
	v_pk_mul_f32 v[160:161], v[152:153], v[48:49] op_sel_hi:[0,1]
	v_pk_mul_f32 v[158:159], v[188:189], v[94:95] op_sel_hi:[0,1]
	v_pk_mul_f32 v[156:157], v[188:189], v[92:93] op_sel_hi:[0,1]
	v_pk_mul_f32 v[154:155], v[188:189], v[90:91] op_sel_hi:[0,1]
	v_pk_mul_f32 v[152:153], v[188:189], v[88:89] op_sel_hi:[0,1]
	v_pk_mul_f32 v[150:151], v[188:189], v[86:87] op_sel_hi:[0,1]
	v_pk_mul_f32 v[148:149], v[188:189], v[84:85] op_sel_hi:[0,1]
	v_pk_mul_f32 v[130:131], v[188:189], v[82:83] op_sel_hi:[0,1]
	v_pk_mul_f32 v[128:129], v[188:189], v[80:81] op_sel_hi:[0,1]
	v_pk_mul_f32 v[94:95], v[190:191], v[126:127] op_sel_hi:[0,1]
	v_pk_mul_f32 v[92:93], v[190:191], v[124:125] op_sel_hi:[0,1]
	v_pk_mul_f32 v[90:91], v[190:191], v[122:123] op_sel_hi:[0,1]
	v_pk_mul_f32 v[88:89], v[190:191], v[120:121] op_sel_hi:[0,1]
	v_pk_mul_f32 v[86:87], v[190:191], v[118:119] op_sel_hi:[0,1]
	v_pk_mul_f32 v[84:85], v[190:191], v[116:117] op_sel_hi:[0,1]
	v_pk_mul_f32 v[82:83], v[190:191], v[114:115] op_sel_hi:[0,1]
	v_pk_mul_f32 v[80:81], v[190:191], v[112:113] op_sel_hi:[0,1]
	v_pk_mul_f32 v[78:79], v[192:193], v[110:111] op_sel_hi:[0,1]
	v_pk_mul_f32 v[76:77], v[192:193], v[108:109] op_sel_hi:[0,1]
	v_pk_mul_f32 v[74:75], v[192:193], v[106:107] op_sel_hi:[0,1]
	v_pk_mul_f32 v[72:73], v[192:193], v[104:105] op_sel_hi:[0,1]
	v_pk_mul_f32 v[70:71], v[192:193], v[102:103] op_sel_hi:[0,1]
	v_pk_mul_f32 v[68:69], v[192:193], v[100:101] op_sel_hi:[0,1]
	v_pk_mul_f32 v[66:67], v[192:193], v[98:99] op_sel_hi:[0,1]
	v_pk_mul_f32 v[64:65], v[192:193], v[96:97] op_sel_hi:[0,1]
	v_pk_mul_f32 v[62:63], v[194:195], v[146:147] op_sel_hi:[0,1]
	v_pk_mul_f32 v[60:61], v[194:195], v[144:145] op_sel_hi:[0,1]
	v_pk_mul_f32 v[58:59], v[194:195], v[142:143] op_sel_hi:[0,1]
	v_pk_mul_f32 v[56:57], v[194:195], v[140:141] op_sel_hi:[0,1]
	v_pk_mul_f32 v[54:55], v[194:195], v[138:139] op_sel_hi:[0,1]
	v_pk_mul_f32 v[52:53], v[194:195], v[136:137] op_sel_hi:[0,1]
	v_pk_mul_f32 v[50:51], v[194:195], v[134:135] op_sel_hi:[0,1]
	v_pk_mul_f32 v[48:49], v[194:195], v[132:133] op_sel_hi:[0,1]
	v_pk_mul_f32 v[46:47], v[196:197], v[46:47] op_sel_hi:[0,1]
	v_pk_mul_f32 v[44:45], v[196:197], v[44:45] op_sel_hi:[0,1]
	v_pk_mul_f32 v[42:43], v[196:197], v[42:43] op_sel_hi:[0,1]
	v_pk_mul_f32 v[40:41], v[196:197], v[40:41] op_sel_hi:[0,1]
	v_pk_mul_f32 v[38:39], v[196:197], v[38:39] op_sel_hi:[0,1]
	v_pk_mul_f32 v[36:37], v[196:197], v[36:37] op_sel_hi:[0,1]
	v_pk_mul_f32 v[34:35], v[196:197], v[34:35] op_sel_hi:[0,1]
	v_pk_mul_f32 v[32:33], v[196:197], v[32:33] op_sel_hi:[0,1]
	v_pk_mul_f32 v[30:31], v[198:199], v[30:31] op_sel_hi:[0,1]
	v_pk_mul_f32 v[28:29], v[198:199], v[28:29] op_sel_hi:[0,1]
	v_pk_mul_f32 v[26:27], v[198:199], v[26:27] op_sel_hi:[0,1]
	v_pk_mul_f32 v[24:25], v[198:199], v[24:25] op_sel_hi:[0,1]
	v_pk_mul_f32 v[22:23], v[198:199], v[22:23] op_sel_hi:[0,1]
	v_pk_mul_f32 v[20:21], v[198:199], v[20:21] op_sel_hi:[0,1]
	v_pk_mul_f32 v[18:19], v[198:199], v[18:19] op_sel_hi:[0,1]
	v_pk_mul_f32 v[16:17], v[198:199], v[16:17] op_sel_hi:[0,1]
	v_pk_mul_f32 v[14:15], v[200:201], v[14:15] op_sel_hi:[0,1]
	v_pk_mul_f32 v[12:13], v[200:201], v[12:13] op_sel_hi:[0,1]
	v_pk_mul_f32 v[10:11], v[200:201], v[10:11] op_sel_hi:[0,1]
	v_pk_mul_f32 v[8:9], v[200:201], v[8:9] op_sel_hi:[0,1]
	v_pk_mul_f32 v[6:7], v[200:201], v[6:7] op_sel_hi:[0,1]
	v_pk_mul_f32 v[4:5], v[200:201], v[4:5] op_sel_hi:[0,1]
	v_pk_mul_f32 v[2:3], v[200:201], v[2:3] op_sel_hi:[0,1]
	v_pk_mul_f32 v[0:1], v[200:201], v[0:1] op_sel_hi:[0,1]
	s_add_u32 s74, s74, 0x80c80
	s_addc_u32 s75, s75, 0
	s_add_u32 vcc_lo, s72, 0xd00
	s_addc_u32 vcc_hi, s73, 0
	s_mov_b32 s88, 22

.Lprio_563:
	ds_read_b128 v[96:99], v213
	ds_read_b128 v[100:103], v213 offset:1024
	ds_read_b128 v[104:107], v213 offset:2048
	ds_read_b128 v[108:111], v213 offset:3072
	s_add_u32 s1, s74, 0xfff80080
	s_addc_u32 s2, s75, -1
	s_cmp_eq_u32 s88, 28
	s_cselect_b32 s77, s71, s2
	s_cselect_b32 s76, s30, s1
	s_cselect_b32 s73, s31, vcc_hi
	s_cselect_b32 s72, s69, vcc_lo
	s_mov_b32 m0, s81
	v_lshl_add_u64 v[190:191], s[74:75], 0, v[184:185]
	ds_read_b128 v[112:115], v211
	ds_read_b128 v[116:119], v211 offset:1024
	ds_read_b128 v[120:123], v211 offset:2048
	ds_read_b128 v[124:127], v211 offset:3072
	ds_read_b128 v[132:135], v211 offset:4096
	ds_read_b128 v[136:139], v211 offset:5120
	ds_read_b128 v[140:143], v211 offset:6144
	ds_read_b128 v[144:147], v211 offset:7168
	global_load_lds_dwordx4 v[190:191], off
	v_lshl_add_u64 v[190:191], s[74:75], 0, v[186:187]
	s_mov_b32 m0, s93
	s_nop 0
	global_load_lds_dwordx4 v[190:191], off
	s_waitcnt lgkmcnt(8)
	s_barrier
	s_waitcnt lgkmcnt(0)
	s_waitcnt lgkmcnt(0)
	v_mfma_f32_16x16x32_bf16 v[172:175], v[96:99], v[112:115], v[172:175]
	v_mfma_f32_16x16x32_bf16 v[168:171], v[104:107], v[112:115], v[168:171]
	v_mfma_f32_16x16x32_bf16 v[156:159], v[96:99], v[120:123], v[156:159]
	v_mfma_f32_16x16x32_bf16 v[152:155], v[104:107], v[120:123], v[152:155]
	v_mfma_f32_16x16x32_bf16 v[92:95], v[96:99], v[132:135], v[92:95]
	v_mfma_f32_16x16x32_bf16 v[88:91], v[104:107], v[132:135], v[88:91]
	v_mfma_f32_16x16x32_bf16 v[76:79], v[96:99], v[140:143], v[76:79]
	v_mfma_f32_16x16x32_bf16 v[72:75], v[104:107], v[140:143], v[72:75]
	v_mfma_f32_16x16x32_bf16 v[172:175], v[100:103], v[116:119], v[172:175]
	v_mfma_f32_16x16x32_bf16 v[168:171], v[108:111], v[116:119], v[168:171]
	v_mfma_f32_16x16x32_bf16 v[156:159], v[100:103], v[124:127], v[156:159]
	v_mfma_f32_16x16x32_bf16 v[152:155], v[108:111], v[124:127], v[152:155]
	v_mfma_f32_16x16x32_bf16 v[92:95], v[100:103], v[136:139], v[92:95]
	v_mfma_f32_16x16x32_bf16 v[88:91], v[108:111], v[136:139], v[88:91]
	v_mfma_f32_16x16x32_bf16 v[76:79], v[100:103], v[144:147], v[76:79]
	v_mfma_f32_16x16x32_bf16 v[72:75], v[108:111], v[144:147], v[72:75]
	s_barrier
	s_mov_b32 m0, s94
	v_lshl_add_u64 v[190:191], s[72:73], 0, v[176:177]
	ds_read_b128 v[200:203], v214
	ds_read_b128 v[218:221], v214 offset:1024
	ds_read_b128 v[222:225], v214 offset:2048
	ds_read_b128 v[226:229], v214 offset:3072
	global_load_lds_dwordx4 v[190:191], off
	v_lshl_add_u64 v[194:195], s[72:73], 0, v[182:183]
	s_mov_b32 m0, s95
	s_nop 0
	global_load_lds_dwordx4 v[194:195], off
	s_barrier
	s_waitcnt lgkmcnt(0)
	s_waitcnt lgkmcnt(0)
	v_mfma_f32_16x16x32_bf16 v[164:167], v[200:203], v[112:115], v[164:167]
	v_mfma_f32_16x16x32_bf16 v[112:115], v[222:225], v[112:115], v[160:163]
	v_mfma_f32_16x16x32_bf16 v[84:87], v[200:203], v[132:135], v[84:87]
	v_mfma_f32_16x16x32_bf16 v[80:83], v[222:225], v[132:135], v[80:83]
	v_mfma_f32_16x16x32_bf16 v[68:71], v[200:203], v[140:143], v[68:71]
	v_mfma_f32_16x16x32_bf16 v[64:67], v[222:225], v[140:143], v[64:67]
	v_mfma_f32_16x16x32_bf16 v[164:167], v[218:221], v[116:119], v[164:167]
	v_mfma_f32_16x16x32_bf16 v[112:115], v[226:229], v[116:119], v[112:115]
	v_mfma_f32_16x16x32_bf16 v[116:119], v[200:203], v[120:123], v[148:151]
	v_mfma_f32_16x16x32_bf16 v[120:123], v[222:225], v[120:123], v[128:131]
	v_mfma_f32_16x16x32_bf16 v[84:87], v[218:221], v[136:139], v[84:87]
	v_mfma_f32_16x16x32_bf16 v[80:83], v[226:229], v[136:139], v[80:83]
	v_mfma_f32_16x16x32_bf16 v[68:71], v[218:221], v[144:147], v[68:71]
	v_mfma_f32_16x16x32_bf16 v[64:67], v[226:229], v[144:147], v[64:67]
	v_mfma_f32_16x16x32_bf16 v[116:119], v[218:221], v[124:127], v[116:119]
	v_mfma_f32_16x16x32_bf16 v[120:123], v[226:229], v[124:127], v[120:123]
	s_mov_b32 m0, s92
	v_lshl_add_u64 v[204:205], s[76:77], 0, v[176:177]
	s_barrier
	ds_read_b128 v[124:127], v211 offset:16384
	ds_read_b128 v[128:131], v211 offset:17408
	ds_read_b128 v[132:135], v211 offset:18432
	ds_read_b128 v[136:139], v211 offset:19456
	ds_read_b128 v[140:143], v211 offset:20480
	ds_read_b128 v[144:147], v211 offset:21504
	ds_read_b128 v[148:151], v211 offset:22528
	ds_read_b128 v[160:163], v211 offset:23552
	global_load_lds_dwordx4 v[204:205], off
	v_lshl_add_u64 v[238:239], s[76:77], 0, v[182:183]
	s_mov_b32 m0, s82
	s_nop 0
	global_load_lds_dwordx4 v[238:239], off
	s_barrier
	s_waitcnt lgkmcnt(0)
	s_waitcnt lgkmcnt(0)
	v_mfma_f32_16x16x32_bf16 v[60:63], v[96:99], v[124:127], v[60:63]
	v_mfma_f32_16x16x32_bf16 v[56:59], v[104:107], v[124:127], v[56:59]
	v_mfma_f32_16x16x32_bf16 v[44:47], v[96:99], v[132:135], v[44:47]
	v_mfma_f32_16x16x32_bf16 v[40:43], v[104:107], v[132:135], v[40:43]
	v_mfma_f32_16x16x32_bf16 v[28:31], v[96:99], v[140:143], v[28:31]
	v_mfma_f32_16x16x32_bf16 v[24:27], v[104:107], v[140:143], v[24:27]
	v_mfma_f32_16x16x32_bf16 v[12:15], v[96:99], v[148:151], v[12:15]
	v_mfma_f32_16x16x32_bf16 v[8:11], v[104:107], v[148:151], v[8:11]
	v_mfma_f32_16x16x32_bf16 v[60:63], v[100:103], v[128:131], v[60:63]
	v_mfma_f32_16x16x32_bf16 v[56:59], v[108:111], v[128:131], v[56:59]
	v_mfma_f32_16x16x32_bf16 v[44:47], v[100:103], v[136:139], v[44:47]
	v_mfma_f32_16x16x32_bf16 v[40:43], v[108:111], v[136:139], v[40:43]
	v_mfma_f32_16x16x32_bf16 v[28:31], v[100:103], v[144:147], v[28:31]
	v_mfma_f32_16x16x32_bf16 v[24:27], v[108:111], v[144:147], v[24:27]
	v_mfma_f32_16x16x32_bf16 v[12:15], v[100:103], v[160:163], v[12:15]
	v_mfma_f32_16x16x32_bf16 v[8:11], v[108:111], v[160:163], v[8:11]
	s_barrier
	s_add_u32 s2, s72, 0x80000
	s_addc_u32 s3, s73, 0
	s_mov_b32 m0, s96
	v_lshl_add_u64 v[96:97], s[2:3], 0, v[176:177]
	global_load_lds_dwordx4 v[96:97], off
	v_lshl_add_u64 v[96:97], s[2:3], 0, v[182:183]
	s_mov_b32 m0, s97
	s_nop 0
	global_load_lds_dwordx4 v[96:97], off
	s_waitcnt vmcnt(6)
	s_barrier
	v_mfma_f32_16x16x32_bf16 v[52:55], v[200:203], v[124:127], v[52:55]
	v_mfma_f32_16x16x32_bf16 v[48:51], v[222:225], v[124:127], v[48:51]
	v_mfma_f32_16x16x32_bf16 v[36:39], v[200:203], v[132:135], v[36:39]
	v_mfma_f32_16x16x32_bf16 v[32:35], v[222:225], v[132:135], v[32:35]
	v_mfma_f32_16x16x32_bf16 v[20:23], v[200:203], v[140:143], v[20:23]
	v_mfma_f32_16x16x32_bf16 v[16:19], v[222:225], v[140:143], v[16:19]
	v_mfma_f32_16x16x32_bf16 v[4:7], v[200:203], v[148:151], v[4:7]
	v_mfma_f32_16x16x32_bf16 v[0:3], v[222:225], v[148:151], v[0:3]
	v_mfma_f32_16x16x32_bf16 v[52:55], v[218:221], v[128:131], v[52:55]
	v_mfma_f32_16x16x32_bf16 v[48:51], v[226:229], v[128:131], v[48:51]
	v_mfma_f32_16x16x32_bf16 v[36:39], v[218:221], v[136:139], v[36:39]
	v_mfma_f32_16x16x32_bf16 v[32:35], v[226:229], v[136:139], v[32:35]
	v_mfma_f32_16x16x32_bf16 v[20:23], v[218:221], v[144:147], v[20:23]
	v_mfma_f32_16x16x32_bf16 v[16:19], v[226:229], v[144:147], v[16:19]
	v_mfma_f32_16x16x32_bf16 v[4:7], v[218:221], v[160:163], v[4:7]
	v_mfma_f32_16x16x32_bf16 v[0:3], v[226:229], v[160:163], v[0:3]
	s_barrier
	ds_read_b128 v[96:99], v215
	ds_read_b128 v[100:103], v215 offset:1024
	ds_read_b128 v[104:107], v215 offset:2048
	ds_read_b128 v[108:111], v215 offset:3072
	s_add_u32 s2, s76, 0x80000
	s_addc_u32 s3, s77, 0
	s_mov_b32 m0, s83
	v_lshl_add_u64 v[148:149], s[2:3], 0, v[176:177]
	ds_read_b128 v[124:127], v211 offset:32768
	ds_read_b128 v[128:131], v211 offset:33792
	ds_read_b128 v[132:135], v211 offset:34816
	ds_read_b128 v[136:139], v211 offset:35840
	ds_read_b128 v[140:143], v211 offset:36864
	ds_read_b128 v[144:147], v211 offset:37888
	ds_read_b128 v[200:203], v211 offset:38912
	ds_read_b128 v[218:221], v211 offset:39936
	global_load_lds_dwordx4 v[148:149], off
	v_lshl_add_u64 v[148:149], s[2:3], 0, v[182:183]
	s_mov_b32 m0, s86
	s_nop 0
	global_load_lds_dwordx4 v[148:149], off
	s_waitcnt lgkmcnt(8)
	s_barrier
	s_waitcnt lgkmcnt(0)
	s_waitcnt lgkmcnt(0)
	v_mfma_f32_16x16x32_bf16 v[148:151], v[96:99], v[124:127], v[172:175]
	v_mfma_f32_16x16x32_bf16 v[172:175], v[100:103], v[128:131], v[148:151]
	v_mfma_f32_16x16x32_bf16 v[148:151], v[104:107], v[124:127], v[168:171]
	v_mfma_f32_16x16x32_bf16 v[168:171], v[108:111], v[128:131], v[148:151]
	v_mfma_f32_16x16x32_bf16 v[148:151], v[96:99], v[132:135], v[156:159]
	v_mfma_f32_16x16x32_bf16 v[156:159], v[100:103], v[136:139], v[148:151]
	v_mfma_f32_16x16x32_bf16 v[148:151], v[104:107], v[132:135], v[152:155]
	v_mfma_f32_16x16x32_bf16 v[92:95], v[96:99], v[140:143], v[92:95]
	v_mfma_f32_16x16x32_bf16 v[88:91], v[104:107], v[140:143], v[88:91]
	v_mfma_f32_16x16x32_bf16 v[76:79], v[96:99], v[200:203], v[76:79]
	v_mfma_f32_16x16x32_bf16 v[72:75], v[104:107], v[200:203], v[72:75]
	v_mfma_f32_16x16x32_bf16 v[152:155], v[108:111], v[136:139], v[148:151]
	v_mfma_f32_16x16x32_bf16 v[92:95], v[100:103], v[144:147], v[92:95]
	v_mfma_f32_16x16x32_bf16 v[88:91], v[108:111], v[144:147], v[88:91]
	v_mfma_f32_16x16x32_bf16 v[76:79], v[100:103], v[218:221], v[76:79]
	v_mfma_f32_16x16x32_bf16 v[72:75], v[108:111], v[218:221], v[72:75]
	s_barrier
	s_mov_b32 m0, s60
	v_lshl_add_u64 v[148:149], v[190:191], 0, s[20:21]
	ds_read_b128 v[222:225], v216
	ds_read_b128 v[226:229], v216 offset:1024
	ds_read_b128 v[230:233], v216 offset:2048
	ds_read_b128 v[234:237], v216 offset:3072
	global_load_lds_dwordx4 v[148:149], off
	v_lshl_add_u64 v[148:149], v[194:195], 0, s[20:21]
	s_mov_b32 m0, s61
	s_nop 0
	global_load_lds_dwordx4 v[148:149], off
	s_barrier
	s_waitcnt lgkmcnt(0)
	s_waitcnt lgkmcnt(0)
	v_mfma_f32_16x16x32_bf16 v[112:115], v[230:233], v[124:127], v[112:115]
	v_mfma_f32_16x16x32_bf16 v[148:151], v[222:225], v[124:127], v[164:167]
	v_mfma_f32_16x16x32_bf16 v[160:163], v[234:237], v[128:131], v[112:115]
	v_mfma_f32_16x16x32_bf16 v[112:115], v[222:225], v[132:135], v[116:119]
	v_mfma_f32_16x16x32_bf16 v[164:167], v[226:229], v[128:131], v[148:151]
	v_mfma_f32_16x16x32_bf16 v[148:151], v[226:229], v[136:139], v[112:115]
	v_mfma_f32_16x16x32_bf16 v[112:115], v[230:233], v[132:135], v[120:123]
	v_mfma_f32_16x16x32_bf16 v[84:87], v[222:225], v[140:143], v[84:87]
	v_mfma_f32_16x16x32_bf16 v[80:83], v[230:233], v[140:143], v[80:83]
	v_mfma_f32_16x16x32_bf16 v[68:71], v[222:225], v[200:203], v[68:71]
	v_mfma_f32_16x16x32_bf16 v[64:67], v[230:233], v[200:203], v[64:67]
	v_mfma_f32_16x16x32_bf16 v[128:131], v[234:237], v[136:139], v[112:115]
	v_mfma_f32_16x16x32_bf16 v[84:87], v[226:229], v[144:147], v[84:87]
	v_mfma_f32_16x16x32_bf16 v[80:83], v[234:237], v[144:147], v[80:83]
	v_mfma_f32_16x16x32_bf16 v[68:71], v[226:229], v[218:221], v[68:71]
	v_mfma_f32_16x16x32_bf16 v[64:67], v[234:237], v[218:221], v[64:67]
	s_mov_b32 m0, s89
	v_lshl_add_u64 v[190:191], v[204:205], 0, s[20:21]
	s_barrier
	ds_read_b128 v[112:115], v211 offset:49152
	ds_read_b128 v[116:119], v211 offset:50176
	ds_read_b128 v[120:123], v211 offset:51200
	ds_read_b128 v[124:127], v211 offset:52224
	ds_read_b128 v[132:135], v211 offset:53248
	ds_read_b128 v[136:139], v211 offset:54272
	ds_read_b128 v[140:143], v211 offset:55296
	ds_read_b128 v[144:147], v211 offset:56320
	global_load_lds_dwordx4 v[190:191], off
	v_lshl_add_u64 v[190:191], v[238:239], 0, s[20:21]
	s_mov_b32 m0, s79
	s_nop 0
	global_load_lds_dwordx4 v[190:191], off
	s_barrier
	s_waitcnt lgkmcnt(0)
	s_waitcnt lgkmcnt(0)
	v_mfma_f32_16x16x32_bf16 v[60:63], v[96:99], v[112:115], v[60:63]
	v_mfma_f32_16x16x32_bf16 v[56:59], v[104:107], v[112:115], v[56:59]
	v_mfma_f32_16x16x32_bf16 v[44:47], v[96:99], v[120:123], v[44:47]
	v_mfma_f32_16x16x32_bf16 v[40:43], v[104:107], v[120:123], v[40:43]
	v_mfma_f32_16x16x32_bf16 v[28:31], v[96:99], v[132:135], v[28:31]
	v_mfma_f32_16x16x32_bf16 v[24:27], v[104:107], v[132:135], v[24:27]
	v_mfma_f32_16x16x32_bf16 v[12:15], v[96:99], v[140:143], v[12:15]
	v_mfma_f32_16x16x32_bf16 v[8:11], v[104:107], v[140:143], v[8:11]
	v_mfma_f32_16x16x32_bf16 v[60:63], v[100:103], v[116:119], v[60:63]
	v_mfma_f32_16x16x32_bf16 v[56:59], v[108:111], v[116:119], v[56:59]
	v_mfma_f32_16x16x32_bf16 v[44:47], v[100:103], v[124:127], v[44:47]
	v_mfma_f32_16x16x32_bf16 v[40:43], v[108:111], v[124:127], v[40:43]
	v_mfma_f32_16x16x32_bf16 v[28:31], v[100:103], v[136:139], v[28:31]
	v_mfma_f32_16x16x32_bf16 v[24:27], v[108:111], v[136:139], v[24:27]
	v_mfma_f32_16x16x32_bf16 v[12:15], v[100:103], v[144:147], v[12:15]
	v_mfma_f32_16x16x32_bf16 v[8:11], v[108:111], v[144:147], v[8:11]
	s_barrier
	s_add_u32 s2, s72, 0x80080
	s_addc_u32 s3, s73, 0
	s_mov_b32 m0, s49
	v_lshl_add_u64 v[96:97], s[2:3], 0, v[176:177]
	global_load_lds_dwordx4 v[96:97], off
	v_lshl_add_u64 v[96:97], s[2:3], 0, v[182:183]
	s_mov_b32 m0, s52
	s_nop 0
	global_load_lds_dwordx4 v[96:97], off
	s_waitcnt vmcnt(6)
	s_barrier
	v_mfma_f32_16x16x32_bf16 v[52:55], v[222:225], v[112:115], v[52:55]
	v_mfma_f32_16x16x32_bf16 v[48:51], v[230:233], v[112:115], v[48:51]
	v_mfma_f32_16x16x32_bf16 v[36:39], v[222:225], v[120:123], v[36:39]
	v_mfma_f32_16x16x32_bf16 v[32:35], v[230:233], v[120:123], v[32:35]
	v_mfma_f32_16x16x32_bf16 v[20:23], v[222:225], v[132:135], v[20:23]
	v_mfma_f32_16x16x32_bf16 v[16:19], v[230:233], v[132:135], v[16:19]
	v_mfma_f32_16x16x32_bf16 v[4:7], v[222:225], v[140:143], v[4:7]
	v_mfma_f32_16x16x32_bf16 v[0:3], v[230:233], v[140:143], v[0:3]
	v_mfma_f32_16x16x32_bf16 v[52:55], v[226:229], v[116:119], v[52:55]
	v_mfma_f32_16x16x32_bf16 v[48:51], v[234:237], v[116:119], v[48:51]
	v_mfma_f32_16x16x32_bf16 v[36:39], v[226:229], v[124:127], v[36:39]
	v_mfma_f32_16x16x32_bf16 v[32:35], v[234:237], v[124:127], v[32:35]
	v_mfma_f32_16x16x32_bf16 v[20:23], v[226:229], v[136:139], v[20:23]
	v_mfma_f32_16x16x32_bf16 v[16:19], v[234:237], v[136:139], v[16:19]
	v_mfma_f32_16x16x32_bf16 v[4:7], v[226:229], v[144:147], v[4:7]
	v_mfma_f32_16x16x32_bf16 v[0:3], v[234:237], v[144:147], v[0:3]
	s_add_i32 s88, s88, 2
	s_add_u32 s74, s74, 0x100
	s_addc_u32 s75, s75, 0
	s_add_u32 vcc_lo, vcc_lo, 0x100
	s_addc_u32 vcc_hi, vcc_hi, 0
	s_cmp_lt_u32 s88, 30
	s_barrier
	s_cbranch_scc1 .LBB0_563
	s_setprio 0
	v_readlane_b32 s96, v255, 17
	v_readlane_b32 s94, v255, 19
	v_readlane_b32 s93, v255, 25
	v_readlane_b32 s97, v255, 18
	v_readlane_b32 s95, v255, 20
	s_movk_i32 s14, 0x3fff
	v_add_u32_e32 v213, s53, v209
	v_lshl_or_b32 v252, s91, 8, v212
	v_lshl_add_u32 v198, v213, 11, v252
	v_lshlrev_b32_e32 v196, 2, v198
	v_lshlrev_b32_e32 v198, 1, v198
	s_lshl_b32 s1, s91, 2
	s_or_b32 s1, s1, s87
	s_lshl_b32 s1, s1, 2
	v_lshl_add_u32 v188, v213, 7, s1
	v_mov_b32_e32 v192, v196
	global_load_dwordx4 v[96:99], v192, s[38:39] offset:0
	global_load_dwordx4 v[100:103], v192, s[38:39] offset:64
	global_load_dwordx4 v[104:107], v192, s[38:39] offset:512
	global_load_dwordx4 v[108:111], v192, s[38:39] offset:576
	v_add_u32_e32 v124, 0x20000, v196
	global_load_dwordx4 v[200:203], v124, s[38:39] offset:0
	global_load_dwordx4 v[214:217], v124, s[38:39] offset:64
	global_load_dwordx4 v[218:221], v124, s[38:39] offset:512
	global_load_dwordx4 v[222:225], v124, s[38:39] offset:576
	v_add_u32_e32 v190, 0x40000, v196
	global_load_dwordx4 v[226:229], v190, s[38:39] offset:0
	global_load_dwordx4 v[230:233], v190, s[38:39] offset:64
	global_load_dwordx4 v[234:237], v190, s[38:39] offset:512
	global_load_dwordx4 v[238:241], v190, s[38:39] offset:576
	v_add_u32_e32 v194, 0x60000, v196
	global_load_dwordx4 v[242:245], v194, s[38:39] offset:0
	global_load_dwordx4 v[246:249], v194, s[38:39] offset:64
	s_waitcnt vmcnt(10)
	v_mov_b32_e32 v205, v198
	v_add_f32_e32 v172, v172, v96
	v_add_f32_e32 v173, v173, v97
	v_add_f32_e32 v174, v174, v98
	v_add_f32_e32 v175, v175, v99
	v_cvt_pk_bf16_f32 v96, v172, v173
	v_cvt_pk_bf16_f32 v97, v174, v175
	global_store_dwordx2 v205, v[96:97], s[58:59] offset:0
	v_mul_f32_e32 v146, v173, v173
	v_fmac_f32_e32 v146, v172, v172
	v_fmac_f32_e32 v146, v174, v174
	v_fmac_f32_e32 v146, v175, v175
	v_mov_b32_e32 v172, v146
	v_add_f32_e32 v168, v168, v100
	v_add_f32_e32 v169, v169, v101
	v_add_f32_e32 v170, v170, v102
	v_add_f32_e32 v171, v171, v103
	v_cvt_pk_bf16_f32 v100, v168, v169
	v_cvt_pk_bf16_f32 v101, v170, v171
	global_store_dwordx2 v205, v[100:101], s[58:59] offset:32
	v_fmac_f32_e32 v172, v168, v168
	v_fmac_f32_e32 v172, v169, v169
	v_fmac_f32_e32 v172, v170, v170
	v_fmac_f32_e32 v172, v171, v171
	v_add_f32_e32 v164, v164, v104
	v_add_f32_e32 v165, v165, v105
	v_add_f32_e32 v166, v166, v106
	v_add_f32_e32 v167, v167, v107
	v_cvt_pk_bf16_f32 v104, v164, v165
	v_cvt_pk_bf16_f32 v105, v166, v167
	global_store_dwordx2 v205, v[104:105], s[58:59] offset:256
	v_fmac_f32_e32 v172, v164, v164
	v_fmac_f32_e32 v172, v165, v165
	v_fmac_f32_e32 v172, v166, v166
	v_fmac_f32_e32 v172, v167, v167
	v_add_f32_e32 v160, v160, v108
	v_add_f32_e32 v161, v161, v109
	v_add_f32_e32 v162, v162, v110
	v_add_f32_e32 v163, v163, v111
	v_cvt_pk_bf16_f32 v108, v160, v161
	v_cvt_pk_bf16_f32 v109, v162, v163
	global_store_dwordx2 v205, v[108:109], s[58:59] offset:288
	v_fmac_f32_e32 v172, v160, v160
	v_fmac_f32_e32 v172, v161, v161
	v_fmac_f32_e32 v172, v162, v162
	v_fmac_f32_e32 v172, v163, v163
	global_load_dwordx4 v[96:99], v194, s[38:39] offset:512
	global_load_dwordx4 v[100:103], v194, s[38:39] offset:576
	v_add_u32_e32 v192, 0x100000, v196
	global_load_dwordx4 v[168:171], v192, s[38:39] offset:0
	global_load_dwordx4 v[104:107], v192, s[38:39] offset:64
	global_load_dwordx4 v[164:167], v192, s[38:39] offset:512
	global_load_dwordx4 v[108:111], v192, s[38:39] offset:576
	v_add_u32_e32 v124, 0x120000, v196
	global_load_dwordx4 v[160:163], v124, s[38:39] offset:0
	s_waitcnt vmcnt(17)
	v_add_u32_e32 v204, 0x10000, v198
	v_add_f32_e32 v156, v156, v200
	v_add_f32_e32 v157, v157, v201
	v_add_f32_e32 v158, v158, v202
	v_add_f32_e32 v159, v159, v203
	v_cvt_pk_bf16_f32 v200, v156, v157
	v_cvt_pk_bf16_f32 v201, v158, v159
	global_store_dwordx2 v204, v[200:201], s[58:59] offset:0
	v_mul_f32_e32 v146, v157, v157
	v_fmac_f32_e32 v146, v156, v156
	v_fmac_f32_e32 v146, v158, v158
	v_fmac_f32_e32 v146, v159, v159
	v_mov_b32_e32 v156, v146
	v_add_f32_e32 v152, v152, v214
	v_add_f32_e32 v153, v153, v215
	v_add_f32_e32 v154, v154, v216
	v_add_f32_e32 v155, v155, v217
	v_cvt_pk_bf16_f32 v214, v152, v153
	v_cvt_pk_bf16_f32 v215, v154, v155
	global_store_dwordx2 v204, v[214:215], s[58:59] offset:32
	v_fmac_f32_e32 v156, v152, v152
	v_fmac_f32_e32 v156, v153, v153
	v_fmac_f32_e32 v156, v154, v154
	v_fmac_f32_e32 v156, v155, v155
	v_add_f32_e32 v148, v148, v218
	v_add_f32_e32 v149, v149, v219
	v_add_f32_e32 v150, v150, v220
	v_add_f32_e32 v151, v151, v221
	v_cvt_pk_bf16_f32 v218, v148, v149
	v_cvt_pk_bf16_f32 v219, v150, v151
	global_store_dwordx2 v204, v[218:219], s[58:59] offset:256
	v_fmac_f32_e32 v156, v148, v148
	v_fmac_f32_e32 v156, v149, v149
	v_fmac_f32_e32 v156, v150, v150
	v_fmac_f32_e32 v156, v151, v151
	v_add_f32_e32 v128, v128, v222
	v_add_f32_e32 v129, v129, v223
	v_add_f32_e32 v130, v130, v224
	v_add_f32_e32 v131, v131, v225
	v_cvt_pk_bf16_f32 v222, v128, v129
	v_cvt_pk_bf16_f32 v223, v130, v131
	global_store_dwordx2 v204, v[222:223], s[58:59] offset:288
	v_fmac_f32_e32 v156, v128, v128
	v_fmac_f32_e32 v156, v129, v129
	v_fmac_f32_e32 v156, v130, v130
	v_fmac_f32_e32 v156, v131, v131
	global_load_dwordx4 v[200:203], v124, s[38:39] offset:64
	global_load_dwordx4 v[214:217], v124, s[38:39] offset:512
	global_load_dwordx4 v[152:155], v124, s[38:39] offset:576
	v_add_u32_e32 v190, 0x140000, v196
	global_load_dwordx4 v[218:221], v190, s[38:39] offset:0
	global_load_dwordx4 v[148:151], v190, s[38:39] offset:64
	global_load_dwordx4 v[222:225], v190, s[38:39] offset:512
	global_load_dwordx4 v[128:131], v190, s[38:39] offset:576
	s_waitcnt vmcnt(24)
	v_add_u32_e32 v205, 0x20000, v198
	v_add_f32_e32 v92, v92, v226
	v_add_f32_e32 v93, v93, v227
	v_add_f32_e32 v94, v94, v228
	v_add_f32_e32 v95, v95, v229
	v_cvt_pk_bf16_f32 v226, v92, v93
	v_cvt_pk_bf16_f32 v227, v94, v95
	global_store_dwordx2 v205, v[226:227], s[58:59] offset:0
	v_mul_f32_e32 v146, v93, v93
	v_fmac_f32_e32 v146, v92, v92
	v_fmac_f32_e32 v146, v94, v94
	v_fmac_f32_e32 v146, v95, v95
	v_mov_b32_e32 v92, v146
	v_add_f32_e32 v88, v88, v230
	v_add_f32_e32 v89, v89, v231
	v_add_f32_e32 v90, v90, v232
	v_add_f32_e32 v91, v91, v233
	v_cvt_pk_bf16_f32 v230, v88, v89
	v_cvt_pk_bf16_f32 v231, v90, v91
	global_store_dwordx2 v205, v[230:231], s[58:59] offset:32
	v_fmac_f32_e32 v92, v88, v88
	v_fmac_f32_e32 v92, v89, v89
	v_fmac_f32_e32 v92, v90, v90
	v_fmac_f32_e32 v92, v91, v91
	v_add_f32_e32 v84, v84, v234
	v_add_f32_e32 v85, v85, v235
	v_add_f32_e32 v86, v86, v236
	v_add_f32_e32 v87, v87, v237
	v_cvt_pk_bf16_f32 v234, v84, v85
	v_cvt_pk_bf16_f32 v235, v86, v87
	global_store_dwordx2 v205, v[234:235], s[58:59] offset:256
	v_fmac_f32_e32 v92, v84, v84
	v_fmac_f32_e32 v92, v85, v85
	v_fmac_f32_e32 v92, v86, v86
	v_fmac_f32_e32 v92, v87, v87
	v_add_f32_e32 v80, v80, v238
	v_add_f32_e32 v81, v81, v239
	v_add_f32_e32 v82, v82, v240
	v_add_f32_e32 v83, v83, v241
	v_cvt_pk_bf16_f32 v238, v80, v81
	v_cvt_pk_bf16_f32 v239, v82, v83
	global_store_dwordx2 v205, v[238:239], s[58:59] offset:288
	v_fmac_f32_e32 v92, v80, v80
	v_fmac_f32_e32 v92, v81, v81
	v_fmac_f32_e32 v92, v82, v82
	v_fmac_f32_e32 v92, v83, v83
	v_add_u32_e32 v194, 0x160000, v196
	global_load_dwordx4 v[226:229], v194, s[38:39] offset:0
	global_load_dwordx4 v[230:233], v194, s[38:39] offset:64
	global_load_dwordx4 v[88:91], v194, s[38:39] offset:512
	global_load_dwordx4 v[234:237], v194, s[38:39] offset:576
	s_waitcnt vmcnt(24)
	v_add_u32_e32 v204, 0x30000, v198
	v_add_f32_e32 v76, v76, v242
	v_add_f32_e32 v77, v77, v243
	v_add_f32_e32 v78, v78, v244
	v_add_f32_e32 v79, v79, v245
	v_cvt_pk_bf16_f32 v242, v76, v77
	v_cvt_pk_bf16_f32 v243, v78, v79
	global_store_dwordx2 v204, v[242:243], s[58:59] offset:0
	v_mul_f32_e32 v146, v77, v77
	v_fmac_f32_e32 v146, v76, v76
	v_fmac_f32_e32 v146, v78, v78
	v_fmac_f32_e32 v146, v79, v79
	v_mov_b32_e32 v76, v146
	v_add_f32_e32 v72, v72, v246
	v_add_f32_e32 v73, v73, v247
	v_add_f32_e32 v74, v74, v248
	v_add_f32_e32 v75, v75, v249
	v_cvt_pk_bf16_f32 v246, v72, v73
	v_cvt_pk_bf16_f32 v247, v74, v75
	global_store_dwordx2 v204, v[246:247], s[58:59] offset:32
	v_fmac_f32_e32 v76, v72, v72
	v_fmac_f32_e32 v76, v73, v73
	v_fmac_f32_e32 v76, v74, v74
	v_fmac_f32_e32 v76, v75, v75
	v_add_f32_e32 v68, v68, v96
	v_add_f32_e32 v69, v69, v97
	v_add_f32_e32 v70, v70, v98
	v_add_f32_e32 v71, v71, v99
	v_cvt_pk_bf16_f32 v96, v68, v69
	v_cvt_pk_bf16_f32 v97, v70, v71
	global_store_dwordx2 v204, v[96:97], s[58:59] offset:256
	v_fmac_f32_e32 v76, v68, v68
	v_fmac_f32_e32 v76, v69, v69
	v_fmac_f32_e32 v76, v70, v70
	v_fmac_f32_e32 v76, v71, v71
	v_add_f32_e32 v64, v64, v100
	v_add_f32_e32 v65, v65, v101
	v_add_f32_e32 v66, v66, v102
	v_add_f32_e32 v67, v67, v103
	v_cvt_pk_bf16_f32 v100, v64, v65
	v_cvt_pk_bf16_f32 v101, v66, v67
	global_store_dwordx2 v204, v[100:101], s[58:59] offset:288
	v_fmac_f32_e32 v76, v64, v64
	v_fmac_f32_e32 v76, v65, v65
	v_fmac_f32_e32 v76, v66, v66
	v_fmac_f32_e32 v76, v67, v67
	s_waitcnt vmcnt(24)
	v_add_u32_e32 v205, 0x80000, v198
	v_add_f32_e32 v60, v60, v168
	v_add_f32_e32 v61, v61, v169
	v_add_f32_e32 v62, v62, v170
	v_add_f32_e32 v63, v63, v171
	v_cvt_pk_bf16_f32 v168, v60, v61
	v_cvt_pk_bf16_f32 v169, v62, v63
	global_store_dwordx2 v205, v[168:169], s[58:59] offset:0
	v_mul_f32_e32 v146, v61, v61
	v_fmac_f32_e32 v146, v60, v60
	v_fmac_f32_e32 v146, v62, v62
	v_fmac_f32_e32 v146, v63, v63
	v_mov_b32_e32 v60, v146
	v_add_f32_e32 v56, v56, v104
	v_add_f32_e32 v57, v57, v105
	v_add_f32_e32 v58, v58, v106
	v_add_f32_e32 v59, v59, v107
	v_cvt_pk_bf16_f32 v104, v56, v57
	v_cvt_pk_bf16_f32 v105, v58, v59
	global_store_dwordx2 v205, v[104:105], s[58:59] offset:32
	v_fmac_f32_e32 v60, v56, v56
	v_fmac_f32_e32 v60, v57, v57
	v_fmac_f32_e32 v60, v58, v58
	v_fmac_f32_e32 v60, v59, v59
	v_add_f32_e32 v52, v52, v164
	v_add_f32_e32 v53, v53, v165
	v_add_f32_e32 v54, v54, v166
	v_add_f32_e32 v55, v55, v167
	v_cvt_pk_bf16_f32 v164, v52, v53
	v_cvt_pk_bf16_f32 v165, v54, v55
	global_store_dwordx2 v205, v[164:165], s[58:59] offset:256
	v_fmac_f32_e32 v60, v52, v52
	v_fmac_f32_e32 v60, v53, v53
	v_fmac_f32_e32 v60, v54, v54
	v_fmac_f32_e32 v60, v55, v55
	v_add_f32_e32 v48, v48, v108
	v_add_f32_e32 v49, v49, v109
	v_add_f32_e32 v50, v50, v110
	v_add_f32_e32 v51, v51, v111
	v_cvt_pk_bf16_f32 v108, v48, v49
	v_cvt_pk_bf16_f32 v109, v50, v51
	global_store_dwordx2 v205, v[108:109], s[58:59] offset:288
	v_fmac_f32_e32 v60, v48, v48
	v_fmac_f32_e32 v60, v49, v49
	v_fmac_f32_e32 v60, v50, v50
	v_fmac_f32_e32 v60, v51, v51
	s_waitcnt vmcnt(20)
	v_add_u32_e32 v204, 0x90000, v198
	v_add_f32_e32 v44, v44, v160
	v_add_f32_e32 v45, v45, v161
	v_add_f32_e32 v46, v46, v162
	v_add_f32_e32 v47, v47, v163
	v_cvt_pk_bf16_f32 v160, v44, v45
	v_cvt_pk_bf16_f32 v161, v46, v47
	global_store_dwordx2 v204, v[160:161], s[58:59] offset:0
	v_mul_f32_e32 v146, v45, v45
	v_fmac_f32_e32 v146, v44, v44
	v_fmac_f32_e32 v146, v46, v46
	v_fmac_f32_e32 v146, v47, v47
	v_mov_b32_e32 v44, v146
	v_add_f32_e32 v40, v40, v200
	v_add_f32_e32 v41, v41, v201
	v_add_f32_e32 v42, v42, v202
	v_add_f32_e32 v43, v43, v203
	v_cvt_pk_bf16_f32 v200, v40, v41
	v_cvt_pk_bf16_f32 v201, v42, v43
	global_store_dwordx2 v204, v[200:201], s[58:59] offset:32
	v_fmac_f32_e32 v44, v40, v40
	v_fmac_f32_e32 v44, v41, v41
	v_fmac_f32_e32 v44, v42, v42
	v_fmac_f32_e32 v44, v43, v43
	v_add_f32_e32 v36, v36, v214
	v_add_f32_e32 v37, v37, v215
	v_add_f32_e32 v38, v38, v216
	v_add_f32_e32 v39, v39, v217
	v_cvt_pk_bf16_f32 v214, v36, v37
	v_cvt_pk_bf16_f32 v215, v38, v39
	global_store_dwordx2 v204, v[214:215], s[58:59] offset:256
	v_fmac_f32_e32 v44, v36, v36
	v_fmac_f32_e32 v44, v37, v37
	v_fmac_f32_e32 v44, v38, v38
	v_fmac_f32_e32 v44, v39, v39
	v_add_f32_e32 v32, v32, v152
	v_add_f32_e32 v33, v33, v153
	v_add_f32_e32 v34, v34, v154
	v_add_f32_e32 v35, v35, v155
	v_cvt_pk_bf16_f32 v152, v32, v33
	v_cvt_pk_bf16_f32 v153, v34, v35
	global_store_dwordx2 v204, v[152:153], s[58:59] offset:288
	v_fmac_f32_e32 v44, v32, v32
	v_fmac_f32_e32 v44, v33, v33
	v_fmac_f32_e32 v44, v34, v34
	v_fmac_f32_e32 v44, v35, v35
	s_waitcnt vmcnt(20)
	v_add_u32_e32 v205, 0xa0000, v198
	v_add_f32_e32 v28, v28, v218
	v_add_f32_e32 v29, v29, v219
	v_add_f32_e32 v30, v30, v220
	v_add_f32_e32 v31, v31, v221
	v_cvt_pk_bf16_f32 v218, v28, v29
	v_cvt_pk_bf16_f32 v219, v30, v31
	global_store_dwordx2 v205, v[218:219], s[58:59] offset:0
	v_mul_f32_e32 v146, v29, v29
	v_fmac_f32_e32 v146, v28, v28
	v_fmac_f32_e32 v146, v30, v30
	v_fmac_f32_e32 v146, v31, v31
	v_mov_b32_e32 v28, v146
	v_add_f32_e32 v24, v24, v148
	v_add_f32_e32 v25, v25, v149
	v_add_f32_e32 v26, v26, v150
	v_add_f32_e32 v27, v27, v151
	v_cvt_pk_bf16_f32 v148, v24, v25
	v_cvt_pk_bf16_f32 v149, v26, v27
	global_store_dwordx2 v205, v[148:149], s[58:59] offset:32
	v_fmac_f32_e32 v28, v24, v24
	v_fmac_f32_e32 v28, v25, v25
	v_fmac_f32_e32 v28, v26, v26
	v_fmac_f32_e32 v28, v27, v27
	v_add_f32_e32 v20, v20, v222
	v_add_f32_e32 v21, v21, v223
	v_add_f32_e32 v22, v22, v224
	v_add_f32_e32 v23, v23, v225
	v_cvt_pk_bf16_f32 v222, v20, v21
	v_cvt_pk_bf16_f32 v223, v22, v23
	global_store_dwordx2 v205, v[222:223], s[58:59] offset:256
	v_fmac_f32_e32 v28, v20, v20
	v_fmac_f32_e32 v28, v21, v21
	v_fmac_f32_e32 v28, v22, v22
	v_fmac_f32_e32 v28, v23, v23
	v_add_f32_e32 v16, v16, v128
	v_add_f32_e32 v17, v17, v129
	v_add_f32_e32 v18, v18, v130
	v_add_f32_e32 v19, v19, v131
	v_cvt_pk_bf16_f32 v128, v16, v17
	v_cvt_pk_bf16_f32 v129, v18, v19
	global_store_dwordx2 v205, v[128:129], s[58:59] offset:288
	v_fmac_f32_e32 v28, v16, v16
	v_fmac_f32_e32 v28, v17, v17
	v_fmac_f32_e32 v28, v18, v18
	v_fmac_f32_e32 v28, v19, v19
	s_waitcnt vmcnt(16)
	v_add_u32_e32 v204, 0xb0000, v198
	v_add_f32_e32 v12, v12, v226
	v_add_f32_e32 v13, v13, v227
	v_add_f32_e32 v14, v14, v228
	v_add_f32_e32 v15, v15, v229
	v_cvt_pk_bf16_f32 v226, v12, v13
	v_cvt_pk_bf16_f32 v227, v14, v15
	global_store_dwordx2 v204, v[226:227], s[58:59] offset:0
	v_mul_f32_e32 v146, v13, v13
	v_fmac_f32_e32 v146, v12, v12
	v_fmac_f32_e32 v146, v14, v14
	v_fmac_f32_e32 v146, v15, v15
	v_mov_b32_e32 v12, v146
	v_add_f32_e32 v8, v8, v230
	v_add_f32_e32 v9, v9, v231
	v_add_f32_e32 v10, v10, v232
	v_add_f32_e32 v11, v11, v233
	v_cvt_pk_bf16_f32 v230, v8, v9
	v_cvt_pk_bf16_f32 v231, v10, v11
	global_store_dwordx2 v204, v[230:231], s[58:59] offset:32
	v_fmac_f32_e32 v12, v8, v8
	v_fmac_f32_e32 v12, v9, v9
	v_fmac_f32_e32 v12, v10, v10
	v_fmac_f32_e32 v12, v11, v11
	v_add_f32_e32 v4, v4, v88
	v_add_f32_e32 v5, v5, v89
	v_add_f32_e32 v6, v6, v90
	v_add_f32_e32 v7, v7, v91
	v_cvt_pk_bf16_f32 v88, v4, v5
	v_cvt_pk_bf16_f32 v89, v6, v7
	global_store_dwordx2 v204, v[88:89], s[58:59] offset:256
	v_fmac_f32_e32 v12, v4, v4
	v_fmac_f32_e32 v12, v5, v5
	v_fmac_f32_e32 v12, v6, v6
	v_fmac_f32_e32 v12, v7, v7
	v_add_f32_e32 v0, v0, v234
	v_add_f32_e32 v1, v1, v235
	v_add_f32_e32 v2, v2, v236
	v_add_f32_e32 v3, v3, v237
	v_cvt_pk_bf16_f32 v234, v0, v1
	v_cvt_pk_bf16_f32 v235, v2, v3
	global_store_dwordx2 v204, v[234:235], s[58:59] offset:288
	v_fmac_f32_e32 v12, v0, v0
	v_fmac_f32_e32 v12, v1, v1
	v_fmac_f32_e32 v12, v2, v2
	v_fmac_f32_e32 v12, v3, v3
	ds_bpermute_b32 v96, v207, v172
	ds_bpermute_b32 v97, v207, v156
	ds_bpermute_b32 v98, v207, v92
	ds_bpermute_b32 v99, v207, v76
	ds_bpermute_b32 v100, v207, v60
	ds_bpermute_b32 v101, v207, v44
	ds_bpermute_b32 v102, v207, v28
	ds_bpermute_b32 v103, v207, v12
	s_waitcnt lgkmcnt(0)
	v_add_f32_e32 v172, v172, v96
	v_add_f32_e32 v156, v156, v97
	v_add_f32_e32 v92, v92, v98
	v_add_f32_e32 v76, v76, v99
	v_add_f32_e32 v60, v60, v100
	v_add_f32_e32 v44, v44, v101
	v_add_f32_e32 v28, v28, v102
	v_add_f32_e32 v12, v12, v103
	ds_bpermute_b32 v96, v206, v172
	ds_bpermute_b32 v97, v206, v156
	ds_bpermute_b32 v98, v206, v92
	ds_bpermute_b32 v99, v206, v76
	ds_bpermute_b32 v100, v206, v60
	ds_bpermute_b32 v101, v206, v44
	ds_bpermute_b32 v102, v206, v28
	ds_bpermute_b32 v103, v206, v12
	s_waitcnt lgkmcnt(0)
	v_add_f32_e32 v172, v172, v96
	v_add_f32_e32 v156, v156, v97
	v_add_f32_e32 v92, v92, v98
	v_add_f32_e32 v76, v76, v99
	v_add_f32_e32 v60, v60, v100
	v_add_f32_e32 v44, v44, v101
	v_add_f32_e32 v28, v28, v102
	v_add_f32_e32 v12, v12, v103
	s_and_saveexec_b64 s[2:3], s[40:41]
	v_mov_b32_e32 v192, v188
	global_store_dword v192, v172, s[16:17]
	v_add_u32_e32 v124, 0x800, v188
	global_store_dword v124, v156, s[16:17]
	v_add_u32_e32 v192, 0x1000, v188
	global_store_dword v192, v92, s[16:17]
	v_add_u32_e32 v124, 0x1800, v188
	global_store_dword v124, v76, s[16:17]
	v_add_u32_e32 v192, 0x4000, v188
	global_store_dword v192, v60, s[16:17]
	v_add_u32_e32 v124, 0x4800, v188
	global_store_dword v124, v44, s[16:17]
	v_add_u32_e32 v192, 0x5000, v188
	global_store_dword v192, v28, s[16:17]
	v_add_u32_e32 v124, 0x5800, v188
	global_store_dword v124, v12, s[16:17]
	s_or_b64 exec, exec, s[2:3]
	s_branch .LBB0_551

.Lprio_647:
	s_add_u32 s1, s42, 0xfff80080
	s_addc_u32 s2, s43, -1
	s_add_i32 s3, 0, 0x10000
	v_add_u32_e32 v138, s3, v141
	ds_read_b128 v[134:137], v138
	ds_read_b128 v[142:145], v138 offset:1024
	ds_read_b128 v[150:153], v138 offset:2048
	ds_read_b128 v[154:157], v138 offset:3072
	s_cmp_eq_u32 s88, 28
	s_cselect_b32 s73, s45, s2
	s_cselect_b32 s72, s53, s1
	s_cselect_b32 s71, s47, s87
	s_cselect_b32 s70, s60, s61
	v_lshl_add_u64 v[138:139], s[42:43], 0, v[130:131]
	s_add_i32 m0, s77, 0xc000
	ds_read_b128 v[158:161], v149
	ds_read_b128 v[162:165], v149 offset:1024
	ds_read_b128 v[166:169], v149 offset:2048
	ds_read_b128 v[170:173], v149 offset:3072
	ds_read_b128 v[182:185], v149 offset:4096
	ds_read_b128 v[200:203], v149 offset:5120
	ds_read_b128 v[208:211], v149 offset:6144
	ds_read_b128 v[212:215], v149 offset:7168
	global_load_lds_dwordx4 v[138:139], off
	v_lshl_add_u64 v[138:139], s[42:43], 0, v[132:133]
	s_add_i32 m0, s77, 0xe000
	s_nop 0
	global_load_lds_dwordx4 v[138:139], off
	s_waitcnt lgkmcnt(8)
	s_barrier
	s_waitcnt lgkmcnt(0)
	s_waitcnt lgkmcnt(0)
	v_mfma_f32_16x16x32_bf16 v[124:127], v[134:137], v[158:161], v[124:127]
	v_mfma_f32_16x16x32_bf16 v[120:123], v[150:153], v[158:161], v[120:123]
	v_mfma_f32_16x16x32_bf16 v[108:111], v[134:137], v[166:169], v[108:111]
	v_mfma_f32_16x16x32_bf16 v[104:107], v[150:153], v[166:169], v[104:107]
	v_mfma_f32_16x16x32_bf16 v[92:95], v[134:137], v[182:185], v[92:95]
	v_mfma_f32_16x16x32_bf16 v[88:91], v[150:153], v[182:185], v[88:91]
	v_mfma_f32_16x16x32_bf16 v[76:79], v[134:137], v[208:211], v[76:79]
	v_mfma_f32_16x16x32_bf16 v[72:75], v[150:153], v[208:211], v[72:75]
	v_mfma_f32_16x16x32_bf16 v[124:127], v[142:145], v[162:165], v[124:127]
	v_mfma_f32_16x16x32_bf16 v[120:123], v[154:157], v[162:165], v[120:123]
	v_mfma_f32_16x16x32_bf16 v[108:111], v[142:145], v[170:173], v[108:111]
	v_mfma_f32_16x16x32_bf16 v[104:107], v[154:157], v[170:173], v[104:107]
	v_mfma_f32_16x16x32_bf16 v[92:95], v[142:145], v[200:203], v[92:95]
	v_mfma_f32_16x16x32_bf16 v[88:91], v[154:157], v[200:203], v[88:91]
	v_mfma_f32_16x16x32_bf16 v[76:79], v[142:145], v[212:215], v[76:79]
	v_mfma_f32_16x16x32_bf16 v[72:75], v[154:157], v[212:215], v[72:75]
	s_barrier
	s_add_i32 s1, 0, 0x14000
	v_add_u32_e32 v138, s1, v141
	s_add_i32 s2, s3, s75
	ds_read_b128 v[216:219], v138
	ds_read_b128 v[220:223], v138 offset:1024
	ds_read_b128 v[224:227], v138 offset:2048
	ds_read_b128 v[228:231], v138 offset:3072
	v_lshl_add_u64 v[138:139], s[70:71], 0, v[176:177]
	s_mov_b32 m0, s2
	v_lshl_add_u64 v[174:175], s[70:71], 0, v[128:129]
	global_load_lds_dwordx4 v[138:139], off
	s_add_i32 m0, s2, 0x2000
	s_nop 0
	global_load_lds_dwordx4 v[174:175], off
	s_barrier
	s_waitcnt lgkmcnt(0)
	s_waitcnt lgkmcnt(0)
	v_mfma_f32_16x16x32_bf16 v[116:119], v[216:219], v[158:161], v[116:119]
	v_mfma_f32_16x16x32_bf16 v[112:115], v[224:227], v[158:161], v[112:115]
	v_mfma_f32_16x16x32_bf16 v[100:103], v[216:219], v[166:169], v[100:103]
	v_mfma_f32_16x16x32_bf16 v[96:99], v[224:227], v[166:169], v[96:99]
	v_mfma_f32_16x16x32_bf16 v[84:87], v[216:219], v[182:185], v[84:87]
	v_mfma_f32_16x16x32_bf16 v[80:83], v[224:227], v[182:185], v[80:83]
	v_mfma_f32_16x16x32_bf16 v[68:71], v[216:219], v[208:211], v[68:71]
	v_mfma_f32_16x16x32_bf16 v[64:67], v[224:227], v[208:211], v[64:67]
	v_mfma_f32_16x16x32_bf16 v[116:119], v[220:223], v[162:165], v[116:119]
	v_mfma_f32_16x16x32_bf16 v[112:115], v[228:231], v[162:165], v[112:115]
	v_mfma_f32_16x16x32_bf16 v[100:103], v[220:223], v[170:173], v[100:103]
	v_mfma_f32_16x16x32_bf16 v[96:99], v[228:231], v[170:173], v[96:99]
	v_mfma_f32_16x16x32_bf16 v[84:87], v[220:223], v[200:203], v[84:87]
	v_mfma_f32_16x16x32_bf16 v[80:83], v[228:231], v[200:203], v[80:83]
	v_mfma_f32_16x16x32_bf16 v[68:71], v[220:223], v[212:215], v[68:71]
	v_mfma_f32_16x16x32_bf16 v[64:67], v[228:231], v[212:215], v[64:67]
	s_mov_b32 m0, s77
	v_lshl_add_u64 v[186:187], s[72:73], 0, v[176:177]
	s_barrier
	ds_read_b128 v[158:161], v149 offset:16384
	ds_read_b128 v[162:165], v149 offset:17408
	ds_read_b128 v[166:169], v149 offset:18432
	ds_read_b128 v[170:173], v149 offset:19456
	ds_read_b128 v[182:185], v149 offset:20480
	ds_read_b128 v[200:203], v149 offset:21504
	ds_read_b128 v[208:211], v149 offset:22528
	ds_read_b128 v[212:215], v149 offset:23552
	global_load_lds_dwordx4 v[186:187], off
	v_lshl_add_u64 v[190:191], s[72:73], 0, v[128:129]
	s_mov_b32 m0, s78
	s_nop 0
	global_load_lds_dwordx4 v[190:191], off
	s_barrier
	s_waitcnt lgkmcnt(0)
	s_waitcnt lgkmcnt(0)
	v_mfma_f32_16x16x32_bf16 v[60:63], v[134:137], v[158:161], v[60:63]
	v_mfma_f32_16x16x32_bf16 v[56:59], v[150:153], v[158:161], v[56:59]
	v_mfma_f32_16x16x32_bf16 v[44:47], v[134:137], v[166:169], v[44:47]
	v_mfma_f32_16x16x32_bf16 v[40:43], v[150:153], v[166:169], v[40:43]
	v_mfma_f32_16x16x32_bf16 v[28:31], v[134:137], v[182:185], v[28:31]
	v_mfma_f32_16x16x32_bf16 v[24:27], v[150:153], v[182:185], v[24:27]
	v_mfma_f32_16x16x32_bf16 v[12:15], v[134:137], v[208:211], v[12:15]
	v_mfma_f32_16x16x32_bf16 v[8:11], v[150:153], v[208:211], v[8:11]
	v_mfma_f32_16x16x32_bf16 v[60:63], v[142:145], v[162:165], v[60:63]
	v_mfma_f32_16x16x32_bf16 v[56:59], v[154:157], v[162:165], v[56:59]
	v_mfma_f32_16x16x32_bf16 v[44:47], v[142:145], v[170:173], v[44:47]
	v_mfma_f32_16x16x32_bf16 v[40:43], v[154:157], v[170:173], v[40:43]
	v_mfma_f32_16x16x32_bf16 v[28:31], v[142:145], v[200:203], v[28:31]
	v_mfma_f32_16x16x32_bf16 v[24:27], v[154:157], v[200:203], v[24:27]
	v_mfma_f32_16x16x32_bf16 v[12:15], v[142:145], v[212:215], v[12:15]
	v_mfma_f32_16x16x32_bf16 v[8:11], v[154:157], v[212:215], v[8:11]
	s_barrier
	s_add_u32 s2, s70, 0x80000
	s_addc_u32 s3, s71, 0
	s_add_i32 s1, s1, s75
	v_lshl_add_u64 v[134:135], s[2:3], 0, v[176:177]
	s_mov_b32 m0, s1
	s_nop 0
	global_load_lds_dwordx4 v[134:135], off
	v_lshl_add_u64 v[134:135], s[2:3], 0, v[128:129]
	s_add_i32 m0, s1, 0x2000
	s_nop 0
	global_load_lds_dwordx4 v[134:135], off
	s_waitcnt vmcnt(6)
	s_barrier
	v_mfma_f32_16x16x32_bf16 v[52:55], v[216:219], v[158:161], v[52:55]
	v_mfma_f32_16x16x32_bf16 v[48:51], v[224:227], v[158:161], v[48:51]
	v_mfma_f32_16x16x32_bf16 v[36:39], v[216:219], v[166:169], v[36:39]
	v_mfma_f32_16x16x32_bf16 v[32:35], v[224:227], v[166:169], v[32:35]
	v_mfma_f32_16x16x32_bf16 v[20:23], v[216:219], v[182:185], v[20:23]
	v_mfma_f32_16x16x32_bf16 v[16:19], v[224:227], v[182:185], v[16:19]
	v_mfma_f32_16x16x32_bf16 v[4:7], v[216:219], v[208:211], v[4:7]
	v_mfma_f32_16x16x32_bf16 v[0:3], v[224:227], v[208:211], v[0:3]
	v_mfma_f32_16x16x32_bf16 v[52:55], v[220:223], v[162:165], v[52:55]
	v_mfma_f32_16x16x32_bf16 v[48:51], v[228:231], v[162:165], v[48:51]
	v_mfma_f32_16x16x32_bf16 v[36:39], v[220:223], v[170:173], v[36:39]
	v_mfma_f32_16x16x32_bf16 v[32:35], v[228:231], v[170:173], v[32:35]
	v_mfma_f32_16x16x32_bf16 v[20:23], v[220:223], v[200:203], v[20:23]
	v_mfma_f32_16x16x32_bf16 v[16:19], v[228:231], v[200:203], v[16:19]
	v_mfma_f32_16x16x32_bf16 v[4:7], v[220:223], v[212:215], v[4:7]
	v_mfma_f32_16x16x32_bf16 v[0:3], v[228:231], v[212:215], v[0:3]
	s_add_i32 s1, 0, 0x18000
	v_add_u32_e32 v140, s1, v141
	s_barrier
	ds_read_b128 v[134:137], v140
	ds_read_b128 v[142:145], v140 offset:1024
	ds_read_b128 v[150:153], v140 offset:2048
	ds_read_b128 v[154:157], v140 offset:3072
	s_add_u32 s2, s72, 0x80000
	s_addc_u32 s3, s73, 0
	s_mov_b32 m0, s79
	v_lshl_add_u64 v[194:195], s[2:3], 0, v[176:177]
	ds_read_b128 v[158:161], v149 offset:32768
	ds_read_b128 v[162:165], v149 offset:33792
	ds_read_b128 v[166:169], v149 offset:34816
	ds_read_b128 v[170:173], v149 offset:35840
	ds_read_b128 v[182:185], v149 offset:36864
	ds_read_b128 v[200:203], v149 offset:37888
	ds_read_b128 v[208:211], v149 offset:38912
	ds_read_b128 v[212:215], v149 offset:39936
	global_load_lds_dwordx4 v[194:195], off
	v_lshl_add_u64 v[194:195], s[2:3], 0, v[128:129]
	s_mov_b32 m0, s80
	s_nop 0
	global_load_lds_dwordx4 v[194:195], off
	s_waitcnt lgkmcnt(8)
	s_barrier
	s_waitcnt lgkmcnt(0)
	s_waitcnt lgkmcnt(0)
	v_mfma_f32_16x16x32_bf16 v[124:127], v[134:137], v[158:161], v[124:127]
	v_mfma_f32_16x16x32_bf16 v[120:123], v[150:153], v[158:161], v[120:123]
	v_mfma_f32_16x16x32_bf16 v[108:111], v[134:137], v[166:169], v[108:111]
	v_mfma_f32_16x16x32_bf16 v[104:107], v[150:153], v[166:169], v[104:107]
	v_mfma_f32_16x16x32_bf16 v[92:95], v[134:137], v[182:185], v[92:95]
	v_mfma_f32_16x16x32_bf16 v[88:91], v[150:153], v[182:185], v[88:91]
	v_mfma_f32_16x16x32_bf16 v[76:79], v[134:137], v[208:211], v[76:79]
	v_mfma_f32_16x16x32_bf16 v[72:75], v[150:153], v[208:211], v[72:75]
	v_mfma_f32_16x16x32_bf16 v[124:127], v[142:145], v[162:165], v[124:127]
	v_mfma_f32_16x16x32_bf16 v[120:123], v[154:157], v[162:165], v[120:123]
	v_mfma_f32_16x16x32_bf16 v[108:111], v[142:145], v[170:173], v[108:111]
	v_mfma_f32_16x16x32_bf16 v[104:107], v[154:157], v[170:173], v[104:107]
	v_mfma_f32_16x16x32_bf16 v[92:95], v[142:145], v[200:203], v[92:95]
	v_mfma_f32_16x16x32_bf16 v[88:91], v[154:157], v[200:203], v[88:91]
	v_mfma_f32_16x16x32_bf16 v[76:79], v[142:145], v[212:215], v[76:79]
	v_mfma_f32_16x16x32_bf16 v[72:75], v[154:157], v[212:215], v[72:75]
	s_barrier
	s_add_i32 s12, 0, 0x1c000
	s_add_i32 s1, s1, s75
	v_add_u32_e32 v140, s12, v141
	v_lshl_add_u64 v[138:139], v[138:139], 0, s[20:21]
	s_mov_b32 m0, s1
	ds_read_b128 v[216:219], v140
	ds_read_b128 v[220:223], v140 offset:1024
	ds_read_b128 v[224:227], v140 offset:2048
	ds_read_b128 v[228:231], v140 offset:3072
	global_load_lds_dwordx4 v[138:139], off
	v_lshl_add_u64 v[138:139], v[174:175], 0, s[20:21]
	s_add_i32 m0, s1, 0x2000
	s_nop 0
	global_load_lds_dwordx4 v[138:139], off
	s_barrier
	s_waitcnt lgkmcnt(0)
	s_waitcnt lgkmcnt(0)
	v_mfma_f32_16x16x32_bf16 v[116:119], v[216:219], v[158:161], v[116:119]
	v_mfma_f32_16x16x32_bf16 v[112:115], v[224:227], v[158:161], v[112:115]
	v_mfma_f32_16x16x32_bf16 v[100:103], v[216:219], v[166:169], v[100:103]
	v_mfma_f32_16x16x32_bf16 v[96:99], v[224:227], v[166:169], v[96:99]
	v_mfma_f32_16x16x32_bf16 v[84:87], v[216:219], v[182:185], v[84:87]
	v_mfma_f32_16x16x32_bf16 v[80:83], v[224:227], v[182:185], v[80:83]
	v_mfma_f32_16x16x32_bf16 v[68:71], v[216:219], v[208:211], v[68:71]
	v_mfma_f32_16x16x32_bf16 v[64:67], v[224:227], v[208:211], v[64:67]
	v_mfma_f32_16x16x32_bf16 v[116:119], v[220:223], v[162:165], v[116:119]
	v_mfma_f32_16x16x32_bf16 v[112:115], v[228:231], v[162:165], v[112:115]
	v_mfma_f32_16x16x32_bf16 v[100:103], v[220:223], v[170:173], v[100:103]
	v_mfma_f32_16x16x32_bf16 v[96:99], v[228:231], v[170:173], v[96:99]
	v_mfma_f32_16x16x32_bf16 v[84:87], v[220:223], v[200:203], v[84:87]
	v_mfma_f32_16x16x32_bf16 v[80:83], v[228:231], v[200:203], v[80:83]
	v_mfma_f32_16x16x32_bf16 v[68:71], v[220:223], v[212:215], v[68:71]
	v_mfma_f32_16x16x32_bf16 v[64:67], v[228:231], v[212:215], v[64:67]
	s_mov_b32 m0, s83
	v_lshl_add_u64 v[138:139], v[186:187], 0, s[20:21]
	s_barrier
	ds_read_b128 v[158:161], v149 offset:49152
	ds_read_b128 v[162:165], v149 offset:50176
	ds_read_b128 v[166:169], v149 offset:51200
	ds_read_b128 v[170:173], v149 offset:52224
	ds_read_b128 v[182:185], v149 offset:53248
	ds_read_b128 v[200:203], v149 offset:54272
	ds_read_b128 v[208:211], v149 offset:55296
	ds_read_b128 v[212:215], v149 offset:56320
	global_load_lds_dwordx4 v[138:139], off
	v_lshl_add_u64 v[138:139], v[190:191], 0, s[20:21]
	s_mov_b32 m0, s74
	s_nop 0
	global_load_lds_dwordx4 v[138:139], off
	s_barrier
	s_waitcnt lgkmcnt(0)
	s_waitcnt lgkmcnt(0)
	v_mfma_f32_16x16x32_bf16 v[60:63], v[134:137], v[158:161], v[60:63]
	v_mfma_f32_16x16x32_bf16 v[56:59], v[150:153], v[158:161], v[56:59]
	v_mfma_f32_16x16x32_bf16 v[44:47], v[134:137], v[166:169], v[44:47]
	v_mfma_f32_16x16x32_bf16 v[40:43], v[150:153], v[166:169], v[40:43]
	v_mfma_f32_16x16x32_bf16 v[28:31], v[134:137], v[182:185], v[28:31]
	v_mfma_f32_16x16x32_bf16 v[24:27], v[150:153], v[182:185], v[24:27]
	v_mfma_f32_16x16x32_bf16 v[12:15], v[134:137], v[208:211], v[12:15]
	v_mfma_f32_16x16x32_bf16 v[8:11], v[150:153], v[208:211], v[8:11]
	v_mfma_f32_16x16x32_bf16 v[60:63], v[142:145], v[162:165], v[60:63]
	v_mfma_f32_16x16x32_bf16 v[56:59], v[154:157], v[162:165], v[56:59]
	v_mfma_f32_16x16x32_bf16 v[44:47], v[142:145], v[170:173], v[44:47]
	v_mfma_f32_16x16x32_bf16 v[40:43], v[154:157], v[170:173], v[40:43]
	v_mfma_f32_16x16x32_bf16 v[28:31], v[142:145], v[200:203], v[28:31]
	v_mfma_f32_16x16x32_bf16 v[24:27], v[154:157], v[200:203], v[24:27]
	v_mfma_f32_16x16x32_bf16 v[12:15], v[142:145], v[212:215], v[12:15]
	v_mfma_f32_16x16x32_bf16 v[8:11], v[154:157], v[212:215], v[8:11]
	s_barrier
	s_add_u32 s2, s70, 0x80080
	s_addc_u32 s3, s71, 0
	s_add_i32 s1, s12, s75
	v_lshl_add_u64 v[134:135], s[2:3], 0, v[176:177]
	s_mov_b32 m0, s1
	s_nop 0
	global_load_lds_dwordx4 v[134:135], off
	v_lshl_add_u64 v[134:135], s[2:3], 0, v[128:129]
	s_add_i32 m0, s1, 0x2000
	s_nop 0
	global_load_lds_dwordx4 v[134:135], off
	s_waitcnt vmcnt(6)
	s_barrier
	v_mfma_f32_16x16x32_bf16 v[52:55], v[216:219], v[158:161], v[52:55]
	v_mfma_f32_16x16x32_bf16 v[48:51], v[224:227], v[158:161], v[48:51]
	v_mfma_f32_16x16x32_bf16 v[36:39], v[216:219], v[166:169], v[36:39]
	v_mfma_f32_16x16x32_bf16 v[32:35], v[224:227], v[166:169], v[32:35]
	v_mfma_f32_16x16x32_bf16 v[20:23], v[216:219], v[182:185], v[20:23]
	v_mfma_f32_16x16x32_bf16 v[16:19], v[224:227], v[182:185], v[16:19]
	v_mfma_f32_16x16x32_bf16 v[4:7], v[216:219], v[208:211], v[4:7]
	v_mfma_f32_16x16x32_bf16 v[0:3], v[224:227], v[208:211], v[0:3]
	v_mfma_f32_16x16x32_bf16 v[52:55], v[220:223], v[162:165], v[52:55]
	v_mfma_f32_16x16x32_bf16 v[48:51], v[228:231], v[162:165], v[48:51]
	v_mfma_f32_16x16x32_bf16 v[36:39], v[220:223], v[170:173], v[36:39]
	v_mfma_f32_16x16x32_bf16 v[32:35], v[228:231], v[170:173], v[32:35]
	v_mfma_f32_16x16x32_bf16 v[20:23], v[220:223], v[200:203], v[20:23]
	v_mfma_f32_16x16x32_bf16 v[16:19], v[228:231], v[200:203], v[16:19]
	v_mfma_f32_16x16x32_bf16 v[4:7], v[220:223], v[212:215], v[4:7]
	v_mfma_f32_16x16x32_bf16 v[0:3], v[228:231], v[212:215], v[0:3]
	s_add_i32 s88, s88, 2
	s_add_u32 s42, s42, 0x100
	s_addc_u32 s43, s43, 0
	s_add_u32 s61, s61, 0x100
	s_addc_u32 s87, s87, 0
	s_cmp_gt_u32 s88, 29
	s_barrier
	s_cbranch_scc0 .LBB0_647
	s_setprio 0
	v_and_b32_e32 v198, 15, v147
	v_ashrrev_i32_e32 v252, 4, v147
	s_lshl_b32 s1, s52, 8
	s_add_i32 s1, s1, s81
	v_or_b32_e32 v198, s1, v198
	s_lshl_b32 s1, s49, 8
	s_or_b32 s1, s1, s82
	v_lshl_add_u32 v140, v252, 2, s1
	v_lshl_add_u32 v140, v198, 11, v140
	v_lshlrev_b32_e32 v140, 1, v140
	v_lshlrev_b32_e32 v146, 5, v252
	v_lshl_add_u32 v146, v198, 7, v146
	s_lshr_b32 s1, s82, 5
	s_lshl2_add_u32 s1, s49, s1
	s_lshl_b32 s1, s1, 2
	v_lshl_add_u32 v198, v198, 7, s1
	v_readlane_b32 s98, v255, 1
	v_readlane_b32 s99, v255, 2
	s_mov_b32 s49, s46
	s_mov_b32 s52, s44
	s_mov_b64 s[70:71], s[68:69]
	s_movk_i32 s14, 0x3fff
	s_mov_b64 s[42:43], s[38:39]
	v_mov_b32_e32 v148, v146
	global_load_dwordx4 v[208:211], v148, s[16:17]
	global_load_dwordx4 v[212:215], v148, s[16:17] offset:16
	v_add_u32_e32 v188, 0x800, v146
	global_load_dwordx4 v[216:219], v188, s[16:17]
	global_load_dwordx4 v[220:223], v188, s[16:17] offset:16
	v_add_u32_e32 v192, 0x1000, v146
	global_load_dwordx4 v[224:227], v192, s[16:17]
	global_load_dwordx4 v[228:231], v192, s[16:17] offset:16
	v_add_u32_e32 v196, 0x1800, v146
	global_load_dwordx4 v[232:235], v196, s[16:17]
	global_load_dwordx4 v[236:239], v196, s[16:17] offset:16
	v_mov_b32_e32 v148, v140
	global_load_dwordx2 v[152:153], v148, s[58:59] offset:0
	global_load_dwordx2 v[154:155], v148, s[56:57] offset:0
	global_load_dwordx2 v[156:157], v148, s[58:59] offset:32
	global_load_dwordx2 v[158:159], v148, s[56:57] offset:32
	global_load_dwordx2 v[160:161], v148, s[58:59] offset:256
	global_load_dwordx2 v[162:163], v148, s[56:57] offset:256
	global_load_dwordx2 v[164:165], v148, s[58:59] offset:288
	global_load_dwordx2 v[166:167], v148, s[56:57] offset:288
	v_add_u32_e32 v188, 0x10000, v140
	global_load_dwordx2 v[168:169], v188, s[58:59] offset:0
	global_load_dwordx2 v[170:171], v188, s[56:57] offset:0
	global_load_dwordx2 v[172:173], v188, s[58:59] offset:32
	global_load_dwordx2 v[174:175], v188, s[56:57] offset:32
	global_load_dwordx2 v[240:241], v188, s[58:59] offset:256
	global_load_dwordx2 v[242:243], v188, s[56:57] offset:256
	global_load_dwordx2 v[244:245], v188, s[58:59] offset:288
	global_load_dwordx2 v[246:247], v188, s[56:57] offset:288
	v_add_u32_e32 v192, 0x20000, v140
	global_load_dwordx2 v[182:183], v192, s[58:59] offset:0
	global_load_dwordx2 v[184:185], v192, s[56:57] offset:0
	global_load_dwordx2 v[186:187], v192, s[58:59] offset:32
	global_load_dwordx2 v[200:201], v192, s[56:57] offset:32
	global_load_dwordx2 v[202:203], v192, s[58:59] offset:256
	global_load_dwordx2 v[204:205], v192, s[56:57] offset:256
	global_load_dwordx2 v[134:135], v192, s[58:59] offset:288
	global_load_dwordx2 v[136:137], v192, s[56:57] offset:288
	v_add_u32_e32 v196, 0x30000, v140
	global_load_dwordx2 v[138:139], v196, s[58:59] offset:0
	global_load_dwordx2 v[142:143], v196, s[56:57] offset:0
	global_load_dwordx2 v[144:145], v196, s[58:59] offset:32
	global_load_dwordx2 v[190:191], v196, s[56:57] offset:32
	global_load_dwordx2 v[194:195], v196, s[58:59] offset:256
	global_load_dwordx2 v[248:249], v196, s[56:57] offset:256
	global_load_dwordx2 v[150:151], v196, s[58:59] offset:288
	s_waitcnt vmcnt(31)
	v_add_f32_e32 v208, v208, v209
	v_add_f32_e32 v210, v210, v211
	v_add_f32_e32 v212, v212, v213
	v_add_f32_e32 v214, v214, v215
	v_add_f32_e32 v208, v208, v210
	v_add_f32_e32 v212, v212, v214
	v_add_f32_e32 v208, v208, v212
	v_add_f32_e32 v216, v216, v217
	v_add_f32_e32 v218, v218, v219
	v_add_f32_e32 v220, v220, v221
	v_add_f32_e32 v222, v222, v223
	v_add_f32_e32 v216, v216, v218
	v_add_f32_e32 v220, v220, v222
	v_add_f32_e32 v216, v216, v220
	v_add_f32_e32 v224, v224, v225
	v_add_f32_e32 v226, v226, v227
	v_add_f32_e32 v228, v228, v229
	v_add_f32_e32 v230, v230, v231
	v_add_f32_e32 v224, v224, v226
	v_add_f32_e32 v228, v228, v230
	v_add_f32_e32 v224, v224, v228
	v_add_f32_e32 v232, v232, v233
	v_add_f32_e32 v234, v234, v235
	v_add_f32_e32 v236, v236, v237
	v_add_f32_e32 v238, v238, v239
	v_add_f32_e32 v232, v232, v234
	v_add_f32_e32 v236, v236, v238
	v_add_f32_e32 v232, v232, v236
	ds_bpermute_b32 v209, v207, v208
	ds_bpermute_b32 v217, v207, v216
	ds_bpermute_b32 v225, v207, v224
	ds_bpermute_b32 v233, v207, v232
	s_waitcnt lgkmcnt(0)
	v_add_f32_e32 v208, v208, v209
	v_add_f32_e32 v216, v216, v217
	v_add_f32_e32 v224, v224, v225
	v_add_f32_e32 v232, v232, v233
	ds_bpermute_b32 v209, v206, v208
	ds_bpermute_b32 v217, v206, v216
	ds_bpermute_b32 v225, v206, v224
	ds_bpermute_b32 v233, v206, v232
	s_waitcnt lgkmcnt(0)
	v_add_f32_e32 v208, v208, v209
	v_add_f32_e32 v216, v216, v217
	v_add_f32_e32 v224, v224, v225
	v_add_f32_e32 v232, v232, v233
	v_mul_f32_e32 v208, 0x3a000000, v208
	v_add_f32_e32 v208, 0x358637bd, v208
	v_mul_f32_e32 v216, 0x3a000000, v216
	v_add_f32_e32 v216, 0x358637bd, v216
	v_mul_f32_e32 v224, 0x3a000000, v224
	v_add_f32_e32 v224, 0x358637bd, v224
	v_mul_f32_e32 v232, 0x3a000000, v232
	v_add_f32_e32 v232, 0x358637bd, v232
	v_rsq_f32_e32 v208, v208
	v_rsq_f32_e32 v216, v216
	v_rsq_f32_e32 v224, v224
	v_rsq_f32_e32 v232, v232
	s_nop 0
	v_mov_b32_e32 v209, v216
	v_mov_b32_e32 v210, v224
	v_mov_b32_e32 v211, v232
	v_add_u32_e32 v148, 0x30000, v140
	global_load_dwordx2 v[238:239], v148, s[56:57] offset:288
	s_waitcnt vmcnt(16)
	v_mov_b32_e32 v188, v140
	v_mul_f32_e32 v124, v124, v208
	v_mul_f32_e32 v125, v125, v208
	v_mul_f32_e32 v126, v126, v208
	v_mul_f32_e32 v127, v127, v208
	v_mul_f32_e32 v124, 0xbfb8aa3b, v124
	v_mul_f32_e32 v125, 0xbfb8aa3b, v125
	v_mul_f32_e32 v126, 0xbfb8aa3b, v126
	v_mul_f32_e32 v127, 0xbfb8aa3b, v127
	v_exp_f32_e32 v124, v124
	v_exp_f32_e32 v125, v125
	v_exp_f32_e32 v126, v126
	v_exp_f32_e32 v127, v127
	v_add_f32_e32 v124, 1.0, v124
	v_add_f32_e32 v125, 1.0, v125
	v_add_f32_e32 v126, 1.0, v126
	v_add_f32_e32 v127, 1.0, v127
	v_rcp_f32_e32 v220, v124
	v_rcp_f32_e32 v221, v125
	v_rcp_f32_e32 v222, v126
	v_rcp_f32_e32 v223, v127
	v_fma_f32 v224, -v124, v220, 1.0
	v_fma_f32 v225, -v125, v221, 1.0
	v_fma_f32 v226, -v126, v222, 1.0
	v_fma_f32 v227, -v127, v223, 1.0
	v_fma_f32 v124, v224, v220, v220
	v_fma_f32 v125, v225, v221, v221
	v_fma_f32 v126, v226, v222, v222
	v_fma_f32 v127, v227, v223, v223
	v_lshlrev_b32_e32 v230, 16, v152
	v_and_b32_e32 v152, 0xffff0000, v152
	v_lshlrev_b32_e32 v231, 16, v153
	v_and_b32_e32 v153, 0xffff0000, v153
	v_lshlrev_b32_e32 v232, 16, v154
	v_and_b32_e32 v154, 0xffff0000, v154
	v_lshlrev_b32_e32 v233, 16, v155
	v_and_b32_e32 v155, 0xffff0000, v155
	v_fma_f32 v124, v124, v232, v230
	v_fma_f32 v125, v125, v154, v152
	v_fma_f32 v126, v126, v233, v231
	v_fma_f32 v127, v127, v155, v153
	v_mul_f32_e32 v228, v124, v124
	v_fmac_f32_e32 v228, v125, v125
	v_fmac_f32_e32 v228, v126, v126
	v_fmac_f32_e32 v228, v127, v127
	v_cvt_pk_bf16_f32 v152, v124, v125
	v_cvt_pk_bf16_f32 v153, v126, v127
	global_store_dwordx2 v188, v[152:153], s[62:63] offset:0
	v_mul_f32_e32 v120, v120, v208
	v_mul_f32_e32 v121, v121, v208
	v_mul_f32_e32 v122, v122, v208
	v_mul_f32_e32 v123, v123, v208
	v_mul_f32_e32 v120, 0xbfb8aa3b, v120
	v_mul_f32_e32 v121, 0xbfb8aa3b, v121
	v_mul_f32_e32 v122, 0xbfb8aa3b, v122
	v_mul_f32_e32 v123, 0xbfb8aa3b, v123
	v_exp_f32_e32 v120, v120
	v_exp_f32_e32 v121, v121
	v_exp_f32_e32 v122, v122
	v_exp_f32_e32 v123, v123
	v_add_f32_e32 v120, 1.0, v120
	v_add_f32_e32 v121, 1.0, v121
	v_add_f32_e32 v122, 1.0, v122
	v_add_f32_e32 v123, 1.0, v123
	v_rcp_f32_e32 v220, v120
	v_rcp_f32_e32 v221, v121
	v_rcp_f32_e32 v222, v122
	v_rcp_f32_e32 v223, v123
	v_fma_f32 v224, -v120, v220, 1.0
	v_fma_f32 v225, -v121, v221, 1.0
	v_fma_f32 v226, -v122, v222, 1.0
	v_fma_f32 v227, -v123, v223, 1.0
	v_fma_f32 v120, v224, v220, v220
	v_fma_f32 v121, v225, v221, v221
	v_fma_f32 v122, v226, v222, v222
	v_fma_f32 v123, v227, v223, v223
	v_lshlrev_b32_e32 v230, 16, v156
	v_and_b32_e32 v156, 0xffff0000, v156
	v_lshlrev_b32_e32 v231, 16, v157
	v_and_b32_e32 v157, 0xffff0000, v157
	v_lshlrev_b32_e32 v232, 16, v158
	v_and_b32_e32 v158, 0xffff0000, v158
	v_lshlrev_b32_e32 v233, 16, v159
	v_and_b32_e32 v159, 0xffff0000, v159
	v_fma_f32 v120, v120, v232, v230
	v_fma_f32 v121, v121, v158, v156
	v_fma_f32 v122, v122, v233, v231
	v_fma_f32 v123, v123, v159, v157
	v_fmac_f32_e32 v228, v120, v120
	v_fmac_f32_e32 v228, v121, v121
	v_fmac_f32_e32 v228, v122, v122
	v_fmac_f32_e32 v228, v123, v123
	v_cvt_pk_bf16_f32 v156, v120, v121
	v_cvt_pk_bf16_f32 v157, v122, v123
	global_store_dwordx2 v188, v[156:157], s[62:63] offset:32
	v_mul_f32_e32 v116, v116, v208
	v_mul_f32_e32 v117, v117, v208
	v_mul_f32_e32 v118, v118, v208
	v_mul_f32_e32 v119, v119, v208
	v_mul_f32_e32 v116, 0xbfb8aa3b, v116
	v_mul_f32_e32 v117, 0xbfb8aa3b, v117
	v_mul_f32_e32 v118, 0xbfb8aa3b, v118
	v_mul_f32_e32 v119, 0xbfb8aa3b, v119
	v_exp_f32_e32 v116, v116
	v_exp_f32_e32 v117, v117
	v_exp_f32_e32 v118, v118
	v_exp_f32_e32 v119, v119
	v_add_f32_e32 v116, 1.0, v116
	v_add_f32_e32 v117, 1.0, v117
	v_add_f32_e32 v118, 1.0, v118
	v_add_f32_e32 v119, 1.0, v119
	v_rcp_f32_e32 v220, v116
	v_rcp_f32_e32 v221, v117
	v_rcp_f32_e32 v222, v118
	v_rcp_f32_e32 v223, v119
	v_fma_f32 v224, -v116, v220, 1.0
	v_fma_f32 v225, -v117, v221, 1.0
	v_fma_f32 v226, -v118, v222, 1.0
	v_fma_f32 v227, -v119, v223, 1.0
	v_fma_f32 v116, v224, v220, v220
	v_fma_f32 v117, v225, v221, v221
	v_fma_f32 v118, v226, v222, v222
	v_fma_f32 v119, v227, v223, v223
	v_lshlrev_b32_e32 v230, 16, v160
	v_and_b32_e32 v160, 0xffff0000, v160
	v_lshlrev_b32_e32 v231, 16, v161
	v_and_b32_e32 v161, 0xffff0000, v161
	v_lshlrev_b32_e32 v232, 16, v162
	v_and_b32_e32 v162, 0xffff0000, v162
	v_lshlrev_b32_e32 v233, 16, v163
	v_and_b32_e32 v163, 0xffff0000, v163
	v_fma_f32 v116, v116, v232, v230
	v_fma_f32 v117, v117, v162, v160
	v_fma_f32 v118, v118, v233, v231
	v_fma_f32 v119, v119, v163, v161
	v_fmac_f32_e32 v228, v116, v116
	v_fmac_f32_e32 v228, v117, v117
	v_fmac_f32_e32 v228, v118, v118
	v_fmac_f32_e32 v228, v119, v119
	v_cvt_pk_bf16_f32 v160, v116, v117
	v_cvt_pk_bf16_f32 v161, v118, v119
	global_store_dwordx2 v188, v[160:161], s[62:63] offset:256
	v_mul_f32_e32 v112, v112, v208
	v_mul_f32_e32 v113, v113, v208
	v_mul_f32_e32 v114, v114, v208
	v_mul_f32_e32 v115, v115, v208
	v_mul_f32_e32 v112, 0xbfb8aa3b, v112
	v_mul_f32_e32 v113, 0xbfb8aa3b, v113
	v_mul_f32_e32 v114, 0xbfb8aa3b, v114
	v_mul_f32_e32 v115, 0xbfb8aa3b, v115
	v_exp_f32_e32 v112, v112
	v_exp_f32_e32 v113, v113
	v_exp_f32_e32 v114, v114
	v_exp_f32_e32 v115, v115
	v_add_f32_e32 v112, 1.0, v112
	v_add_f32_e32 v113, 1.0, v113
	v_add_f32_e32 v114, 1.0, v114
	v_add_f32_e32 v115, 1.0, v115
	v_rcp_f32_e32 v220, v112
	v_rcp_f32_e32 v221, v113
	v_rcp_f32_e32 v222, v114
	v_rcp_f32_e32 v223, v115
	v_fma_f32 v224, -v112, v220, 1.0
	v_fma_f32 v225, -v113, v221, 1.0
	v_fma_f32 v226, -v114, v222, 1.0
	v_fma_f32 v227, -v115, v223, 1.0
	v_fma_f32 v112, v224, v220, v220
	v_fma_f32 v113, v225, v221, v221
	v_fma_f32 v114, v226, v222, v222
	v_fma_f32 v115, v227, v223, v223
	v_lshlrev_b32_e32 v230, 16, v164
	v_and_b32_e32 v164, 0xffff0000, v164
	v_lshlrev_b32_e32 v231, 16, v165
	v_and_b32_e32 v165, 0xffff0000, v165
	v_lshlrev_b32_e32 v232, 16, v166
	v_and_b32_e32 v166, 0xffff0000, v166
	v_lshlrev_b32_e32 v233, 16, v167
	v_and_b32_e32 v167, 0xffff0000, v167
	v_fma_f32 v112, v112, v232, v230
	v_fma_f32 v113, v113, v166, v164
	v_fma_f32 v114, v114, v233, v231
	v_fma_f32 v115, v115, v167, v165
	v_fmac_f32_e32 v228, v112, v112
	v_fmac_f32_e32 v228, v113, v113
	v_fmac_f32_e32 v228, v114, v114
	v_fmac_f32_e32 v228, v115, v115
	v_cvt_pk_bf16_f32 v164, v112, v113
	v_cvt_pk_bf16_f32 v165, v114, v115
	global_store_dwordx2 v188, v[164:165], s[62:63] offset:288
	ds_bpermute_b32 v229, v207, v228
	s_waitcnt lgkmcnt(0)
	v_add_f32_e32 v228, v228, v229
	ds_bpermute_b32 v229, v206, v228
	s_waitcnt lgkmcnt(0)
	v_add_f32_e32 v228, v228, v229
	v_mov_b32_e32 v252, v198
	v_cmp_gt_u32_e32 vcc, 16, v147
	s_and_saveexec_b64 s[2:3], vcc
	global_store_dword v252, v228, s[98:99]
	s_or_b64 exec, exec, s[2:3]
	v_add_u32_e32 v192, 0x10000, v140
	v_mul_f32_e32 v108, v108, v209
	v_mul_f32_e32 v109, v109, v209
	v_mul_f32_e32 v110, v110, v209
	v_mul_f32_e32 v111, v111, v209
	v_mul_f32_e32 v108, 0xbfb8aa3b, v108
	v_mul_f32_e32 v109, 0xbfb8aa3b, v109
	v_mul_f32_e32 v110, 0xbfb8aa3b, v110
	v_mul_f32_e32 v111, 0xbfb8aa3b, v111
	v_exp_f32_e32 v108, v108
	v_exp_f32_e32 v109, v109
	v_exp_f32_e32 v110, v110
	v_exp_f32_e32 v111, v111
	v_add_f32_e32 v108, 1.0, v108
	v_add_f32_e32 v109, 1.0, v109
	v_add_f32_e32 v110, 1.0, v110
	v_add_f32_e32 v111, 1.0, v111
	v_rcp_f32_e32 v220, v108
	v_rcp_f32_e32 v221, v109
	v_rcp_f32_e32 v222, v110
	v_rcp_f32_e32 v223, v111
	v_fma_f32 v224, -v108, v220, 1.0
	v_fma_f32 v225, -v109, v221, 1.0
	v_fma_f32 v226, -v110, v222, 1.0
	v_fma_f32 v227, -v111, v223, 1.0
	v_fma_f32 v108, v224, v220, v220
	v_fma_f32 v109, v225, v221, v221
	v_fma_f32 v110, v226, v222, v222
	v_fma_f32 v111, v227, v223, v223
	v_lshlrev_b32_e32 v230, 16, v168
	v_and_b32_e32 v168, 0xffff0000, v168
	v_lshlrev_b32_e32 v231, 16, v169
	v_and_b32_e32 v169, 0xffff0000, v169
	v_lshlrev_b32_e32 v232, 16, v170
	v_and_b32_e32 v170, 0xffff0000, v170
	v_lshlrev_b32_e32 v233, 16, v171
	v_and_b32_e32 v171, 0xffff0000, v171
	v_fma_f32 v108, v108, v232, v230
	v_fma_f32 v109, v109, v170, v168
	v_fma_f32 v110, v110, v233, v231
	v_fma_f32 v111, v111, v171, v169
	v_mul_f32_e32 v228, v108, v108
	v_fmac_f32_e32 v228, v109, v109
	v_fmac_f32_e32 v228, v110, v110
	v_fmac_f32_e32 v228, v111, v111
	v_cvt_pk_bf16_f32 v168, v108, v109
	v_cvt_pk_bf16_f32 v169, v110, v111
	global_store_dwordx2 v192, v[168:169], s[62:63] offset:0
	v_mul_f32_e32 v104, v104, v209
	v_mul_f32_e32 v105, v105, v209
	v_mul_f32_e32 v106, v106, v209
	v_mul_f32_e32 v107, v107, v209
	v_mul_f32_e32 v104, 0xbfb8aa3b, v104
	v_mul_f32_e32 v105, 0xbfb8aa3b, v105
	v_mul_f32_e32 v106, 0xbfb8aa3b, v106
	v_mul_f32_e32 v107, 0xbfb8aa3b, v107
	v_exp_f32_e32 v104, v104
	v_exp_f32_e32 v105, v105
	v_exp_f32_e32 v106, v106
	v_exp_f32_e32 v107, v107
	v_add_f32_e32 v104, 1.0, v104
	v_add_f32_e32 v105, 1.0, v105
	v_add_f32_e32 v106, 1.0, v106
	v_add_f32_e32 v107, 1.0, v107
	v_rcp_f32_e32 v220, v104
	v_rcp_f32_e32 v221, v105
	v_rcp_f32_e32 v222, v106
	v_rcp_f32_e32 v223, v107
	v_fma_f32 v224, -v104, v220, 1.0
	v_fma_f32 v225, -v105, v221, 1.0
	v_fma_f32 v226, -v106, v222, 1.0
	v_fma_f32 v227, -v107, v223, 1.0
	v_fma_f32 v104, v224, v220, v220
	v_fma_f32 v105, v225, v221, v221
	v_fma_f32 v106, v226, v222, v222
	v_fma_f32 v107, v227, v223, v223
	v_lshlrev_b32_e32 v230, 16, v172
	v_and_b32_e32 v172, 0xffff0000, v172
	v_lshlrev_b32_e32 v231, 16, v173
	v_and_b32_e32 v173, 0xffff0000, v173
	v_lshlrev_b32_e32 v232, 16, v174
	v_and_b32_e32 v174, 0xffff0000, v174
	v_lshlrev_b32_e32 v233, 16, v175
	v_and_b32_e32 v175, 0xffff0000, v175
	v_fma_f32 v104, v104, v232, v230
	v_fma_f32 v105, v105, v174, v172
	v_fma_f32 v106, v106, v233, v231
	v_fma_f32 v107, v107, v175, v173
	v_fmac_f32_e32 v228, v104, v104
	v_fmac_f32_e32 v228, v105, v105
	v_fmac_f32_e32 v228, v106, v106
	v_fmac_f32_e32 v228, v107, v107
	v_cvt_pk_bf16_f32 v172, v104, v105
	v_cvt_pk_bf16_f32 v173, v106, v107
	global_store_dwordx2 v192, v[172:173], s[62:63] offset:32
	v_mul_f32_e32 v100, v100, v209
	v_mul_f32_e32 v101, v101, v209
	v_mul_f32_e32 v102, v102, v209
	v_mul_f32_e32 v103, v103, v209
	v_mul_f32_e32 v100, 0xbfb8aa3b, v100
	v_mul_f32_e32 v101, 0xbfb8aa3b, v101
	v_mul_f32_e32 v102, 0xbfb8aa3b, v102
	v_mul_f32_e32 v103, 0xbfb8aa3b, v103
	v_exp_f32_e32 v100, v100
	v_exp_f32_e32 v101, v101
	v_exp_f32_e32 v102, v102
	v_exp_f32_e32 v103, v103
	v_add_f32_e32 v100, 1.0, v100
	v_add_f32_e32 v101, 1.0, v101
	v_add_f32_e32 v102, 1.0, v102
	v_add_f32_e32 v103, 1.0, v103
	v_rcp_f32_e32 v220, v100
	v_rcp_f32_e32 v221, v101
	v_rcp_f32_e32 v222, v102
	v_rcp_f32_e32 v223, v103
	v_fma_f32 v224, -v100, v220, 1.0
	v_fma_f32 v225, -v101, v221, 1.0
	v_fma_f32 v226, -v102, v222, 1.0
	v_fma_f32 v227, -v103, v223, 1.0
	v_fma_f32 v100, v224, v220, v220
	v_fma_f32 v101, v225, v221, v221
	v_fma_f32 v102, v226, v222, v222
	v_fma_f32 v103, v227, v223, v223
	v_lshlrev_b32_e32 v230, 16, v240
	v_and_b32_e32 v240, 0xffff0000, v240
	v_lshlrev_b32_e32 v231, 16, v241
	v_and_b32_e32 v241, 0xffff0000, v241
	v_lshlrev_b32_e32 v232, 16, v242
	v_and_b32_e32 v242, 0xffff0000, v242
	v_lshlrev_b32_e32 v233, 16, v243
	v_and_b32_e32 v243, 0xffff0000, v243
	v_fma_f32 v100, v100, v232, v230
	v_fma_f32 v101, v101, v242, v240
	v_fma_f32 v102, v102, v233, v231
	v_fma_f32 v103, v103, v243, v241
	v_fmac_f32_e32 v228, v100, v100
	v_fmac_f32_e32 v228, v101, v101
	v_fmac_f32_e32 v228, v102, v102
	v_fmac_f32_e32 v228, v103, v103
	v_cvt_pk_bf16_f32 v240, v100, v101
	v_cvt_pk_bf16_f32 v241, v102, v103
	global_store_dwordx2 v192, v[240:241], s[62:63] offset:256
	v_mul_f32_e32 v96, v96, v209
	v_mul_f32_e32 v97, v97, v209
	v_mul_f32_e32 v98, v98, v209
	v_mul_f32_e32 v99, v99, v209
	v_mul_f32_e32 v96, 0xbfb8aa3b, v96
	v_mul_f32_e32 v97, 0xbfb8aa3b, v97
	v_mul_f32_e32 v98, 0xbfb8aa3b, v98
	v_mul_f32_e32 v99, 0xbfb8aa3b, v99
	v_exp_f32_e32 v96, v96
	v_exp_f32_e32 v97, v97
	v_exp_f32_e32 v98, v98
	v_exp_f32_e32 v99, v99
	v_add_f32_e32 v96, 1.0, v96
	v_add_f32_e32 v97, 1.0, v97
	v_add_f32_e32 v98, 1.0, v98
	v_add_f32_e32 v99, 1.0, v99
	v_rcp_f32_e32 v220, v96
	v_rcp_f32_e32 v221, v97
	v_rcp_f32_e32 v222, v98
	v_rcp_f32_e32 v223, v99
	v_fma_f32 v224, -v96, v220, 1.0
	v_fma_f32 v225, -v97, v221, 1.0
	v_fma_f32 v226, -v98, v222, 1.0
	v_fma_f32 v227, -v99, v223, 1.0
	v_fma_f32 v96, v224, v220, v220
	v_fma_f32 v97, v225, v221, v221
	v_fma_f32 v98, v226, v222, v222
	v_fma_f32 v99, v227, v223, v223
	v_lshlrev_b32_e32 v230, 16, v244
	v_and_b32_e32 v244, 0xffff0000, v244
	v_lshlrev_b32_e32 v231, 16, v245
	v_and_b32_e32 v245, 0xffff0000, v245
	v_lshlrev_b32_e32 v232, 16, v246
	v_and_b32_e32 v246, 0xffff0000, v246
	v_lshlrev_b32_e32 v233, 16, v247
	v_and_b32_e32 v247, 0xffff0000, v247
	v_fma_f32 v96, v96, v232, v230
	v_fma_f32 v97, v97, v246, v244
	v_fma_f32 v98, v98, v233, v231
	v_fma_f32 v99, v99, v247, v245
	v_fmac_f32_e32 v228, v96, v96
	v_fmac_f32_e32 v228, v97, v97
	v_fmac_f32_e32 v228, v98, v98
	v_fmac_f32_e32 v228, v99, v99
	v_cvt_pk_bf16_f32 v244, v96, v97
	v_cvt_pk_bf16_f32 v245, v98, v99
	global_store_dwordx2 v192, v[244:245], s[62:63] offset:288
	ds_bpermute_b32 v229, v207, v228
	s_waitcnt lgkmcnt(0)
	v_add_f32_e32 v228, v228, v229
	ds_bpermute_b32 v229, v206, v228
	s_waitcnt lgkmcnt(0)
	v_add_f32_e32 v228, v228, v229
	v_add_u32_e32 v252, 0x800, v198
	v_cmp_gt_u32_e32 vcc, 16, v147
	s_and_saveexec_b64 s[2:3], vcc
	global_store_dword v252, v228, s[98:99]
	s_or_b64 exec, exec, s[2:3]
	v_add_u32_e32 v196, 0x4000, v146
	global_load_dwordx4 v[96:99], v196, s[16:17]
	global_load_dwordx4 v[100:103], v196, s[16:17] offset:16
	v_add_u32_e32 v148, 0x4800, v146
	global_load_dwordx4 v[104:107], v148, s[16:17]
	global_load_dwordx4 v[108:111], v148, s[16:17] offset:16
	v_add_u32_e32 v188, 0x5000, v146
	global_load_dwordx4 v[112:115], v188, s[16:17]
	global_load_dwordx4 v[116:119], v188, s[16:17] offset:16
	v_add_u32_e32 v192, 0x5800, v146
	global_load_dwordx4 v[120:123], v192, s[16:17]
	global_load_dwordx4 v[124:127], v192, s[16:17] offset:16
	v_add_u32_e32 v196, 0x80000, v140
	global_load_dwordx2 v[152:153], v196, s[58:59] offset:0
	global_load_dwordx2 v[154:155], v196, s[56:57] offset:0
	global_load_dwordx2 v[156:157], v196, s[58:59] offset:32
	global_load_dwordx2 v[158:159], v196, s[56:57] offset:32
	global_load_dwordx2 v[160:161], v196, s[58:59] offset:256
	global_load_dwordx2 v[162:163], v196, s[56:57] offset:256
	global_load_dwordx2 v[164:165], v196, s[58:59] offset:288
	global_load_dwordx2 v[166:167], v196, s[56:57] offset:288
	v_add_u32_e32 v148, 0x90000, v140
	global_load_dwordx2 v[168:169], v148, s[58:59] offset:0
	global_load_dwordx2 v[170:171], v148, s[56:57] offset:0
	global_load_dwordx2 v[172:173], v148, s[58:59] offset:32
	global_load_dwordx2 v[174:175], v148, s[56:57] offset:32
	global_load_dwordx2 v[240:241], v148, s[58:59] offset:256
	global_load_dwordx2 v[242:243], v148, s[56:57] offset:256
	global_load_dwordx2 v[244:245], v148, s[58:59] offset:288
	global_load_dwordx2 v[246:247], v148, s[56:57] offset:288
	s_waitcnt vmcnt(34)
	v_add_u32_e32 v188, 0x20000, v140
	v_mul_f32_e32 v92, v92, v210
	v_mul_f32_e32 v93, v93, v210
	v_mul_f32_e32 v94, v94, v210
	v_mul_f32_e32 v95, v95, v210
	v_mul_f32_e32 v92, 0xbfb8aa3b, v92
	v_mul_f32_e32 v93, 0xbfb8aa3b, v93
	v_mul_f32_e32 v94, 0xbfb8aa3b, v94
	v_mul_f32_e32 v95, 0xbfb8aa3b, v95
	v_exp_f32_e32 v92, v92
	v_exp_f32_e32 v93, v93
	v_exp_f32_e32 v94, v94
	v_exp_f32_e32 v95, v95
	v_add_f32_e32 v92, 1.0, v92
	v_add_f32_e32 v93, 1.0, v93
	v_add_f32_e32 v94, 1.0, v94
	v_add_f32_e32 v95, 1.0, v95
	v_rcp_f32_e32 v220, v92
	v_rcp_f32_e32 v221, v93
	v_rcp_f32_e32 v222, v94
	v_rcp_f32_e32 v223, v95
	v_fma_f32 v224, -v92, v220, 1.0
	v_fma_f32 v225, -v93, v221, 1.0
	v_fma_f32 v226, -v94, v222, 1.0
	v_fma_f32 v227, -v95, v223, 1.0
	v_fma_f32 v92, v224, v220, v220
	v_fma_f32 v93, v225, v221, v221
	v_fma_f32 v94, v226, v222, v222
	v_fma_f32 v95, v227, v223, v223
	v_lshlrev_b32_e32 v230, 16, v182
	v_and_b32_e32 v182, 0xffff0000, v182
	v_lshlrev_b32_e32 v231, 16, v183
	v_and_b32_e32 v183, 0xffff0000, v183
	v_lshlrev_b32_e32 v232, 16, v184
	v_and_b32_e32 v184, 0xffff0000, v184
	v_lshlrev_b32_e32 v233, 16, v185
	v_and_b32_e32 v185, 0xffff0000, v185
	v_fma_f32 v92, v92, v232, v230
	v_fma_f32 v93, v93, v184, v182
	v_fma_f32 v94, v94, v233, v231
	v_fma_f32 v95, v95, v185, v183
	v_mul_f32_e32 v228, v92, v92
	v_fmac_f32_e32 v228, v93, v93
	v_fmac_f32_e32 v228, v94, v94
	v_fmac_f32_e32 v228, v95, v95
	v_cvt_pk_bf16_f32 v182, v92, v93
	v_cvt_pk_bf16_f32 v183, v94, v95
	global_store_dwordx2 v188, v[182:183], s[62:63] offset:0
	v_mul_f32_e32 v88, v88, v210
	v_mul_f32_e32 v89, v89, v210
	v_mul_f32_e32 v90, v90, v210
	v_mul_f32_e32 v91, v91, v210
	v_mul_f32_e32 v88, 0xbfb8aa3b, v88
	v_mul_f32_e32 v89, 0xbfb8aa3b, v89
	v_mul_f32_e32 v90, 0xbfb8aa3b, v90
	v_mul_f32_e32 v91, 0xbfb8aa3b, v91
	v_exp_f32_e32 v88, v88
	v_exp_f32_e32 v89, v89
	v_exp_f32_e32 v90, v90
	v_exp_f32_e32 v91, v91
	v_add_f32_e32 v88, 1.0, v88
	v_add_f32_e32 v89, 1.0, v89
	v_add_f32_e32 v90, 1.0, v90
	v_add_f32_e32 v91, 1.0, v91
	v_rcp_f32_e32 v220, v88
	v_rcp_f32_e32 v221, v89
	v_rcp_f32_e32 v222, v90
	v_rcp_f32_e32 v223, v91
	v_fma_f32 v224, -v88, v220, 1.0
	v_fma_f32 v225, -v89, v221, 1.0
	v_fma_f32 v226, -v90, v222, 1.0
	v_fma_f32 v227, -v91, v223, 1.0
	v_fma_f32 v88, v224, v220, v220
	v_fma_f32 v89, v225, v221, v221
	v_fma_f32 v90, v226, v222, v222
	v_fma_f32 v91, v227, v223, v223
	v_lshlrev_b32_e32 v230, 16, v186
	v_and_b32_e32 v186, 0xffff0000, v186
	v_lshlrev_b32_e32 v231, 16, v187
	v_and_b32_e32 v187, 0xffff0000, v187
	v_lshlrev_b32_e32 v232, 16, v200
	v_and_b32_e32 v200, 0xffff0000, v200
	v_lshlrev_b32_e32 v233, 16, v201
	v_and_b32_e32 v201, 0xffff0000, v201
	v_fma_f32 v88, v88, v232, v230
	v_fma_f32 v89, v89, v200, v186
	v_fma_f32 v90, v90, v233, v231
	v_fma_f32 v91, v91, v201, v187
	v_fmac_f32_e32 v228, v88, v88
	v_fmac_f32_e32 v228, v89, v89
	v_fmac_f32_e32 v228, v90, v90
	v_fmac_f32_e32 v228, v91, v91
	v_cvt_pk_bf16_f32 v186, v88, v89
	v_cvt_pk_bf16_f32 v187, v90, v91
	global_store_dwordx2 v188, v[186:187], s[62:63] offset:32
	v_mul_f32_e32 v84, v84, v210
	v_mul_f32_e32 v85, v85, v210
	v_mul_f32_e32 v86, v86, v210
	v_mul_f32_e32 v87, v87, v210
	v_mul_f32_e32 v84, 0xbfb8aa3b, v84
	v_mul_f32_e32 v85, 0xbfb8aa3b, v85
	v_mul_f32_e32 v86, 0xbfb8aa3b, v86
	v_mul_f32_e32 v87, 0xbfb8aa3b, v87
	v_exp_f32_e32 v84, v84
	v_exp_f32_e32 v85, v85
	v_exp_f32_e32 v86, v86
	v_exp_f32_e32 v87, v87
	v_add_f32_e32 v84, 1.0, v84
	v_add_f32_e32 v85, 1.0, v85
	v_add_f32_e32 v86, 1.0, v86
	v_add_f32_e32 v87, 1.0, v87
	v_rcp_f32_e32 v220, v84
	v_rcp_f32_e32 v221, v85
	v_rcp_f32_e32 v222, v86
	v_rcp_f32_e32 v223, v87
	v_fma_f32 v224, -v84, v220, 1.0
	v_fma_f32 v225, -v85, v221, 1.0
	v_fma_f32 v226, -v86, v222, 1.0
	v_fma_f32 v227, -v87, v223, 1.0
	v_fma_f32 v84, v224, v220, v220
	v_fma_f32 v85, v225, v221, v221
	v_fma_f32 v86, v226, v222, v222
	v_fma_f32 v87, v227, v223, v223
	v_lshlrev_b32_e32 v230, 16, v202
	v_and_b32_e32 v202, 0xffff0000, v202
	v_lshlrev_b32_e32 v231, 16, v203
	v_and_b32_e32 v203, 0xffff0000, v203
	v_lshlrev_b32_e32 v232, 16, v204
	v_and_b32_e32 v204, 0xffff0000, v204
	v_lshlrev_b32_e32 v233, 16, v205
	v_and_b32_e32 v205, 0xffff0000, v205
	v_fma_f32 v84, v84, v232, v230
	v_fma_f32 v85, v85, v204, v202
	v_fma_f32 v86, v86, v233, v231
	v_fma_f32 v87, v87, v205, v203
	v_fmac_f32_e32 v228, v84, v84
	v_fmac_f32_e32 v228, v85, v85
	v_fmac_f32_e32 v228, v86, v86
	v_fmac_f32_e32 v228, v87, v87
	v_cvt_pk_bf16_f32 v202, v84, v85
	v_cvt_pk_bf16_f32 v203, v86, v87
	global_store_dwordx2 v188, v[202:203], s[62:63] offset:256
	v_mul_f32_e32 v80, v80, v210
	v_mul_f32_e32 v81, v81, v210
	v_mul_f32_e32 v82, v82, v210
	v_mul_f32_e32 v83, v83, v210
	v_mul_f32_e32 v80, 0xbfb8aa3b, v80
	v_mul_f32_e32 v81, 0xbfb8aa3b, v81
	v_mul_f32_e32 v82, 0xbfb8aa3b, v82
	v_mul_f32_e32 v83, 0xbfb8aa3b, v83
	v_exp_f32_e32 v80, v80
	v_exp_f32_e32 v81, v81
	v_exp_f32_e32 v82, v82
	v_exp_f32_e32 v83, v83
	v_add_f32_e32 v80, 1.0, v80
	v_add_f32_e32 v81, 1.0, v81
	v_add_f32_e32 v82, 1.0, v82
	v_add_f32_e32 v83, 1.0, v83
	v_rcp_f32_e32 v220, v80
	v_rcp_f32_e32 v221, v81
	v_rcp_f32_e32 v222, v82
	v_rcp_f32_e32 v223, v83
	v_fma_f32 v224, -v80, v220, 1.0
	v_fma_f32 v225, -v81, v221, 1.0
	v_fma_f32 v226, -v82, v222, 1.0
	v_fma_f32 v227, -v83, v223, 1.0
	v_fma_f32 v80, v224, v220, v220
	v_fma_f32 v81, v225, v221, v221
	v_fma_f32 v82, v226, v222, v222
	v_fma_f32 v83, v227, v223, v223
	v_lshlrev_b32_e32 v230, 16, v134
	v_and_b32_e32 v134, 0xffff0000, v134
	v_lshlrev_b32_e32 v231, 16, v135
	v_and_b32_e32 v135, 0xffff0000, v135
	v_lshlrev_b32_e32 v232, 16, v136
	v_and_b32_e32 v136, 0xffff0000, v136
	v_lshlrev_b32_e32 v233, 16, v137
	v_and_b32_e32 v137, 0xffff0000, v137
	v_fma_f32 v80, v80, v232, v230
	v_fma_f32 v81, v81, v136, v134
	v_fma_f32 v82, v82, v233, v231
	v_fma_f32 v83, v83, v137, v135
	v_fmac_f32_e32 v228, v80, v80
	v_fmac_f32_e32 v228, v81, v81
	v_fmac_f32_e32 v228, v82, v82
	v_fmac_f32_e32 v228, v83, v83
	v_cvt_pk_bf16_f32 v134, v80, v81
	v_cvt_pk_bf16_f32 v135, v82, v83
	global_store_dwordx2 v188, v[134:135], s[62:63] offset:288
	ds_bpermute_b32 v229, v207, v228
	s_waitcnt lgkmcnt(0)
	v_add_f32_e32 v228, v228, v229
	ds_bpermute_b32 v229, v206, v228
	s_waitcnt lgkmcnt(0)
	v_add_f32_e32 v228, v228, v229
	v_add_u32_e32 v252, 0x1000, v198
	v_cmp_gt_u32_e32 vcc, 16, v147
	s_and_saveexec_b64 s[2:3], vcc
	global_store_dword v252, v228, s[98:99]
	s_or_b64 exec, exec, s[2:3]
	v_add_u32_e32 v192, 0x30000, v140
	v_mul_f32_e32 v76, v76, v211
	v_mul_f32_e32 v77, v77, v211
	v_mul_f32_e32 v78, v78, v211
	v_mul_f32_e32 v79, v79, v211
	v_mul_f32_e32 v76, 0xbfb8aa3b, v76
	v_mul_f32_e32 v77, 0xbfb8aa3b, v77
	v_mul_f32_e32 v78, 0xbfb8aa3b, v78
	v_mul_f32_e32 v79, 0xbfb8aa3b, v79
	v_exp_f32_e32 v76, v76
	v_exp_f32_e32 v77, v77
	v_exp_f32_e32 v78, v78
	v_exp_f32_e32 v79, v79
	v_add_f32_e32 v76, 1.0, v76
	v_add_f32_e32 v77, 1.0, v77
	v_add_f32_e32 v78, 1.0, v78
	v_add_f32_e32 v79, 1.0, v79
	v_rcp_f32_e32 v220, v76
	v_rcp_f32_e32 v221, v77
	v_rcp_f32_e32 v222, v78
	v_rcp_f32_e32 v223, v79
	v_fma_f32 v224, -v76, v220, 1.0
	v_fma_f32 v225, -v77, v221, 1.0
	v_fma_f32 v226, -v78, v222, 1.0
	v_fma_f32 v227, -v79, v223, 1.0
	v_fma_f32 v76, v224, v220, v220
	v_fma_f32 v77, v225, v221, v221
	v_fma_f32 v78, v226, v222, v222
	v_fma_f32 v79, v227, v223, v223
	v_lshlrev_b32_e32 v230, 16, v138
	v_and_b32_e32 v138, 0xffff0000, v138
	v_lshlrev_b32_e32 v231, 16, v139
	v_and_b32_e32 v139, 0xffff0000, v139
	v_lshlrev_b32_e32 v232, 16, v142
	v_and_b32_e32 v142, 0xffff0000, v142
	v_lshlrev_b32_e32 v233, 16, v143
	v_and_b32_e32 v143, 0xffff0000, v143
	v_fma_f32 v76, v76, v232, v230
	v_fma_f32 v77, v77, v142, v138
	v_fma_f32 v78, v78, v233, v231
	v_fma_f32 v79, v79, v143, v139
	v_mul_f32_e32 v228, v76, v76
	v_fmac_f32_e32 v228, v77, v77
	v_fmac_f32_e32 v228, v78, v78
	v_fmac_f32_e32 v228, v79, v79
	v_cvt_pk_bf16_f32 v138, v76, v77
	v_cvt_pk_bf16_f32 v139, v78, v79
	global_store_dwordx2 v192, v[138:139], s[62:63] offset:0
	v_mul_f32_e32 v72, v72, v211
	v_mul_f32_e32 v73, v73, v211
	v_mul_f32_e32 v74, v74, v211
	v_mul_f32_e32 v75, v75, v211
	v_mul_f32_e32 v72, 0xbfb8aa3b, v72
	v_mul_f32_e32 v73, 0xbfb8aa3b, v73
	v_mul_f32_e32 v74, 0xbfb8aa3b, v74
	v_mul_f32_e32 v75, 0xbfb8aa3b, v75
	v_exp_f32_e32 v72, v72
	v_exp_f32_e32 v73, v73
	v_exp_f32_e32 v74, v74
	v_exp_f32_e32 v75, v75
	v_add_f32_e32 v72, 1.0, v72
	v_add_f32_e32 v73, 1.0, v73
	v_add_f32_e32 v74, 1.0, v74
	v_add_f32_e32 v75, 1.0, v75
	v_rcp_f32_e32 v220, v72
	v_rcp_f32_e32 v221, v73
	v_rcp_f32_e32 v222, v74
	v_rcp_f32_e32 v223, v75
	v_fma_f32 v224, -v72, v220, 1.0
	v_fma_f32 v225, -v73, v221, 1.0
	v_fma_f32 v226, -v74, v222, 1.0
	v_fma_f32 v227, -v75, v223, 1.0
	v_fma_f32 v72, v224, v220, v220
	v_fma_f32 v73, v225, v221, v221
	v_fma_f32 v74, v226, v222, v222
	v_fma_f32 v75, v227, v223, v223
	v_lshlrev_b32_e32 v230, 16, v144
	v_and_b32_e32 v144, 0xffff0000, v144
	v_lshlrev_b32_e32 v231, 16, v145
	v_and_b32_e32 v145, 0xffff0000, v145
	v_lshlrev_b32_e32 v232, 16, v190
	v_and_b32_e32 v190, 0xffff0000, v190
	v_lshlrev_b32_e32 v233, 16, v191
	v_and_b32_e32 v191, 0xffff0000, v191
	v_fma_f32 v72, v72, v232, v230
	v_fma_f32 v73, v73, v190, v144
	v_fma_f32 v74, v74, v233, v231
	v_fma_f32 v75, v75, v191, v145
	v_fmac_f32_e32 v228, v72, v72
	v_fmac_f32_e32 v228, v73, v73
	v_fmac_f32_e32 v228, v74, v74
	v_fmac_f32_e32 v228, v75, v75
	v_cvt_pk_bf16_f32 v144, v72, v73
	v_cvt_pk_bf16_f32 v145, v74, v75
	global_store_dwordx2 v192, v[144:145], s[62:63] offset:32
	v_mul_f32_e32 v68, v68, v211
	v_mul_f32_e32 v69, v69, v211
	v_mul_f32_e32 v70, v70, v211
	v_mul_f32_e32 v71, v71, v211
	v_mul_f32_e32 v68, 0xbfb8aa3b, v68
	v_mul_f32_e32 v69, 0xbfb8aa3b, v69
	v_mul_f32_e32 v70, 0xbfb8aa3b, v70
	v_mul_f32_e32 v71, 0xbfb8aa3b, v71
	v_exp_f32_e32 v68, v68
	v_exp_f32_e32 v69, v69
	v_exp_f32_e32 v70, v70
	v_exp_f32_e32 v71, v71
	v_add_f32_e32 v68, 1.0, v68
	v_add_f32_e32 v69, 1.0, v69
	v_add_f32_e32 v70, 1.0, v70
	v_add_f32_e32 v71, 1.0, v71
	v_rcp_f32_e32 v220, v68
	v_rcp_f32_e32 v221, v69
	v_rcp_f32_e32 v222, v70
	v_rcp_f32_e32 v223, v71
	v_fma_f32 v224, -v68, v220, 1.0
	v_fma_f32 v225, -v69, v221, 1.0
	v_fma_f32 v226, -v70, v222, 1.0
	v_fma_f32 v227, -v71, v223, 1.0
	v_fma_f32 v68, v224, v220, v220
	v_fma_f32 v69, v225, v221, v221
	v_fma_f32 v70, v226, v222, v222
	v_fma_f32 v71, v227, v223, v223
	v_lshlrev_b32_e32 v230, 16, v194
	v_and_b32_e32 v194, 0xffff0000, v194
	v_lshlrev_b32_e32 v231, 16, v195
	v_and_b32_e32 v195, 0xffff0000, v195
	v_lshlrev_b32_e32 v232, 16, v248
	v_and_b32_e32 v248, 0xffff0000, v248
	v_lshlrev_b32_e32 v233, 16, v249
	v_and_b32_e32 v249, 0xffff0000, v249
	v_fma_f32 v68, v68, v232, v230
	v_fma_f32 v69, v69, v248, v194
	v_fma_f32 v70, v70, v233, v231
	v_fma_f32 v71, v71, v249, v195
	v_fmac_f32_e32 v228, v68, v68
	v_fmac_f32_e32 v228, v69, v69
	v_fmac_f32_e32 v228, v70, v70
	v_fmac_f32_e32 v228, v71, v71
	v_cvt_pk_bf16_f32 v194, v68, v69
	v_cvt_pk_bf16_f32 v195, v70, v71
	global_store_dwordx2 v192, v[194:195], s[62:63] offset:256
	v_mul_f32_e32 v64, v64, v211
	v_mul_f32_e32 v65, v65, v211
	v_mul_f32_e32 v66, v66, v211
	v_mul_f32_e32 v67, v67, v211
	v_mul_f32_e32 v64, 0xbfb8aa3b, v64
	v_mul_f32_e32 v65, 0xbfb8aa3b, v65
	v_mul_f32_e32 v66, 0xbfb8aa3b, v66
	v_mul_f32_e32 v67, 0xbfb8aa3b, v67
	v_exp_f32_e32 v64, v64
	v_exp_f32_e32 v65, v65
	v_exp_f32_e32 v66, v66
	v_exp_f32_e32 v67, v67
	v_add_f32_e32 v64, 1.0, v64
	v_add_f32_e32 v65, 1.0, v65
	v_add_f32_e32 v66, 1.0, v66
	v_add_f32_e32 v67, 1.0, v67
	v_rcp_f32_e32 v220, v64
	v_rcp_f32_e32 v221, v65
	v_rcp_f32_e32 v222, v66
	v_rcp_f32_e32 v223, v67
	v_fma_f32 v224, -v64, v220, 1.0
	v_fma_f32 v225, -v65, v221, 1.0
	v_fma_f32 v226, -v66, v222, 1.0
	v_fma_f32 v227, -v67, v223, 1.0
	v_fma_f32 v64, v224, v220, v220
	v_fma_f32 v65, v225, v221, v221
	v_fma_f32 v66, v226, v222, v222
	v_fma_f32 v67, v227, v223, v223
	v_lshlrev_b32_e32 v230, 16, v150
	v_and_b32_e32 v150, 0xffff0000, v150
	v_lshlrev_b32_e32 v231, 16, v151
	v_and_b32_e32 v151, 0xffff0000, v151
	v_lshlrev_b32_e32 v232, 16, v238
	v_and_b32_e32 v238, 0xffff0000, v238
	v_lshlrev_b32_e32 v233, 16, v239
	v_and_b32_e32 v239, 0xffff0000, v239
	v_fma_f32 v64, v64, v232, v230
	v_fma_f32 v65, v65, v238, v150
	v_fma_f32 v66, v66, v233, v231
	v_fma_f32 v67, v67, v239, v151
	v_fmac_f32_e32 v228, v64, v64
	v_fmac_f32_e32 v228, v65, v65
	v_fmac_f32_e32 v228, v66, v66
	v_fmac_f32_e32 v228, v67, v67
	v_cvt_pk_bf16_f32 v150, v64, v65
	v_cvt_pk_bf16_f32 v151, v66, v67
	global_store_dwordx2 v192, v[150:151], s[62:63] offset:288
	ds_bpermute_b32 v229, v207, v228
	s_waitcnt lgkmcnt(0)
	v_add_f32_e32 v228, v228, v229
	ds_bpermute_b32 v229, v206, v228
	s_waitcnt lgkmcnt(0)
	v_add_f32_e32 v228, v228, v229
	v_add_u32_e32 v252, 0x1800, v198
	v_cmp_gt_u32_e32 vcc, 16, v147
	s_and_saveexec_b64 s[2:3], vcc
	global_store_dword v252, v228, s[98:99]
	s_or_b64 exec, exec, s[2:3]
	v_add_u32_e32 v196, 0xa0000, v140
	global_load_dwordx2 v[182:183], v196, s[58:59] offset:0
	global_load_dwordx2 v[184:185], v196, s[56:57] offset:0
	global_load_dwordx2 v[186:187], v196, s[58:59] offset:32
	global_load_dwordx2 v[200:201], v196, s[56:57] offset:32
	global_load_dwordx2 v[202:203], v196, s[58:59] offset:256
	global_load_dwordx2 v[204:205], v196, s[56:57] offset:256
	global_load_dwordx2 v[134:135], v196, s[58:59] offset:288
	global_load_dwordx2 v[136:137], v196, s[56:57] offset:288
	v_add_u32_e32 v148, 0xb0000, v140
	global_load_dwordx2 v[138:139], v148, s[58:59] offset:0
	global_load_dwordx2 v[142:143], v148, s[56:57] offset:0
	global_load_dwordx2 v[144:145], v148, s[58:59] offset:32
	global_load_dwordx2 v[190:191], v148, s[56:57] offset:32
	global_load_dwordx2 v[194:195], v148, s[58:59] offset:256
	global_load_dwordx2 v[248:249], v148, s[56:57] offset:256
	global_load_dwordx2 v[150:151], v148, s[58:59] offset:288
	v_add_u32_e32 v188, 0xb0000, v140
	global_load_dwordx2 v[234:235], v188, s[56:57] offset:288
	s_waitcnt vmcnt(42)
	v_add_f32_e32 v96, v96, v97
	v_add_f32_e32 v98, v98, v99
	v_add_f32_e32 v100, v100, v101
	v_add_f32_e32 v102, v102, v103
	v_add_f32_e32 v96, v96, v98
	v_add_f32_e32 v100, v100, v102
	v_add_f32_e32 v96, v96, v100
	v_add_f32_e32 v104, v104, v105
	v_add_f32_e32 v106, v106, v107
	v_add_f32_e32 v108, v108, v109
	v_add_f32_e32 v110, v110, v111
	v_add_f32_e32 v104, v104, v106
	v_add_f32_e32 v108, v108, v110
	v_add_f32_e32 v104, v104, v108
	v_add_f32_e32 v112, v112, v113
	v_add_f32_e32 v114, v114, v115
	v_add_f32_e32 v116, v116, v117
	v_add_f32_e32 v118, v118, v119
	v_add_f32_e32 v112, v112, v114
	v_add_f32_e32 v116, v116, v118
	v_add_f32_e32 v112, v112, v116
	v_add_f32_e32 v120, v120, v121
	v_add_f32_e32 v122, v122, v123
	v_add_f32_e32 v124, v124, v125
	v_add_f32_e32 v126, v126, v127
	v_add_f32_e32 v120, v120, v122
	v_add_f32_e32 v124, v124, v126
	v_add_f32_e32 v120, v120, v124
	ds_bpermute_b32 v97, v207, v96
	ds_bpermute_b32 v105, v207, v104
	ds_bpermute_b32 v113, v207, v112
	ds_bpermute_b32 v121, v207, v120
	s_waitcnt lgkmcnt(0)
	v_add_f32_e32 v96, v96, v97
	v_add_f32_e32 v104, v104, v105
	v_add_f32_e32 v112, v112, v113
	v_add_f32_e32 v120, v120, v121
	ds_bpermute_b32 v97, v206, v96
	ds_bpermute_b32 v105, v206, v104
	ds_bpermute_b32 v113, v206, v112
	ds_bpermute_b32 v121, v206, v120
	s_waitcnt lgkmcnt(0)
	v_add_f32_e32 v96, v96, v97
	v_add_f32_e32 v104, v104, v105
	v_add_f32_e32 v112, v112, v113
	v_add_f32_e32 v120, v120, v121
	v_mul_f32_e32 v96, 0x3a000000, v96
	v_add_f32_e32 v96, 0x358637bd, v96
	v_mul_f32_e32 v104, 0x3a000000, v104
	v_add_f32_e32 v104, 0x358637bd, v104
	v_mul_f32_e32 v112, 0x3a000000, v112
	v_add_f32_e32 v112, 0x358637bd, v112
	v_mul_f32_e32 v120, 0x3a000000, v120
	v_add_f32_e32 v120, 0x358637bd, v120
	v_rsq_f32_e32 v96, v96
	v_rsq_f32_e32 v104, v104
	v_rsq_f32_e32 v112, v112
	v_rsq_f32_e32 v120, v120
	s_nop 0
	v_mov_b32_e32 v212, v96
	v_mov_b32_e32 v213, v104
	v_mov_b32_e32 v214, v112
	v_mov_b32_e32 v215, v120
	s_waitcnt vmcnt(26)
	v_add_u32_e32 v192, 0x80000, v140
	v_mul_f32_e32 v60, v60, v212
	v_mul_f32_e32 v61, v61, v212
	v_mul_f32_e32 v62, v62, v212
	v_mul_f32_e32 v63, v63, v212
	v_mul_f32_e32 v60, 0xbfb8aa3b, v60
	v_mul_f32_e32 v61, 0xbfb8aa3b, v61
	v_mul_f32_e32 v62, 0xbfb8aa3b, v62
	v_mul_f32_e32 v63, 0xbfb8aa3b, v63
	v_exp_f32_e32 v60, v60
	v_exp_f32_e32 v61, v61
	v_exp_f32_e32 v62, v62
	v_exp_f32_e32 v63, v63
	v_add_f32_e32 v60, 1.0, v60
	v_add_f32_e32 v61, 1.0, v61
	v_add_f32_e32 v62, 1.0, v62
	v_add_f32_e32 v63, 1.0, v63
	v_rcp_f32_e32 v220, v60
	v_rcp_f32_e32 v221, v61
	v_rcp_f32_e32 v222, v62
	v_rcp_f32_e32 v223, v63
	v_fma_f32 v224, -v60, v220, 1.0
	v_fma_f32 v225, -v61, v221, 1.0
	v_fma_f32 v226, -v62, v222, 1.0
	v_fma_f32 v227, -v63, v223, 1.0
	v_fma_f32 v60, v224, v220, v220
	v_fma_f32 v61, v225, v221, v221
	v_fma_f32 v62, v226, v222, v222
	v_fma_f32 v63, v227, v223, v223
	v_lshlrev_b32_e32 v230, 16, v152
	v_and_b32_e32 v152, 0xffff0000, v152
	v_lshlrev_b32_e32 v231, 16, v153
	v_and_b32_e32 v153, 0xffff0000, v153
	v_lshlrev_b32_e32 v232, 16, v154
	v_and_b32_e32 v154, 0xffff0000, v154
	v_lshlrev_b32_e32 v233, 16, v155
	v_and_b32_e32 v155, 0xffff0000, v155
	v_fma_f32 v60, v60, v232, v230
	v_fma_f32 v61, v61, v154, v152
	v_fma_f32 v62, v62, v233, v231
	v_fma_f32 v63, v63, v155, v153
	v_mul_f32_e32 v228, v60, v60
	v_fmac_f32_e32 v228, v61, v61
	v_fmac_f32_e32 v228, v62, v62
	v_fmac_f32_e32 v228, v63, v63
	v_cvt_pk_bf16_f32 v152, v60, v61
	v_cvt_pk_bf16_f32 v153, v62, v63
	global_store_dwordx2 v192, v[152:153], s[62:63] offset:0
	v_mul_f32_e32 v56, v56, v212
	v_mul_f32_e32 v57, v57, v212
	v_mul_f32_e32 v58, v58, v212
	v_mul_f32_e32 v59, v59, v212
	v_mul_f32_e32 v56, 0xbfb8aa3b, v56
	v_mul_f32_e32 v57, 0xbfb8aa3b, v57
	v_mul_f32_e32 v58, 0xbfb8aa3b, v58
	v_mul_f32_e32 v59, 0xbfb8aa3b, v59
	v_exp_f32_e32 v56, v56
	v_exp_f32_e32 v57, v57
	v_exp_f32_e32 v58, v58
	v_exp_f32_e32 v59, v59
	v_add_f32_e32 v56, 1.0, v56
	v_add_f32_e32 v57, 1.0, v57
	v_add_f32_e32 v58, 1.0, v58
	v_add_f32_e32 v59, 1.0, v59
	v_rcp_f32_e32 v220, v56
	v_rcp_f32_e32 v221, v57
	v_rcp_f32_e32 v222, v58
	v_rcp_f32_e32 v223, v59
	v_fma_f32 v224, -v56, v220, 1.0
	v_fma_f32 v225, -v57, v221, 1.0
	v_fma_f32 v226, -v58, v222, 1.0
	v_fma_f32 v227, -v59, v223, 1.0
	v_fma_f32 v56, v224, v220, v220
	v_fma_f32 v57, v225, v221, v221
	v_fma_f32 v58, v226, v222, v222
	v_fma_f32 v59, v227, v223, v223
	v_lshlrev_b32_e32 v230, 16, v156
	v_and_b32_e32 v156, 0xffff0000, v156
	v_lshlrev_b32_e32 v231, 16, v157
	v_and_b32_e32 v157, 0xffff0000, v157
	v_lshlrev_b32_e32 v232, 16, v158
	v_and_b32_e32 v158, 0xffff0000, v158
	v_lshlrev_b32_e32 v233, 16, v159
	v_and_b32_e32 v159, 0xffff0000, v159
	v_fma_f32 v56, v56, v232, v230
	v_fma_f32 v57, v57, v158, v156
	v_fma_f32 v58, v58, v233, v231
	v_fma_f32 v59, v59, v159, v157
	v_fmac_f32_e32 v228, v56, v56
	v_fmac_f32_e32 v228, v57, v57
	v_fmac_f32_e32 v228, v58, v58
	v_fmac_f32_e32 v228, v59, v59
	v_cvt_pk_bf16_f32 v156, v56, v57
	v_cvt_pk_bf16_f32 v157, v58, v59
	global_store_dwordx2 v192, v[156:157], s[62:63] offset:32
	v_mul_f32_e32 v52, v52, v212
	v_mul_f32_e32 v53, v53, v212
	v_mul_f32_e32 v54, v54, v212
	v_mul_f32_e32 v55, v55, v212
	v_mul_f32_e32 v52, 0xbfb8aa3b, v52
	v_mul_f32_e32 v53, 0xbfb8aa3b, v53
	v_mul_f32_e32 v54, 0xbfb8aa3b, v54
	v_mul_f32_e32 v55, 0xbfb8aa3b, v55
	v_exp_f32_e32 v52, v52
	v_exp_f32_e32 v53, v53
	v_exp_f32_e32 v54, v54
	v_exp_f32_e32 v55, v55
	v_add_f32_e32 v52, 1.0, v52
	v_add_f32_e32 v53, 1.0, v53
	v_add_f32_e32 v54, 1.0, v54
	v_add_f32_e32 v55, 1.0, v55
	v_rcp_f32_e32 v220, v52
	v_rcp_f32_e32 v221, v53
	v_rcp_f32_e32 v222, v54
	v_rcp_f32_e32 v223, v55
	v_fma_f32 v224, -v52, v220, 1.0
	v_fma_f32 v225, -v53, v221, 1.0
	v_fma_f32 v226, -v54, v222, 1.0
	v_fma_f32 v227, -v55, v223, 1.0
	v_fma_f32 v52, v224, v220, v220
	v_fma_f32 v53, v225, v221, v221
	v_fma_f32 v54, v226, v222, v222
	v_fma_f32 v55, v227, v223, v223
	v_lshlrev_b32_e32 v230, 16, v160
	v_and_b32_e32 v160, 0xffff0000, v160
	v_lshlrev_b32_e32 v231, 16, v161
	v_and_b32_e32 v161, 0xffff0000, v161
	v_lshlrev_b32_e32 v232, 16, v162
	v_and_b32_e32 v162, 0xffff0000, v162
	v_lshlrev_b32_e32 v233, 16, v163
	v_and_b32_e32 v163, 0xffff0000, v163
	v_fma_f32 v52, v52, v232, v230
	v_fma_f32 v53, v53, v162, v160
	v_fma_f32 v54, v54, v233, v231
	v_fma_f32 v55, v55, v163, v161
	v_fmac_f32_e32 v228, v52, v52
	v_fmac_f32_e32 v228, v53, v53
	v_fmac_f32_e32 v228, v54, v54
	v_fmac_f32_e32 v228, v55, v55
	v_cvt_pk_bf16_f32 v160, v52, v53
	v_cvt_pk_bf16_f32 v161, v54, v55
	global_store_dwordx2 v192, v[160:161], s[62:63] offset:256
	v_mul_f32_e32 v48, v48, v212
	v_mul_f32_e32 v49, v49, v212
	v_mul_f32_e32 v50, v50, v212
	v_mul_f32_e32 v51, v51, v212
	v_mul_f32_e32 v48, 0xbfb8aa3b, v48
	v_mul_f32_e32 v49, 0xbfb8aa3b, v49
	v_mul_f32_e32 v50, 0xbfb8aa3b, v50
	v_mul_f32_e32 v51, 0xbfb8aa3b, v51
	v_exp_f32_e32 v48, v48
	v_exp_f32_e32 v49, v49
	v_exp_f32_e32 v50, v50
	v_exp_f32_e32 v51, v51
	v_add_f32_e32 v48, 1.0, v48
	v_add_f32_e32 v49, 1.0, v49
	v_add_f32_e32 v50, 1.0, v50
	v_add_f32_e32 v51, 1.0, v51
	v_rcp_f32_e32 v220, v48
	v_rcp_f32_e32 v221, v49
	v_rcp_f32_e32 v222, v50
	v_rcp_f32_e32 v223, v51
	v_fma_f32 v224, -v48, v220, 1.0
	v_fma_f32 v225, -v49, v221, 1.0
	v_fma_f32 v226, -v50, v222, 1.0
	v_fma_f32 v227, -v51, v223, 1.0
	v_fma_f32 v48, v224, v220, v220
	v_fma_f32 v49, v225, v221, v221
	v_fma_f32 v50, v226, v222, v222
	v_fma_f32 v51, v227, v223, v223
	v_lshlrev_b32_e32 v230, 16, v164
	v_and_b32_e32 v164, 0xffff0000, v164
	v_lshlrev_b32_e32 v231, 16, v165
	v_and_b32_e32 v165, 0xffff0000, v165
	v_lshlrev_b32_e32 v232, 16, v166
	v_and_b32_e32 v166, 0xffff0000, v166
	v_lshlrev_b32_e32 v233, 16, v167
	v_and_b32_e32 v167, 0xffff0000, v167
	v_fma_f32 v48, v48, v232, v230
	v_fma_f32 v49, v49, v166, v164
	v_fma_f32 v50, v50, v233, v231
	v_fma_f32 v51, v51, v167, v165
	v_fmac_f32_e32 v228, v48, v48
	v_fmac_f32_e32 v228, v49, v49
	v_fmac_f32_e32 v228, v50, v50
	v_fmac_f32_e32 v228, v51, v51
	v_cvt_pk_bf16_f32 v164, v48, v49
	v_cvt_pk_bf16_f32 v165, v50, v51
	global_store_dwordx2 v192, v[164:165], s[62:63] offset:288
	ds_bpermute_b32 v229, v207, v228
	s_waitcnt lgkmcnt(0)
	v_add_f32_e32 v228, v228, v229
	ds_bpermute_b32 v229, v206, v228
	s_waitcnt lgkmcnt(0)
	v_add_f32_e32 v228, v228, v229
	v_add_u32_e32 v252, 0x4000, v198
	v_cmp_gt_u32_e32 vcc, 16, v147
	s_and_saveexec_b64 s[2:3], vcc
	global_store_dword v252, v228, s[98:99]
	s_or_b64 exec, exec, s[2:3]
	v_add_u32_e32 v196, 0x90000, v140
	v_mul_f32_e32 v44, v44, v213
	v_mul_f32_e32 v45, v45, v213
	v_mul_f32_e32 v46, v46, v213
	v_mul_f32_e32 v47, v47, v213
	v_mul_f32_e32 v44, 0xbfb8aa3b, v44
	v_mul_f32_e32 v45, 0xbfb8aa3b, v45
	v_mul_f32_e32 v46, 0xbfb8aa3b, v46
	v_mul_f32_e32 v47, 0xbfb8aa3b, v47
	v_exp_f32_e32 v44, v44
	v_exp_f32_e32 v45, v45
	v_exp_f32_e32 v46, v46
	v_exp_f32_e32 v47, v47
	v_add_f32_e32 v44, 1.0, v44
	v_add_f32_e32 v45, 1.0, v45
	v_add_f32_e32 v46, 1.0, v46
	v_add_f32_e32 v47, 1.0, v47
	v_rcp_f32_e32 v220, v44
	v_rcp_f32_e32 v221, v45
	v_rcp_f32_e32 v222, v46
	v_rcp_f32_e32 v223, v47
	v_fma_f32 v224, -v44, v220, 1.0
	v_fma_f32 v225, -v45, v221, 1.0
	v_fma_f32 v226, -v46, v222, 1.0
	v_fma_f32 v227, -v47, v223, 1.0
	v_fma_f32 v44, v224, v220, v220
	v_fma_f32 v45, v225, v221, v221
	v_fma_f32 v46, v226, v222, v222
	v_fma_f32 v47, v227, v223, v223
	v_lshlrev_b32_e32 v230, 16, v168
	v_and_b32_e32 v168, 0xffff0000, v168
	v_lshlrev_b32_e32 v231, 16, v169
	v_and_b32_e32 v169, 0xffff0000, v169
	v_lshlrev_b32_e32 v232, 16, v170
	v_and_b32_e32 v170, 0xffff0000, v170
	v_lshlrev_b32_e32 v233, 16, v171
	v_and_b32_e32 v171, 0xffff0000, v171
	v_fma_f32 v44, v44, v232, v230
	v_fma_f32 v45, v45, v170, v168
	v_fma_f32 v46, v46, v233, v231
	v_fma_f32 v47, v47, v171, v169
	v_mul_f32_e32 v228, v44, v44
	v_fmac_f32_e32 v228, v45, v45
	v_fmac_f32_e32 v228, v46, v46
	v_fmac_f32_e32 v228, v47, v47
	v_cvt_pk_bf16_f32 v168, v44, v45
	v_cvt_pk_bf16_f32 v169, v46, v47
	global_store_dwordx2 v196, v[168:169], s[62:63] offset:0
	v_mul_f32_e32 v40, v40, v213
	v_mul_f32_e32 v41, v41, v213
	v_mul_f32_e32 v42, v42, v213
	v_mul_f32_e32 v43, v43, v213
	v_mul_f32_e32 v40, 0xbfb8aa3b, v40
	v_mul_f32_e32 v41, 0xbfb8aa3b, v41
	v_mul_f32_e32 v42, 0xbfb8aa3b, v42
	v_mul_f32_e32 v43, 0xbfb8aa3b, v43
	v_exp_f32_e32 v40, v40
	v_exp_f32_e32 v41, v41
	v_exp_f32_e32 v42, v42
	v_exp_f32_e32 v43, v43
	v_add_f32_e32 v40, 1.0, v40
	v_add_f32_e32 v41, 1.0, v41
	v_add_f32_e32 v42, 1.0, v42
	v_add_f32_e32 v43, 1.0, v43
	v_rcp_f32_e32 v220, v40
	v_rcp_f32_e32 v221, v41
	v_rcp_f32_e32 v222, v42
	v_rcp_f32_e32 v223, v43
	v_fma_f32 v224, -v40, v220, 1.0
	v_fma_f32 v225, -v41, v221, 1.0
	v_fma_f32 v226, -v42, v222, 1.0
	v_fma_f32 v227, -v43, v223, 1.0
	v_fma_f32 v40, v224, v220, v220
	v_fma_f32 v41, v225, v221, v221
	v_fma_f32 v42, v226, v222, v222
	v_fma_f32 v43, v227, v223, v223
	v_lshlrev_b32_e32 v230, 16, v172
	v_and_b32_e32 v172, 0xffff0000, v172
	v_lshlrev_b32_e32 v231, 16, v173
	v_and_b32_e32 v173, 0xffff0000, v173
	v_lshlrev_b32_e32 v232, 16, v174
	v_and_b32_e32 v174, 0xffff0000, v174
	v_lshlrev_b32_e32 v233, 16, v175
	v_and_b32_e32 v175, 0xffff0000, v175
	v_fma_f32 v40, v40, v232, v230
	v_fma_f32 v41, v41, v174, v172
	v_fma_f32 v42, v42, v233, v231
	v_fma_f32 v43, v43, v175, v173
	v_fmac_f32_e32 v228, v40, v40
	v_fmac_f32_e32 v228, v41, v41
	v_fmac_f32_e32 v228, v42, v42
	v_fmac_f32_e32 v228, v43, v43
	v_cvt_pk_bf16_f32 v172, v40, v41
	v_cvt_pk_bf16_f32 v173, v42, v43
	global_store_dwordx2 v196, v[172:173], s[62:63] offset:32
	v_mul_f32_e32 v36, v36, v213
	v_mul_f32_e32 v37, v37, v213
	v_mul_f32_e32 v38, v38, v213
	v_mul_f32_e32 v39, v39, v213
	v_mul_f32_e32 v36, 0xbfb8aa3b, v36
	v_mul_f32_e32 v37, 0xbfb8aa3b, v37
	v_mul_f32_e32 v38, 0xbfb8aa3b, v38
	v_mul_f32_e32 v39, 0xbfb8aa3b, v39
	v_exp_f32_e32 v36, v36
	v_exp_f32_e32 v37, v37
	v_exp_f32_e32 v38, v38
	v_exp_f32_e32 v39, v39
	v_add_f32_e32 v36, 1.0, v36
	v_add_f32_e32 v37, 1.0, v37
	v_add_f32_e32 v38, 1.0, v38
	v_add_f32_e32 v39, 1.0, v39
	v_rcp_f32_e32 v220, v36
	v_rcp_f32_e32 v221, v37
	v_rcp_f32_e32 v222, v38
	v_rcp_f32_e32 v223, v39
	v_fma_f32 v224, -v36, v220, 1.0
	v_fma_f32 v225, -v37, v221, 1.0
	v_fma_f32 v226, -v38, v222, 1.0
	v_fma_f32 v227, -v39, v223, 1.0
	v_fma_f32 v36, v224, v220, v220
	v_fma_f32 v37, v225, v221, v221
	v_fma_f32 v38, v226, v222, v222
	v_fma_f32 v39, v227, v223, v223
	v_lshlrev_b32_e32 v230, 16, v240
	v_and_b32_e32 v240, 0xffff0000, v240
	v_lshlrev_b32_e32 v231, 16, v241
	v_and_b32_e32 v241, 0xffff0000, v241
	v_lshlrev_b32_e32 v232, 16, v242
	v_and_b32_e32 v242, 0xffff0000, v242
	v_lshlrev_b32_e32 v233, 16, v243
	v_and_b32_e32 v243, 0xffff0000, v243
	v_fma_f32 v36, v36, v232, v230
	v_fma_f32 v37, v37, v242, v240
	v_fma_f32 v38, v38, v233, v231
	v_fma_f32 v39, v39, v243, v241
	v_fmac_f32_e32 v228, v36, v36
	v_fmac_f32_e32 v228, v37, v37
	v_fmac_f32_e32 v228, v38, v38
	v_fmac_f32_e32 v228, v39, v39
	v_cvt_pk_bf16_f32 v240, v36, v37
	v_cvt_pk_bf16_f32 v241, v38, v39
	global_store_dwordx2 v196, v[240:241], s[62:63] offset:256
	v_mul_f32_e32 v32, v32, v213
	v_mul_f32_e32 v33, v33, v213
	v_mul_f32_e32 v34, v34, v213
	v_mul_f32_e32 v35, v35, v213
	v_mul_f32_e32 v32, 0xbfb8aa3b, v32
	v_mul_f32_e32 v33, 0xbfb8aa3b, v33
	v_mul_f32_e32 v34, 0xbfb8aa3b, v34
	v_mul_f32_e32 v35, 0xbfb8aa3b, v35
	v_exp_f32_e32 v32, v32
	v_exp_f32_e32 v33, v33
	v_exp_f32_e32 v34, v34
	v_exp_f32_e32 v35, v35
	v_add_f32_e32 v32, 1.0, v32
	v_add_f32_e32 v33, 1.0, v33
	v_add_f32_e32 v34, 1.0, v34
	v_add_f32_e32 v35, 1.0, v35
	v_rcp_f32_e32 v220, v32
	v_rcp_f32_e32 v221, v33
	v_rcp_f32_e32 v222, v34
	v_rcp_f32_e32 v223, v35
	v_fma_f32 v224, -v32, v220, 1.0
	v_fma_f32 v225, -v33, v221, 1.0
	v_fma_f32 v226, -v34, v222, 1.0
	v_fma_f32 v227, -v35, v223, 1.0
	v_fma_f32 v32, v224, v220, v220
	v_fma_f32 v33, v225, v221, v221
	v_fma_f32 v34, v226, v222, v222
	v_fma_f32 v35, v227, v223, v223
	v_lshlrev_b32_e32 v230, 16, v244
	v_and_b32_e32 v244, 0xffff0000, v244
	v_lshlrev_b32_e32 v231, 16, v245
	v_and_b32_e32 v245, 0xffff0000, v245
	v_lshlrev_b32_e32 v232, 16, v246
	v_and_b32_e32 v246, 0xffff0000, v246
	v_lshlrev_b32_e32 v233, 16, v247
	v_and_b32_e32 v247, 0xffff0000, v247
	v_fma_f32 v32, v32, v232, v230
	v_fma_f32 v33, v33, v246, v244
	v_fma_f32 v34, v34, v233, v231
	v_fma_f32 v35, v35, v247, v245
	v_fmac_f32_e32 v228, v32, v32
	v_fmac_f32_e32 v228, v33, v33
	v_fmac_f32_e32 v228, v34, v34
	v_fmac_f32_e32 v228, v35, v35
	v_cvt_pk_bf16_f32 v244, v32, v33
	v_cvt_pk_bf16_f32 v245, v34, v35
	global_store_dwordx2 v196, v[244:245], s[62:63] offset:288
	ds_bpermute_b32 v229, v207, v228
	s_waitcnt lgkmcnt(0)
	v_add_f32_e32 v228, v228, v229
	ds_bpermute_b32 v229, v206, v228
	s_waitcnt lgkmcnt(0)
	v_add_f32_e32 v228, v228, v229
	v_add_u32_e32 v252, 0x4800, v198
	v_cmp_gt_u32_e32 vcc, 16, v147
	s_and_saveexec_b64 s[2:3], vcc
	global_store_dword v252, v228, s[98:99]
	s_or_b64 exec, exec, s[2:3]
	s_waitcnt vmcnt(10)
	v_add_u32_e32 v148, 0xa0000, v140
	v_mul_f32_e32 v28, v28, v214
	v_mul_f32_e32 v29, v29, v214
	v_mul_f32_e32 v30, v30, v214
	v_mul_f32_e32 v31, v31, v214
	v_mul_f32_e32 v28, 0xbfb8aa3b, v28
	v_mul_f32_e32 v29, 0xbfb8aa3b, v29
	v_mul_f32_e32 v30, 0xbfb8aa3b, v30
	v_mul_f32_e32 v31, 0xbfb8aa3b, v31
	v_exp_f32_e32 v28, v28
	v_exp_f32_e32 v29, v29
	v_exp_f32_e32 v30, v30
	v_exp_f32_e32 v31, v31
	v_add_f32_e32 v28, 1.0, v28
	v_add_f32_e32 v29, 1.0, v29
	v_add_f32_e32 v30, 1.0, v30
	v_add_f32_e32 v31, 1.0, v31
	v_rcp_f32_e32 v220, v28
	v_rcp_f32_e32 v221, v29
	v_rcp_f32_e32 v222, v30
	v_rcp_f32_e32 v223, v31
	v_fma_f32 v224, -v28, v220, 1.0
	v_fma_f32 v225, -v29, v221, 1.0
	v_fma_f32 v226, -v30, v222, 1.0
	v_fma_f32 v227, -v31, v223, 1.0
	v_fma_f32 v28, v224, v220, v220
	v_fma_f32 v29, v225, v221, v221
	v_fma_f32 v30, v226, v222, v222
	v_fma_f32 v31, v227, v223, v223
	v_lshlrev_b32_e32 v230, 16, v182
	v_and_b32_e32 v182, 0xffff0000, v182
	v_lshlrev_b32_e32 v231, 16, v183
	v_and_b32_e32 v183, 0xffff0000, v183
	v_lshlrev_b32_e32 v232, 16, v184
	v_and_b32_e32 v184, 0xffff0000, v184
	v_lshlrev_b32_e32 v233, 16, v185
	v_and_b32_e32 v185, 0xffff0000, v185
	v_fma_f32 v28, v28, v232, v230
	v_fma_f32 v29, v29, v184, v182
	v_fma_f32 v30, v30, v233, v231
	v_fma_f32 v31, v31, v185, v183
	v_mul_f32_e32 v228, v28, v28
	v_fmac_f32_e32 v228, v29, v29
	v_fmac_f32_e32 v228, v30, v30
	v_fmac_f32_e32 v228, v31, v31
	v_cvt_pk_bf16_f32 v182, v28, v29
	v_cvt_pk_bf16_f32 v183, v30, v31
	global_store_dwordx2 v148, v[182:183], s[62:63] offset:0
	v_mul_f32_e32 v24, v24, v214
	v_mul_f32_e32 v25, v25, v214
	v_mul_f32_e32 v26, v26, v214
	v_mul_f32_e32 v27, v27, v214
	v_mul_f32_e32 v24, 0xbfb8aa3b, v24
	v_mul_f32_e32 v25, 0xbfb8aa3b, v25
	v_mul_f32_e32 v26, 0xbfb8aa3b, v26
	v_mul_f32_e32 v27, 0xbfb8aa3b, v27
	v_exp_f32_e32 v24, v24
	v_exp_f32_e32 v25, v25
	v_exp_f32_e32 v26, v26
	v_exp_f32_e32 v27, v27
	v_add_f32_e32 v24, 1.0, v24
	v_add_f32_e32 v25, 1.0, v25
	v_add_f32_e32 v26, 1.0, v26
	v_add_f32_e32 v27, 1.0, v27
	v_rcp_f32_e32 v220, v24
	v_rcp_f32_e32 v221, v25
	v_rcp_f32_e32 v222, v26
	v_rcp_f32_e32 v223, v27
	v_fma_f32 v224, -v24, v220, 1.0
	v_fma_f32 v225, -v25, v221, 1.0
	v_fma_f32 v226, -v26, v222, 1.0
	v_fma_f32 v227, -v27, v223, 1.0
	v_fma_f32 v24, v224, v220, v220
	v_fma_f32 v25, v225, v221, v221
	v_fma_f32 v26, v226, v222, v222
	v_fma_f32 v27, v227, v223, v223
	v_lshlrev_b32_e32 v230, 16, v186
	v_and_b32_e32 v186, 0xffff0000, v186
	v_lshlrev_b32_e32 v231, 16, v187
	v_and_b32_e32 v187, 0xffff0000, v187
	v_lshlrev_b32_e32 v232, 16, v200
	v_and_b32_e32 v200, 0xffff0000, v200
	v_lshlrev_b32_e32 v233, 16, v201
	v_and_b32_e32 v201, 0xffff0000, v201
	v_fma_f32 v24, v24, v232, v230
	v_fma_f32 v25, v25, v200, v186
	v_fma_f32 v26, v26, v233, v231
	v_fma_f32 v27, v27, v201, v187
	v_fmac_f32_e32 v228, v24, v24
	v_fmac_f32_e32 v228, v25, v25
	v_fmac_f32_e32 v228, v26, v26
	v_fmac_f32_e32 v228, v27, v27
	v_cvt_pk_bf16_f32 v186, v24, v25
	v_cvt_pk_bf16_f32 v187, v26, v27
	global_store_dwordx2 v148, v[186:187], s[62:63] offset:32
	v_mul_f32_e32 v20, v20, v214
	v_mul_f32_e32 v21, v21, v214
	v_mul_f32_e32 v22, v22, v214
	v_mul_f32_e32 v23, v23, v214
	v_mul_f32_e32 v20, 0xbfb8aa3b, v20
	v_mul_f32_e32 v21, 0xbfb8aa3b, v21
	v_mul_f32_e32 v22, 0xbfb8aa3b, v22
	v_mul_f32_e32 v23, 0xbfb8aa3b, v23
	v_exp_f32_e32 v20, v20
	v_exp_f32_e32 v21, v21
	v_exp_f32_e32 v22, v22
	v_exp_f32_e32 v23, v23
	v_add_f32_e32 v20, 1.0, v20
	v_add_f32_e32 v21, 1.0, v21
	v_add_f32_e32 v22, 1.0, v22
	v_add_f32_e32 v23, 1.0, v23
	v_rcp_f32_e32 v220, v20
	v_rcp_f32_e32 v221, v21
	v_rcp_f32_e32 v222, v22
	v_rcp_f32_e32 v223, v23
	v_fma_f32 v224, -v20, v220, 1.0
	v_fma_f32 v225, -v21, v221, 1.0
	v_fma_f32 v226, -v22, v222, 1.0
	v_fma_f32 v227, -v23, v223, 1.0
	v_fma_f32 v20, v224, v220, v220
	v_fma_f32 v21, v225, v221, v221
	v_fma_f32 v22, v226, v222, v222
	v_fma_f32 v23, v227, v223, v223
	v_lshlrev_b32_e32 v230, 16, v202
	v_and_b32_e32 v202, 0xffff0000, v202
	v_lshlrev_b32_e32 v231, 16, v203
	v_and_b32_e32 v203, 0xffff0000, v203
	v_lshlrev_b32_e32 v232, 16, v204
	v_and_b32_e32 v204, 0xffff0000, v204
	v_lshlrev_b32_e32 v233, 16, v205
	v_and_b32_e32 v205, 0xffff0000, v205
	v_fma_f32 v20, v20, v232, v230
	v_fma_f32 v21, v21, v204, v202
	v_fma_f32 v22, v22, v233, v231
	v_fma_f32 v23, v23, v205, v203
	v_fmac_f32_e32 v228, v20, v20
	v_fmac_f32_e32 v228, v21, v21
	v_fmac_f32_e32 v228, v22, v22
	v_fmac_f32_e32 v228, v23, v23
	v_cvt_pk_bf16_f32 v202, v20, v21
	v_cvt_pk_bf16_f32 v203, v22, v23
	global_store_dwordx2 v148, v[202:203], s[62:63] offset:256
	v_mul_f32_e32 v16, v16, v214
	v_mul_f32_e32 v17, v17, v214
	v_mul_f32_e32 v18, v18, v214
	v_mul_f32_e32 v19, v19, v214
	v_mul_f32_e32 v16, 0xbfb8aa3b, v16
	v_mul_f32_e32 v17, 0xbfb8aa3b, v17
	v_mul_f32_e32 v18, 0xbfb8aa3b, v18
	v_mul_f32_e32 v19, 0xbfb8aa3b, v19
	v_exp_f32_e32 v16, v16
	v_exp_f32_e32 v17, v17
	v_exp_f32_e32 v18, v18
	v_exp_f32_e32 v19, v19
	v_add_f32_e32 v16, 1.0, v16
	v_add_f32_e32 v17, 1.0, v17
	v_add_f32_e32 v18, 1.0, v18
	v_add_f32_e32 v19, 1.0, v19
	v_rcp_f32_e32 v220, v16
	v_rcp_f32_e32 v221, v17
	v_rcp_f32_e32 v222, v18
	v_rcp_f32_e32 v223, v19
	v_fma_f32 v224, -v16, v220, 1.0
	v_fma_f32 v225, -v17, v221, 1.0
	v_fma_f32 v226, -v18, v222, 1.0
	v_fma_f32 v227, -v19, v223, 1.0
	v_fma_f32 v16, v224, v220, v220
	v_fma_f32 v17, v225, v221, v221
	v_fma_f32 v18, v226, v222, v222
	v_fma_f32 v19, v227, v223, v223
	v_lshlrev_b32_e32 v230, 16, v134
	v_and_b32_e32 v134, 0xffff0000, v134
	v_lshlrev_b32_e32 v231, 16, v135
	v_and_b32_e32 v135, 0xffff0000, v135
	v_lshlrev_b32_e32 v232, 16, v136
	v_and_b32_e32 v136, 0xffff0000, v136
	v_lshlrev_b32_e32 v233, 16, v137
	v_and_b32_e32 v137, 0xffff0000, v137
	v_fma_f32 v16, v16, v232, v230
	v_fma_f32 v17, v17, v136, v134
	v_fma_f32 v18, v18, v233, v231
	v_fma_f32 v19, v19, v137, v135
	v_fmac_f32_e32 v228, v16, v16
	v_fmac_f32_e32 v228, v17, v17
	v_fmac_f32_e32 v228, v18, v18
	v_fmac_f32_e32 v228, v19, v19
	v_cvt_pk_bf16_f32 v134, v16, v17
	v_cvt_pk_bf16_f32 v135, v18, v19
	global_store_dwordx2 v148, v[134:135], s[62:63] offset:288
	ds_bpermute_b32 v229, v207, v228
	s_waitcnt lgkmcnt(0)
	v_add_f32_e32 v228, v228, v229
	ds_bpermute_b32 v229, v206, v228
	s_waitcnt lgkmcnt(0)
	v_add_f32_e32 v228, v228, v229
	v_add_u32_e32 v252, 0x5000, v198
	v_cmp_gt_u32_e32 vcc, 16, v147
	s_and_saveexec_b64 s[2:3], vcc
	global_store_dword v252, v228, s[98:99]
	s_or_b64 exec, exec, s[2:3]
	v_add_u32_e32 v188, 0xb0000, v140
	v_mul_f32_e32 v12, v12, v215
	v_mul_f32_e32 v13, v13, v215
	v_mul_f32_e32 v14, v14, v215
	v_mul_f32_e32 v15, v15, v215
	v_mul_f32_e32 v12, 0xbfb8aa3b, v12
	v_mul_f32_e32 v13, 0xbfb8aa3b, v13
	v_mul_f32_e32 v14, 0xbfb8aa3b, v14
	v_mul_f32_e32 v15, 0xbfb8aa3b, v15
	v_exp_f32_e32 v12, v12
	v_exp_f32_e32 v13, v13
	v_exp_f32_e32 v14, v14
	v_exp_f32_e32 v15, v15
	v_add_f32_e32 v12, 1.0, v12
	v_add_f32_e32 v13, 1.0, v13
	v_add_f32_e32 v14, 1.0, v14
	v_add_f32_e32 v15, 1.0, v15
	v_rcp_f32_e32 v220, v12
	v_rcp_f32_e32 v221, v13
	v_rcp_f32_e32 v222, v14
	v_rcp_f32_e32 v223, v15
	v_fma_f32 v224, -v12, v220, 1.0
	v_fma_f32 v225, -v13, v221, 1.0
	v_fma_f32 v226, -v14, v222, 1.0
	v_fma_f32 v227, -v15, v223, 1.0
	v_fma_f32 v12, v224, v220, v220
	v_fma_f32 v13, v225, v221, v221
	v_fma_f32 v14, v226, v222, v222
	v_fma_f32 v15, v227, v223, v223
	v_lshlrev_b32_e32 v230, 16, v138
	v_and_b32_e32 v138, 0xffff0000, v138
	v_lshlrev_b32_e32 v231, 16, v139
	v_and_b32_e32 v139, 0xffff0000, v139
	v_lshlrev_b32_e32 v232, 16, v142
	v_and_b32_e32 v142, 0xffff0000, v142
	v_lshlrev_b32_e32 v233, 16, v143
	v_and_b32_e32 v143, 0xffff0000, v143
	v_fma_f32 v12, v12, v232, v230
	v_fma_f32 v13, v13, v142, v138
	v_fma_f32 v14, v14, v233, v231
	v_fma_f32 v15, v15, v143, v139
	v_mul_f32_e32 v228, v12, v12
	v_fmac_f32_e32 v228, v13, v13
	v_fmac_f32_e32 v228, v14, v14
	v_fmac_f32_e32 v228, v15, v15
	v_cvt_pk_bf16_f32 v138, v12, v13
	v_cvt_pk_bf16_f32 v139, v14, v15
	global_store_dwordx2 v188, v[138:139], s[62:63] offset:0
	v_mul_f32_e32 v8, v8, v215
	v_mul_f32_e32 v9, v9, v215
	v_mul_f32_e32 v10, v10, v215
	v_mul_f32_e32 v11, v11, v215
	v_mul_f32_e32 v8, 0xbfb8aa3b, v8
	v_mul_f32_e32 v9, 0xbfb8aa3b, v9
	v_mul_f32_e32 v10, 0xbfb8aa3b, v10
	v_mul_f32_e32 v11, 0xbfb8aa3b, v11
	v_exp_f32_e32 v8, v8
	v_exp_f32_e32 v9, v9
	v_exp_f32_e32 v10, v10
	v_exp_f32_e32 v11, v11
	v_add_f32_e32 v8, 1.0, v8
	v_add_f32_e32 v9, 1.0, v9
	v_add_f32_e32 v10, 1.0, v10
	v_add_f32_e32 v11, 1.0, v11
	v_rcp_f32_e32 v220, v8
	v_rcp_f32_e32 v221, v9
	v_rcp_f32_e32 v222, v10
	v_rcp_f32_e32 v223, v11
	v_fma_f32 v224, -v8, v220, 1.0
	v_fma_f32 v225, -v9, v221, 1.0
	v_fma_f32 v226, -v10, v222, 1.0
	v_fma_f32 v227, -v11, v223, 1.0
	v_fma_f32 v8, v224, v220, v220
	v_fma_f32 v9, v225, v221, v221
	v_fma_f32 v10, v226, v222, v222
	v_fma_f32 v11, v227, v223, v223
	v_lshlrev_b32_e32 v230, 16, v144
	v_and_b32_e32 v144, 0xffff0000, v144
	v_lshlrev_b32_e32 v231, 16, v145
	v_and_b32_e32 v145, 0xffff0000, v145
	v_lshlrev_b32_e32 v232, 16, v190
	v_and_b32_e32 v190, 0xffff0000, v190
	v_lshlrev_b32_e32 v233, 16, v191
	v_and_b32_e32 v191, 0xffff0000, v191
	v_fma_f32 v8, v8, v232, v230
	v_fma_f32 v9, v9, v190, v144
	v_fma_f32 v10, v10, v233, v231
	v_fma_f32 v11, v11, v191, v145
	v_fmac_f32_e32 v228, v8, v8
	v_fmac_f32_e32 v228, v9, v9
	v_fmac_f32_e32 v228, v10, v10
	v_fmac_f32_e32 v228, v11, v11
	v_cvt_pk_bf16_f32 v144, v8, v9
	v_cvt_pk_bf16_f32 v145, v10, v11
	global_store_dwordx2 v188, v[144:145], s[62:63] offset:32
	v_mul_f32_e32 v4, v4, v215
	v_mul_f32_e32 v5, v5, v215
	v_mul_f32_e32 v6, v6, v215
	v_mul_f32_e32 v7, v7, v215
	v_mul_f32_e32 v4, 0xbfb8aa3b, v4
	v_mul_f32_e32 v5, 0xbfb8aa3b, v5
	v_mul_f32_e32 v6, 0xbfb8aa3b, v6
	v_mul_f32_e32 v7, 0xbfb8aa3b, v7
	v_exp_f32_e32 v4, v4
	v_exp_f32_e32 v5, v5
	v_exp_f32_e32 v6, v6
	v_exp_f32_e32 v7, v7
	v_add_f32_e32 v4, 1.0, v4
	v_add_f32_e32 v5, 1.0, v5
	v_add_f32_e32 v6, 1.0, v6
	v_add_f32_e32 v7, 1.0, v7
	v_rcp_f32_e32 v220, v4
	v_rcp_f32_e32 v221, v5
	v_rcp_f32_e32 v222, v6
	v_rcp_f32_e32 v223, v7
	v_fma_f32 v224, -v4, v220, 1.0
	v_fma_f32 v225, -v5, v221, 1.0
	v_fma_f32 v226, -v6, v222, 1.0
	v_fma_f32 v227, -v7, v223, 1.0
	v_fma_f32 v4, v224, v220, v220
	v_fma_f32 v5, v225, v221, v221
	v_fma_f32 v6, v226, v222, v222
	v_fma_f32 v7, v227, v223, v223
	v_lshlrev_b32_e32 v230, 16, v194
	v_and_b32_e32 v194, 0xffff0000, v194
	v_lshlrev_b32_e32 v231, 16, v195
	v_and_b32_e32 v195, 0xffff0000, v195
	v_lshlrev_b32_e32 v232, 16, v248
	v_and_b32_e32 v248, 0xffff0000, v248
	v_lshlrev_b32_e32 v233, 16, v249
	v_and_b32_e32 v249, 0xffff0000, v249
	v_fma_f32 v4, v4, v232, v230
	v_fma_f32 v5, v5, v248, v194
	v_fma_f32 v6, v6, v233, v231
	v_fma_f32 v7, v7, v249, v195
	v_fmac_f32_e32 v228, v4, v4
	v_fmac_f32_e32 v228, v5, v5
	v_fmac_f32_e32 v228, v6, v6
	v_fmac_f32_e32 v228, v7, v7
	v_cvt_pk_bf16_f32 v194, v4, v5
	v_cvt_pk_bf16_f32 v195, v6, v7
	global_store_dwordx2 v188, v[194:195], s[62:63] offset:256
	v_mul_f32_e32 v0, v0, v215
	v_mul_f32_e32 v1, v1, v215
	v_mul_f32_e32 v2, v2, v215
	v_mul_f32_e32 v3, v3, v215
	v_mul_f32_e32 v0, 0xbfb8aa3b, v0
	v_mul_f32_e32 v1, 0xbfb8aa3b, v1
	v_mul_f32_e32 v2, 0xbfb8aa3b, v2
	v_mul_f32_e32 v3, 0xbfb8aa3b, v3
	v_exp_f32_e32 v0, v0
	v_exp_f32_e32 v1, v1
	v_exp_f32_e32 v2, v2
	v_exp_f32_e32 v3, v3
	v_add_f32_e32 v0, 1.0, v0
	v_add_f32_e32 v1, 1.0, v1
	v_add_f32_e32 v2, 1.0, v2
	v_add_f32_e32 v3, 1.0, v3
	v_rcp_f32_e32 v220, v0
	v_rcp_f32_e32 v221, v1
	v_rcp_f32_e32 v222, v2
	v_rcp_f32_e32 v223, v3
	v_fma_f32 v224, -v0, v220, 1.0
	v_fma_f32 v225, -v1, v221, 1.0
	v_fma_f32 v226, -v2, v222, 1.0
	v_fma_f32 v227, -v3, v223, 1.0
	v_fma_f32 v0, v224, v220, v220
	v_fma_f32 v1, v225, v221, v221
	v_fma_f32 v2, v226, v222, v222
	v_fma_f32 v3, v227, v223, v223
	v_lshlrev_b32_e32 v230, 16, v150
	v_and_b32_e32 v150, 0xffff0000, v150
	v_lshlrev_b32_e32 v231, 16, v151
	v_and_b32_e32 v151, 0xffff0000, v151
	v_lshlrev_b32_e32 v232, 16, v234
	v_and_b32_e32 v234, 0xffff0000, v234
	v_lshlrev_b32_e32 v233, 16, v235
	v_and_b32_e32 v235, 0xffff0000, v235
	v_fma_f32 v0, v0, v232, v230
	v_fma_f32 v1, v1, v234, v150
	v_fma_f32 v2, v2, v233, v231
	v_fma_f32 v3, v3, v235, v151
	v_fmac_f32_e32 v228, v0, v0
	v_fmac_f32_e32 v228, v1, v1
	v_fmac_f32_e32 v228, v2, v2
	v_fmac_f32_e32 v228, v3, v3
	v_cvt_pk_bf16_f32 v150, v0, v1
	v_cvt_pk_bf16_f32 v151, v2, v3
	global_store_dwordx2 v188, v[150:151], s[62:63] offset:288
	ds_bpermute_b32 v229, v207, v228
	s_waitcnt lgkmcnt(0)
	v_add_f32_e32 v228, v228, v229
	ds_bpermute_b32 v229, v206, v228
	s_waitcnt lgkmcnt(0)
	v_add_f32_e32 v228, v228, v229
	v_add_u32_e32 v252, 0x5800, v198
	v_cmp_gt_u32_e32 vcc, 16, v147
	s_and_saveexec_b64 s[2:3], vcc
	global_store_dword v252, v228, s[98:99]
	s_or_b64 exec, exec, s[2:3]
	s_and_b64 vcc, exec, s[40:41]
	s_cbranch_vccz .LBB0_640
	s_waitcnt vmcnt(0)
	s_cmpk_gt_u32 s89, 0xff
	s_cbranch_scc1 .LBB0_651
	s_barrier

.Lprio_665:
	s_add_u32 s1, s40, 0xfff80080
	s_addc_u32 s2, s41, -1
	s_add_i32 s3, 0, 0x10000
	v_add_u32_e32 v138, s3, v141
	ds_read_b128 v[134:137], v138
	ds_read_b128 v[142:145], v138 offset:1024
	ds_read_b128 v[150:153], v138 offset:2048
	ds_read_b128 v[154:157], v138 offset:3072
	s_cmp_eq_u32 s90, 28
	s_cselect_b32 s75, s47, s2
	s_cselect_b32 s74, s53, s1
	s_cselect_b32 s73, s45, s89
	s_cselect_b32 s72, s60, s61
	v_lshl_add_u64 v[138:139], s[40:41], 0, v[130:131]
	s_add_i32 m0, s79, 0xc000
	ds_read_b128 v[158:161], v149
	ds_read_b128 v[162:165], v149 offset:1024
	ds_read_b128 v[166:169], v149 offset:2048
	ds_read_b128 v[170:173], v149 offset:3072
	ds_read_b128 v[182:185], v149 offset:4096
	ds_read_b128 v[200:203], v149 offset:5120
	ds_read_b128 v[208:211], v149 offset:6144
	ds_read_b128 v[212:215], v149 offset:7168
	global_load_lds_dwordx4 v[138:139], off
	v_lshl_add_u64 v[138:139], s[40:41], 0, v[132:133]
	s_add_i32 m0, s79, 0xe000
	s_nop 0
	global_load_lds_dwordx4 v[138:139], off
	s_waitcnt lgkmcnt(8)
	s_barrier
	s_waitcnt lgkmcnt(0)
	s_waitcnt lgkmcnt(0)
	v_mfma_f32_16x16x32_bf16 v[124:127], v[134:137], v[158:161], v[124:127]
	v_mfma_f32_16x16x32_bf16 v[120:123], v[150:153], v[158:161], v[120:123]
	v_mfma_f32_16x16x32_bf16 v[108:111], v[134:137], v[166:169], v[108:111]
	v_mfma_f32_16x16x32_bf16 v[104:107], v[150:153], v[166:169], v[104:107]
	v_mfma_f32_16x16x32_bf16 v[92:95], v[134:137], v[182:185], v[92:95]
	v_mfma_f32_16x16x32_bf16 v[88:91], v[150:153], v[182:185], v[88:91]
	v_mfma_f32_16x16x32_bf16 v[76:79], v[134:137], v[208:211], v[76:79]
	v_mfma_f32_16x16x32_bf16 v[72:75], v[150:153], v[208:211], v[72:75]
	v_mfma_f32_16x16x32_bf16 v[124:127], v[142:145], v[162:165], v[124:127]
	v_mfma_f32_16x16x32_bf16 v[120:123], v[154:157], v[162:165], v[120:123]
	v_mfma_f32_16x16x32_bf16 v[108:111], v[142:145], v[170:173], v[108:111]
	v_mfma_f32_16x16x32_bf16 v[104:107], v[154:157], v[170:173], v[104:107]
	v_mfma_f32_16x16x32_bf16 v[92:95], v[142:145], v[200:203], v[92:95]
	v_mfma_f32_16x16x32_bf16 v[88:91], v[154:157], v[200:203], v[88:91]
	v_mfma_f32_16x16x32_bf16 v[76:79], v[142:145], v[212:215], v[76:79]
	v_mfma_f32_16x16x32_bf16 v[72:75], v[154:157], v[212:215], v[72:75]
	s_barrier
	s_add_i32 s1, 0, 0x14000
	v_add_u32_e32 v138, s1, v141
	s_add_i32 s2, s3, s78
	ds_read_b128 v[216:219], v138
	ds_read_b128 v[220:223], v138 offset:1024
	ds_read_b128 v[224:227], v138 offset:2048
	ds_read_b128 v[228:231], v138 offset:3072
	v_lshl_add_u64 v[138:139], s[72:73], 0, v[176:177]
	s_mov_b32 m0, s2
	v_lshl_add_u64 v[174:175], s[72:73], 0, v[128:129]
	global_load_lds_dwordx4 v[138:139], off
	s_add_i32 m0, s2, 0x2000
	s_nop 0
	global_load_lds_dwordx4 v[174:175], off
	s_barrier
	s_waitcnt lgkmcnt(0)
	s_waitcnt lgkmcnt(0)
	v_mfma_f32_16x16x32_bf16 v[116:119], v[216:219], v[158:161], v[116:119]
	v_mfma_f32_16x16x32_bf16 v[112:115], v[224:227], v[158:161], v[112:115]
	v_mfma_f32_16x16x32_bf16 v[100:103], v[216:219], v[166:169], v[100:103]
	v_mfma_f32_16x16x32_bf16 v[96:99], v[224:227], v[166:169], v[96:99]
	v_mfma_f32_16x16x32_bf16 v[84:87], v[216:219], v[182:185], v[84:87]
	v_mfma_f32_16x16x32_bf16 v[80:83], v[224:227], v[182:185], v[80:83]
	v_mfma_f32_16x16x32_bf16 v[68:71], v[216:219], v[208:211], v[68:71]
	v_mfma_f32_16x16x32_bf16 v[64:67], v[224:227], v[208:211], v[64:67]
	v_mfma_f32_16x16x32_bf16 v[116:119], v[220:223], v[162:165], v[116:119]
	v_mfma_f32_16x16x32_bf16 v[112:115], v[228:231], v[162:165], v[112:115]
	v_mfma_f32_16x16x32_bf16 v[100:103], v[220:223], v[170:173], v[100:103]
	v_mfma_f32_16x16x32_bf16 v[96:99], v[228:231], v[170:173], v[96:99]
	v_mfma_f32_16x16x32_bf16 v[84:87], v[220:223], v[200:203], v[84:87]
	v_mfma_f32_16x16x32_bf16 v[80:83], v[228:231], v[200:203], v[80:83]
	v_mfma_f32_16x16x32_bf16 v[68:71], v[220:223], v[212:215], v[68:71]
	v_mfma_f32_16x16x32_bf16 v[64:67], v[228:231], v[212:215], v[64:67]
	s_mov_b32 m0, s79
	v_lshl_add_u64 v[186:187], s[74:75], 0, v[176:177]
	s_barrier
	ds_read_b128 v[158:161], v149 offset:16384
	ds_read_b128 v[162:165], v149 offset:17408
	ds_read_b128 v[166:169], v149 offset:18432
	ds_read_b128 v[170:173], v149 offset:19456
	ds_read_b128 v[182:185], v149 offset:20480
	ds_read_b128 v[200:203], v149 offset:21504
	ds_read_b128 v[208:211], v149 offset:22528
	ds_read_b128 v[212:215], v149 offset:23552
	global_load_lds_dwordx4 v[186:187], off
	v_lshl_add_u64 v[190:191], s[74:75], 0, v[128:129]
	s_mov_b32 m0, s80
	s_nop 0
	global_load_lds_dwordx4 v[190:191], off
	s_barrier
	s_waitcnt lgkmcnt(0)
	s_waitcnt lgkmcnt(0)
	v_mfma_f32_16x16x32_bf16 v[60:63], v[134:137], v[158:161], v[60:63]
	v_mfma_f32_16x16x32_bf16 v[56:59], v[150:153], v[158:161], v[56:59]
	v_mfma_f32_16x16x32_bf16 v[44:47], v[134:137], v[166:169], v[44:47]
	v_mfma_f32_16x16x32_bf16 v[40:43], v[150:153], v[166:169], v[40:43]
	v_mfma_f32_16x16x32_bf16 v[28:31], v[134:137], v[182:185], v[28:31]
	v_mfma_f32_16x16x32_bf16 v[24:27], v[150:153], v[182:185], v[24:27]
	v_mfma_f32_16x16x32_bf16 v[12:15], v[134:137], v[208:211], v[12:15]
	v_mfma_f32_16x16x32_bf16 v[8:11], v[150:153], v[208:211], v[8:11]
	v_mfma_f32_16x16x32_bf16 v[60:63], v[142:145], v[162:165], v[60:63]
	v_mfma_f32_16x16x32_bf16 v[56:59], v[154:157], v[162:165], v[56:59]
	v_mfma_f32_16x16x32_bf16 v[44:47], v[142:145], v[170:173], v[44:47]
	v_mfma_f32_16x16x32_bf16 v[40:43], v[154:157], v[170:173], v[40:43]
	v_mfma_f32_16x16x32_bf16 v[28:31], v[142:145], v[200:203], v[28:31]
	v_mfma_f32_16x16x32_bf16 v[24:27], v[154:157], v[200:203], v[24:27]
	v_mfma_f32_16x16x32_bf16 v[12:15], v[142:145], v[212:215], v[12:15]
	v_mfma_f32_16x16x32_bf16 v[8:11], v[154:157], v[212:215], v[8:11]
	s_barrier
	s_add_u32 s2, s72, 0x80000
	s_addc_u32 s3, s73, 0
	s_add_i32 s1, s1, s78
	v_lshl_add_u64 v[134:135], s[2:3], 0, v[176:177]
	s_mov_b32 m0, s1
	s_nop 0
	global_load_lds_dwordx4 v[134:135], off
	v_lshl_add_u64 v[134:135], s[2:3], 0, v[128:129]
	s_add_i32 m0, s1, 0x2000
	s_nop 0
	global_load_lds_dwordx4 v[134:135], off
	s_waitcnt vmcnt(6)
	s_barrier
	v_mfma_f32_16x16x32_bf16 v[52:55], v[216:219], v[158:161], v[52:55]
	v_mfma_f32_16x16x32_bf16 v[48:51], v[224:227], v[158:161], v[48:51]
	v_mfma_f32_16x16x32_bf16 v[36:39], v[216:219], v[166:169], v[36:39]
	v_mfma_f32_16x16x32_bf16 v[32:35], v[224:227], v[166:169], v[32:35]
	v_mfma_f32_16x16x32_bf16 v[20:23], v[216:219], v[182:185], v[20:23]
	v_mfma_f32_16x16x32_bf16 v[16:19], v[224:227], v[182:185], v[16:19]
	v_mfma_f32_16x16x32_bf16 v[4:7], v[216:219], v[208:211], v[4:7]
	v_mfma_f32_16x16x32_bf16 v[0:3], v[224:227], v[208:211], v[0:3]
	v_mfma_f32_16x16x32_bf16 v[52:55], v[220:223], v[162:165], v[52:55]
	v_mfma_f32_16x16x32_bf16 v[48:51], v[228:231], v[162:165], v[48:51]
	v_mfma_f32_16x16x32_bf16 v[36:39], v[220:223], v[170:173], v[36:39]
	v_mfma_f32_16x16x32_bf16 v[32:35], v[228:231], v[170:173], v[32:35]
	v_mfma_f32_16x16x32_bf16 v[20:23], v[220:223], v[200:203], v[20:23]
	v_mfma_f32_16x16x32_bf16 v[16:19], v[228:231], v[200:203], v[16:19]
	v_mfma_f32_16x16x32_bf16 v[4:7], v[220:223], v[212:215], v[4:7]
	v_mfma_f32_16x16x32_bf16 v[0:3], v[228:231], v[212:215], v[0:3]
	s_add_i32 s1, 0, 0x18000
	v_add_u32_e32 v140, s1, v141
	s_barrier
	ds_read_b128 v[134:137], v140
	ds_read_b128 v[142:145], v140 offset:1024
	ds_read_b128 v[150:153], v140 offset:2048
	ds_read_b128 v[154:157], v140 offset:3072
	s_add_u32 s2, s74, 0x80000
	s_addc_u32 s3, s75, 0
	s_mov_b32 m0, s81
	v_lshl_add_u64 v[194:195], s[2:3], 0, v[176:177]
	ds_read_b128 v[158:161], v149 offset:32768
	ds_read_b128 v[162:165], v149 offset:33792
	ds_read_b128 v[166:169], v149 offset:34816
	ds_read_b128 v[170:173], v149 offset:35840
	ds_read_b128 v[182:185], v149 offset:36864
	ds_read_b128 v[200:203], v149 offset:37888
	ds_read_b128 v[208:211], v149 offset:38912
	ds_read_b128 v[212:215], v149 offset:39936
	global_load_lds_dwordx4 v[194:195], off
	v_lshl_add_u64 v[194:195], s[2:3], 0, v[128:129]
	s_mov_b32 m0, s82
	s_nop 0
	global_load_lds_dwordx4 v[194:195], off
	s_waitcnt lgkmcnt(8)
	s_barrier
	s_waitcnt lgkmcnt(0)
	s_waitcnt lgkmcnt(0)
	v_mfma_f32_16x16x32_bf16 v[124:127], v[134:137], v[158:161], v[124:127]
	v_mfma_f32_16x16x32_bf16 v[120:123], v[150:153], v[158:161], v[120:123]
	v_mfma_f32_16x16x32_bf16 v[108:111], v[134:137], v[166:169], v[108:111]
	v_mfma_f32_16x16x32_bf16 v[104:107], v[150:153], v[166:169], v[104:107]
	v_mfma_f32_16x16x32_bf16 v[92:95], v[134:137], v[182:185], v[92:95]
	v_mfma_f32_16x16x32_bf16 v[88:91], v[150:153], v[182:185], v[88:91]
	v_mfma_f32_16x16x32_bf16 v[76:79], v[134:137], v[208:211], v[76:79]
	v_mfma_f32_16x16x32_bf16 v[72:75], v[150:153], v[208:211], v[72:75]
	v_mfma_f32_16x16x32_bf16 v[124:127], v[142:145], v[162:165], v[124:127]
	v_mfma_f32_16x16x32_bf16 v[120:123], v[154:157], v[162:165], v[120:123]
	v_mfma_f32_16x16x32_bf16 v[108:111], v[142:145], v[170:173], v[108:111]
	v_mfma_f32_16x16x32_bf16 v[104:107], v[154:157], v[170:173], v[104:107]
	v_mfma_f32_16x16x32_bf16 v[92:95], v[142:145], v[200:203], v[92:95]
	v_mfma_f32_16x16x32_bf16 v[88:91], v[154:157], v[200:203], v[88:91]
	v_mfma_f32_16x16x32_bf16 v[76:79], v[142:145], v[212:215], v[76:79]
	v_mfma_f32_16x16x32_bf16 v[72:75], v[154:157], v[212:215], v[72:75]
	s_barrier
	s_add_i32 s12, 0, 0x1c000
	s_add_i32 s1, s1, s78
	v_add_u32_e32 v140, s12, v141
	v_lshl_add_u64 v[138:139], v[138:139], 0, s[20:21]
	s_mov_b32 m0, s1
	ds_read_b128 v[216:219], v140
	ds_read_b128 v[220:223], v140 offset:1024
	ds_read_b128 v[224:227], v140 offset:2048
	ds_read_b128 v[228:231], v140 offset:3072
	global_load_lds_dwordx4 v[138:139], off
	v_lshl_add_u64 v[138:139], v[174:175], 0, s[20:21]
	s_add_i32 m0, s1, 0x2000
	s_nop 0
	global_load_lds_dwordx4 v[138:139], off
	s_barrier
	s_waitcnt lgkmcnt(0)
	s_waitcnt lgkmcnt(0)
	v_mfma_f32_16x16x32_bf16 v[116:119], v[216:219], v[158:161], v[116:119]
	v_mfma_f32_16x16x32_bf16 v[112:115], v[224:227], v[158:161], v[112:115]
	v_mfma_f32_16x16x32_bf16 v[100:103], v[216:219], v[166:169], v[100:103]
	v_mfma_f32_16x16x32_bf16 v[96:99], v[224:227], v[166:169], v[96:99]
	v_mfma_f32_16x16x32_bf16 v[84:87], v[216:219], v[182:185], v[84:87]
	v_mfma_f32_16x16x32_bf16 v[80:83], v[224:227], v[182:185], v[80:83]
	v_mfma_f32_16x16x32_bf16 v[68:71], v[216:219], v[208:211], v[68:71]
	v_mfma_f32_16x16x32_bf16 v[64:67], v[224:227], v[208:211], v[64:67]
	v_mfma_f32_16x16x32_bf16 v[116:119], v[220:223], v[162:165], v[116:119]
	v_mfma_f32_16x16x32_bf16 v[112:115], v[228:231], v[162:165], v[112:115]
	v_mfma_f32_16x16x32_bf16 v[100:103], v[220:223], v[170:173], v[100:103]
	v_mfma_f32_16x16x32_bf16 v[96:99], v[228:231], v[170:173], v[96:99]
	v_mfma_f32_16x16x32_bf16 v[84:87], v[220:223], v[200:203], v[84:87]
	v_mfma_f32_16x16x32_bf16 v[80:83], v[228:231], v[200:203], v[80:83]
	v_mfma_f32_16x16x32_bf16 v[68:71], v[220:223], v[212:215], v[68:71]
	v_mfma_f32_16x16x32_bf16 v[64:67], v[228:231], v[212:215], v[64:67]
	s_mov_b32 m0, s87
	v_lshl_add_u64 v[138:139], v[186:187], 0, s[20:21]
	s_barrier
	ds_read_b128 v[158:161], v149 offset:49152
	ds_read_b128 v[162:165], v149 offset:50176
	ds_read_b128 v[166:169], v149 offset:51200
	ds_read_b128 v[170:173], v149 offset:52224
	ds_read_b128 v[182:185], v149 offset:53248
	ds_read_b128 v[200:203], v149 offset:54272
	ds_read_b128 v[208:211], v149 offset:55296
	ds_read_b128 v[212:215], v149 offset:56320
	global_load_lds_dwordx4 v[138:139], off
	v_lshl_add_u64 v[138:139], v[190:191], 0, s[20:21]
	s_mov_b32 m0, s77
	s_nop 0
	global_load_lds_dwordx4 v[138:139], off
	s_barrier
	s_waitcnt lgkmcnt(0)
	s_waitcnt lgkmcnt(0)
	v_mfma_f32_16x16x32_bf16 v[60:63], v[134:137], v[158:161], v[60:63]
	v_mfma_f32_16x16x32_bf16 v[56:59], v[150:153], v[158:161], v[56:59]
	v_mfma_f32_16x16x32_bf16 v[44:47], v[134:137], v[166:169], v[44:47]
	v_mfma_f32_16x16x32_bf16 v[40:43], v[150:153], v[166:169], v[40:43]
	v_mfma_f32_16x16x32_bf16 v[28:31], v[134:137], v[182:185], v[28:31]
	v_mfma_f32_16x16x32_bf16 v[24:27], v[150:153], v[182:185], v[24:27]
	v_mfma_f32_16x16x32_bf16 v[12:15], v[134:137], v[208:211], v[12:15]
	v_mfma_f32_16x16x32_bf16 v[8:11], v[150:153], v[208:211], v[8:11]
	v_mfma_f32_16x16x32_bf16 v[60:63], v[142:145], v[162:165], v[60:63]
	v_mfma_f32_16x16x32_bf16 v[56:59], v[154:157], v[162:165], v[56:59]
	v_mfma_f32_16x16x32_bf16 v[44:47], v[142:145], v[170:173], v[44:47]
	v_mfma_f32_16x16x32_bf16 v[40:43], v[154:157], v[170:173], v[40:43]
	v_mfma_f32_16x16x32_bf16 v[28:31], v[142:145], v[200:203], v[28:31]
	v_mfma_f32_16x16x32_bf16 v[24:27], v[154:157], v[200:203], v[24:27]
	v_mfma_f32_16x16x32_bf16 v[12:15], v[142:145], v[212:215], v[12:15]
	v_mfma_f32_16x16x32_bf16 v[8:11], v[154:157], v[212:215], v[8:11]
	s_barrier
	s_add_u32 s2, s72, 0x80080
	s_addc_u32 s3, s73, 0
	s_add_i32 s1, s12, s78
	v_lshl_add_u64 v[134:135], s[2:3], 0, v[176:177]
	s_mov_b32 m0, s1
	s_nop 0
	global_load_lds_dwordx4 v[134:135], off
	v_lshl_add_u64 v[134:135], s[2:3], 0, v[128:129]
	s_add_i32 m0, s1, 0x2000
	s_nop 0
	global_load_lds_dwordx4 v[134:135], off
	s_waitcnt vmcnt(6)
	s_barrier
	v_mfma_f32_16x16x32_bf16 v[52:55], v[216:219], v[158:161], v[52:55]
	v_mfma_f32_16x16x32_bf16 v[48:51], v[224:227], v[158:161], v[48:51]
	v_mfma_f32_16x16x32_bf16 v[36:39], v[216:219], v[166:169], v[36:39]
	v_mfma_f32_16x16x32_bf16 v[32:35], v[224:227], v[166:169], v[32:35]
	v_mfma_f32_16x16x32_bf16 v[20:23], v[216:219], v[182:185], v[20:23]
	v_mfma_f32_16x16x32_bf16 v[16:19], v[224:227], v[182:185], v[16:19]
	v_mfma_f32_16x16x32_bf16 v[4:7], v[216:219], v[208:211], v[4:7]
	v_mfma_f32_16x16x32_bf16 v[0:3], v[224:227], v[208:211], v[0:3]
	v_mfma_f32_16x16x32_bf16 v[52:55], v[220:223], v[162:165], v[52:55]
	v_mfma_f32_16x16x32_bf16 v[48:51], v[228:231], v[162:165], v[48:51]
	v_mfma_f32_16x16x32_bf16 v[36:39], v[220:223], v[170:173], v[36:39]
	v_mfma_f32_16x16x32_bf16 v[32:35], v[228:231], v[170:173], v[32:35]
	v_mfma_f32_16x16x32_bf16 v[20:23], v[220:223], v[200:203], v[20:23]
	v_mfma_f32_16x16x32_bf16 v[16:19], v[228:231], v[200:203], v[16:19]
	v_mfma_f32_16x16x32_bf16 v[4:7], v[220:223], v[212:215], v[4:7]
	v_mfma_f32_16x16x32_bf16 v[0:3], v[228:231], v[212:215], v[0:3]
	s_add_i32 s90, s90, 2
	s_add_u32 s40, s40, 0x100
	s_addc_u32 s41, s41, 0
	s_add_u32 s61, s61, 0x100
	s_addc_u32 s89, s89, 0
	s_cmp_gt_u32 s90, 29
	s_barrier
	s_cbranch_scc0 .LBB0_665
	s_setprio 0
	v_and_b32_e32 v198, 15, v147
	v_ashrrev_i32_e32 v252, 4, v147
	s_lshl_b32 s1, s52, 8
	s_add_i32 s1, s1, s83
	v_or_b32_e32 v198, s1, v198
	s_lshl_b32 s1, s49, 8
	s_or_b32 s1, s1, s86
	v_lshl_add_u32 v140, v252, 2, s1
	v_lshl_add_u32 v140, v198, 11, v140
	v_lshlrev_b32_e32 v140, 1, v140
	v_lshlrev_b32_e32 v146, 5, v252
	v_lshl_add_u32 v146, v198, 7, v146
	v_readlane_b32 s90, v255, 23
	v_readlane_b32 s30, v255, 27
	s_mov_b32 s49, s44
	s_mov_b32 s52, s46
	s_mov_b64 s[72:73], s[70:71]
	v_readlane_b32 s91, v255, 24
	v_readlane_b32 s31, v255, 28
	s_mov_b64 s[40:41], s[68:69]
	v_mov_b32_e32 v148, v146
	global_load_dwordx4 v[208:211], v148, s[16:17]
	global_load_dwordx4 v[212:215], v148, s[16:17] offset:16
	v_add_u32_e32 v188, 0x800, v146
	global_load_dwordx4 v[216:219], v188, s[16:17]
	global_load_dwordx4 v[220:223], v188, s[16:17] offset:16
	v_add_u32_e32 v192, 0x1000, v146
	global_load_dwordx4 v[224:227], v192, s[16:17]
	global_load_dwordx4 v[228:231], v192, s[16:17] offset:16
	v_add_u32_e32 v196, 0x1800, v146
	global_load_dwordx4 v[232:235], v196, s[16:17]
	global_load_dwordx4 v[236:239], v196, s[16:17] offset:16
	v_mov_b32_e32 v148, v140
	global_load_dwordx2 v[152:153], v148, s[58:59] offset:0
	global_load_dwordx2 v[154:155], v148, s[56:57] offset:0
	global_load_dwordx2 v[156:157], v148, s[58:59] offset:32
	global_load_dwordx2 v[158:159], v148, s[56:57] offset:32
	global_load_dwordx2 v[160:161], v148, s[58:59] offset:256
	global_load_dwordx2 v[162:163], v148, s[56:57] offset:256
	global_load_dwordx2 v[164:165], v148, s[58:59] offset:288
	global_load_dwordx2 v[166:167], v148, s[56:57] offset:288
	v_add_u32_e32 v188, 0x10000, v140
	global_load_dwordx2 v[168:169], v188, s[58:59] offset:0
	global_load_dwordx2 v[170:171], v188, s[56:57] offset:0
	global_load_dwordx2 v[172:173], v188, s[58:59] offset:32
	global_load_dwordx2 v[174:175], v188, s[56:57] offset:32
	global_load_dwordx2 v[240:241], v188, s[58:59] offset:256
	global_load_dwordx2 v[242:243], v188, s[56:57] offset:256
	global_load_dwordx2 v[244:245], v188, s[58:59] offset:288
	global_load_dwordx2 v[246:247], v188, s[56:57] offset:288
	v_add_u32_e32 v192, 0x20000, v140
	global_load_dwordx2 v[182:183], v192, s[58:59] offset:0
	global_load_dwordx2 v[184:185], v192, s[56:57] offset:0
	global_load_dwordx2 v[186:187], v192, s[58:59] offset:32
	global_load_dwordx2 v[200:201], v192, s[56:57] offset:32
	global_load_dwordx2 v[202:203], v192, s[58:59] offset:256
	global_load_dwordx2 v[204:205], v192, s[56:57] offset:256
	global_load_dwordx2 v[134:135], v192, s[58:59] offset:288
	global_load_dwordx2 v[136:137], v192, s[56:57] offset:288
	v_add_u32_e32 v196, 0x30000, v140
	global_load_dwordx2 v[138:139], v196, s[58:59] offset:0
	global_load_dwordx2 v[142:143], v196, s[56:57] offset:0
	global_load_dwordx2 v[144:145], v196, s[58:59] offset:32
	global_load_dwordx2 v[190:191], v196, s[56:57] offset:32
	global_load_dwordx2 v[194:195], v196, s[58:59] offset:256
	global_load_dwordx2 v[248:249], v196, s[56:57] offset:256
	global_load_dwordx2 v[150:151], v196, s[58:59] offset:288
	s_waitcnt vmcnt(31)
	v_add_f32_e32 v208, v208, v209
	v_add_f32_e32 v210, v210, v211
	v_add_f32_e32 v212, v212, v213
	v_add_f32_e32 v214, v214, v215
	v_add_f32_e32 v208, v208, v210
	v_add_f32_e32 v212, v212, v214
	v_add_f32_e32 v208, v208, v212
	v_add_f32_e32 v216, v216, v217
	v_add_f32_e32 v218, v218, v219
	v_add_f32_e32 v220, v220, v221
	v_add_f32_e32 v222, v222, v223
	v_add_f32_e32 v216, v216, v218
	v_add_f32_e32 v220, v220, v222
	v_add_f32_e32 v216, v216, v220
	v_add_f32_e32 v224, v224, v225
	v_add_f32_e32 v226, v226, v227
	v_add_f32_e32 v228, v228, v229
	v_add_f32_e32 v230, v230, v231
	v_add_f32_e32 v224, v224, v226
	v_add_f32_e32 v228, v228, v230
	v_add_f32_e32 v224, v224, v228
	v_add_f32_e32 v232, v232, v233
	v_add_f32_e32 v234, v234, v235
	v_add_f32_e32 v236, v236, v237
	v_add_f32_e32 v238, v238, v239
	v_add_f32_e32 v232, v232, v234
	v_add_f32_e32 v236, v236, v238
	v_add_f32_e32 v232, v232, v236
	ds_bpermute_b32 v209, v207, v208
	ds_bpermute_b32 v217, v207, v216
	ds_bpermute_b32 v225, v207, v224
	ds_bpermute_b32 v233, v207, v232
	s_waitcnt lgkmcnt(0)
	v_add_f32_e32 v208, v208, v209
	v_add_f32_e32 v216, v216, v217
	v_add_f32_e32 v224, v224, v225
	v_add_f32_e32 v232, v232, v233
	ds_bpermute_b32 v209, v206, v208
	ds_bpermute_b32 v217, v206, v216
	ds_bpermute_b32 v225, v206, v224
	ds_bpermute_b32 v233, v206, v232
	s_waitcnt lgkmcnt(0)
	v_add_f32_e32 v208, v208, v209
	v_add_f32_e32 v216, v216, v217
	v_add_f32_e32 v224, v224, v225
	v_add_f32_e32 v232, v232, v233
	v_mul_f32_e32 v208, 0x3a000000, v208
	v_add_f32_e32 v208, 0x358637bd, v208
	v_mul_f32_e32 v216, 0x3a000000, v216
	v_add_f32_e32 v216, 0x358637bd, v216
	v_mul_f32_e32 v224, 0x3a000000, v224
	v_add_f32_e32 v224, 0x358637bd, v224
	v_mul_f32_e32 v232, 0x3a000000, v232
	v_add_f32_e32 v232, 0x358637bd, v232
	v_rsq_f32_e32 v208, v208
	v_rsq_f32_e32 v216, v216
	v_rsq_f32_e32 v224, v224
	v_rsq_f32_e32 v232, v232
	s_nop 0
	v_mov_b32_e32 v209, v216
	v_mov_b32_e32 v210, v224
	v_mov_b32_e32 v211, v232
	v_add_u32_e32 v148, 0x30000, v140
	global_load_dwordx2 v[238:239], v148, s[56:57] offset:288
	s_waitcnt vmcnt(16)
	v_mov_b32_e32 v188, v140
	v_mul_f32_e32 v124, v124, v208
	v_mul_f32_e32 v125, v125, v208
	v_mul_f32_e32 v126, v126, v208
	v_mul_f32_e32 v127, v127, v208
	v_mul_f32_e32 v124, 0xbfb8aa3b, v124
	v_mul_f32_e32 v125, 0xbfb8aa3b, v125
	v_mul_f32_e32 v126, 0xbfb8aa3b, v126
	v_mul_f32_e32 v127, 0xbfb8aa3b, v127
	v_exp_f32_e32 v124, v124
	v_exp_f32_e32 v125, v125
	v_exp_f32_e32 v126, v126
	v_exp_f32_e32 v127, v127
	v_add_f32_e32 v124, 1.0, v124
	v_add_f32_e32 v125, 1.0, v125
	v_add_f32_e32 v126, 1.0, v126
	v_add_f32_e32 v127, 1.0, v127
	v_rcp_f32_e32 v220, v124
	v_rcp_f32_e32 v221, v125
	v_rcp_f32_e32 v222, v126
	v_rcp_f32_e32 v223, v127
	v_fma_f32 v224, -v124, v220, 1.0
	v_fma_f32 v225, -v125, v221, 1.0
	v_fma_f32 v226, -v126, v222, 1.0
	v_fma_f32 v227, -v127, v223, 1.0
	v_fma_f32 v124, v224, v220, v220
	v_fma_f32 v125, v225, v221, v221
	v_fma_f32 v126, v226, v222, v222
	v_fma_f32 v127, v227, v223, v223
	v_lshlrev_b32_e32 v230, 16, v152
	v_and_b32_e32 v152, 0xffff0000, v152
	v_lshlrev_b32_e32 v231, 16, v153
	v_and_b32_e32 v153, 0xffff0000, v153
	v_lshlrev_b32_e32 v232, 16, v154
	v_and_b32_e32 v154, 0xffff0000, v154
	v_lshlrev_b32_e32 v233, 16, v155
	v_and_b32_e32 v155, 0xffff0000, v155
	v_fma_f32 v124, v124, v232, v230
	v_fma_f32 v125, v125, v154, v152
	v_fma_f32 v126, v126, v233, v231
	v_fma_f32 v127, v127, v155, v153
	v_lshlrev_b32_e32 v252, 1, v188
	global_store_dwordx4 v252, v[124:127], s[42:43] offset:0
	v_mul_f32_e32 v120, v120, v208
	v_mul_f32_e32 v121, v121, v208
	v_mul_f32_e32 v122, v122, v208
	v_mul_f32_e32 v123, v123, v208
	v_mul_f32_e32 v120, 0xbfb8aa3b, v120
	v_mul_f32_e32 v121, 0xbfb8aa3b, v121
	v_mul_f32_e32 v122, 0xbfb8aa3b, v122
	v_mul_f32_e32 v123, 0xbfb8aa3b, v123
	v_exp_f32_e32 v120, v120
	v_exp_f32_e32 v121, v121
	v_exp_f32_e32 v122, v122
	v_exp_f32_e32 v123, v123
	v_add_f32_e32 v120, 1.0, v120
	v_add_f32_e32 v121, 1.0, v121
	v_add_f32_e32 v122, 1.0, v122
	v_add_f32_e32 v123, 1.0, v123
	v_rcp_f32_e32 v220, v120
	v_rcp_f32_e32 v221, v121
	v_rcp_f32_e32 v222, v122
	v_rcp_f32_e32 v223, v123
	v_fma_f32 v224, -v120, v220, 1.0
	v_fma_f32 v225, -v121, v221, 1.0
	v_fma_f32 v226, -v122, v222, 1.0
	v_fma_f32 v227, -v123, v223, 1.0
	v_fma_f32 v120, v224, v220, v220
	v_fma_f32 v121, v225, v221, v221
	v_fma_f32 v122, v226, v222, v222
	v_fma_f32 v123, v227, v223, v223
	v_lshlrev_b32_e32 v230, 16, v156
	v_and_b32_e32 v156, 0xffff0000, v156
	v_lshlrev_b32_e32 v231, 16, v157
	v_and_b32_e32 v157, 0xffff0000, v157
	v_lshlrev_b32_e32 v232, 16, v158
	v_and_b32_e32 v158, 0xffff0000, v158
	v_lshlrev_b32_e32 v233, 16, v159
	v_and_b32_e32 v159, 0xffff0000, v159
	v_fma_f32 v120, v120, v232, v230
	v_fma_f32 v121, v121, v158, v156
	v_fma_f32 v122, v122, v233, v231
	v_fma_f32 v123, v123, v159, v157
	global_store_dwordx4 v252, v[120:123], s[42:43] offset:64
	v_mul_f32_e32 v116, v116, v208
	v_mul_f32_e32 v117, v117, v208
	v_mul_f32_e32 v118, v118, v208
	v_mul_f32_e32 v119, v119, v208
	v_mul_f32_e32 v116, 0xbfb8aa3b, v116
	v_mul_f32_e32 v117, 0xbfb8aa3b, v117
	v_mul_f32_e32 v118, 0xbfb8aa3b, v118
	v_mul_f32_e32 v119, 0xbfb8aa3b, v119
	v_exp_f32_e32 v116, v116
	v_exp_f32_e32 v117, v117
	v_exp_f32_e32 v118, v118
	v_exp_f32_e32 v119, v119
	v_add_f32_e32 v116, 1.0, v116
	v_add_f32_e32 v117, 1.0, v117
	v_add_f32_e32 v118, 1.0, v118
	v_add_f32_e32 v119, 1.0, v119
	v_rcp_f32_e32 v220, v116
	v_rcp_f32_e32 v221, v117
	v_rcp_f32_e32 v222, v118
	v_rcp_f32_e32 v223, v119
	v_fma_f32 v224, -v116, v220, 1.0
	v_fma_f32 v225, -v117, v221, 1.0
	v_fma_f32 v226, -v118, v222, 1.0
	v_fma_f32 v227, -v119, v223, 1.0
	v_fma_f32 v116, v224, v220, v220
	v_fma_f32 v117, v225, v221, v221
	v_fma_f32 v118, v226, v222, v222
	v_fma_f32 v119, v227, v223, v223
	v_lshlrev_b32_e32 v230, 16, v160
	v_and_b32_e32 v160, 0xffff0000, v160
	v_lshlrev_b32_e32 v231, 16, v161
	v_and_b32_e32 v161, 0xffff0000, v161
	v_lshlrev_b32_e32 v232, 16, v162
	v_and_b32_e32 v162, 0xffff0000, v162
	v_lshlrev_b32_e32 v233, 16, v163
	v_and_b32_e32 v163, 0xffff0000, v163
	v_fma_f32 v116, v116, v232, v230
	v_fma_f32 v117, v117, v162, v160
	v_fma_f32 v118, v118, v233, v231
	v_fma_f32 v119, v119, v163, v161
	global_store_dwordx4 v252, v[116:119], s[42:43] offset:512
	v_mul_f32_e32 v112, v112, v208
	v_mul_f32_e32 v113, v113, v208
	v_mul_f32_e32 v114, v114, v208
	v_mul_f32_e32 v115, v115, v208
	v_mul_f32_e32 v112, 0xbfb8aa3b, v112
	v_mul_f32_e32 v113, 0xbfb8aa3b, v113
	v_mul_f32_e32 v114, 0xbfb8aa3b, v114
	v_mul_f32_e32 v115, 0xbfb8aa3b, v115
	v_exp_f32_e32 v112, v112
	v_exp_f32_e32 v113, v113
	v_exp_f32_e32 v114, v114
	v_exp_f32_e32 v115, v115
	v_add_f32_e32 v112, 1.0, v112
	v_add_f32_e32 v113, 1.0, v113
	v_add_f32_e32 v114, 1.0, v114
	v_add_f32_e32 v115, 1.0, v115
	v_rcp_f32_e32 v220, v112
	v_rcp_f32_e32 v221, v113
	v_rcp_f32_e32 v222, v114
	v_rcp_f32_e32 v223, v115
	v_fma_f32 v224, -v112, v220, 1.0
	v_fma_f32 v225, -v113, v221, 1.0
	v_fma_f32 v226, -v114, v222, 1.0
	v_fma_f32 v227, -v115, v223, 1.0
	v_fma_f32 v112, v224, v220, v220
	v_fma_f32 v113, v225, v221, v221
	v_fma_f32 v114, v226, v222, v222
	v_fma_f32 v115, v227, v223, v223
	v_lshlrev_b32_e32 v230, 16, v164
	v_and_b32_e32 v164, 0xffff0000, v164
	v_lshlrev_b32_e32 v231, 16, v165
	v_and_b32_e32 v165, 0xffff0000, v165
	v_lshlrev_b32_e32 v232, 16, v166
	v_and_b32_e32 v166, 0xffff0000, v166
	v_lshlrev_b32_e32 v233, 16, v167
	v_and_b32_e32 v167, 0xffff0000, v167
	v_fma_f32 v112, v112, v232, v230
	v_fma_f32 v113, v113, v166, v164
	v_fma_f32 v114, v114, v233, v231
	v_fma_f32 v115, v115, v167, v165
	global_store_dwordx4 v252, v[112:115], s[42:43] offset:576
	v_add_u32_e32 v192, 0x10000, v140
	v_mul_f32_e32 v108, v108, v209
	v_mul_f32_e32 v109, v109, v209
	v_mul_f32_e32 v110, v110, v209
	v_mul_f32_e32 v111, v111, v209
	v_mul_f32_e32 v108, 0xbfb8aa3b, v108
	v_mul_f32_e32 v109, 0xbfb8aa3b, v109
	v_mul_f32_e32 v110, 0xbfb8aa3b, v110
	v_mul_f32_e32 v111, 0xbfb8aa3b, v111
	v_exp_f32_e32 v108, v108
	v_exp_f32_e32 v109, v109
	v_exp_f32_e32 v110, v110
	v_exp_f32_e32 v111, v111
	v_add_f32_e32 v108, 1.0, v108
	v_add_f32_e32 v109, 1.0, v109
	v_add_f32_e32 v110, 1.0, v110
	v_add_f32_e32 v111, 1.0, v111
	v_rcp_f32_e32 v220, v108
	v_rcp_f32_e32 v221, v109
	v_rcp_f32_e32 v222, v110
	v_rcp_f32_e32 v223, v111
	v_fma_f32 v224, -v108, v220, 1.0
	v_fma_f32 v225, -v109, v221, 1.0
	v_fma_f32 v226, -v110, v222, 1.0
	v_fma_f32 v227, -v111, v223, 1.0
	v_fma_f32 v108, v224, v220, v220
	v_fma_f32 v109, v225, v221, v221
	v_fma_f32 v110, v226, v222, v222
	v_fma_f32 v111, v227, v223, v223
	v_lshlrev_b32_e32 v230, 16, v168
	v_and_b32_e32 v168, 0xffff0000, v168
	v_lshlrev_b32_e32 v231, 16, v169
	v_and_b32_e32 v169, 0xffff0000, v169
	v_lshlrev_b32_e32 v232, 16, v170
	v_and_b32_e32 v170, 0xffff0000, v170
	v_lshlrev_b32_e32 v233, 16, v171
	v_and_b32_e32 v171, 0xffff0000, v171
	v_fma_f32 v108, v108, v232, v230
	v_fma_f32 v109, v109, v170, v168
	v_fma_f32 v110, v110, v233, v231
	v_fma_f32 v111, v111, v171, v169
	v_lshlrev_b32_e32 v252, 1, v192
	global_store_dwordx4 v252, v[108:111], s[42:43] offset:0
	v_mul_f32_e32 v104, v104, v209
	v_mul_f32_e32 v105, v105, v209
	v_mul_f32_e32 v106, v106, v209
	v_mul_f32_e32 v107, v107, v209
	v_mul_f32_e32 v104, 0xbfb8aa3b, v104
	v_mul_f32_e32 v105, 0xbfb8aa3b, v105
	v_mul_f32_e32 v106, 0xbfb8aa3b, v106
	v_mul_f32_e32 v107, 0xbfb8aa3b, v107
	v_exp_f32_e32 v104, v104
	v_exp_f32_e32 v105, v105
	v_exp_f32_e32 v106, v106
	v_exp_f32_e32 v107, v107
	v_add_f32_e32 v104, 1.0, v104
	v_add_f32_e32 v105, 1.0, v105
	v_add_f32_e32 v106, 1.0, v106
	v_add_f32_e32 v107, 1.0, v107
	v_rcp_f32_e32 v220, v104
	v_rcp_f32_e32 v221, v105
	v_rcp_f32_e32 v222, v106
	v_rcp_f32_e32 v223, v107
	v_fma_f32 v224, -v104, v220, 1.0
	v_fma_f32 v225, -v105, v221, 1.0
	v_fma_f32 v226, -v106, v222, 1.0
	v_fma_f32 v227, -v107, v223, 1.0
	v_fma_f32 v104, v224, v220, v220
	v_fma_f32 v105, v225, v221, v221
	v_fma_f32 v106, v226, v222, v222
	v_fma_f32 v107, v227, v223, v223
	v_lshlrev_b32_e32 v230, 16, v172
	v_and_b32_e32 v172, 0xffff0000, v172
	v_lshlrev_b32_e32 v231, 16, v173
	v_and_b32_e32 v173, 0xffff0000, v173
	v_lshlrev_b32_e32 v232, 16, v174
	v_and_b32_e32 v174, 0xffff0000, v174
	v_lshlrev_b32_e32 v233, 16, v175
	v_and_b32_e32 v175, 0xffff0000, v175
	v_fma_f32 v104, v104, v232, v230
	v_fma_f32 v105, v105, v174, v172
	v_fma_f32 v106, v106, v233, v231
	v_fma_f32 v107, v107, v175, v173
	global_store_dwordx4 v252, v[104:107], s[42:43] offset:64
	v_mul_f32_e32 v100, v100, v209
	v_mul_f32_e32 v101, v101, v209
	v_mul_f32_e32 v102, v102, v209
	v_mul_f32_e32 v103, v103, v209
	v_mul_f32_e32 v100, 0xbfb8aa3b, v100
	v_mul_f32_e32 v101, 0xbfb8aa3b, v101
	v_mul_f32_e32 v102, 0xbfb8aa3b, v102
	v_mul_f32_e32 v103, 0xbfb8aa3b, v103
	v_exp_f32_e32 v100, v100
	v_exp_f32_e32 v101, v101
	v_exp_f32_e32 v102, v102
	v_exp_f32_e32 v103, v103
	v_add_f32_e32 v100, 1.0, v100
	v_add_f32_e32 v101, 1.0, v101
	v_add_f32_e32 v102, 1.0, v102
	v_add_f32_e32 v103, 1.0, v103
	v_rcp_f32_e32 v220, v100
	v_rcp_f32_e32 v221, v101
	v_rcp_f32_e32 v222, v102
	v_rcp_f32_e32 v223, v103
	v_fma_f32 v224, -v100, v220, 1.0
	v_fma_f32 v225, -v101, v221, 1.0
	v_fma_f32 v226, -v102, v222, 1.0
	v_fma_f32 v227, -v103, v223, 1.0
	v_fma_f32 v100, v224, v220, v220
	v_fma_f32 v101, v225, v221, v221
	v_fma_f32 v102, v226, v222, v222
	v_fma_f32 v103, v227, v223, v223
	v_lshlrev_b32_e32 v230, 16, v240
	v_and_b32_e32 v240, 0xffff0000, v240
	v_lshlrev_b32_e32 v231, 16, v241
	v_and_b32_e32 v241, 0xffff0000, v241
	v_lshlrev_b32_e32 v232, 16, v242
	v_and_b32_e32 v242, 0xffff0000, v242
	v_lshlrev_b32_e32 v233, 16, v243
	v_and_b32_e32 v243, 0xffff0000, v243
	v_fma_f32 v100, v100, v232, v230
	v_fma_f32 v101, v101, v242, v240
	v_fma_f32 v102, v102, v233, v231
	v_fma_f32 v103, v103, v243, v241
	global_store_dwordx4 v252, v[100:103], s[42:43] offset:512
	v_mul_f32_e32 v96, v96, v209
	v_mul_f32_e32 v97, v97, v209
	v_mul_f32_e32 v98, v98, v209
	v_mul_f32_e32 v99, v99, v209
	v_mul_f32_e32 v96, 0xbfb8aa3b, v96
	v_mul_f32_e32 v97, 0xbfb8aa3b, v97
	v_mul_f32_e32 v98, 0xbfb8aa3b, v98
	v_mul_f32_e32 v99, 0xbfb8aa3b, v99
	v_exp_f32_e32 v96, v96
	v_exp_f32_e32 v97, v97
	v_exp_f32_e32 v98, v98
	v_exp_f32_e32 v99, v99
	v_add_f32_e32 v96, 1.0, v96
	v_add_f32_e32 v97, 1.0, v97
	v_add_f32_e32 v98, 1.0, v98
	v_add_f32_e32 v99, 1.0, v99
	v_rcp_f32_e32 v220, v96
	v_rcp_f32_e32 v221, v97
	v_rcp_f32_e32 v222, v98
	v_rcp_f32_e32 v223, v99
	v_fma_f32 v224, -v96, v220, 1.0
	v_fma_f32 v225, -v97, v221, 1.0
	v_fma_f32 v226, -v98, v222, 1.0
	v_fma_f32 v227, -v99, v223, 1.0
	v_fma_f32 v96, v224, v220, v220
	v_fma_f32 v97, v225, v221, v221
	v_fma_f32 v98, v226, v222, v222
	v_fma_f32 v99, v227, v223, v223
	v_lshlrev_b32_e32 v230, 16, v244
	v_and_b32_e32 v244, 0xffff0000, v244
	v_lshlrev_b32_e32 v231, 16, v245
	v_and_b32_e32 v245, 0xffff0000, v245
	v_lshlrev_b32_e32 v232, 16, v246
	v_and_b32_e32 v246, 0xffff0000, v246
	v_lshlrev_b32_e32 v233, 16, v247
	v_and_b32_e32 v247, 0xffff0000, v247
	v_fma_f32 v96, v96, v232, v230
	v_fma_f32 v97, v97, v246, v244
	v_fma_f32 v98, v98, v233, v231
	v_fma_f32 v99, v99, v247, v245
	global_store_dwordx4 v252, v[96:99], s[42:43] offset:576
	v_add_u32_e32 v196, 0x4000, v146
	global_load_dwordx4 v[96:99], v196, s[16:17]
	global_load_dwordx4 v[100:103], v196, s[16:17] offset:16
	v_add_u32_e32 v148, 0x4800, v146
	global_load_dwordx4 v[104:107], v148, s[16:17]
	global_load_dwordx4 v[108:111], v148, s[16:17] offset:16
	v_add_u32_e32 v188, 0x5000, v146
	global_load_dwordx4 v[112:115], v188, s[16:17]
	global_load_dwordx4 v[116:119], v188, s[16:17] offset:16
	v_add_u32_e32 v192, 0x5800, v146
	global_load_dwordx4 v[120:123], v192, s[16:17]
	global_load_dwordx4 v[124:127], v192, s[16:17] offset:16
	v_add_u32_e32 v196, 0x80000, v140
	global_load_dwordx2 v[152:153], v196, s[58:59] offset:0
	global_load_dwordx2 v[154:155], v196, s[56:57] offset:0
	global_load_dwordx2 v[156:157], v196, s[58:59] offset:32
	global_load_dwordx2 v[158:159], v196, s[56:57] offset:32
	global_load_dwordx2 v[160:161], v196, s[58:59] offset:256
	global_load_dwordx2 v[162:163], v196, s[56:57] offset:256
	global_load_dwordx2 v[164:165], v196, s[58:59] offset:288
	global_load_dwordx2 v[166:167], v196, s[56:57] offset:288
	v_add_u32_e32 v148, 0x90000, v140
	global_load_dwordx2 v[168:169], v148, s[58:59] offset:0
	global_load_dwordx2 v[170:171], v148, s[56:57] offset:0
	global_load_dwordx2 v[172:173], v148, s[58:59] offset:32
	global_load_dwordx2 v[174:175], v148, s[56:57] offset:32
	global_load_dwordx2 v[240:241], v148, s[58:59] offset:256
	global_load_dwordx2 v[242:243], v148, s[56:57] offset:256
	global_load_dwordx2 v[244:245], v148, s[58:59] offset:288
	global_load_dwordx2 v[246:247], v148, s[56:57] offset:288
	s_waitcnt vmcnt(32)
	v_add_u32_e32 v188, 0x20000, v140
	v_mul_f32_e32 v92, v92, v210
	v_mul_f32_e32 v93, v93, v210
	v_mul_f32_e32 v94, v94, v210
	v_mul_f32_e32 v95, v95, v210
	v_mul_f32_e32 v92, 0xbfb8aa3b, v92
	v_mul_f32_e32 v93, 0xbfb8aa3b, v93
	v_mul_f32_e32 v94, 0xbfb8aa3b, v94
	v_mul_f32_e32 v95, 0xbfb8aa3b, v95
	v_exp_f32_e32 v92, v92
	v_exp_f32_e32 v93, v93
	v_exp_f32_e32 v94, v94
	v_exp_f32_e32 v95, v95
	v_add_f32_e32 v92, 1.0, v92
	v_add_f32_e32 v93, 1.0, v93
	v_add_f32_e32 v94, 1.0, v94
	v_add_f32_e32 v95, 1.0, v95
	v_rcp_f32_e32 v220, v92
	v_rcp_f32_e32 v221, v93
	v_rcp_f32_e32 v222, v94
	v_rcp_f32_e32 v223, v95
	v_fma_f32 v224, -v92, v220, 1.0
	v_fma_f32 v225, -v93, v221, 1.0
	v_fma_f32 v226, -v94, v222, 1.0
	v_fma_f32 v227, -v95, v223, 1.0
	v_fma_f32 v92, v224, v220, v220
	v_fma_f32 v93, v225, v221, v221
	v_fma_f32 v94, v226, v222, v222
	v_fma_f32 v95, v227, v223, v223
	v_lshlrev_b32_e32 v230, 16, v182
	v_and_b32_e32 v182, 0xffff0000, v182
	v_lshlrev_b32_e32 v231, 16, v183
	v_and_b32_e32 v183, 0xffff0000, v183
	v_lshlrev_b32_e32 v232, 16, v184
	v_and_b32_e32 v184, 0xffff0000, v184
	v_lshlrev_b32_e32 v233, 16, v185
	v_and_b32_e32 v185, 0xffff0000, v185
	v_fma_f32 v92, v92, v232, v230
	v_fma_f32 v93, v93, v184, v182
	v_fma_f32 v94, v94, v233, v231
	v_fma_f32 v95, v95, v185, v183
	v_lshlrev_b32_e32 v252, 1, v188
	global_store_dwordx4 v252, v[92:95], s[42:43] offset:0
	v_mul_f32_e32 v88, v88, v210
	v_mul_f32_e32 v89, v89, v210
	v_mul_f32_e32 v90, v90, v210
	v_mul_f32_e32 v91, v91, v210
	v_mul_f32_e32 v88, 0xbfb8aa3b, v88
	v_mul_f32_e32 v89, 0xbfb8aa3b, v89
	v_mul_f32_e32 v90, 0xbfb8aa3b, v90
	v_mul_f32_e32 v91, 0xbfb8aa3b, v91
	v_exp_f32_e32 v88, v88
	v_exp_f32_e32 v89, v89
	v_exp_f32_e32 v90, v90
	v_exp_f32_e32 v91, v91
	v_add_f32_e32 v88, 1.0, v88
	v_add_f32_e32 v89, 1.0, v89
	v_add_f32_e32 v90, 1.0, v90
	v_add_f32_e32 v91, 1.0, v91
	v_rcp_f32_e32 v220, v88
	v_rcp_f32_e32 v221, v89
	v_rcp_f32_e32 v222, v90
	v_rcp_f32_e32 v223, v91
	v_fma_f32 v224, -v88, v220, 1.0
	v_fma_f32 v225, -v89, v221, 1.0
	v_fma_f32 v226, -v90, v222, 1.0
	v_fma_f32 v227, -v91, v223, 1.0
	v_fma_f32 v88, v224, v220, v220
	v_fma_f32 v89, v225, v221, v221
	v_fma_f32 v90, v226, v222, v222
	v_fma_f32 v91, v227, v223, v223
	v_lshlrev_b32_e32 v230, 16, v186
	v_and_b32_e32 v186, 0xffff0000, v186
	v_lshlrev_b32_e32 v231, 16, v187
	v_and_b32_e32 v187, 0xffff0000, v187
	v_lshlrev_b32_e32 v232, 16, v200
	v_and_b32_e32 v200, 0xffff0000, v200
	v_lshlrev_b32_e32 v233, 16, v201
	v_and_b32_e32 v201, 0xffff0000, v201
	v_fma_f32 v88, v88, v232, v230
	v_fma_f32 v89, v89, v200, v186
	v_fma_f32 v90, v90, v233, v231
	v_fma_f32 v91, v91, v201, v187
	global_store_dwordx4 v252, v[88:91], s[42:43] offset:64
	v_mul_f32_e32 v84, v84, v210
	v_mul_f32_e32 v85, v85, v210
	v_mul_f32_e32 v86, v86, v210
	v_mul_f32_e32 v87, v87, v210
	v_mul_f32_e32 v84, 0xbfb8aa3b, v84
	v_mul_f32_e32 v85, 0xbfb8aa3b, v85
	v_mul_f32_e32 v86, 0xbfb8aa3b, v86
	v_mul_f32_e32 v87, 0xbfb8aa3b, v87
	v_exp_f32_e32 v84, v84
	v_exp_f32_e32 v85, v85
	v_exp_f32_e32 v86, v86
	v_exp_f32_e32 v87, v87
	v_add_f32_e32 v84, 1.0, v84
	v_add_f32_e32 v85, 1.0, v85
	v_add_f32_e32 v86, 1.0, v86
	v_add_f32_e32 v87, 1.0, v87
	v_rcp_f32_e32 v220, v84
	v_rcp_f32_e32 v221, v85
	v_rcp_f32_e32 v222, v86
	v_rcp_f32_e32 v223, v87
	v_fma_f32 v224, -v84, v220, 1.0
	v_fma_f32 v225, -v85, v221, 1.0
	v_fma_f32 v226, -v86, v222, 1.0
	v_fma_f32 v227, -v87, v223, 1.0
	v_fma_f32 v84, v224, v220, v220
	v_fma_f32 v85, v225, v221, v221
	v_fma_f32 v86, v226, v222, v222
	v_fma_f32 v87, v227, v223, v223
	v_lshlrev_b32_e32 v230, 16, v202
	v_and_b32_e32 v202, 0xffff0000, v202
	v_lshlrev_b32_e32 v231, 16, v203
	v_and_b32_e32 v203, 0xffff0000, v203
	v_lshlrev_b32_e32 v232, 16, v204
	v_and_b32_e32 v204, 0xffff0000, v204
	v_lshlrev_b32_e32 v233, 16, v205
	v_and_b32_e32 v205, 0xffff0000, v205
	v_fma_f32 v84, v84, v232, v230
	v_fma_f32 v85, v85, v204, v202
	v_fma_f32 v86, v86, v233, v231
	v_fma_f32 v87, v87, v205, v203
	global_store_dwordx4 v252, v[84:87], s[42:43] offset:512
	v_mul_f32_e32 v80, v80, v210
	v_mul_f32_e32 v81, v81, v210
	v_mul_f32_e32 v82, v82, v210
	v_mul_f32_e32 v83, v83, v210
	v_mul_f32_e32 v80, 0xbfb8aa3b, v80
	v_mul_f32_e32 v81, 0xbfb8aa3b, v81
	v_mul_f32_e32 v82, 0xbfb8aa3b, v82
	v_mul_f32_e32 v83, 0xbfb8aa3b, v83
	v_exp_f32_e32 v80, v80
	v_exp_f32_e32 v81, v81
	v_exp_f32_e32 v82, v82
	v_exp_f32_e32 v83, v83
	v_add_f32_e32 v80, 1.0, v80
	v_add_f32_e32 v81, 1.0, v81
	v_add_f32_e32 v82, 1.0, v82
	v_add_f32_e32 v83, 1.0, v83
	v_rcp_f32_e32 v220, v80
	v_rcp_f32_e32 v221, v81
	v_rcp_f32_e32 v222, v82
	v_rcp_f32_e32 v223, v83
	v_fma_f32 v224, -v80, v220, 1.0
	v_fma_f32 v225, -v81, v221, 1.0
	v_fma_f32 v226, -v82, v222, 1.0
	v_fma_f32 v227, -v83, v223, 1.0
	v_fma_f32 v80, v224, v220, v220
	v_fma_f32 v81, v225, v221, v221
	v_fma_f32 v82, v226, v222, v222
	v_fma_f32 v83, v227, v223, v223
	v_lshlrev_b32_e32 v230, 16, v134
	v_and_b32_e32 v134, 0xffff0000, v134
	v_lshlrev_b32_e32 v231, 16, v135
	v_and_b32_e32 v135, 0xffff0000, v135
	v_lshlrev_b32_e32 v232, 16, v136
	v_and_b32_e32 v136, 0xffff0000, v136
	v_lshlrev_b32_e32 v233, 16, v137
	v_and_b32_e32 v137, 0xffff0000, v137
	v_fma_f32 v80, v80, v232, v230
	v_fma_f32 v81, v81, v136, v134
	v_fma_f32 v82, v82, v233, v231
	v_fma_f32 v83, v83, v137, v135
	global_store_dwordx4 v252, v[80:83], s[42:43] offset:576
	v_add_u32_e32 v192, 0x30000, v140
	v_mul_f32_e32 v76, v76, v211
	v_mul_f32_e32 v77, v77, v211
	v_mul_f32_e32 v78, v78, v211
	v_mul_f32_e32 v79, v79, v211
	v_mul_f32_e32 v76, 0xbfb8aa3b, v76
	v_mul_f32_e32 v77, 0xbfb8aa3b, v77
	v_mul_f32_e32 v78, 0xbfb8aa3b, v78
	v_mul_f32_e32 v79, 0xbfb8aa3b, v79
	v_exp_f32_e32 v76, v76
	v_exp_f32_e32 v77, v77
	v_exp_f32_e32 v78, v78
	v_exp_f32_e32 v79, v79
	v_add_f32_e32 v76, 1.0, v76
	v_add_f32_e32 v77, 1.0, v77
	v_add_f32_e32 v78, 1.0, v78
	v_add_f32_e32 v79, 1.0, v79
	v_rcp_f32_e32 v220, v76
	v_rcp_f32_e32 v221, v77
	v_rcp_f32_e32 v222, v78
	v_rcp_f32_e32 v223, v79
	v_fma_f32 v224, -v76, v220, 1.0
	v_fma_f32 v225, -v77, v221, 1.0
	v_fma_f32 v226, -v78, v222, 1.0
	v_fma_f32 v227, -v79, v223, 1.0
	v_fma_f32 v76, v224, v220, v220
	v_fma_f32 v77, v225, v221, v221
	v_fma_f32 v78, v226, v222, v222
	v_fma_f32 v79, v227, v223, v223
	v_lshlrev_b32_e32 v230, 16, v138
	v_and_b32_e32 v138, 0xffff0000, v138
	v_lshlrev_b32_e32 v231, 16, v139
	v_and_b32_e32 v139, 0xffff0000, v139
	v_lshlrev_b32_e32 v232, 16, v142
	v_and_b32_e32 v142, 0xffff0000, v142
	v_lshlrev_b32_e32 v233, 16, v143
	v_and_b32_e32 v143, 0xffff0000, v143
	v_fma_f32 v76, v76, v232, v230
	v_fma_f32 v77, v77, v142, v138
	v_fma_f32 v78, v78, v233, v231
	v_fma_f32 v79, v79, v143, v139
	v_lshlrev_b32_e32 v252, 1, v192
	global_store_dwordx4 v252, v[76:79], s[42:43] offset:0
	v_mul_f32_e32 v72, v72, v211
	v_mul_f32_e32 v73, v73, v211
	v_mul_f32_e32 v74, v74, v211
	v_mul_f32_e32 v75, v75, v211
	v_mul_f32_e32 v72, 0xbfb8aa3b, v72
	v_mul_f32_e32 v73, 0xbfb8aa3b, v73
	v_mul_f32_e32 v74, 0xbfb8aa3b, v74
	v_mul_f32_e32 v75, 0xbfb8aa3b, v75
	v_exp_f32_e32 v72, v72
	v_exp_f32_e32 v73, v73
	v_exp_f32_e32 v74, v74
	v_exp_f32_e32 v75, v75
	v_add_f32_e32 v72, 1.0, v72
	v_add_f32_e32 v73, 1.0, v73
	v_add_f32_e32 v74, 1.0, v74
	v_add_f32_e32 v75, 1.0, v75
	v_rcp_f32_e32 v220, v72
	v_rcp_f32_e32 v221, v73
	v_rcp_f32_e32 v222, v74
	v_rcp_f32_e32 v223, v75
	v_fma_f32 v224, -v72, v220, 1.0
	v_fma_f32 v225, -v73, v221, 1.0
	v_fma_f32 v226, -v74, v222, 1.0
	v_fma_f32 v227, -v75, v223, 1.0
	v_fma_f32 v72, v224, v220, v220
	v_fma_f32 v73, v225, v221, v221
	v_fma_f32 v74, v226, v222, v222
	v_fma_f32 v75, v227, v223, v223
	v_lshlrev_b32_e32 v230, 16, v144
	v_and_b32_e32 v144, 0xffff0000, v144
	v_lshlrev_b32_e32 v231, 16, v145
	v_and_b32_e32 v145, 0xffff0000, v145
	v_lshlrev_b32_e32 v232, 16, v190
	v_and_b32_e32 v190, 0xffff0000, v190
	v_lshlrev_b32_e32 v233, 16, v191
	v_and_b32_e32 v191, 0xffff0000, v191
	v_fma_f32 v72, v72, v232, v230
	v_fma_f32 v73, v73, v190, v144
	v_fma_f32 v74, v74, v233, v231
	v_fma_f32 v75, v75, v191, v145
	global_store_dwordx4 v252, v[72:75], s[42:43] offset:64
	v_mul_f32_e32 v68, v68, v211
	v_mul_f32_e32 v69, v69, v211
	v_mul_f32_e32 v70, v70, v211
	v_mul_f32_e32 v71, v71, v211
	v_mul_f32_e32 v68, 0xbfb8aa3b, v68
	v_mul_f32_e32 v69, 0xbfb8aa3b, v69
	v_mul_f32_e32 v70, 0xbfb8aa3b, v70
	v_mul_f32_e32 v71, 0xbfb8aa3b, v71
	v_exp_f32_e32 v68, v68
	v_exp_f32_e32 v69, v69
	v_exp_f32_e32 v70, v70
	v_exp_f32_e32 v71, v71
	v_add_f32_e32 v68, 1.0, v68
	v_add_f32_e32 v69, 1.0, v69
	v_add_f32_e32 v70, 1.0, v70
	v_add_f32_e32 v71, 1.0, v71
	v_rcp_f32_e32 v220, v68
	v_rcp_f32_e32 v221, v69
	v_rcp_f32_e32 v222, v70
	v_rcp_f32_e32 v223, v71
	v_fma_f32 v224, -v68, v220, 1.0
	v_fma_f32 v225, -v69, v221, 1.0
	v_fma_f32 v226, -v70, v222, 1.0
	v_fma_f32 v227, -v71, v223, 1.0
	v_fma_f32 v68, v224, v220, v220
	v_fma_f32 v69, v225, v221, v221
	v_fma_f32 v70, v226, v222, v222
	v_fma_f32 v71, v227, v223, v223
	v_lshlrev_b32_e32 v230, 16, v194
	v_and_b32_e32 v194, 0xffff0000, v194
	v_lshlrev_b32_e32 v231, 16, v195
	v_and_b32_e32 v195, 0xffff0000, v195
	v_lshlrev_b32_e32 v232, 16, v248
	v_and_b32_e32 v248, 0xffff0000, v248
	v_lshlrev_b32_e32 v233, 16, v249
	v_and_b32_e32 v249, 0xffff0000, v249
	v_fma_f32 v68, v68, v232, v230
	v_fma_f32 v69, v69, v248, v194
	v_fma_f32 v70, v70, v233, v231
	v_fma_f32 v71, v71, v249, v195
	global_store_dwordx4 v252, v[68:71], s[42:43] offset:512
	v_mul_f32_e32 v64, v64, v211
	v_mul_f32_e32 v65, v65, v211
	v_mul_f32_e32 v66, v66, v211
	v_mul_f32_e32 v67, v67, v211
	v_mul_f32_e32 v64, 0xbfb8aa3b, v64
	v_mul_f32_e32 v65, 0xbfb8aa3b, v65
	v_mul_f32_e32 v66, 0xbfb8aa3b, v66
	v_mul_f32_e32 v67, 0xbfb8aa3b, v67
	v_exp_f32_e32 v64, v64
	v_exp_f32_e32 v65, v65
	v_exp_f32_e32 v66, v66
	v_exp_f32_e32 v67, v67
	v_add_f32_e32 v64, 1.0, v64
	v_add_f32_e32 v65, 1.0, v65
	v_add_f32_e32 v66, 1.0, v66
	v_add_f32_e32 v67, 1.0, v67
	v_rcp_f32_e32 v220, v64
	v_rcp_f32_e32 v221, v65
	v_rcp_f32_e32 v222, v66
	v_rcp_f32_e32 v223, v67
	v_fma_f32 v224, -v64, v220, 1.0
	v_fma_f32 v225, -v65, v221, 1.0
	v_fma_f32 v226, -v66, v222, 1.0
	v_fma_f32 v227, -v67, v223, 1.0
	v_fma_f32 v64, v224, v220, v220
	v_fma_f32 v65, v225, v221, v221
	v_fma_f32 v66, v226, v222, v222
	v_fma_f32 v67, v227, v223, v223
	v_lshlrev_b32_e32 v230, 16, v150
	v_and_b32_e32 v150, 0xffff0000, v150
	v_lshlrev_b32_e32 v231, 16, v151
	v_and_b32_e32 v151, 0xffff0000, v151
	v_lshlrev_b32_e32 v232, 16, v238
	v_and_b32_e32 v238, 0xffff0000, v238
	v_lshlrev_b32_e32 v233, 16, v239
	v_and_b32_e32 v239, 0xffff0000, v239
	v_fma_f32 v64, v64, v232, v230
	v_fma_f32 v65, v65, v238, v150
	v_fma_f32 v66, v66, v233, v231
	v_fma_f32 v67, v67, v239, v151
	global_store_dwordx4 v252, v[64:67], s[42:43] offset:576
	v_add_u32_e32 v196, 0xa0000, v140
	global_load_dwordx2 v[182:183], v196, s[58:59] offset:0
	global_load_dwordx2 v[184:185], v196, s[56:57] offset:0
	global_load_dwordx2 v[186:187], v196, s[58:59] offset:32
	global_load_dwordx2 v[200:201], v196, s[56:57] offset:32
	global_load_dwordx2 v[202:203], v196, s[58:59] offset:256
	global_load_dwordx2 v[204:205], v196, s[56:57] offset:256
	global_load_dwordx2 v[134:135], v196, s[58:59] offset:288
	global_load_dwordx2 v[136:137], v196, s[56:57] offset:288
	v_add_u32_e32 v148, 0xb0000, v140
	global_load_dwordx2 v[138:139], v148, s[58:59] offset:0
	global_load_dwordx2 v[142:143], v148, s[56:57] offset:0
	global_load_dwordx2 v[144:145], v148, s[58:59] offset:32
	global_load_dwordx2 v[190:191], v148, s[56:57] offset:32
	global_load_dwordx2 v[194:195], v148, s[58:59] offset:256
	global_load_dwordx2 v[248:249], v148, s[56:57] offset:256
	global_load_dwordx2 v[150:151], v148, s[58:59] offset:288
	v_add_u32_e32 v188, 0xb0000, v140
	global_load_dwordx2 v[234:235], v188, s[56:57] offset:288
	s_waitcnt vmcnt(40)
	v_add_f32_e32 v96, v96, v97
	v_add_f32_e32 v98, v98, v99
	v_add_f32_e32 v100, v100, v101
	v_add_f32_e32 v102, v102, v103
	v_add_f32_e32 v96, v96, v98
	v_add_f32_e32 v100, v100, v102
	v_add_f32_e32 v96, v96, v100
	v_add_f32_e32 v104, v104, v105
	v_add_f32_e32 v106, v106, v107
	v_add_f32_e32 v108, v108, v109
	v_add_f32_e32 v110, v110, v111
	v_add_f32_e32 v104, v104, v106
	v_add_f32_e32 v108, v108, v110
	v_add_f32_e32 v104, v104, v108
	v_add_f32_e32 v112, v112, v113
	v_add_f32_e32 v114, v114, v115
	v_add_f32_e32 v116, v116, v117
	v_add_f32_e32 v118, v118, v119
	v_add_f32_e32 v112, v112, v114
	v_add_f32_e32 v116, v116, v118
	v_add_f32_e32 v112, v112, v116
	v_add_f32_e32 v120, v120, v121
	v_add_f32_e32 v122, v122, v123
	v_add_f32_e32 v124, v124, v125
	v_add_f32_e32 v126, v126, v127
	v_add_f32_e32 v120, v120, v122
	v_add_f32_e32 v124, v124, v126
	v_add_f32_e32 v120, v120, v124
	ds_bpermute_b32 v97, v207, v96
	ds_bpermute_b32 v105, v207, v104
	ds_bpermute_b32 v113, v207, v112
	ds_bpermute_b32 v121, v207, v120
	s_waitcnt lgkmcnt(0)
	v_add_f32_e32 v96, v96, v97
	v_add_f32_e32 v104, v104, v105
	v_add_f32_e32 v112, v112, v113
	v_add_f32_e32 v120, v120, v121
	ds_bpermute_b32 v97, v206, v96
	ds_bpermute_b32 v105, v206, v104
	ds_bpermute_b32 v113, v206, v112
	ds_bpermute_b32 v121, v206, v120
	s_waitcnt lgkmcnt(0)
	v_add_f32_e32 v96, v96, v97
	v_add_f32_e32 v104, v104, v105
	v_add_f32_e32 v112, v112, v113
	v_add_f32_e32 v120, v120, v121
	v_mul_f32_e32 v96, 0x3a000000, v96
	v_add_f32_e32 v96, 0x358637bd, v96
	v_mul_f32_e32 v104, 0x3a000000, v104
	v_add_f32_e32 v104, 0x358637bd, v104
	v_mul_f32_e32 v112, 0x3a000000, v112
	v_add_f32_e32 v112, 0x358637bd, v112
	v_mul_f32_e32 v120, 0x3a000000, v120
	v_add_f32_e32 v120, 0x358637bd, v120
	v_rsq_f32_e32 v96, v96
	v_rsq_f32_e32 v104, v104
	v_rsq_f32_e32 v112, v112
	v_rsq_f32_e32 v120, v120
	s_nop 0
	v_mov_b32_e32 v212, v96
	v_mov_b32_e32 v213, v104
	v_mov_b32_e32 v214, v112
	v_mov_b32_e32 v215, v120
	s_waitcnt vmcnt(24)
	v_add_u32_e32 v192, 0x80000, v140
	v_mul_f32_e32 v60, v60, v212
	v_mul_f32_e32 v61, v61, v212
	v_mul_f32_e32 v62, v62, v212
	v_mul_f32_e32 v63, v63, v212
	v_mul_f32_e32 v60, 0xbfb8aa3b, v60
	v_mul_f32_e32 v61, 0xbfb8aa3b, v61
	v_mul_f32_e32 v62, 0xbfb8aa3b, v62
	v_mul_f32_e32 v63, 0xbfb8aa3b, v63
	v_exp_f32_e32 v60, v60
	v_exp_f32_e32 v61, v61
	v_exp_f32_e32 v62, v62
	v_exp_f32_e32 v63, v63
	v_add_f32_e32 v60, 1.0, v60
	v_add_f32_e32 v61, 1.0, v61
	v_add_f32_e32 v62, 1.0, v62
	v_add_f32_e32 v63, 1.0, v63
	v_rcp_f32_e32 v220, v60
	v_rcp_f32_e32 v221, v61
	v_rcp_f32_e32 v222, v62
	v_rcp_f32_e32 v223, v63
	v_fma_f32 v224, -v60, v220, 1.0
	v_fma_f32 v225, -v61, v221, 1.0
	v_fma_f32 v226, -v62, v222, 1.0
	v_fma_f32 v227, -v63, v223, 1.0
	v_fma_f32 v60, v224, v220, v220
	v_fma_f32 v61, v225, v221, v221
	v_fma_f32 v62, v226, v222, v222
	v_fma_f32 v63, v227, v223, v223
	v_lshlrev_b32_e32 v230, 16, v152
	v_and_b32_e32 v152, 0xffff0000, v152
	v_lshlrev_b32_e32 v231, 16, v153
	v_and_b32_e32 v153, 0xffff0000, v153
	v_lshlrev_b32_e32 v232, 16, v154
	v_and_b32_e32 v154, 0xffff0000, v154
	v_lshlrev_b32_e32 v233, 16, v155
	v_and_b32_e32 v155, 0xffff0000, v155
	v_fma_f32 v60, v60, v232, v230
	v_fma_f32 v61, v61, v154, v152
	v_fma_f32 v62, v62, v233, v231
	v_fma_f32 v63, v63, v155, v153
	v_lshlrev_b32_e32 v252, 1, v192
	global_store_dwordx4 v252, v[60:63], s[42:43] offset:0
	v_mul_f32_e32 v56, v56, v212
	v_mul_f32_e32 v57, v57, v212
	v_mul_f32_e32 v58, v58, v212
	v_mul_f32_e32 v59, v59, v212
	v_mul_f32_e32 v56, 0xbfb8aa3b, v56
	v_mul_f32_e32 v57, 0xbfb8aa3b, v57
	v_mul_f32_e32 v58, 0xbfb8aa3b, v58
	v_mul_f32_e32 v59, 0xbfb8aa3b, v59
	v_exp_f32_e32 v56, v56
	v_exp_f32_e32 v57, v57
	v_exp_f32_e32 v58, v58
	v_exp_f32_e32 v59, v59
	v_add_f32_e32 v56, 1.0, v56
	v_add_f32_e32 v57, 1.0, v57
	v_add_f32_e32 v58, 1.0, v58
	v_add_f32_e32 v59, 1.0, v59
	v_rcp_f32_e32 v220, v56
	v_rcp_f32_e32 v221, v57
	v_rcp_f32_e32 v222, v58
	v_rcp_f32_e32 v223, v59
	v_fma_f32 v224, -v56, v220, 1.0
	v_fma_f32 v225, -v57, v221, 1.0
	v_fma_f32 v226, -v58, v222, 1.0
	v_fma_f32 v227, -v59, v223, 1.0
	v_fma_f32 v56, v224, v220, v220
	v_fma_f32 v57, v225, v221, v221
	v_fma_f32 v58, v226, v222, v222
	v_fma_f32 v59, v227, v223, v223
	v_lshlrev_b32_e32 v230, 16, v156
	v_and_b32_e32 v156, 0xffff0000, v156
	v_lshlrev_b32_e32 v231, 16, v157
	v_and_b32_e32 v157, 0xffff0000, v157
	v_lshlrev_b32_e32 v232, 16, v158
	v_and_b32_e32 v158, 0xffff0000, v158
	v_lshlrev_b32_e32 v233, 16, v159
	v_and_b32_e32 v159, 0xffff0000, v159
	v_fma_f32 v56, v56, v232, v230
	v_fma_f32 v57, v57, v158, v156
	v_fma_f32 v58, v58, v233, v231
	v_fma_f32 v59, v59, v159, v157
	global_store_dwordx4 v252, v[56:59], s[42:43] offset:64
	v_mul_f32_e32 v52, v52, v212
	v_mul_f32_e32 v53, v53, v212
	v_mul_f32_e32 v54, v54, v212
	v_mul_f32_e32 v55, v55, v212
	v_mul_f32_e32 v52, 0xbfb8aa3b, v52
	v_mul_f32_e32 v53, 0xbfb8aa3b, v53
	v_mul_f32_e32 v54, 0xbfb8aa3b, v54
	v_mul_f32_e32 v55, 0xbfb8aa3b, v55
	v_exp_f32_e32 v52, v52
	v_exp_f32_e32 v53, v53
	v_exp_f32_e32 v54, v54
	v_exp_f32_e32 v55, v55
	v_add_f32_e32 v52, 1.0, v52
	v_add_f32_e32 v53, 1.0, v53
	v_add_f32_e32 v54, 1.0, v54
	v_add_f32_e32 v55, 1.0, v55
	v_rcp_f32_e32 v220, v52
	v_rcp_f32_e32 v221, v53
	v_rcp_f32_e32 v222, v54
	v_rcp_f32_e32 v223, v55
	v_fma_f32 v224, -v52, v220, 1.0
	v_fma_f32 v225, -v53, v221, 1.0
	v_fma_f32 v226, -v54, v222, 1.0
	v_fma_f32 v227, -v55, v223, 1.0
	v_fma_f32 v52, v224, v220, v220
	v_fma_f32 v53, v225, v221, v221
	v_fma_f32 v54, v226, v222, v222
	v_fma_f32 v55, v227, v223, v223
	v_lshlrev_b32_e32 v230, 16, v160
	v_and_b32_e32 v160, 0xffff0000, v160
	v_lshlrev_b32_e32 v231, 16, v161
	v_and_b32_e32 v161, 0xffff0000, v161
	v_lshlrev_b32_e32 v232, 16, v162
	v_and_b32_e32 v162, 0xffff0000, v162
	v_lshlrev_b32_e32 v233, 16, v163
	v_and_b32_e32 v163, 0xffff0000, v163
	v_fma_f32 v52, v52, v232, v230
	v_fma_f32 v53, v53, v162, v160
	v_fma_f32 v54, v54, v233, v231
	v_fma_f32 v55, v55, v163, v161
	global_store_dwordx4 v252, v[52:55], s[42:43] offset:512
	v_mul_f32_e32 v48, v48, v212
	v_mul_f32_e32 v49, v49, v212
	v_mul_f32_e32 v50, v50, v212
	v_mul_f32_e32 v51, v51, v212
	v_mul_f32_e32 v48, 0xbfb8aa3b, v48
	v_mul_f32_e32 v49, 0xbfb8aa3b, v49
	v_mul_f32_e32 v50, 0xbfb8aa3b, v50
	v_mul_f32_e32 v51, 0xbfb8aa3b, v51
	v_exp_f32_e32 v48, v48
	v_exp_f32_e32 v49, v49
	v_exp_f32_e32 v50, v50
	v_exp_f32_e32 v51, v51
	v_add_f32_e32 v48, 1.0, v48
	v_add_f32_e32 v49, 1.0, v49
	v_add_f32_e32 v50, 1.0, v50
	v_add_f32_e32 v51, 1.0, v51
	v_rcp_f32_e32 v220, v48
	v_rcp_f32_e32 v221, v49
	v_rcp_f32_e32 v222, v50
	v_rcp_f32_e32 v223, v51
	v_fma_f32 v224, -v48, v220, 1.0
	v_fma_f32 v225, -v49, v221, 1.0
	v_fma_f32 v226, -v50, v222, 1.0
	v_fma_f32 v227, -v51, v223, 1.0
	v_fma_f32 v48, v224, v220, v220
	v_fma_f32 v49, v225, v221, v221
	v_fma_f32 v50, v226, v222, v222
	v_fma_f32 v51, v227, v223, v223
	v_lshlrev_b32_e32 v230, 16, v164
	v_and_b32_e32 v164, 0xffff0000, v164
	v_lshlrev_b32_e32 v231, 16, v165
	v_and_b32_e32 v165, 0xffff0000, v165
	v_lshlrev_b32_e32 v232, 16, v166
	v_and_b32_e32 v166, 0xffff0000, v166
	v_lshlrev_b32_e32 v233, 16, v167
	v_and_b32_e32 v167, 0xffff0000, v167
	v_fma_f32 v48, v48, v232, v230
	v_fma_f32 v49, v49, v166, v164
	v_fma_f32 v50, v50, v233, v231
	v_fma_f32 v51, v51, v167, v165
	global_store_dwordx4 v252, v[48:51], s[42:43] offset:576
	v_add_u32_e32 v196, 0x90000, v140
	v_mul_f32_e32 v44, v44, v213
	v_mul_f32_e32 v45, v45, v213
	v_mul_f32_e32 v46, v46, v213
	v_mul_f32_e32 v47, v47, v213
	v_mul_f32_e32 v44, 0xbfb8aa3b, v44
	v_mul_f32_e32 v45, 0xbfb8aa3b, v45
	v_mul_f32_e32 v46, 0xbfb8aa3b, v46
	v_mul_f32_e32 v47, 0xbfb8aa3b, v47
	v_exp_f32_e32 v44, v44
	v_exp_f32_e32 v45, v45
	v_exp_f32_e32 v46, v46
	v_exp_f32_e32 v47, v47
	v_add_f32_e32 v44, 1.0, v44
	v_add_f32_e32 v45, 1.0, v45
	v_add_f32_e32 v46, 1.0, v46
	v_add_f32_e32 v47, 1.0, v47
	v_rcp_f32_e32 v220, v44
	v_rcp_f32_e32 v221, v45
	v_rcp_f32_e32 v222, v46
	v_rcp_f32_e32 v223, v47
	v_fma_f32 v224, -v44, v220, 1.0
	v_fma_f32 v225, -v45, v221, 1.0
	v_fma_f32 v226, -v46, v222, 1.0
	v_fma_f32 v227, -v47, v223, 1.0
	v_fma_f32 v44, v224, v220, v220
	v_fma_f32 v45, v225, v221, v221
	v_fma_f32 v46, v226, v222, v222
	v_fma_f32 v47, v227, v223, v223
	v_lshlrev_b32_e32 v230, 16, v168
	v_and_b32_e32 v168, 0xffff0000, v168
	v_lshlrev_b32_e32 v231, 16, v169
	v_and_b32_e32 v169, 0xffff0000, v169
	v_lshlrev_b32_e32 v232, 16, v170
	v_and_b32_e32 v170, 0xffff0000, v170
	v_lshlrev_b32_e32 v233, 16, v171
	v_and_b32_e32 v171, 0xffff0000, v171
	v_fma_f32 v44, v44, v232, v230
	v_fma_f32 v45, v45, v170, v168
	v_fma_f32 v46, v46, v233, v231
	v_fma_f32 v47, v47, v171, v169
	v_lshlrev_b32_e32 v252, 1, v196
	global_store_dwordx4 v252, v[44:47], s[42:43] offset:0
	v_mul_f32_e32 v40, v40, v213
	v_mul_f32_e32 v41, v41, v213
	v_mul_f32_e32 v42, v42, v213
	v_mul_f32_e32 v43, v43, v213
	v_mul_f32_e32 v40, 0xbfb8aa3b, v40
	v_mul_f32_e32 v41, 0xbfb8aa3b, v41
	v_mul_f32_e32 v42, 0xbfb8aa3b, v42
	v_mul_f32_e32 v43, 0xbfb8aa3b, v43
	v_exp_f32_e32 v40, v40
	v_exp_f32_e32 v41, v41
	v_exp_f32_e32 v42, v42
	v_exp_f32_e32 v43, v43
	v_add_f32_e32 v40, 1.0, v40
	v_add_f32_e32 v41, 1.0, v41
	v_add_f32_e32 v42, 1.0, v42
	v_add_f32_e32 v43, 1.0, v43
	v_rcp_f32_e32 v220, v40
	v_rcp_f32_e32 v221, v41
	v_rcp_f32_e32 v222, v42
	v_rcp_f32_e32 v223, v43
	v_fma_f32 v224, -v40, v220, 1.0
	v_fma_f32 v225, -v41, v221, 1.0
	v_fma_f32 v226, -v42, v222, 1.0
	v_fma_f32 v227, -v43, v223, 1.0
	v_fma_f32 v40, v224, v220, v220
	v_fma_f32 v41, v225, v221, v221
	v_fma_f32 v42, v226, v222, v222
	v_fma_f32 v43, v227, v223, v223
	v_lshlrev_b32_e32 v230, 16, v172
	v_and_b32_e32 v172, 0xffff0000, v172
	v_lshlrev_b32_e32 v231, 16, v173
	v_and_b32_e32 v173, 0xffff0000, v173
	v_lshlrev_b32_e32 v232, 16, v174
	v_and_b32_e32 v174, 0xffff0000, v174
	v_lshlrev_b32_e32 v233, 16, v175
	v_and_b32_e32 v175, 0xffff0000, v175
	v_fma_f32 v40, v40, v232, v230
	v_fma_f32 v41, v41, v174, v172
	v_fma_f32 v42, v42, v233, v231
	v_fma_f32 v43, v43, v175, v173
	global_store_dwordx4 v252, v[40:43], s[42:43] offset:64
	v_mul_f32_e32 v36, v36, v213
	v_mul_f32_e32 v37, v37, v213
	v_mul_f32_e32 v38, v38, v213
	v_mul_f32_e32 v39, v39, v213
	v_mul_f32_e32 v36, 0xbfb8aa3b, v36
	v_mul_f32_e32 v37, 0xbfb8aa3b, v37
	v_mul_f32_e32 v38, 0xbfb8aa3b, v38
	v_mul_f32_e32 v39, 0xbfb8aa3b, v39
	v_exp_f32_e32 v36, v36
	v_exp_f32_e32 v37, v37
	v_exp_f32_e32 v38, v38
	v_exp_f32_e32 v39, v39
	v_add_f32_e32 v36, 1.0, v36
	v_add_f32_e32 v37, 1.0, v37
	v_add_f32_e32 v38, 1.0, v38
	v_add_f32_e32 v39, 1.0, v39
	v_rcp_f32_e32 v220, v36
	v_rcp_f32_e32 v221, v37
	v_rcp_f32_e32 v222, v38
	v_rcp_f32_e32 v223, v39
	v_fma_f32 v224, -v36, v220, 1.0
	v_fma_f32 v225, -v37, v221, 1.0
	v_fma_f32 v226, -v38, v222, 1.0
	v_fma_f32 v227, -v39, v223, 1.0
	v_fma_f32 v36, v224, v220, v220
	v_fma_f32 v37, v225, v221, v221
	v_fma_f32 v38, v226, v222, v222
	v_fma_f32 v39, v227, v223, v223
	v_lshlrev_b32_e32 v230, 16, v240
	v_and_b32_e32 v240, 0xffff0000, v240
	v_lshlrev_b32_e32 v231, 16, v241
	v_and_b32_e32 v241, 0xffff0000, v241
	v_lshlrev_b32_e32 v232, 16, v242
	v_and_b32_e32 v242, 0xffff0000, v242
	v_lshlrev_b32_e32 v233, 16, v243
	v_and_b32_e32 v243, 0xffff0000, v243
	v_fma_f32 v36, v36, v232, v230
	v_fma_f32 v37, v37, v242, v240
	v_fma_f32 v38, v38, v233, v231
	v_fma_f32 v39, v39, v243, v241
	global_store_dwordx4 v252, v[36:39], s[42:43] offset:512
	v_mul_f32_e32 v32, v32, v213
	v_mul_f32_e32 v33, v33, v213
	v_mul_f32_e32 v34, v34, v213
	v_mul_f32_e32 v35, v35, v213
	v_mul_f32_e32 v32, 0xbfb8aa3b, v32
	v_mul_f32_e32 v33, 0xbfb8aa3b, v33
	v_mul_f32_e32 v34, 0xbfb8aa3b, v34
	v_mul_f32_e32 v35, 0xbfb8aa3b, v35
	v_exp_f32_e32 v32, v32
	v_exp_f32_e32 v33, v33
	v_exp_f32_e32 v34, v34
	v_exp_f32_e32 v35, v35
	v_add_f32_e32 v32, 1.0, v32
	v_add_f32_e32 v33, 1.0, v33
	v_add_f32_e32 v34, 1.0, v34
	v_add_f32_e32 v35, 1.0, v35
	v_rcp_f32_e32 v220, v32
	v_rcp_f32_e32 v221, v33
	v_rcp_f32_e32 v222, v34
	v_rcp_f32_e32 v223, v35
	v_fma_f32 v224, -v32, v220, 1.0
	v_fma_f32 v225, -v33, v221, 1.0
	v_fma_f32 v226, -v34, v222, 1.0
	v_fma_f32 v227, -v35, v223, 1.0
	v_fma_f32 v32, v224, v220, v220
	v_fma_f32 v33, v225, v221, v221
	v_fma_f32 v34, v226, v222, v222
	v_fma_f32 v35, v227, v223, v223
	v_lshlrev_b32_e32 v230, 16, v244
	v_and_b32_e32 v244, 0xffff0000, v244
	v_lshlrev_b32_e32 v231, 16, v245
	v_and_b32_e32 v245, 0xffff0000, v245
	v_lshlrev_b32_e32 v232, 16, v246
	v_and_b32_e32 v246, 0xffff0000, v246
	v_lshlrev_b32_e32 v233, 16, v247
	v_and_b32_e32 v247, 0xffff0000, v247
	v_fma_f32 v32, v32, v232, v230
	v_fma_f32 v33, v33, v246, v244
	v_fma_f32 v34, v34, v233, v231
	v_fma_f32 v35, v35, v247, v245
	global_store_dwordx4 v252, v[32:35], s[42:43] offset:576
	s_waitcnt vmcnt(8)
	v_add_u32_e32 v148, 0xa0000, v140
	v_mul_f32_e32 v28, v28, v214
	v_mul_f32_e32 v29, v29, v214
	v_mul_f32_e32 v30, v30, v214
	v_mul_f32_e32 v31, v31, v214
	v_mul_f32_e32 v28, 0xbfb8aa3b, v28
	v_mul_f32_e32 v29, 0xbfb8aa3b, v29
	v_mul_f32_e32 v30, 0xbfb8aa3b, v30
	v_mul_f32_e32 v31, 0xbfb8aa3b, v31
	v_exp_f32_e32 v28, v28
	v_exp_f32_e32 v29, v29
	v_exp_f32_e32 v30, v30
	v_exp_f32_e32 v31, v31
	v_add_f32_e32 v28, 1.0, v28
	v_add_f32_e32 v29, 1.0, v29
	v_add_f32_e32 v30, 1.0, v30
	v_add_f32_e32 v31, 1.0, v31
	v_rcp_f32_e32 v220, v28
	v_rcp_f32_e32 v221, v29
	v_rcp_f32_e32 v222, v30
	v_rcp_f32_e32 v223, v31
	v_fma_f32 v224, -v28, v220, 1.0
	v_fma_f32 v225, -v29, v221, 1.0
	v_fma_f32 v226, -v30, v222, 1.0
	v_fma_f32 v227, -v31, v223, 1.0
	v_fma_f32 v28, v224, v220, v220
	v_fma_f32 v29, v225, v221, v221
	v_fma_f32 v30, v226, v222, v222
	v_fma_f32 v31, v227, v223, v223
	v_lshlrev_b32_e32 v230, 16, v182
	v_and_b32_e32 v182, 0xffff0000, v182
	v_lshlrev_b32_e32 v231, 16, v183
	v_and_b32_e32 v183, 0xffff0000, v183
	v_lshlrev_b32_e32 v232, 16, v184
	v_and_b32_e32 v184, 0xffff0000, v184
	v_lshlrev_b32_e32 v233, 16, v185
	v_and_b32_e32 v185, 0xffff0000, v185
	v_fma_f32 v28, v28, v232, v230
	v_fma_f32 v29, v29, v184, v182
	v_fma_f32 v30, v30, v233, v231
	v_fma_f32 v31, v31, v185, v183
	v_lshlrev_b32_e32 v252, 1, v148
	global_store_dwordx4 v252, v[28:31], s[42:43] offset:0
	v_mul_f32_e32 v24, v24, v214
	v_mul_f32_e32 v25, v25, v214
	v_mul_f32_e32 v26, v26, v214
	v_mul_f32_e32 v27, v27, v214
	v_mul_f32_e32 v24, 0xbfb8aa3b, v24
	v_mul_f32_e32 v25, 0xbfb8aa3b, v25
	v_mul_f32_e32 v26, 0xbfb8aa3b, v26
	v_mul_f32_e32 v27, 0xbfb8aa3b, v27
	v_exp_f32_e32 v24, v24
	v_exp_f32_e32 v25, v25
	v_exp_f32_e32 v26, v26
	v_exp_f32_e32 v27, v27
	v_add_f32_e32 v24, 1.0, v24
	v_add_f32_e32 v25, 1.0, v25
	v_add_f32_e32 v26, 1.0, v26
	v_add_f32_e32 v27, 1.0, v27
	v_rcp_f32_e32 v220, v24
	v_rcp_f32_e32 v221, v25
	v_rcp_f32_e32 v222, v26
	v_rcp_f32_e32 v223, v27
	v_fma_f32 v224, -v24, v220, 1.0
	v_fma_f32 v225, -v25, v221, 1.0
	v_fma_f32 v226, -v26, v222, 1.0
	v_fma_f32 v227, -v27, v223, 1.0
	v_fma_f32 v24, v224, v220, v220
	v_fma_f32 v25, v225, v221, v221
	v_fma_f32 v26, v226, v222, v222
	v_fma_f32 v27, v227, v223, v223
	v_lshlrev_b32_e32 v230, 16, v186
	v_and_b32_e32 v186, 0xffff0000, v186
	v_lshlrev_b32_e32 v231, 16, v187
	v_and_b32_e32 v187, 0xffff0000, v187
	v_lshlrev_b32_e32 v232, 16, v200
	v_and_b32_e32 v200, 0xffff0000, v200
	v_lshlrev_b32_e32 v233, 16, v201
	v_and_b32_e32 v201, 0xffff0000, v201
	v_fma_f32 v24, v24, v232, v230
	v_fma_f32 v25, v25, v200, v186
	v_fma_f32 v26, v26, v233, v231
	v_fma_f32 v27, v27, v201, v187
	global_store_dwordx4 v252, v[24:27], s[42:43] offset:64
	v_mul_f32_e32 v20, v20, v214
	v_mul_f32_e32 v21, v21, v214
	v_mul_f32_e32 v22, v22, v214
	v_mul_f32_e32 v23, v23, v214
	v_mul_f32_e32 v20, 0xbfb8aa3b, v20
	v_mul_f32_e32 v21, 0xbfb8aa3b, v21
	v_mul_f32_e32 v22, 0xbfb8aa3b, v22
	v_mul_f32_e32 v23, 0xbfb8aa3b, v23
	v_exp_f32_e32 v20, v20
	v_exp_f32_e32 v21, v21
	v_exp_f32_e32 v22, v22
	v_exp_f32_e32 v23, v23
	v_add_f32_e32 v20, 1.0, v20
	v_add_f32_e32 v21, 1.0, v21
	v_add_f32_e32 v22, 1.0, v22
	v_add_f32_e32 v23, 1.0, v23
	v_rcp_f32_e32 v220, v20
	v_rcp_f32_e32 v221, v21
	v_rcp_f32_e32 v222, v22
	v_rcp_f32_e32 v223, v23
	v_fma_f32 v224, -v20, v220, 1.0
	v_fma_f32 v225, -v21, v221, 1.0
	v_fma_f32 v226, -v22, v222, 1.0
	v_fma_f32 v227, -v23, v223, 1.0
	v_fma_f32 v20, v224, v220, v220
	v_fma_f32 v21, v225, v221, v221
	v_fma_f32 v22, v226, v222, v222
	v_fma_f32 v23, v227, v223, v223
	v_lshlrev_b32_e32 v230, 16, v202
	v_and_b32_e32 v202, 0xffff0000, v202
	v_lshlrev_b32_e32 v231, 16, v203
	v_and_b32_e32 v203, 0xffff0000, v203
	v_lshlrev_b32_e32 v232, 16, v204
	v_and_b32_e32 v204, 0xffff0000, v204
	v_lshlrev_b32_e32 v233, 16, v205
	v_and_b32_e32 v205, 0xffff0000, v205
	v_fma_f32 v20, v20, v232, v230
	v_fma_f32 v21, v21, v204, v202
	v_fma_f32 v22, v22, v233, v231
	v_fma_f32 v23, v23, v205, v203
	global_store_dwordx4 v252, v[20:23], s[42:43] offset:512
	v_mul_f32_e32 v16, v16, v214
	v_mul_f32_e32 v17, v17, v214
	v_mul_f32_e32 v18, v18, v214
	v_mul_f32_e32 v19, v19, v214
	v_mul_f32_e32 v16, 0xbfb8aa3b, v16
	v_mul_f32_e32 v17, 0xbfb8aa3b, v17
	v_mul_f32_e32 v18, 0xbfb8aa3b, v18
	v_mul_f32_e32 v19, 0xbfb8aa3b, v19
	v_exp_f32_e32 v16, v16
	v_exp_f32_e32 v17, v17
	v_exp_f32_e32 v18, v18
	v_exp_f32_e32 v19, v19
	v_add_f32_e32 v16, 1.0, v16
	v_add_f32_e32 v17, 1.0, v17
	v_add_f32_e32 v18, 1.0, v18
	v_add_f32_e32 v19, 1.0, v19
	v_rcp_f32_e32 v220, v16
	v_rcp_f32_e32 v221, v17
	v_rcp_f32_e32 v222, v18
	v_rcp_f32_e32 v223, v19
	v_fma_f32 v224, -v16, v220, 1.0
	v_fma_f32 v225, -v17, v221, 1.0
	v_fma_f32 v226, -v18, v222, 1.0
	v_fma_f32 v227, -v19, v223, 1.0
	v_fma_f32 v16, v224, v220, v220
	v_fma_f32 v17, v225, v221, v221
	v_fma_f32 v18, v226, v222, v222
	v_fma_f32 v19, v227, v223, v223
	v_lshlrev_b32_e32 v230, 16, v134
	v_and_b32_e32 v134, 0xffff0000, v134
	v_lshlrev_b32_e32 v231, 16, v135
	v_and_b32_e32 v135, 0xffff0000, v135
	v_lshlrev_b32_e32 v232, 16, v136
	v_and_b32_e32 v136, 0xffff0000, v136
	v_lshlrev_b32_e32 v233, 16, v137
	v_and_b32_e32 v137, 0xffff0000, v137
	v_fma_f32 v16, v16, v232, v230
	v_fma_f32 v17, v17, v136, v134
	v_fma_f32 v18, v18, v233, v231
	v_fma_f32 v19, v19, v137, v135
	global_store_dwordx4 v252, v[16:19], s[42:43] offset:576
	v_add_u32_e32 v188, 0xb0000, v140
	v_mul_f32_e32 v12, v12, v215
	v_mul_f32_e32 v13, v13, v215
	v_mul_f32_e32 v14, v14, v215
	v_mul_f32_e32 v15, v15, v215
	v_mul_f32_e32 v12, 0xbfb8aa3b, v12
	v_mul_f32_e32 v13, 0xbfb8aa3b, v13
	v_mul_f32_e32 v14, 0xbfb8aa3b, v14
	v_mul_f32_e32 v15, 0xbfb8aa3b, v15
	v_exp_f32_e32 v12, v12
	v_exp_f32_e32 v13, v13
	v_exp_f32_e32 v14, v14
	v_exp_f32_e32 v15, v15
	v_add_f32_e32 v12, 1.0, v12
	v_add_f32_e32 v13, 1.0, v13
	v_add_f32_e32 v14, 1.0, v14
	v_add_f32_e32 v15, 1.0, v15
	v_rcp_f32_e32 v220, v12
	v_rcp_f32_e32 v221, v13
	v_rcp_f32_e32 v222, v14
	v_rcp_f32_e32 v223, v15
	v_fma_f32 v224, -v12, v220, 1.0
	v_fma_f32 v225, -v13, v221, 1.0
	v_fma_f32 v226, -v14, v222, 1.0
	v_fma_f32 v227, -v15, v223, 1.0
	v_fma_f32 v12, v224, v220, v220
	v_fma_f32 v13, v225, v221, v221
	v_fma_f32 v14, v226, v222, v222
	v_fma_f32 v15, v227, v223, v223
	v_lshlrev_b32_e32 v230, 16, v138
	v_and_b32_e32 v138, 0xffff0000, v138
	v_lshlrev_b32_e32 v231, 16, v139
	v_and_b32_e32 v139, 0xffff0000, v139
	v_lshlrev_b32_e32 v232, 16, v142
	v_and_b32_e32 v142, 0xffff0000, v142
	v_lshlrev_b32_e32 v233, 16, v143
	v_and_b32_e32 v143, 0xffff0000, v143
	v_fma_f32 v12, v12, v232, v230
	v_fma_f32 v13, v13, v142, v138
	v_fma_f32 v14, v14, v233, v231
	v_fma_f32 v15, v15, v143, v139
	v_lshlrev_b32_e32 v252, 1, v188
	global_store_dwordx4 v252, v[12:15], s[42:43] offset:0
	v_mul_f32_e32 v8, v8, v215
	v_mul_f32_e32 v9, v9, v215
	v_mul_f32_e32 v10, v10, v215
	v_mul_f32_e32 v11, v11, v215
	v_mul_f32_e32 v8, 0xbfb8aa3b, v8
	v_mul_f32_e32 v9, 0xbfb8aa3b, v9
	v_mul_f32_e32 v10, 0xbfb8aa3b, v10
	v_mul_f32_e32 v11, 0xbfb8aa3b, v11
	v_exp_f32_e32 v8, v8
	v_exp_f32_e32 v9, v9
	v_exp_f32_e32 v10, v10
	v_exp_f32_e32 v11, v11
	v_add_f32_e32 v8, 1.0, v8
	v_add_f32_e32 v9, 1.0, v9
	v_add_f32_e32 v10, 1.0, v10
	v_add_f32_e32 v11, 1.0, v11
	v_rcp_f32_e32 v220, v8
	v_rcp_f32_e32 v221, v9
	v_rcp_f32_e32 v222, v10
	v_rcp_f32_e32 v223, v11
	v_fma_f32 v224, -v8, v220, 1.0
	v_fma_f32 v225, -v9, v221, 1.0
	v_fma_f32 v226, -v10, v222, 1.0
	v_fma_f32 v227, -v11, v223, 1.0
	v_fma_f32 v8, v224, v220, v220
	v_fma_f32 v9, v225, v221, v221
	v_fma_f32 v10, v226, v222, v222
	v_fma_f32 v11, v227, v223, v223
	v_lshlrev_b32_e32 v230, 16, v144
	v_and_b32_e32 v144, 0xffff0000, v144
	v_lshlrev_b32_e32 v231, 16, v145
	v_and_b32_e32 v145, 0xffff0000, v145
	v_lshlrev_b32_e32 v232, 16, v190
	v_and_b32_e32 v190, 0xffff0000, v190
	v_lshlrev_b32_e32 v233, 16, v191
	v_and_b32_e32 v191, 0xffff0000, v191
	v_fma_f32 v8, v8, v232, v230
	v_fma_f32 v9, v9, v190, v144
	v_fma_f32 v10, v10, v233, v231
	v_fma_f32 v11, v11, v191, v145
	global_store_dwordx4 v252, v[8:11], s[42:43] offset:64
	v_mul_f32_e32 v4, v4, v215
	v_mul_f32_e32 v5, v5, v215
	v_mul_f32_e32 v6, v6, v215
	v_mul_f32_e32 v7, v7, v215
	v_mul_f32_e32 v4, 0xbfb8aa3b, v4
	v_mul_f32_e32 v5, 0xbfb8aa3b, v5
	v_mul_f32_e32 v6, 0xbfb8aa3b, v6
	v_mul_f32_e32 v7, 0xbfb8aa3b, v7
	v_exp_f32_e32 v4, v4
	v_exp_f32_e32 v5, v5
	v_exp_f32_e32 v6, v6
	v_exp_f32_e32 v7, v7
	v_add_f32_e32 v4, 1.0, v4
	v_add_f32_e32 v5, 1.0, v5
	v_add_f32_e32 v6, 1.0, v6
	v_add_f32_e32 v7, 1.0, v7
	v_rcp_f32_e32 v220, v4
	v_rcp_f32_e32 v221, v5
	v_rcp_f32_e32 v222, v6
	v_rcp_f32_e32 v223, v7
	v_fma_f32 v224, -v4, v220, 1.0
	v_fma_f32 v225, -v5, v221, 1.0
	v_fma_f32 v226, -v6, v222, 1.0
	v_fma_f32 v227, -v7, v223, 1.0
	v_fma_f32 v4, v224, v220, v220
	v_fma_f32 v5, v225, v221, v221
	v_fma_f32 v6, v226, v222, v222
	v_fma_f32 v7, v227, v223, v223
	v_lshlrev_b32_e32 v230, 16, v194
	v_and_b32_e32 v194, 0xffff0000, v194
	v_lshlrev_b32_e32 v231, 16, v195
	v_and_b32_e32 v195, 0xffff0000, v195
	v_lshlrev_b32_e32 v232, 16, v248
	v_and_b32_e32 v248, 0xffff0000, v248
	v_lshlrev_b32_e32 v233, 16, v249
	v_and_b32_e32 v249, 0xffff0000, v249
	v_fma_f32 v4, v4, v232, v230
	v_fma_f32 v5, v5, v248, v194
	v_fma_f32 v6, v6, v233, v231
	v_fma_f32 v7, v7, v249, v195
	global_store_dwordx4 v252, v[4:7], s[42:43] offset:512
	v_mul_f32_e32 v0, v0, v215
	v_mul_f32_e32 v1, v1, v215
	v_mul_f32_e32 v2, v2, v215
	v_mul_f32_e32 v3, v3, v215
	v_mul_f32_e32 v0, 0xbfb8aa3b, v0
	v_mul_f32_e32 v1, 0xbfb8aa3b, v1
	v_mul_f32_e32 v2, 0xbfb8aa3b, v2
	v_mul_f32_e32 v3, 0xbfb8aa3b, v3
	v_exp_f32_e32 v0, v0
	v_exp_f32_e32 v1, v1
	v_exp_f32_e32 v2, v2
	v_exp_f32_e32 v3, v3
	v_add_f32_e32 v0, 1.0, v0
	v_add_f32_e32 v1, 1.0, v1
	v_add_f32_e32 v2, 1.0, v2
	v_add_f32_e32 v3, 1.0, v3
	v_rcp_f32_e32 v220, v0
	v_rcp_f32_e32 v221, v1
	v_rcp_f32_e32 v222, v2
	v_rcp_f32_e32 v223, v3
	v_fma_f32 v224, -v0, v220, 1.0
	v_fma_f32 v225, -v1, v221, 1.0
	v_fma_f32 v226, -v2, v222, 1.0
	v_fma_f32 v227, -v3, v223, 1.0
	v_fma_f32 v0, v224, v220, v220
	v_fma_f32 v1, v225, v221, v221
	v_fma_f32 v2, v226, v222, v222
	v_fma_f32 v3, v227, v223, v223
	v_lshlrev_b32_e32 v230, 16, v150
	v_and_b32_e32 v150, 0xffff0000, v150
	v_lshlrev_b32_e32 v231, 16, v151
	v_and_b32_e32 v151, 0xffff0000, v151
	v_lshlrev_b32_e32 v232, 16, v234
	v_and_b32_e32 v234, 0xffff0000, v234
	v_lshlrev_b32_e32 v233, 16, v235
	v_and_b32_e32 v235, 0xffff0000, v235
	v_fma_f32 v0, v0, v232, v230
	v_fma_f32 v1, v1, v234, v150
	v_fma_f32 v2, v2, v233, v231
	v_fma_f32 v3, v3, v235, v151
	global_store_dwordx4 v252, v[0:3], s[42:43] offset:576
	v_readlane_b32 s2, v255, 21
	v_readlane_b32 s3, v255, 22
	s_and_b64 vcc, exec, s[38:39]
	s_cbranch_vccz .LBB0_658
	s_waitcnt vmcnt(0)
	v_readlane_b32 s40, v255, 32
	s_mov_b32 s48, s2
	s_cmpk_gt_u32 s95, 0xff
	v_readlane_b32 s41, v255, 33
	s_cbranch_scc1 .LBB0_669
	s_barrier
